# GEMM loader phases: LDS-DMA pieces issued before the fragment ds_reads in every mainloop phase
# speedup vs baseline: 1.0009x; 1.0009x over previous
; #define STAGE(P, BASE, br, kt) do { const bf16_t* g_ = (BASE) + (size_t)(br) * K + (size_t)(kt) * 64; \
;         _Pragma("unroll") for (int i_ = 0; i_ < 2; ++i_) \
;             __builtin_amdgcn_global_load_lds((const unsigned*)(g_ + gofs[i_]), (lds_ptr_t)((P) + wb + i_ * 8192), 16, 0, 0); } while (0)
; #define LDA(dst, b, hh) _Pragma("unroll") for (int m = 0; m < 4; ++m) _Pragma("unroll") for (int k = 0; k < 2; ++k) \
;         dst[m][k] = *(const bf16x8*)(SA(b, hh) + lds_byte(wr * 64 + m * 16 + fr, k * 32 + fq * 8))
; #define LDB(dst, b, hh) _Pragma("unroll") for (int n = 0; n < 2; ++n) _Pragma("unroll") for (int k = 0; k < 2; ++k) \
;         dst[n][k] = *(const bf16x8*)(SB(b, hh) + lds_byte(wc * 32 + n * 16 + fr, k * 32 + fq * 8))
; #define MMA(ai, bj, At_, Bt_) do { __builtin_amdgcn_s_setprio(1); \
;         _Pragma("unroll") for (int m = 0; m < 4; ++m) _Pragma("unroll") for (int n = 0; n < 2; ++n) _Pragma("unroll") for (int k = 0; k < 2; ++k) \
;             acc[ai][bj][m][n] = MFMA16(At_[m][k], Bt_[n][k], acc[ai][bj][m][n]); \
;         __builtin_amdgcn_s_setprio(0); } while (0)
; #define WAIT_V(n) asm volatile("s_waitcnt vmcnt(" #n ")" ::: "memory")
; #define WAIT_L(n) asm volatile("s_waitcnt lgkmcnt(" #n ")" ::: "memory")
; #define BAR __builtin_amdgcn_s_barrier()
; #define SCHED __builtin_amdgcn_sched_barrier(0)
; #define STAGE(P, BASE, br, kt) do { const int sg_ = (kt) >> 3; const bf16_t* g_ = (sg_ == 0 ? BASE##0 : sg_ == 1 ? BASE##1 : BASE##2) + (size_t)(br) * K + (size_t)((kt) & 7) * 64; \
;         _Pragma("unroll") for (int i_ = 0; i_ < 2; ++i_) \
;             __builtin_amdgcn_global_load_lds((const unsigned*)(g_ + gofs[i_]), (lds_ptr_t)((P) + wb + i_ * 8192), 16, 0, 0); } while (0)
; #define WAIT_V(n) asm volatile("s_waitcnt vmcnt(" #n ")" ::: "memory")
; DI void gemm8(f32x4 (&acc)[2][2][4][2], const bf16_t* __restrict__ Rm, const bf16_t* __restrict__ Cm, int K, char* shm) {
;     ...
;         LDB(B0, 0, 0); SCHED; LDA(At, 0, 0); STAGE(SA(1, 1), Rm, 128, tt + 1);
;         WAIT_L(8); BAR; WAIT_L(0); MMA(0, 0, At, B0); BAR; SCHED;
;         LDB(B1, 0, 1); STAGE(SB(0, 0), Cm, 0, tt + 2);
;         BAR; WAIT_L(0); MMA(0, 1, At, B1); BAR;
;         LDA(At, 0, 1); STAGE(SA(0, 0), Rm, 0, tt + 2);
;         BAR; WAIT_L(0); MMA(1, 0, At, B0); BAR; SCHED;
;         STAGE(SB(0, 1), Cm, 128, tt + 2);
;         WAIT_V(6); BAR; MMA(1, 1, At, B1); BAR;
.LBB0_26:
	v_lshl_add_u64 v[172:173], s[62:63], 0, v[138:139]
	v_readfirstlane_b32 s15, v166
	v_lshl_add_u64 v[228:229], v[172:173], 0, s[16:17]
	s_mov_b32 m0, s15
	v_lshl_add_u64 v[244:245], s[62:63], 0, v[140:141]
	v_readfirstlane_b32 s15, v165
	global_load_lds_dwordx4 v[228:229], off
	v_lshl_add_u64 v[228:229], v[244:245], 0, s[16:17]
	s_mov_b32 m0, s15
	s_nop 0
	global_load_lds_dwordx4 v[228:229], off
	ds_read_b128 v[168:171], v167
	ds_read_b128 v[184:187], v167 offset:1024
	ds_read_b128 v[188:191], v167 offset:2048
	ds_read_b128 v[192:195], v167 offset:3072
	ds_read_b128 v[196:199], v145
	ds_read_b128 v[200:203], v145 offset:1024
	ds_read_b128 v[204:207], v144
	ds_read_b128 v[208:211], v144 offset:1024
	ds_read_b128 v[212:215], v143
	ds_read_b128 v[216:219], v143 offset:1024
	ds_read_b128 v[220:223], v142
	ds_read_b128 v[224:227], v142 offset:1024
	s_waitcnt lgkmcnt(8)
	s_barrier
	s_waitcnt lgkmcnt(0)
	s_setprio 1
	s_waitcnt lgkmcnt(0)
	v_mfma_f32_16x16x32_bf16 v[126:129], v[196:199], v[168:171], v[126:129]
	v_mfma_f32_16x16x32_bf16 v[122:125], v[196:199], v[188:191], v[122:125]
	v_mfma_f32_16x16x32_bf16 v[118:121], v[204:207], v[168:171], v[118:121]
	v_mfma_f32_16x16x32_bf16 v[114:117], v[204:207], v[188:191], v[114:117]
	v_mfma_f32_16x16x32_bf16 v[110:113], v[212:215], v[168:171], v[110:113]
	v_mfma_f32_16x16x32_bf16 v[106:109], v[212:215], v[188:191], v[106:109]
	v_mfma_f32_16x16x32_bf16 v[102:105], v[220:223], v[168:171], v[102:105]
	v_mfma_f32_16x16x32_bf16 v[98:101], v[220:223], v[188:191], v[98:101]
	v_mfma_f32_16x16x32_bf16 v[126:129], v[200:203], v[184:187], v[126:129]
	v_mfma_f32_16x16x32_bf16 v[122:125], v[200:203], v[192:195], v[122:125]
	v_mfma_f32_16x16x32_bf16 v[118:121], v[208:211], v[184:187], v[118:121]
	v_mfma_f32_16x16x32_bf16 v[114:117], v[208:211], v[192:195], v[114:117]
	v_mfma_f32_16x16x32_bf16 v[110:113], v[216:219], v[184:187], v[110:113]
	v_mfma_f32_16x16x32_bf16 v[106:109], v[216:219], v[192:195], v[106:109]
	v_mfma_f32_16x16x32_bf16 v[102:105], v[224:227], v[184:187], v[102:105]
	v_mfma_f32_16x16x32_bf16 v[98:101], v[224:227], v[192:195], v[98:101]
	s_setprio 0
	s_barrier
	v_lshl_add_u64 v[246:247], s[62:63], 0, v[134:135]
	v_readfirstlane_b32 s15, v147
	v_lshl_add_u64 v[248:249], v[246:247], 0, s[90:91]
	s_mov_b32 m0, s15
	s_nop 0
	global_load_lds_dwordx4 v[248:249], off
	v_lshl_add_u64 v[248:249], s[62:63], 0, v[136:137]
	v_readfirstlane_b32 s15, v148
	v_lshl_add_u64 v[250:251], v[248:249], 0, s[90:91]
	s_mov_b32 m0, s15
	s_nop 0
	global_load_lds_dwordx4 v[250:251], off
	ds_read_b128 v[228:231], v164
	ds_read_b128 v[232:235], v164 offset:1024
	ds_read_b128 v[236:239], v164 offset:2048
	ds_read_b128 v[240:243], v164 offset:3072
	s_barrier
	s_waitcnt lgkmcnt(0)
	s_setprio 1
	s_waitcnt lgkmcnt(0)
	v_mfma_f32_16x16x32_bf16 v[94:97], v[196:199], v[228:231], v[94:97]
	v_mfma_f32_16x16x32_bf16 v[90:93], v[196:199], v[236:239], v[90:93]
	v_mfma_f32_16x16x32_bf16 v[86:89], v[204:207], v[228:231], v[86:89]
	v_mfma_f32_16x16x32_bf16 v[82:85], v[204:207], v[236:239], v[82:85]
	v_mfma_f32_16x16x32_bf16 v[78:81], v[212:215], v[228:231], v[78:81]
	v_mfma_f32_16x16x32_bf16 v[74:77], v[212:215], v[236:239], v[74:77]
	v_mfma_f32_16x16x32_bf16 v[70:73], v[220:223], v[228:231], v[70:73]
	v_mfma_f32_16x16x32_bf16 v[66:69], v[220:223], v[236:239], v[66:69]
	v_mfma_f32_16x16x32_bf16 v[94:97], v[200:203], v[232:235], v[94:97]
	v_mfma_f32_16x16x32_bf16 v[90:93], v[200:203], v[240:243], v[90:93]
	v_mfma_f32_16x16x32_bf16 v[86:89], v[208:211], v[232:235], v[86:89]
	v_mfma_f32_16x16x32_bf16 v[82:85], v[208:211], v[240:243], v[82:85]
	v_mfma_f32_16x16x32_bf16 v[78:81], v[216:219], v[232:235], v[78:81]
	v_mfma_f32_16x16x32_bf16 v[74:77], v[216:219], v[240:243], v[74:77]
	v_mfma_f32_16x16x32_bf16 v[70:73], v[224:227], v[232:235], v[70:73]
	v_mfma_f32_16x16x32_bf16 v[66:69], v[224:227], v[240:243], v[66:69]
	s_setprio 0
	v_readfirstlane_b32 s15, v146
	v_lshl_add_u64 v[250:251], v[172:173], 0, s[28:29]
	s_mov_b32 m0, s15
	v_readfirstlane_b32 s15, v150
	s_barrier
	global_load_lds_dwordx4 v[250:251], off
	v_lshl_add_u64 v[250:251], v[244:245], 0, s[28:29]
	s_mov_b32 m0, s15
	s_nop 0
	global_load_lds_dwordx4 v[250:251], off
	ds_read_b128 v[196:199], v145 offset:16384
	ds_read_b128 v[200:203], v145 offset:17408
	ds_read_b128 v[204:207], v144 offset:16384
	ds_read_b128 v[208:211], v144 offset:17408
	ds_read_b128 v[212:215], v143 offset:16384
	ds_read_b128 v[216:219], v143 offset:17408
	ds_read_b128 v[220:223], v142 offset:16384
	ds_read_b128 v[224:227], v142 offset:17408
	s_barrier
	s_waitcnt lgkmcnt(0)
	s_setprio 1
	s_waitcnt lgkmcnt(0)
	v_mfma_f32_16x16x32_bf16 v[62:65], v[196:199], v[168:171], v[62:65]
	v_mfma_f32_16x16x32_bf16 v[58:61], v[196:199], v[188:191], v[58:61]
	v_mfma_f32_16x16x32_bf16 v[54:57], v[204:207], v[168:171], v[54:57]
	v_mfma_f32_16x16x32_bf16 v[50:53], v[204:207], v[188:191], v[50:53]
	v_mfma_f32_16x16x32_bf16 v[46:49], v[212:215], v[168:171], v[46:49]
	v_mfma_f32_16x16x32_bf16 v[42:45], v[212:215], v[188:191], v[42:45]
	v_mfma_f32_16x16x32_bf16 v[38:41], v[220:223], v[168:171], v[38:41]
	v_mfma_f32_16x16x32_bf16 v[34:37], v[220:223], v[188:191], v[34:37]
	v_mfma_f32_16x16x32_bf16 v[62:65], v[200:203], v[184:187], v[62:65]
	v_mfma_f32_16x16x32_bf16 v[58:61], v[200:203], v[192:195], v[58:61]
	v_mfma_f32_16x16x32_bf16 v[54:57], v[208:211], v[184:187], v[54:57]
	v_mfma_f32_16x16x32_bf16 v[50:53], v[208:211], v[192:195], v[50:53]
	v_mfma_f32_16x16x32_bf16 v[46:49], v[216:219], v[184:187], v[46:49]
	v_mfma_f32_16x16x32_bf16 v[42:45], v[216:219], v[192:195], v[42:45]
	v_mfma_f32_16x16x32_bf16 v[38:41], v[224:227], v[184:187], v[38:41]
	v_mfma_f32_16x16x32_bf16 v[34:37], v[224:227], v[192:195], v[34:37]
	s_setprio 0
	s_barrier
; #define STAGE(P, BASE, br, kt) do { const bf16_t* g_ = (BASE) + (size_t)(br) * K + (size_t)(kt) * 64; \
;         _Pragma("unroll") for (int i_ = 0; i_ < 2; ++i_) \
;             __builtin_amdgcn_global_load_lds((const unsigned*)(g_ + gofs[i_]), (lds_ptr_t)((P) + wb + i_ * 8192), 16, 0, 0); } while (0)
; #define LDA(dst, b, hh) _Pragma("unroll") for (int m = 0; m < 4; ++m) _Pragma("unroll") for (int k = 0; k < 2; ++k) \
;         dst[m][k] = *(const bf16x8*)(SA(b, hh) + lds_byte(wr * 64 + m * 16 + fr, k * 32 + fq * 8))
; #define LDB(dst, b, hh) _Pragma("unroll") for (int n = 0; n < 2; ++n) _Pragma("unroll") for (int k = 0; k < 2; ++k) \
;         dst[n][k] = *(const bf16x8*)(SB(b, hh) + lds_byte(wc * 32 + n * 16 + fr, k * 32 + fq * 8))
; #define MMA(ai, bj, At_, Bt_) do { __builtin_amdgcn_s_setprio(1); \
;         _Pragma("unroll") for (int m = 0; m < 4; ++m) _Pragma("unroll") for (int n = 0; n < 2; ++n) _Pragma("unroll") for (int k = 0; k < 2; ++k) \
;             acc[ai][bj][m][n] = MFMA16(At_[m][k], Bt_[n][k], acc[ai][bj][m][n]); \
;         __builtin_amdgcn_s_setprio(0); } while (0)
; #define WAIT_V(n) asm volatile("s_waitcnt vmcnt(" #n ")" ::: "memory")
; #define WAIT_L(n) asm volatile("s_waitcnt lgkmcnt(" #n ")" ::: "memory")
; #define BAR __builtin_amdgcn_s_barrier()
; #define SCHED __builtin_amdgcn_sched_barrier(0)
; #define STAGE(P, BASE, br, kt) do { const int sg_ = (kt) >> 3; const bf16_t* g_ = (sg_ == 0 ? BASE##0 : sg_ == 1 ? BASE##1 : BASE##2) + (size_t)(br) * K + (size_t)((kt) & 7) * 64; \
;         _Pragma("unroll") for (int i_ = 0; i_ < 2; ++i_) \
;             __builtin_amdgcn_global_load_lds((const unsigned*)(g_ + gofs[i_]), (lds_ptr_t)((P) + wb + i_ * 8192), 16, 0, 0); } while (0)
; #define WAIT_V(n) asm volatile("s_waitcnt vmcnt(" #n ")" ::: "memory")
; DI void gemm8(f32x4 (&acc)[2][2][4][2], const bf16_t* __restrict__ Rm, const bf16_t* __restrict__ Cm, int K, char* shm) {
;     ...
;         STAGE(SB(0, 1), Cm, 128, tt + 2);
;         WAIT_V(6); BAR; MMA(1, 1, At, B1); BAR;
;         LDB(B0, 1, 0); SCHED; LDA(At, 1, 0); STAGE(SA(0, 1), Rm, 128, tt + 2);
;         WAIT_L(8); BAR; WAIT_L(0); MMA(0, 0, At, B0); BAR; SCHED;
;         LDB(B1, 1, 1); STAGE(SB(1, 0), Cm, 0, tt + 3);
;         BAR; WAIT_L(0); MMA(0, 1, At, B1); BAR;
;         LDA(At, 1, 1); STAGE(SA(1, 0), Rm, 0, tt + 3);
;         BAR; WAIT_L(0); MMA(1, 0, At, B0); BAR; SCHED;
	v_readfirstlane_b32 s15, v151
	v_lshl_add_u64 v[168:169], v[246:247], 0, s[76:77]
	s_mov_b32 m0, s15
	v_readfirstlane_b32 s15, v152
	global_load_lds_dwordx4 v[168:169], off
	v_lshl_add_u64 v[168:169], v[248:249], 0, s[76:77]
	s_mov_b32 m0, s15
	s_nop 0
	global_load_lds_dwordx4 v[168:169], off
	s_waitcnt vmcnt(6)
	s_barrier
	s_setprio 1
	v_mfma_f32_16x16x32_bf16 v[30:33], v[196:199], v[228:231], v[30:33]
	v_mfma_f32_16x16x32_bf16 v[26:29], v[196:199], v[236:239], v[26:29]
	v_mfma_f32_16x16x32_bf16 v[22:25], v[204:207], v[228:231], v[22:25]
	v_mfma_f32_16x16x32_bf16 v[18:21], v[204:207], v[236:239], v[18:21]
	v_mfma_f32_16x16x32_bf16 v[14:17], v[212:215], v[228:231], v[14:17]
	v_mfma_f32_16x16x32_bf16 v[10:13], v[212:215], v[236:239], v[10:13]
	v_mfma_f32_16x16x32_bf16 v[6:9], v[220:223], v[228:231], v[6:9]
	v_mfma_f32_16x16x32_bf16 v[2:5], v[220:223], v[236:239], v[2:5]
	v_mfma_f32_16x16x32_bf16 v[30:33], v[200:203], v[232:235], v[30:33]
	v_mfma_f32_16x16x32_bf16 v[26:29], v[200:203], v[240:243], v[26:29]
	v_mfma_f32_16x16x32_bf16 v[22:25], v[208:211], v[232:235], v[22:25]
	v_mfma_f32_16x16x32_bf16 v[18:21], v[208:211], v[240:243], v[18:21]
	v_mfma_f32_16x16x32_bf16 v[14:17], v[216:219], v[232:235], v[14:17]
	v_mfma_f32_16x16x32_bf16 v[10:13], v[216:219], v[240:243], v[10:13]
	v_mfma_f32_16x16x32_bf16 v[6:9], v[224:227], v[232:235], v[6:9]
	v_mfma_f32_16x16x32_bf16 v[2:5], v[224:227], v[240:243], v[2:5]
	s_setprio 0
	s_barrier
	v_readfirstlane_b32 s15, v153
	v_lshl_add_u64 v[228:229], v[172:173], 0, s[30:31]
	s_mov_b32 m0, s15
	v_readfirstlane_b32 s15, v154
	global_load_lds_dwordx4 v[228:229], off
	v_lshl_add_u64 v[228:229], v[244:245], 0, s[30:31]
	s_mov_b32 m0, s15
	s_nop 0
	global_load_lds_dwordx4 v[228:229], off
	ds_read_b128 v[168:171], v155
	ds_read_b128 v[184:187], v155 offset:1024
	ds_read_b128 v[188:191], v155 offset:2048
	ds_read_b128 v[192:195], v155 offset:3072
	ds_read_b128 v[196:199], v145 offset:32768
	ds_read_b128 v[200:203], v145 offset:33792
	ds_read_b128 v[204:207], v144 offset:32768
	ds_read_b128 v[208:211], v144 offset:33792
	ds_read_b128 v[212:215], v143 offset:32768
	ds_read_b128 v[216:219], v143 offset:33792
	ds_read_b128 v[220:223], v142 offset:32768
	ds_read_b128 v[224:227], v142 offset:33792
	s_waitcnt lgkmcnt(8)
	s_barrier
	s_waitcnt lgkmcnt(0)
	s_setprio 1
	s_waitcnt lgkmcnt(0)
	v_mfma_f32_16x16x32_bf16 v[126:129], v[196:199], v[168:171], v[126:129]
	v_mfma_f32_16x16x32_bf16 v[122:125], v[196:199], v[188:191], v[122:125]
	v_mfma_f32_16x16x32_bf16 v[118:121], v[204:207], v[168:171], v[118:121]
	v_mfma_f32_16x16x32_bf16 v[114:117], v[204:207], v[188:191], v[114:117]
	v_mfma_f32_16x16x32_bf16 v[110:113], v[212:215], v[168:171], v[110:113]
	v_mfma_f32_16x16x32_bf16 v[106:109], v[212:215], v[188:191], v[106:109]
	v_mfma_f32_16x16x32_bf16 v[102:105], v[220:223], v[168:171], v[102:105]
	v_mfma_f32_16x16x32_bf16 v[98:101], v[220:223], v[188:191], v[98:101]
	v_mfma_f32_16x16x32_bf16 v[126:129], v[200:203], v[184:187], v[126:129]
	v_mfma_f32_16x16x32_bf16 v[122:125], v[200:203], v[192:195], v[122:125]
	v_mfma_f32_16x16x32_bf16 v[118:121], v[208:211], v[184:187], v[118:121]
	v_mfma_f32_16x16x32_bf16 v[114:117], v[208:211], v[192:195], v[114:117]
	v_mfma_f32_16x16x32_bf16 v[110:113], v[216:219], v[184:187], v[110:113]
	v_mfma_f32_16x16x32_bf16 v[106:109], v[216:219], v[192:195], v[106:109]
	v_mfma_f32_16x16x32_bf16 v[102:105], v[224:227], v[184:187], v[102:105]
	v_mfma_f32_16x16x32_bf16 v[98:101], v[224:227], v[192:195], v[98:101]
	s_setprio 0
	s_barrier
	v_readfirstlane_b32 s15, v156
	v_lshl_add_u64 v[250:251], v[246:247], 0, s[72:73]
	s_mov_b32 m0, s15
	v_readfirstlane_b32 s15, v157
	global_load_lds_dwordx4 v[250:251], off
	v_lshl_add_u64 v[250:251], v[248:249], 0, s[72:73]
	s_mov_b32 m0, s15
	s_nop 0
	global_load_lds_dwordx4 v[250:251], off
	ds_read_b128 v[228:231], v149
	ds_read_b128 v[232:235], v149 offset:1024
	ds_read_b128 v[236:239], v149 offset:2048
	ds_read_b128 v[240:243], v149 offset:3072
	s_barrier
	s_waitcnt lgkmcnt(0)
	s_setprio 1
	s_waitcnt lgkmcnt(0)
	v_mfma_f32_16x16x32_bf16 v[94:97], v[196:199], v[228:231], v[94:97]
	v_mfma_f32_16x16x32_bf16 v[90:93], v[196:199], v[236:239], v[90:93]
	v_mfma_f32_16x16x32_bf16 v[86:89], v[204:207], v[228:231], v[86:89]
	v_mfma_f32_16x16x32_bf16 v[82:85], v[204:207], v[236:239], v[82:85]
	v_mfma_f32_16x16x32_bf16 v[78:81], v[212:215], v[228:231], v[78:81]
	v_mfma_f32_16x16x32_bf16 v[74:77], v[212:215], v[236:239], v[74:77]
	v_mfma_f32_16x16x32_bf16 v[70:73], v[220:223], v[228:231], v[70:73]
	v_mfma_f32_16x16x32_bf16 v[66:69], v[220:223], v[236:239], v[66:69]
	v_mfma_f32_16x16x32_bf16 v[94:97], v[200:203], v[232:235], v[94:97]
	v_mfma_f32_16x16x32_bf16 v[90:93], v[200:203], v[240:243], v[90:93]
	v_mfma_f32_16x16x32_bf16 v[86:89], v[208:211], v[232:235], v[86:89]
	v_mfma_f32_16x16x32_bf16 v[82:85], v[208:211], v[240:243], v[82:85]
	v_mfma_f32_16x16x32_bf16 v[78:81], v[216:219], v[232:235], v[78:81]
	v_mfma_f32_16x16x32_bf16 v[74:77], v[216:219], v[240:243], v[74:77]
	v_mfma_f32_16x16x32_bf16 v[70:73], v[224:227], v[232:235], v[70:73]
	v_mfma_f32_16x16x32_bf16 v[66:69], v[224:227], v[240:243], v[66:69]
	s_setprio 0
	v_readfirstlane_b32 s15, v158
	v_lshl_add_u64 v[172:173], v[172:173], 0, s[34:35]
	s_mov_b32 m0, s15
	v_readfirstlane_b32 s15, v159
	s_barrier
	global_load_lds_dwordx4 v[172:173], off
	v_lshl_add_u64 v[172:173], v[244:245], 0, s[34:35]
	s_mov_b32 m0, s15
	s_nop 0
	global_load_lds_dwordx4 v[172:173], off
	ds_read_b128 v[196:199], v145 offset:49152
	ds_read_b128 v[200:203], v145 offset:50176
	ds_read_b128 v[204:207], v144 offset:49152
	ds_read_b128 v[208:211], v144 offset:50176
	ds_read_b128 v[212:215], v143 offset:49152
	ds_read_b128 v[216:219], v143 offset:50176
	ds_read_b128 v[220:223], v142 offset:49152
	ds_read_b128 v[224:227], v142 offset:50176
	s_barrier
; #define STAGE(P, BASE, br, kt) do { const bf16_t* g_ = (BASE) + (size_t)(br) * K + (size_t)(kt) * 64; \
;         _Pragma("unroll") for (int i_ = 0; i_ < 2; ++i_) \
;             __builtin_amdgcn_global_load_lds((const unsigned*)(g_ + gofs[i_]), (lds_ptr_t)((P) + wb + i_ * 8192), 16, 0, 0); } while (0)
; #define LDA(dst, b, hh) _Pragma("unroll") for (int m = 0; m < 4; ++m) _Pragma("unroll") for (int k = 0; k < 2; ++k) \
;         dst[m][k] = *(const bf16x8*)(SA(b, hh) + lds_byte(wr * 64 + m * 16 + fr, k * 32 + fq * 8))
; #define LDB(dst, b, hh) _Pragma("unroll") for (int n = 0; n < 2; ++n) _Pragma("unroll") for (int k = 0; k < 2; ++k) \
;         dst[n][k] = *(const bf16x8*)(SB(b, hh) + lds_byte(wc * 32 + n * 16 + fr, k * 32 + fq * 8))
; #define MMA(ai, bj, At_, Bt_) do { __builtin_amdgcn_s_setprio(1); \
;         _Pragma("unroll") for (int m = 0; m < 4; ++m) _Pragma("unroll") for (int n = 0; n < 2; ++n) _Pragma("unroll") for (int k = 0; k < 2; ++k) \
;             acc[ai][bj][m][n] = MFMA16(At_[m][k], Bt_[n][k], acc[ai][bj][m][n]); \
;         __builtin_amdgcn_s_setprio(0); } while (0)
; #define WAIT_V(n) asm volatile("s_waitcnt vmcnt(" #n ")" ::: "memory")
; #define WAIT_L(n) asm volatile("s_waitcnt lgkmcnt(" #n ")" ::: "memory")
; #define BAR __builtin_amdgcn_s_barrier()
; #define SCHED __builtin_amdgcn_sched_barrier(0)
; #define STAGE(P, BASE, br, kt) do { const int sg_ = (kt) >> 3; const bf16_t* g_ = (sg_ == 0 ? BASE##0 : sg_ == 1 ? BASE##1 : BASE##2) + (size_t)(br) * K + (size_t)((kt) & 7) * 64; \
;         _Pragma("unroll") for (int i_ = 0; i_ < 2; ++i_) \
;             __builtin_amdgcn_global_load_lds((const unsigned*)(g_ + gofs[i_]), (lds_ptr_t)((P) + wb + i_ * 8192), 16, 0, 0); } while (0)
; #define WAIT_V(n) asm volatile("s_waitcnt vmcnt(" #n ")" ::: "memory")
; #define WAIT_L(n) asm volatile("s_waitcnt lgkmcnt(" #n ")" ::: "memory")
; #define BAR __builtin_amdgcn_s_barrier()
; DI void gemm8(f32x4 (&acc)[2][2][4][2], const bf16_t* __restrict__ Rm, const bf16_t* __restrict__ Cm, int K, char* shm) {
;     ...
;         BAR; WAIT_L(0); MMA(1, 0, At, B0); BAR; SCHED;
;         STAGE(SB(1, 1), Cm, 128, tt + 3);
;         WAIT_V(6); BAR; MMA(1, 1, At, B1); BAR;
;     }
;     { LDB(B0, 0, 0); LDA(At, 0, 0); STAGE(SA(1, 1), Rm, 128, nt - 1);
;       BAR; WAIT_L(0); MMA(0, 0, At, B0); BAR;
;       LDB(B1, 0, 1); BAR; WAIT_L(0); MMA(0, 1, At, B1); BAR;
	s_waitcnt lgkmcnt(0)
	s_setprio 1
	s_waitcnt lgkmcnt(0)
	v_mfma_f32_16x16x32_bf16 v[62:65], v[196:199], v[168:171], v[62:65]
	v_mfma_f32_16x16x32_bf16 v[58:61], v[196:199], v[188:191], v[58:61]
	v_mfma_f32_16x16x32_bf16 v[54:57], v[204:207], v[168:171], v[54:57]
	v_mfma_f32_16x16x32_bf16 v[50:53], v[204:207], v[188:191], v[50:53]
	v_mfma_f32_16x16x32_bf16 v[46:49], v[212:215], v[168:171], v[46:49]
	v_mfma_f32_16x16x32_bf16 v[42:45], v[212:215], v[188:191], v[42:45]
	v_mfma_f32_16x16x32_bf16 v[38:41], v[220:223], v[168:171], v[38:41]
	v_mfma_f32_16x16x32_bf16 v[34:37], v[220:223], v[188:191], v[34:37]
	v_mfma_f32_16x16x32_bf16 v[62:65], v[200:203], v[184:187], v[62:65]
	v_mfma_f32_16x16x32_bf16 v[58:61], v[200:203], v[192:195], v[58:61]
	v_mfma_f32_16x16x32_bf16 v[54:57], v[208:211], v[184:187], v[54:57]
	v_mfma_f32_16x16x32_bf16 v[50:53], v[208:211], v[192:195], v[50:53]
	v_mfma_f32_16x16x32_bf16 v[46:49], v[216:219], v[184:187], v[46:49]
	v_mfma_f32_16x16x32_bf16 v[42:45], v[216:219], v[192:195], v[42:45]
	v_mfma_f32_16x16x32_bf16 v[38:41], v[224:227], v[184:187], v[38:41]
	v_mfma_f32_16x16x32_bf16 v[34:37], v[224:227], v[192:195], v[34:37]
	s_setprio 0
	s_barrier
	v_readfirstlane_b32 s15, v160
	v_lshl_add_u64 v[168:169], v[246:247], 0, s[88:89]
	s_mov_b32 m0, s15
	v_readfirstlane_b32 s15, v161
	global_load_lds_dwordx4 v[168:169], off
	v_lshl_add_u64 v[168:169], v[248:249], 0, s[88:89]
	s_mov_b32 m0, s15
	s_nop 0
	global_load_lds_dwordx4 v[168:169], off
	s_waitcnt vmcnt(6)
	s_barrier
	s_setprio 1
	v_mfma_f32_16x16x32_bf16 v[30:33], v[196:199], v[228:231], v[30:33]
	v_mfma_f32_16x16x32_bf16 v[26:29], v[196:199], v[236:239], v[26:29]
	v_mfma_f32_16x16x32_bf16 v[22:25], v[204:207], v[228:231], v[22:25]
	v_mfma_f32_16x16x32_bf16 v[18:21], v[204:207], v[236:239], v[18:21]
	v_mfma_f32_16x16x32_bf16 v[14:17], v[212:215], v[228:231], v[14:17]
	v_mfma_f32_16x16x32_bf16 v[10:13], v[212:215], v[236:239], v[10:13]
	v_mfma_f32_16x16x32_bf16 v[6:9], v[220:223], v[228:231], v[6:9]
	v_mfma_f32_16x16x32_bf16 v[2:5], v[220:223], v[236:239], v[2:5]
	v_mfma_f32_16x16x32_bf16 v[30:33], v[200:203], v[232:235], v[30:33]
	v_mfma_f32_16x16x32_bf16 v[26:29], v[200:203], v[240:243], v[26:29]
	v_mfma_f32_16x16x32_bf16 v[22:25], v[208:211], v[232:235], v[22:25]
	v_mfma_f32_16x16x32_bf16 v[18:21], v[208:211], v[240:243], v[18:21]
	v_mfma_f32_16x16x32_bf16 v[14:17], v[216:219], v[232:235], v[14:17]
	v_mfma_f32_16x16x32_bf16 v[10:13], v[216:219], v[240:243], v[10:13]
	v_mfma_f32_16x16x32_bf16 v[6:9], v[224:227], v[232:235], v[6:9]
	v_mfma_f32_16x16x32_bf16 v[2:5], v[224:227], v[240:243], v[2:5]
	s_setprio 0
	s_add_i32 s14, s14, 2
	v_lshl_add_u64 v[134:135], v[134:135], 0, s[90:91]
	v_lshl_add_u64 v[136:137], v[136:137], 0, s[90:91]
	v_lshl_add_u64 v[138:139], v[138:139], 0, s[90:91]
	s_cmp_lt_u32 s14, 12
	v_lshl_add_u64 v[140:141], v[140:141], 0, s[90:91]
	s_barrier
	s_cbranch_scc1 .LBB0_26
	s_add_u32 s12, s12, 0x40780
	s_addc_u32 s13, s13, 0
	v_readfirstlane_b32 s14, v166
	v_lshl_add_u64 v[130:131], v[130:131], 1, s[12:13]
	s_mov_b32 m0, s14
	ds_read_b128 v[134:137], v167
	ds_read_b128 v[138:141], v167 offset:1024
	ds_read_b128 v[150:153], v167 offset:2048
	ds_read_b128 v[156:159], v167 offset:3072
	ds_read_b128 v[168:171], v145
	ds_read_b128 v[184:187], v145 offset:1024
	ds_read_b128 v[188:191], v144
	ds_read_b128 v[192:195], v144 offset:1024
	ds_read_b128 v[196:199], v143
	ds_read_b128 v[200:203], v143 offset:1024
	ds_read_b128 v[204:207], v142
	ds_read_b128 v[208:211], v142 offset:1024
	global_load_lds_dwordx4 v[130:131], off
	v_lshl_add_u64 v[130:131], v[132:133], 1, s[12:13]
	v_readfirstlane_b32 s12, v165
	s_mov_b32 m0, s12
	s_nop 0
	global_load_lds_dwordx4 v[130:131], off
	s_barrier
	s_waitcnt lgkmcnt(0)
	s_setprio 1
	s_waitcnt lgkmcnt(0)
	v_mfma_f32_16x16x32_bf16 v[126:129], v[168:171], v[134:137], v[126:129]
	v_mfma_f32_16x16x32_bf16 v[122:125], v[168:171], v[150:153], v[122:125]
	v_mfma_f32_16x16x32_bf16 v[118:121], v[188:191], v[134:137], v[118:121]
	v_mfma_f32_16x16x32_bf16 v[110:113], v[196:199], v[134:137], v[110:113]
	v_mfma_f32_16x16x32_bf16 v[106:109], v[196:199], v[150:153], v[106:109]
	v_mfma_f32_16x16x32_bf16 v[102:105], v[204:207], v[134:137], v[102:105]
	v_mfma_f32_16x16x32_bf16 v[98:101], v[204:207], v[150:153], v[98:101]
	v_mfma_f32_16x16x32_bf16 v[126:129], v[184:187], v[138:141], v[126:129]
	v_mfma_f32_16x16x32_bf16 v[122:125], v[184:187], v[156:159], v[122:125]
	v_mfma_f32_16x16x32_bf16 v[118:121], v[192:195], v[138:141], v[118:121]
	v_mfma_f32_16x16x32_bf16 v[114:117], v[188:191], v[150:153], v[114:117]
	v_mfma_f32_16x16x32_bf16 v[110:113], v[200:203], v[138:141], v[110:113]
	v_mfma_f32_16x16x32_bf16 v[106:109], v[200:203], v[156:159], v[106:109]
	v_mfma_f32_16x16x32_bf16 v[102:105], v[208:211], v[138:141], v[102:105]
	v_mfma_f32_16x16x32_bf16 v[98:101], v[208:211], v[156:159], v[98:101]
	v_mfma_f32_16x16x32_bf16 v[130:133], v[192:195], v[156:159], v[114:117]
	s_setprio 0
	s_barrier
	s_nop 0
	ds_read_b128 v[114:117], v164
	ds_read_b128 v[212:215], v164 offset:1024
	ds_read_b128 v[216:219], v164 offset:2048
	ds_read_b128 v[164:167], v164 offset:3072
	s_barrier
; #define LDA(dst, b, hh) _Pragma("unroll") for (int m = 0; m < 4; ++m) _Pragma("unroll") for (int k = 0; k < 2; ++k) \
;         dst[m][k] = *(const bf16x8*)(SA(b, hh) + lds_byte(wr * 64 + m * 16 + fr, k * 32 + fq * 8))
; #define LDB(dst, b, hh) _Pragma("unroll") for (int n = 0; n < 2; ++n) _Pragma("unroll") for (int k = 0; k < 2; ++k) \
;         dst[n][k] = *(const bf16x8*)(SB(b, hh) + lds_byte(wc * 32 + n * 16 + fr, k * 32 + fq * 8))
; #define MMA(ai, bj, At_, Bt_) do { __builtin_amdgcn_s_setprio(1); \
;         _Pragma("unroll") for (int m = 0; m < 4; ++m) _Pragma("unroll") for (int n = 0; n < 2; ++n) _Pragma("unroll") for (int k = 0; k < 2; ++k) \
;             acc[ai][bj][m][n] = MFMA16(At_[m][k], Bt_[n][k], acc[ai][bj][m][n]); \
;         __builtin_amdgcn_s_setprio(0); } while (0)
; #define WAIT_V(n) asm volatile("s_waitcnt vmcnt(" #n ")" ::: "memory")
; #define WAIT_L(n) asm volatile("s_waitcnt lgkmcnt(" #n ")" ::: "memory")
; #define BAR __builtin_amdgcn_s_barrier()
; #define LDA(dst, b, hh) _Pragma("unroll") for (int m = 0; m < 4; ++m) _Pragma("unroll") for (int k = 0; k < 2; ++k) \
;         dst[m][k] = *(const bf16x8*)(SA(b, hh) + lds_byte(wr * 64 + m * 16 + fr, k * 32 + fq * 8))
; #define LDB(dst, b, hh) _Pragma("unroll") for (int n = 0; n < 2; ++n) _Pragma("unroll") for (int k = 0; k < 2; ++k) \
;         dst[n][k] = *(const bf16x8*)(SB(b, hh) + lds_byte(wc * 32 + n * 16 + fr, k * 32 + fq * 8))
; #define MMA(ai, bj, At_, Bt_) do { __builtin_amdgcn_s_setprio(1); \
;         _Pragma("unroll") for (int m = 0; m < 4; ++m) _Pragma("unroll") for (int n = 0; n < 2; ++n) _Pragma("unroll") for (int k = 0; k < 2; ++k) \
;             acc[ai][bj][m][n] = MFMA16(At_[m][k], Bt_[n][k], acc[ai][bj][m][n]); \
;         __builtin_amdgcn_s_setprio(0); } while (0)
; #define WAIT_V(n) asm volatile("s_waitcnt vmcnt(" #n ")" ::: "memory")
; #define WAIT_L(n) asm volatile("s_waitcnt lgkmcnt(" #n ")" ::: "memory")
; #define BAR __builtin_amdgcn_s_barrier()
; DI void gemm8(f32x4 (&acc)[2][2][4][2], const bf16_t* __restrict__ Rm, const bf16_t* __restrict__ Cm, int K, char* shm) {
;     ...
;       LDB(B1, 0, 1); BAR; WAIT_L(0); MMA(0, 1, At, B1); BAR;
;       LDA(At, 0, 1); WAIT_V(4); BAR; WAIT_L(0); MMA(1, 0, At, B0); MMA(1, 1, At, B1); BAR; }
;     { LDB(B0, 1, 0); LDA(At, 1, 0); WAIT_V(2); BAR; WAIT_L(0); MMA(0, 0, At, B0); BAR;
	s_waitcnt lgkmcnt(0)
	s_setprio 1
	s_waitcnt lgkmcnt(0)
	v_mfma_f32_16x16x32_bf16 v[78:81], v[196:199], v[114:117], v[78:81]
	v_mfma_f32_16x16x32_bf16 v[74:77], v[196:199], v[216:219], v[74:77]
	v_mfma_f32_16x16x32_bf16 v[70:73], v[204:207], v[114:117], v[70:73]
	v_mfma_f32_16x16x32_bf16 v[66:69], v[204:207], v[216:219], v[66:69]
	v_mfma_f32_16x16x32_bf16 v[94:97], v[168:171], v[114:117], v[94:97]
	v_mfma_f32_16x16x32_bf16 v[90:93], v[168:171], v[216:219], v[90:93]
	v_mfma_f32_16x16x32_bf16 v[86:89], v[188:191], v[114:117], v[86:89]
	v_mfma_f32_16x16x32_bf16 v[82:85], v[188:191], v[216:219], v[82:85]
	v_mfma_f32_16x16x32_bf16 v[78:81], v[200:203], v[212:215], v[78:81]
	v_mfma_f32_16x16x32_bf16 v[74:77], v[200:203], v[164:167], v[74:77]
	v_mfma_f32_16x16x32_bf16 v[70:73], v[208:211], v[212:215], v[70:73]
	v_mfma_f32_16x16x32_bf16 v[66:69], v[208:211], v[164:167], v[66:69]
	v_mfma_f32_16x16x32_bf16 v[220:223], v[184:187], v[212:215], v[94:97]
	v_mfma_f32_16x16x32_bf16 v[168:171], v[184:187], v[164:167], v[90:93]
	v_mfma_f32_16x16x32_bf16 v[184:187], v[192:195], v[212:215], v[86:89]
	v_mfma_f32_16x16x32_bf16 v[188:191], v[192:195], v[164:167], v[82:85]
	s_setprio 0
	s_barrier
	s_nop 0
	ds_read_b128 v[82:85], v145 offset:16384
	ds_read_b128 v[86:89], v145 offset:17408
	ds_read_b128 v[90:93], v144 offset:16384
	ds_read_b128 v[94:97], v144 offset:17408
	ds_read_b128 v[192:195], v143 offset:16384
	ds_read_b128 v[196:199], v143 offset:17408
	ds_read_b128 v[200:203], v142 offset:16384
	ds_read_b128 v[204:207], v142 offset:17408
	s_waitcnt vmcnt(4)
	s_barrier
	s_waitcnt lgkmcnt(0)
	s_setprio 1
	s_waitcnt lgkmcnt(0)
	v_mfma_f32_16x16x32_bf16 v[46:49], v[192:195], v[134:137], v[46:49]
	v_mfma_f32_16x16x32_bf16 v[42:45], v[192:195], v[150:153], v[42:45]
	v_mfma_f32_16x16x32_bf16 v[38:41], v[200:203], v[134:137], v[38:41]
	v_mfma_f32_16x16x32_bf16 v[34:37], v[200:203], v[150:153], v[34:37]
	v_mfma_f32_16x16x32_bf16 v[62:65], v[82:85], v[134:137], v[62:65]
	v_mfma_f32_16x16x32_bf16 v[58:61], v[82:85], v[150:153], v[58:61]
	v_mfma_f32_16x16x32_bf16 v[54:57], v[90:93], v[134:137], v[54:57]
	v_mfma_f32_16x16x32_bf16 v[50:53], v[90:93], v[150:153], v[50:53]
	v_mfma_f32_16x16x32_bf16 v[46:49], v[196:199], v[138:141], v[46:49]
	v_mfma_f32_16x16x32_bf16 v[42:45], v[196:199], v[156:159], v[42:45]
	v_mfma_f32_16x16x32_bf16 v[38:41], v[204:207], v[138:141], v[38:41]
	v_mfma_f32_16x16x32_bf16 v[34:37], v[204:207], v[156:159], v[34:37]
	v_mfma_f32_16x16x32_bf16 v[208:211], v[86:89], v[138:141], v[62:65]
	v_mfma_f32_16x16x32_bf16 v[224:227], v[86:89], v[156:159], v[58:61]
	v_mfma_f32_16x16x32_bf16 v[228:231], v[94:97], v[138:141], v[54:57]
	v_mfma_f32_16x16x32_bf16 v[232:235], v[94:97], v[156:159], v[50:53]
	s_setprio 0
	s_setprio 1
	v_mfma_f32_16x16x32_bf16 v[14:17], v[192:195], v[114:117], v[14:17]
	v_mfma_f32_16x16x32_bf16 v[10:13], v[192:195], v[216:219], v[10:13]
	v_mfma_f32_16x16x32_bf16 v[30:33], v[82:85], v[114:117], v[30:33]
	v_mfma_f32_16x16x32_bf16 v[26:29], v[82:85], v[216:219], v[26:29]
	v_mfma_f32_16x16x32_bf16 v[22:25], v[90:93], v[114:117], v[22:25]
	v_mfma_f32_16x16x32_bf16 v[18:21], v[90:93], v[216:219], v[18:21]
	v_mfma_f32_16x16x32_bf16 v[14:17], v[196:199], v[212:215], v[14:17]
	v_mfma_f32_16x16x32_bf16 v[10:13], v[196:199], v[164:167], v[10:13]
	v_mfma_f32_16x16x32_bf16 v[6:9], v[200:203], v[114:117], v[6:9]
	v_mfma_f32_16x16x32_bf16 v[2:5], v[200:203], v[216:219], v[2:5]
	v_mfma_f32_16x16x32_bf16 v[134:137], v[86:89], v[212:215], v[30:33]
	v_mfma_f32_16x16x32_bf16 v[138:141], v[86:89], v[164:167], v[26:29]
	v_mfma_f32_16x16x32_bf16 v[150:153], v[94:97], v[212:215], v[22:25]
	v_mfma_f32_16x16x32_bf16 v[156:159], v[94:97], v[164:167], v[18:21]
	v_mfma_f32_16x16x32_bf16 v[192:195], v[204:207], v[212:215], v[6:9]
	v_mfma_f32_16x16x32_bf16 v[164:167], v[204:207], v[164:167], v[2:5]
	s_setprio 0
	s_barrier
	s_nop 0
	ds_read_b128 v[2:5], v155
	ds_read_b128 v[6:9], v155 offset:1024
	ds_read_b128 v[196:199], v155 offset:2048
	ds_read_b128 v[200:203], v155 offset:3072
	ds_read_b128 v[18:21], v145 offset:32768
	ds_read_b128 v[22:25], v145 offset:33792
	ds_read_b128 v[26:29], v144 offset:32768
	ds_read_b128 v[30:33], v144 offset:33792
	ds_read_b128 v[62:65], v143 offset:32768
	ds_read_b128 v[204:207], v143 offset:33792
	ds_read_b128 v[212:215], v142 offset:32768
	ds_read_b128 v[216:219], v142 offset:33792
	s_waitcnt vmcnt(2)
	s_barrier
; #define LDA(dst, b, hh) _Pragma("unroll") for (int m = 0; m < 4; ++m) _Pragma("unroll") for (int k = 0; k < 2; ++k) \
;         dst[m][k] = *(const bf16x8*)(SA(b, hh) + lds_byte(wr * 64 + m * 16 + fr, k * 32 + fq * 8))
; #define LDB(dst, b, hh) _Pragma("unroll") for (int n = 0; n < 2; ++n) _Pragma("unroll") for (int k = 0; k < 2; ++k) \
;         dst[n][k] = *(const bf16x8*)(SB(b, hh) + lds_byte(wc * 32 + n * 16 + fr, k * 32 + fq * 8))
; #define MMA(ai, bj, At_, Bt_) do { __builtin_amdgcn_s_setprio(1); \
;         _Pragma("unroll") for (int m = 0; m < 4; ++m) _Pragma("unroll") for (int n = 0; n < 2; ++n) _Pragma("unroll") for (int k = 0; k < 2; ++k) \
;             acc[ai][bj][m][n] = MFMA16(At_[m][k], Bt_[n][k], acc[ai][bj][m][n]); \
;         __builtin_amdgcn_s_setprio(0); } while (0)
; #define WAIT_V(n) asm volatile("s_waitcnt vmcnt(" #n ")" ::: "memory")
; #define WAIT_L(n) asm volatile("s_waitcnt lgkmcnt(" #n ")" ::: "memory")
; #define BAR __builtin_amdgcn_s_barrier()
; #define LDA(dst, b, hh) _Pragma("unroll") for (int m = 0; m < 4; ++m) _Pragma("unroll") for (int k = 0; k < 2; ++k) \
;         dst[m][k] = *(const bf16x8*)(SA(b, hh) + lds_byte(wr * 64 + m * 16 + fr, k * 32 + fq * 8))
; #define LDB(dst, b, hh) _Pragma("unroll") for (int n = 0; n < 2; ++n) _Pragma("unroll") for (int k = 0; k < 2; ++k) \
;         dst[n][k] = *(const bf16x8*)(SB(b, hh) + lds_byte(wc * 32 + n * 16 + fr, k * 32 + fq * 8))
; #define MMA(ai, bj, At_, Bt_) do { __builtin_amdgcn_s_setprio(1); \
;         _Pragma("unroll") for (int m = 0; m < 4; ++m) _Pragma("unroll") for (int n = 0; n < 2; ++n) _Pragma("unroll") for (int k = 0; k < 2; ++k) \
;             acc[ai][bj][m][n] = MFMA16(At_[m][k], Bt_[n][k], acc[ai][bj][m][n]); \
;         __builtin_amdgcn_s_setprio(0); } while (0)
; #define WAIT_V(n) asm volatile("s_waitcnt vmcnt(" #n ")" ::: "memory")
; #define WAIT_L(n) asm volatile("s_waitcnt lgkmcnt(" #n ")" ::: "memory")
; #define BAR __builtin_amdgcn_s_barrier()
; DI void gemm8(f32x4 (&acc)[2][2][4][2], const bf16_t* __restrict__ Rm, const bf16_t* __restrict__ Cm, int K, char* shm) {
;     ...
;     { LDB(B0, 1, 0); LDA(At, 1, 0); WAIT_V(2); BAR; WAIT_L(0); MMA(0, 0, At, B0); BAR;
;       LDB(B1, 1, 1); WAIT_V(0); BAR; WAIT_L(0); MMA(0, 1, At, B1); BAR;
;       LDA(At, 1, 1); BAR; WAIT_L(0); MMA(1, 0, At, B0); MMA(1, 1, At, B1); BAR; }
;     if (wr == 0) BAR;
	s_waitcnt lgkmcnt(0)
	s_setprio 1
	s_waitcnt lgkmcnt(0)
	v_mfma_f32_16x16x32_bf16 v[50:53], v[18:21], v[2:5], v[126:129]
	v_mfma_f32_16x16x32_bf16 v[114:117], v[22:25], v[6:9], v[50:53]
	v_mfma_f32_16x16x32_bf16 v[50:53], v[18:21], v[196:199], v[122:125]
	v_mfma_f32_16x16x32_bf16 v[82:85], v[22:25], v[200:203], v[50:53]
	v_mfma_f32_16x16x32_bf16 v[50:53], v[26:29], v[2:5], v[118:121]
	v_mfma_f32_16x16x32_bf16 v[118:121], v[30:33], v[6:9], v[50:53]
	v_mfma_f32_16x16x32_bf16 v[50:53], v[26:29], v[196:199], v[130:133]
	v_mfma_f32_16x16x32_bf16 v[86:89], v[30:33], v[200:203], v[50:53]
	v_mfma_f32_16x16x32_bf16 v[50:53], v[62:65], v[2:5], v[110:113]
	v_mfma_f32_16x16x32_bf16 v[122:125], v[204:207], v[6:9], v[50:53]
	v_mfma_f32_16x16x32_bf16 v[50:53], v[62:65], v[196:199], v[106:109]
	v_mfma_f32_16x16x32_bf16 v[90:93], v[204:207], v[200:203], v[50:53]
	v_mfma_f32_16x16x32_bf16 v[50:53], v[212:215], v[2:5], v[102:105]
	v_mfma_f32_16x16x32_bf16 v[126:129], v[216:219], v[6:9], v[50:53]
	v_mfma_f32_16x16x32_bf16 v[50:53], v[212:215], v[196:199], v[98:101]
	v_mfma_f32_16x16x32_bf16 v[94:97], v[216:219], v[200:203], v[50:53]
	s_setprio 0
	s_barrier
	ds_read_b128 v[130:133], v149
	ds_read_b128 v[236:239], v149 offset:1024
	ds_read_b128 v[240:243], v149 offset:2048
	ds_read_b128 v[146:149], v149 offset:3072
	s_waitcnt vmcnt(0)
	s_barrier
	s_waitcnt lgkmcnt(0)
	s_setprio 1
	s_waitcnt lgkmcnt(0)
	v_mfma_f32_16x16x32_bf16 v[50:53], v[18:21], v[130:133], v[220:223]
	v_mfma_f32_16x16x32_bf16 v[18:21], v[18:21], v[240:243], v[168:171]
	v_mfma_f32_16x16x32_bf16 v[50:53], v[22:25], v[236:239], v[50:53]
	v_mfma_f32_16x16x32_bf16 v[18:21], v[22:25], v[146:149], v[18:21]
	v_mfma_f32_16x16x32_bf16 v[22:25], v[26:29], v[130:133], v[184:187]
	v_mfma_f32_16x16x32_bf16 v[54:57], v[30:33], v[236:239], v[22:25]
	v_mfma_f32_16x16x32_bf16 v[22:25], v[26:29], v[240:243], v[188:191]
	v_mfma_f32_16x16x32_bf16 v[22:25], v[30:33], v[146:149], v[22:25]
	v_mfma_f32_16x16x32_bf16 v[26:29], v[62:65], v[130:133], v[78:81]
	v_mfma_f32_16x16x32_bf16 v[30:33], v[212:215], v[130:133], v[70:73]
	v_mfma_f32_16x16x32_bf16 v[58:61], v[204:207], v[236:239], v[26:29]
	v_mfma_f32_16x16x32_bf16 v[26:29], v[62:65], v[240:243], v[74:77]
	v_mfma_f32_16x16x32_bf16 v[62:65], v[216:219], v[236:239], v[30:33]
	v_mfma_f32_16x16x32_bf16 v[30:33], v[212:215], v[240:243], v[66:69]
	v_mfma_f32_16x16x32_bf16 v[26:29], v[204:207], v[146:149], v[26:29]
	v_mfma_f32_16x16x32_bf16 v[30:33], v[216:219], v[146:149], v[30:33]
	s_setprio 0
	s_barrier
	ds_read_b128 v[168:171], v145 offset:49152
	ds_read_b128 v[184:187], v145 offset:50176
	ds_read_b128 v[188:191], v144 offset:49152
	ds_read_b128 v[204:207], v144 offset:50176
	ds_read_b128 v[212:215], v143 offset:49152
	ds_read_b128 v[216:219], v143 offset:50176
	ds_read_b128 v[220:223], v142 offset:49152
	ds_read_b128 v[142:145], v142 offset:50176
	s_barrier
	s_waitcnt lgkmcnt(0)
	s_setprio 1
	s_waitcnt lgkmcnt(0)
	v_mfma_f32_16x16x32_bf16 v[66:69], v[168:171], v[2:5], v[208:211]
	v_mfma_f32_16x16x32_bf16 v[70:73], v[188:191], v[2:5], v[228:231]
	v_mfma_f32_16x16x32_bf16 v[46:49], v[212:215], v[2:5], v[46:49]
	v_mfma_f32_16x16x32_bf16 v[2:5], v[220:223], v[2:5], v[38:41]
	v_mfma_f32_16x16x32_bf16 v[98:101], v[184:187], v[6:9], v[66:69]
	v_mfma_f32_16x16x32_bf16 v[66:69], v[168:171], v[196:199], v[224:227]
	v_mfma_f32_16x16x32_bf16 v[102:105], v[204:207], v[6:9], v[70:73]
	v_mfma_f32_16x16x32_bf16 v[70:73], v[188:191], v[196:199], v[232:235]
	v_mfma_f32_16x16x32_bf16 v[42:45], v[212:215], v[196:199], v[42:45]
	v_mfma_f32_16x16x32_bf16 v[110:113], v[142:145], v[6:9], v[2:5]
	v_mfma_f32_16x16x32_bf16 v[2:5], v[220:223], v[196:199], v[34:37]
	v_mfma_f32_16x16x32_bf16 v[66:69], v[184:187], v[200:203], v[66:69]
	v_mfma_f32_16x16x32_bf16 v[70:73], v[204:207], v[200:203], v[70:73]
	v_mfma_f32_16x16x32_bf16 v[106:109], v[216:219], v[6:9], v[46:49]
	v_mfma_f32_16x16x32_bf16 v[74:77], v[216:219], v[200:203], v[42:45]
	v_mfma_f32_16x16x32_bf16 v[78:81], v[142:145], v[200:203], v[2:5]
	s_setprio 0
	s_setprio 1
	v_mfma_f32_16x16x32_bf16 v[14:17], v[212:215], v[130:133], v[14:17]
	v_mfma_f32_16x16x32_bf16 v[2:5], v[168:171], v[130:133], v[134:137]
	v_mfma_f32_16x16x32_bf16 v[6:9], v[188:191], v[130:133], v[150:153]
	v_mfma_f32_16x16x32_bf16 v[42:45], v[216:219], v[236:239], v[14:17]
	v_mfma_f32_16x16x32_bf16 v[14:17], v[220:223], v[130:133], v[192:195]
	v_mfma_f32_16x16x32_bf16 v[34:37], v[184:187], v[236:239], v[2:5]
	v_mfma_f32_16x16x32_bf16 v[2:5], v[168:171], v[240:243], v[138:141]
	v_mfma_f32_16x16x32_bf16 v[38:41], v[204:207], v[236:239], v[6:9]
	v_mfma_f32_16x16x32_bf16 v[6:9], v[188:191], v[240:243], v[156:159]
	v_mfma_f32_16x16x32_bf16 v[10:13], v[212:215], v[240:243], v[10:13]
	v_mfma_f32_16x16x32_bf16 v[46:49], v[142:145], v[236:239], v[14:17]
	v_mfma_f32_16x16x32_bf16 v[14:17], v[220:223], v[240:243], v[164:167]
	v_mfma_f32_16x16x32_bf16 v[2:5], v[184:187], v[146:149], v[2:5]
	v_mfma_f32_16x16x32_bf16 v[6:9], v[204:207], v[146:149], v[6:9]
	v_mfma_f32_16x16x32_bf16 v[10:13], v[216:219], v[146:149], v[10:13]
	v_mfma_f32_16x16x32_bf16 v[14:17], v[142:145], v[146:149], v[14:17]
	s_setprio 0
	v_cmp_gt_u32_e32 vcc, s96, v0
	s_barrier
	s_and_saveexec_b64 s[12:13], vcc
	s_cbranch_execz .LBB0_29
	s_barrier

; #define STAGE(P, BASE, br, kt) do { const bf16_t* g_ = (BASE) + (size_t)(br) * K + (size_t)(kt) * 64; \
;         _Pragma("unroll") for (int i_ = 0; i_ < 2; ++i_) \
;             __builtin_amdgcn_global_load_lds((const unsigned*)(g_ + gofs[i_]), (lds_ptr_t)((P) + wb + i_ * 8192), 16, 0, 0); } while (0)
; #define LDA(dst, b, hh) _Pragma("unroll") for (int m = 0; m < 4; ++m) _Pragma("unroll") for (int k = 0; k < 2; ++k) \
;         dst[m][k] = *(const bf16x8*)(SA(b, hh) + lds_byte(wr * 64 + m * 16 + fr, k * 32 + fq * 8))
; #define LDB(dst, b, hh) _Pragma("unroll") for (int n = 0; n < 2; ++n) _Pragma("unroll") for (int k = 0; k < 2; ++k) \
;         dst[n][k] = *(const bf16x8*)(SB(b, hh) + lds_byte(wc * 32 + n * 16 + fr, k * 32 + fq * 8))
; #define MMA(ai, bj, At_, Bt_) do { __builtin_amdgcn_s_setprio(1); \
;         _Pragma("unroll") for (int m = 0; m < 4; ++m) _Pragma("unroll") for (int n = 0; n < 2; ++n) _Pragma("unroll") for (int k = 0; k < 2; ++k) \
;             acc[ai][bj][m][n] = MFMA16(At_[m][k], Bt_[n][k], acc[ai][bj][m][n]); \
;         __builtin_amdgcn_s_setprio(0); } while (0)
; #define WAIT_L(n) asm volatile("s_waitcnt lgkmcnt(" #n ")" ::: "memory")
; #define BAR __builtin_amdgcn_s_barrier()
; #define SCHED __builtin_amdgcn_sched_barrier(0)
; #define STAGE(P, BASE, br, kt) do { const int sg_ = (kt) >> 3; const bf16_t* g_ = (sg_ == 0 ? BASE##0 : sg_ == 1 ? BASE##1 : BASE##2) + (size_t)(br) * K + (size_t)((kt) & 7) * 64; \
;         _Pragma("unroll") for (int i_ = 0; i_ < 2; ++i_) \
;             __builtin_amdgcn_global_load_lds((const unsigned*)(g_ + gofs[i_]), (lds_ptr_t)((P) + wb + i_ * 8192), 16, 0, 0); } while (0)
; #define WAIT_L(n) asm volatile("s_waitcnt lgkmcnt(" #n ")" ::: "memory")
; #define BAR __builtin_amdgcn_s_barrier()
; DI void gemm8(f32x4 (&acc)[2][2][4][2], const bf16_t* __restrict__ Rm, const bf16_t* __restrict__ Cm, int K, char* shm) {
;     ...
;     for (int tt = 0; tt < nt - 2; tt += 2) {
;         LDB(B0, 0, 0); SCHED; LDA(At, 0, 0); STAGE(SA(1, 1), Rm, 128, tt + 1);
;         WAIT_L(8); BAR; WAIT_L(0); MMA(0, 0, At, B0); BAR; SCHED;
;         LDB(B1, 0, 1); STAGE(SB(0, 0), Cm, 0, tt + 2);
;         BAR; WAIT_L(0); MMA(0, 1, At, B1); BAR;
;         LDA(At, 0, 1); STAGE(SA(0, 0), Rm, 0, tt + 2);
;         BAR; WAIT_L(0); MMA(1, 0, At, B0); BAR; SCHED;
;         STAGE(SB(0, 1), Cm, 128, tt + 2);
.LBB0_50:
	v_add_u32_e32 v166, 0xc000, v142
	v_lshl_add_u64 v[172:173], s[62:63], 0, v[138:139]
	v_readfirstlane_b32 s15, v166
	v_add_u32_e32 v167, 0xe000, v142
	v_lshl_add_u64 v[228:229], v[172:173], 0, s[92:93]
	s_mov_b32 m0, s15
	v_lshl_add_u64 v[244:245], s[62:63], 0, v[140:141]
	v_readfirstlane_b32 s15, v167
	global_load_lds_dwordx4 v[228:229], off
	v_lshl_add_u64 v[228:229], v[244:245], 0, s[92:93]
	s_mov_b32 m0, s15
	s_nop 0
	global_load_lds_dwordx4 v[228:229], off
	ds_read_b128 v[168:171], v165
	ds_read_b128 v[184:187], v165 offset:1024
	ds_read_b128 v[188:191], v165 offset:2048
	ds_read_b128 v[192:195], v165 offset:3072
	ds_read_b128 v[196:199], v149
	ds_read_b128 v[200:203], v149 offset:1024
	ds_read_b128 v[204:207], v148
	ds_read_b128 v[208:211], v148 offset:1024
	ds_read_b128 v[212:215], v147
	ds_read_b128 v[216:219], v147 offset:1024
	ds_read_b128 v[220:223], v146
	ds_read_b128 v[224:227], v146 offset:1024
	s_waitcnt lgkmcnt(8)
	s_barrier
	s_waitcnt lgkmcnt(0)
	s_setprio 1
	s_waitcnt lgkmcnt(0)
	v_mfma_f32_16x16x32_bf16 v[126:129], v[196:199], v[168:171], v[126:129]
	v_mfma_f32_16x16x32_bf16 v[122:125], v[196:199], v[188:191], v[122:125]
	v_mfma_f32_16x16x32_bf16 v[118:121], v[204:207], v[168:171], v[118:121]
	v_mfma_f32_16x16x32_bf16 v[114:117], v[204:207], v[188:191], v[114:117]
	v_mfma_f32_16x16x32_bf16 v[110:113], v[212:215], v[168:171], v[110:113]
	v_mfma_f32_16x16x32_bf16 v[106:109], v[212:215], v[188:191], v[106:109]
	v_mfma_f32_16x16x32_bf16 v[102:105], v[220:223], v[168:171], v[102:105]
	v_mfma_f32_16x16x32_bf16 v[98:101], v[220:223], v[188:191], v[98:101]
	v_mfma_f32_16x16x32_bf16 v[126:129], v[200:203], v[184:187], v[126:129]
	v_mfma_f32_16x16x32_bf16 v[122:125], v[200:203], v[192:195], v[122:125]
	v_mfma_f32_16x16x32_bf16 v[118:121], v[208:211], v[184:187], v[118:121]
	v_mfma_f32_16x16x32_bf16 v[114:117], v[208:211], v[192:195], v[114:117]
	v_mfma_f32_16x16x32_bf16 v[110:113], v[216:219], v[184:187], v[110:113]
	v_mfma_f32_16x16x32_bf16 v[106:109], v[216:219], v[192:195], v[106:109]
	v_mfma_f32_16x16x32_bf16 v[102:105], v[224:227], v[184:187], v[102:105]
	v_mfma_f32_16x16x32_bf16 v[98:101], v[224:227], v[192:195], v[98:101]
	s_setprio 0
	s_barrier
	v_lshl_add_u64 v[246:247], s[62:63], 0, v[134:135]
	v_readfirstlane_b32 s15, v143
	v_lshl_add_u64 v[248:249], v[246:247], 0, s[90:91]
	s_mov_b32 m0, s15
	s_nop 0
	global_load_lds_dwordx4 v[248:249], off
	v_lshl_add_u64 v[248:249], s[62:63], 0, v[136:137]
	v_readfirstlane_b32 s15, v144
	v_lshl_add_u64 v[250:251], v[248:249], 0, s[90:91]
	s_mov_b32 m0, s15
	s_nop 0
	global_load_lds_dwordx4 v[250:251], off
	ds_read_b128 v[228:231], v164
	ds_read_b128 v[232:235], v164 offset:1024
	ds_read_b128 v[236:239], v164 offset:2048
	ds_read_b128 v[240:243], v164 offset:3072
	s_barrier
	s_waitcnt lgkmcnt(0)
	s_setprio 1
	s_waitcnt lgkmcnt(0)
	v_mfma_f32_16x16x32_bf16 v[94:97], v[196:199], v[228:231], v[94:97]
	v_mfma_f32_16x16x32_bf16 v[90:93], v[196:199], v[236:239], v[90:93]
	v_mfma_f32_16x16x32_bf16 v[86:89], v[204:207], v[228:231], v[86:89]
	v_mfma_f32_16x16x32_bf16 v[82:85], v[204:207], v[236:239], v[82:85]
	v_mfma_f32_16x16x32_bf16 v[78:81], v[212:215], v[228:231], v[78:81]
	v_mfma_f32_16x16x32_bf16 v[74:77], v[212:215], v[236:239], v[74:77]
	v_mfma_f32_16x16x32_bf16 v[70:73], v[220:223], v[228:231], v[70:73]
	v_mfma_f32_16x16x32_bf16 v[66:69], v[220:223], v[236:239], v[66:69]
	v_mfma_f32_16x16x32_bf16 v[94:97], v[200:203], v[232:235], v[94:97]
	v_mfma_f32_16x16x32_bf16 v[90:93], v[200:203], v[240:243], v[90:93]
	v_mfma_f32_16x16x32_bf16 v[86:89], v[208:211], v[232:235], v[86:89]
	v_mfma_f32_16x16x32_bf16 v[82:85], v[208:211], v[240:243], v[82:85]
	v_mfma_f32_16x16x32_bf16 v[78:81], v[216:219], v[232:235], v[78:81]
	v_mfma_f32_16x16x32_bf16 v[74:77], v[216:219], v[240:243], v[74:77]
	v_mfma_f32_16x16x32_bf16 v[70:73], v[224:227], v[232:235], v[70:73]
	v_mfma_f32_16x16x32_bf16 v[66:69], v[224:227], v[240:243], v[66:69]
	s_setprio 0
	v_readfirstlane_b32 s15, v142
	v_lshl_add_u64 v[250:251], v[172:173], 0, s[78:79]
	s_mov_b32 m0, s15
	v_readfirstlane_b32 s15, v145
	s_barrier
	global_load_lds_dwordx4 v[250:251], off
	v_lshl_add_u64 v[250:251], v[244:245], 0, s[78:79]
	s_mov_b32 m0, s15
	s_nop 0
	global_load_lds_dwordx4 v[250:251], off
	ds_read_b128 v[196:199], v149 offset:16384
	ds_read_b128 v[200:203], v149 offset:17408
	ds_read_b128 v[204:207], v148 offset:16384
	ds_read_b128 v[208:211], v148 offset:17408
	ds_read_b128 v[212:215], v147 offset:16384
	ds_read_b128 v[216:219], v147 offset:17408
	ds_read_b128 v[220:223], v146 offset:16384
	ds_read_b128 v[224:227], v146 offset:17408
	s_barrier
	s_waitcnt lgkmcnt(0)
	s_setprio 1
	s_waitcnt lgkmcnt(0)
	v_mfma_f32_16x16x32_bf16 v[62:65], v[196:199], v[168:171], v[62:65]
	v_mfma_f32_16x16x32_bf16 v[58:61], v[196:199], v[188:191], v[58:61]
	v_mfma_f32_16x16x32_bf16 v[54:57], v[204:207], v[168:171], v[54:57]
	v_mfma_f32_16x16x32_bf16 v[50:53], v[204:207], v[188:191], v[50:53]
	v_mfma_f32_16x16x32_bf16 v[46:49], v[212:215], v[168:171], v[46:49]
	v_mfma_f32_16x16x32_bf16 v[42:45], v[212:215], v[188:191], v[42:45]
	v_mfma_f32_16x16x32_bf16 v[38:41], v[220:223], v[168:171], v[38:41]
	v_mfma_f32_16x16x32_bf16 v[34:37], v[220:223], v[188:191], v[34:37]
	v_mfma_f32_16x16x32_bf16 v[62:65], v[200:203], v[184:187], v[62:65]
	v_mfma_f32_16x16x32_bf16 v[58:61], v[200:203], v[192:195], v[58:61]
	v_mfma_f32_16x16x32_bf16 v[54:57], v[208:211], v[184:187], v[54:57]
	v_mfma_f32_16x16x32_bf16 v[50:53], v[208:211], v[192:195], v[50:53]
	v_mfma_f32_16x16x32_bf16 v[46:49], v[216:219], v[184:187], v[46:49]
	v_mfma_f32_16x16x32_bf16 v[42:45], v[216:219], v[192:195], v[42:45]
	v_mfma_f32_16x16x32_bf16 v[38:41], v[224:227], v[184:187], v[38:41]
	v_mfma_f32_16x16x32_bf16 v[34:37], v[224:227], v[192:195], v[34:37]
	s_setprio 0
	s_barrier
; #define STAGE(P, BASE, br, kt) do { const bf16_t* g_ = (BASE) + (size_t)(br) * K + (size_t)(kt) * 64; \
;         _Pragma("unroll") for (int i_ = 0; i_ < 2; ++i_) \
;             __builtin_amdgcn_global_load_lds((const unsigned*)(g_ + gofs[i_]), (lds_ptr_t)((P) + wb + i_ * 8192), 16, 0, 0); } while (0)
; #define LDA(dst, b, hh) _Pragma("unroll") for (int m = 0; m < 4; ++m) _Pragma("unroll") for (int k = 0; k < 2; ++k) \
;         dst[m][k] = *(const bf16x8*)(SA(b, hh) + lds_byte(wr * 64 + m * 16 + fr, k * 32 + fq * 8))
; #define LDB(dst, b, hh) _Pragma("unroll") for (int n = 0; n < 2; ++n) _Pragma("unroll") for (int k = 0; k < 2; ++k) \
;         dst[n][k] = *(const bf16x8*)(SB(b, hh) + lds_byte(wc * 32 + n * 16 + fr, k * 32 + fq * 8))
; #define MMA(ai, bj, At_, Bt_) do { __builtin_amdgcn_s_setprio(1); \
;         _Pragma("unroll") for (int m = 0; m < 4; ++m) _Pragma("unroll") for (int n = 0; n < 2; ++n) _Pragma("unroll") for (int k = 0; k < 2; ++k) \
;             acc[ai][bj][m][n] = MFMA16(At_[m][k], Bt_[n][k], acc[ai][bj][m][n]); \
;         __builtin_amdgcn_s_setprio(0); } while (0)
; #define WAIT_V(n) asm volatile("s_waitcnt vmcnt(" #n ")" ::: "memory")
; #define WAIT_L(n) asm volatile("s_waitcnt lgkmcnt(" #n ")" ::: "memory")
; #define BAR __builtin_amdgcn_s_barrier()
; #define SCHED __builtin_amdgcn_sched_barrier(0)
; #define STAGE(P, BASE, br, kt) do { const int sg_ = (kt) >> 3; const bf16_t* g_ = (sg_ == 0 ? BASE##0 : sg_ == 1 ? BASE##1 : BASE##2) + (size_t)(br) * K + (size_t)((kt) & 7) * 64; \
;         _Pragma("unroll") for (int i_ = 0; i_ < 2; ++i_) \
;             __builtin_amdgcn_global_load_lds((const unsigned*)(g_ + gofs[i_]), (lds_ptr_t)((P) + wb + i_ * 8192), 16, 0, 0); } while (0)
; DI void gemm8(f32x4 (&acc)[2][2][4][2], const bf16_t* __restrict__ Rm, const bf16_t* __restrict__ Cm, int K, char* shm) {
;     ...
;         STAGE(SB(0, 1), Cm, 128, tt + 2);
;         WAIT_V(6); BAR; MMA(1, 1, At, B1); BAR;
;         LDB(B0, 1, 0); SCHED; LDA(At, 1, 0); STAGE(SA(0, 1), Rm, 128, tt + 2);
;         WAIT_L(8); BAR; WAIT_L(0); MMA(0, 0, At, B0); BAR; SCHED;
;         LDB(B1, 1, 1); STAGE(SB(1, 0), Cm, 0, tt + 3);
;         BAR; WAIT_L(0); MMA(0, 1, At, B1); BAR;
;         LDA(At, 1, 1); STAGE(SA(1, 0), Rm, 0, tt + 3);
;         BAR; WAIT_L(0); MMA(1, 0, At, B0); BAR; SCHED;
;         STAGE(SB(1, 1), Cm, 128, tt + 3);
	v_readfirstlane_b32 s15, v151
	v_lshl_add_u64 v[168:169], v[246:247], 0, s[76:77]
	s_mov_b32 m0, s15
	v_readfirstlane_b32 s15, v152
	global_load_lds_dwordx4 v[168:169], off
	v_lshl_add_u64 v[168:169], v[248:249], 0, s[76:77]
	s_mov_b32 m0, s15
	s_nop 0
	global_load_lds_dwordx4 v[168:169], off
	s_waitcnt vmcnt(6)
	s_barrier
	s_setprio 1
	v_mfma_f32_16x16x32_bf16 v[30:33], v[196:199], v[228:231], v[30:33]
	v_mfma_f32_16x16x32_bf16 v[26:29], v[196:199], v[236:239], v[26:29]
	v_mfma_f32_16x16x32_bf16 v[22:25], v[204:207], v[228:231], v[22:25]
	v_mfma_f32_16x16x32_bf16 v[18:21], v[204:207], v[236:239], v[18:21]
	v_mfma_f32_16x16x32_bf16 v[14:17], v[212:215], v[228:231], v[14:17]
	v_mfma_f32_16x16x32_bf16 v[10:13], v[212:215], v[236:239], v[10:13]
	v_mfma_f32_16x16x32_bf16 v[6:9], v[220:223], v[228:231], v[6:9]
	v_mfma_f32_16x16x32_bf16 v[2:5], v[220:223], v[236:239], v[2:5]
	v_mfma_f32_16x16x32_bf16 v[30:33], v[200:203], v[232:235], v[30:33]
	v_mfma_f32_16x16x32_bf16 v[26:29], v[200:203], v[240:243], v[26:29]
	v_mfma_f32_16x16x32_bf16 v[22:25], v[208:211], v[232:235], v[22:25]
	v_mfma_f32_16x16x32_bf16 v[18:21], v[208:211], v[240:243], v[18:21]
	v_mfma_f32_16x16x32_bf16 v[14:17], v[216:219], v[232:235], v[14:17]
	v_mfma_f32_16x16x32_bf16 v[10:13], v[216:219], v[240:243], v[10:13]
	v_mfma_f32_16x16x32_bf16 v[6:9], v[224:227], v[232:235], v[6:9]
	v_mfma_f32_16x16x32_bf16 v[2:5], v[224:227], v[240:243], v[2:5]
	s_setprio 0
	s_barrier
	v_readfirstlane_b32 s15, v154
	v_lshl_add_u64 v[228:229], v[172:173], 0, s[4:5]
	s_mov_b32 m0, s15
	v_readfirstlane_b32 s15, v155
	global_load_lds_dwordx4 v[228:229], off
	v_lshl_add_u64 v[228:229], v[244:245], 0, s[4:5]
	s_mov_b32 m0, s15
	s_nop 0
	global_load_lds_dwordx4 v[228:229], off
	ds_read_b128 v[168:171], v153
	ds_read_b128 v[184:187], v153 offset:1024
	ds_read_b128 v[188:191], v153 offset:2048
	ds_read_b128 v[192:195], v153 offset:3072
	ds_read_b128 v[196:199], v149 offset:32768
	ds_read_b128 v[200:203], v149 offset:33792
	ds_read_b128 v[204:207], v148 offset:32768
	ds_read_b128 v[208:211], v148 offset:33792
	ds_read_b128 v[212:215], v147 offset:32768
	ds_read_b128 v[216:219], v147 offset:33792
	ds_read_b128 v[220:223], v146 offset:32768
	ds_read_b128 v[224:227], v146 offset:33792
	s_waitcnt lgkmcnt(8)
	s_barrier
	s_waitcnt lgkmcnt(0)
	s_setprio 1
	s_waitcnt lgkmcnt(0)
	v_mfma_f32_16x16x32_bf16 v[126:129], v[196:199], v[168:171], v[126:129]
	v_mfma_f32_16x16x32_bf16 v[122:125], v[196:199], v[188:191], v[122:125]
	v_mfma_f32_16x16x32_bf16 v[118:121], v[204:207], v[168:171], v[118:121]
	v_mfma_f32_16x16x32_bf16 v[114:117], v[204:207], v[188:191], v[114:117]
	v_mfma_f32_16x16x32_bf16 v[110:113], v[212:215], v[168:171], v[110:113]
	v_mfma_f32_16x16x32_bf16 v[106:109], v[212:215], v[188:191], v[106:109]
	v_mfma_f32_16x16x32_bf16 v[102:105], v[220:223], v[168:171], v[102:105]
	v_mfma_f32_16x16x32_bf16 v[98:101], v[220:223], v[188:191], v[98:101]
	v_mfma_f32_16x16x32_bf16 v[126:129], v[200:203], v[184:187], v[126:129]
	v_mfma_f32_16x16x32_bf16 v[122:125], v[200:203], v[192:195], v[122:125]
	v_mfma_f32_16x16x32_bf16 v[118:121], v[208:211], v[184:187], v[118:121]
	v_mfma_f32_16x16x32_bf16 v[114:117], v[208:211], v[192:195], v[114:117]
	v_mfma_f32_16x16x32_bf16 v[110:113], v[216:219], v[184:187], v[110:113]
	v_mfma_f32_16x16x32_bf16 v[106:109], v[216:219], v[192:195], v[106:109]
	v_mfma_f32_16x16x32_bf16 v[102:105], v[224:227], v[184:187], v[102:105]
	v_mfma_f32_16x16x32_bf16 v[98:101], v[224:227], v[192:195], v[98:101]
	s_setprio 0
	s_barrier
	v_readfirstlane_b32 s15, v156
	v_lshl_add_u64 v[250:251], v[246:247], 0, s[72:73]
	s_mov_b32 m0, s15
	v_readfirstlane_b32 s15, v157
	global_load_lds_dwordx4 v[250:251], off
	v_lshl_add_u64 v[250:251], v[248:249], 0, s[72:73]
	s_mov_b32 m0, s15
	s_nop 0
	global_load_lds_dwordx4 v[250:251], off
	ds_read_b128 v[228:231], v150
	ds_read_b128 v[232:235], v150 offset:1024
	ds_read_b128 v[236:239], v150 offset:2048
	ds_read_b128 v[240:243], v150 offset:3072
	s_barrier
	s_waitcnt lgkmcnt(0)
	s_setprio 1
	s_waitcnt lgkmcnt(0)
	v_mfma_f32_16x16x32_bf16 v[94:97], v[196:199], v[228:231], v[94:97]
	v_mfma_f32_16x16x32_bf16 v[90:93], v[196:199], v[236:239], v[90:93]
	v_mfma_f32_16x16x32_bf16 v[86:89], v[204:207], v[228:231], v[86:89]
	v_mfma_f32_16x16x32_bf16 v[82:85], v[204:207], v[236:239], v[82:85]
	v_mfma_f32_16x16x32_bf16 v[78:81], v[212:215], v[228:231], v[78:81]
	v_mfma_f32_16x16x32_bf16 v[74:77], v[212:215], v[236:239], v[74:77]
	v_mfma_f32_16x16x32_bf16 v[70:73], v[220:223], v[228:231], v[70:73]
	v_mfma_f32_16x16x32_bf16 v[66:69], v[220:223], v[236:239], v[66:69]
	v_mfma_f32_16x16x32_bf16 v[94:97], v[200:203], v[232:235], v[94:97]
	v_mfma_f32_16x16x32_bf16 v[90:93], v[200:203], v[240:243], v[90:93]
	v_mfma_f32_16x16x32_bf16 v[86:89], v[208:211], v[232:235], v[86:89]
	v_mfma_f32_16x16x32_bf16 v[82:85], v[208:211], v[240:243], v[82:85]
	v_mfma_f32_16x16x32_bf16 v[78:81], v[216:219], v[232:235], v[78:81]
	v_mfma_f32_16x16x32_bf16 v[74:77], v[216:219], v[240:243], v[74:77]
	v_mfma_f32_16x16x32_bf16 v[70:73], v[224:227], v[232:235], v[70:73]
	v_mfma_f32_16x16x32_bf16 v[66:69], v[224:227], v[240:243], v[66:69]
	s_setprio 0
	v_readfirstlane_b32 s15, v158
	v_lshl_add_u64 v[172:173], v[172:173], 0, s[86:87]
	s_mov_b32 m0, s15
	v_readfirstlane_b32 s15, v159
	s_barrier
	global_load_lds_dwordx4 v[172:173], off
	v_lshl_add_u64 v[172:173], v[244:245], 0, s[86:87]
	s_mov_b32 m0, s15
	s_nop 0
	global_load_lds_dwordx4 v[172:173], off
	ds_read_b128 v[196:199], v149 offset:49152
	ds_read_b128 v[200:203], v149 offset:50176
	ds_read_b128 v[204:207], v148 offset:49152
	ds_read_b128 v[208:211], v148 offset:50176
	ds_read_b128 v[212:215], v147 offset:49152
	ds_read_b128 v[216:219], v147 offset:50176
	ds_read_b128 v[220:223], v146 offset:49152
	ds_read_b128 v[224:227], v146 offset:50176
	s_barrier
; #define STAGE(P, BASE, br, kt) do { const bf16_t* g_ = (BASE) + (size_t)(br) * K + (size_t)(kt) * 64; \
;         _Pragma("unroll") for (int i_ = 0; i_ < 2; ++i_) \
;             __builtin_amdgcn_global_load_lds((const unsigned*)(g_ + gofs[i_]), (lds_ptr_t)((P) + wb + i_ * 8192), 16, 0, 0); } while (0)
; #define LDA(dst, b, hh) _Pragma("unroll") for (int m = 0; m < 4; ++m) _Pragma("unroll") for (int k = 0; k < 2; ++k) \
;         dst[m][k] = *(const bf16x8*)(SA(b, hh) + lds_byte(wr * 64 + m * 16 + fr, k * 32 + fq * 8))
; #define LDB(dst, b, hh) _Pragma("unroll") for (int n = 0; n < 2; ++n) _Pragma("unroll") for (int k = 0; k < 2; ++k) \
;         dst[n][k] = *(const bf16x8*)(SB(b, hh) + lds_byte(wc * 32 + n * 16 + fr, k * 32 + fq * 8))
; #define MMA(ai, bj, At_, Bt_) do { __builtin_amdgcn_s_setprio(1); \
;         _Pragma("unroll") for (int m = 0; m < 4; ++m) _Pragma("unroll") for (int n = 0; n < 2; ++n) _Pragma("unroll") for (int k = 0; k < 2; ++k) \
;             acc[ai][bj][m][n] = MFMA16(At_[m][k], Bt_[n][k], acc[ai][bj][m][n]); \
;         __builtin_amdgcn_s_setprio(0); } while (0)
; #define WAIT_V(n) asm volatile("s_waitcnt vmcnt(" #n ")" ::: "memory")
; #define WAIT_L(n) asm volatile("s_waitcnt lgkmcnt(" #n ")" ::: "memory")
; #define BAR __builtin_amdgcn_s_barrier()
; #define SCHED __builtin_amdgcn_sched_barrier(0)
; #define STAGE(P, BASE, br, kt) do { const int sg_ = (kt) >> 3; const bf16_t* g_ = (sg_ == 0 ? BASE##0 : sg_ == 1 ? BASE##1 : BASE##2) + (size_t)(br) * K + (size_t)((kt) & 7) * 64; \
;         _Pragma("unroll") for (int i_ = 0; i_ < 2; ++i_) \
;             __builtin_amdgcn_global_load_lds((const unsigned*)(g_ + gofs[i_]), (lds_ptr_t)((P) + wb + i_ * 8192), 16, 0, 0); } while (0)
; #define WAIT_V(n) asm volatile("s_waitcnt vmcnt(" #n ")" ::: "memory")
; #define WAIT_L(n) asm volatile("s_waitcnt lgkmcnt(" #n ")" ::: "memory")
; #define BAR __builtin_amdgcn_s_barrier()
; DI void gemm8(f32x4 (&acc)[2][2][4][2], const bf16_t* __restrict__ Rm, const bf16_t* __restrict__ Cm, int K, char* shm) {
;     ...
;         BAR; WAIT_L(0); MMA(1, 0, At, B0); BAR; SCHED;
;         STAGE(SB(1, 1), Cm, 128, tt + 3);
;         WAIT_V(6); BAR; MMA(1, 1, At, B1); BAR;
;     }
;     { LDB(B0, 0, 0); LDA(At, 0, 0); STAGE(SA(1, 1), Rm, 128, nt - 1);
;       BAR; WAIT_L(0); MMA(0, 0, At, B0); BAR;
;       LDB(B1, 0, 1); BAR; WAIT_L(0); MMA(0, 1, At, B1); BAR;
	s_waitcnt lgkmcnt(0)
	s_setprio 1
	s_waitcnt lgkmcnt(0)
	v_mfma_f32_16x16x32_bf16 v[62:65], v[196:199], v[168:171], v[62:65]
	v_mfma_f32_16x16x32_bf16 v[58:61], v[196:199], v[188:191], v[58:61]
	v_mfma_f32_16x16x32_bf16 v[54:57], v[204:207], v[168:171], v[54:57]
	v_mfma_f32_16x16x32_bf16 v[50:53], v[204:207], v[188:191], v[50:53]
	v_mfma_f32_16x16x32_bf16 v[46:49], v[212:215], v[168:171], v[46:49]
	v_mfma_f32_16x16x32_bf16 v[42:45], v[212:215], v[188:191], v[42:45]
	v_mfma_f32_16x16x32_bf16 v[38:41], v[220:223], v[168:171], v[38:41]
	v_mfma_f32_16x16x32_bf16 v[34:37], v[220:223], v[188:191], v[34:37]
	v_mfma_f32_16x16x32_bf16 v[62:65], v[200:203], v[184:187], v[62:65]
	v_mfma_f32_16x16x32_bf16 v[58:61], v[200:203], v[192:195], v[58:61]
	v_mfma_f32_16x16x32_bf16 v[54:57], v[208:211], v[184:187], v[54:57]
	v_mfma_f32_16x16x32_bf16 v[50:53], v[208:211], v[192:195], v[50:53]
	v_mfma_f32_16x16x32_bf16 v[46:49], v[216:219], v[184:187], v[46:49]
	v_mfma_f32_16x16x32_bf16 v[42:45], v[216:219], v[192:195], v[42:45]
	v_mfma_f32_16x16x32_bf16 v[38:41], v[224:227], v[184:187], v[38:41]
	v_mfma_f32_16x16x32_bf16 v[34:37], v[224:227], v[192:195], v[34:37]
	s_setprio 0
	s_barrier
	v_readfirstlane_b32 s15, v160
	v_lshl_add_u64 v[168:169], v[246:247], 0, s[88:89]
	s_mov_b32 m0, s15
	v_readfirstlane_b32 s15, v161
	global_load_lds_dwordx4 v[168:169], off
	v_lshl_add_u64 v[168:169], v[248:249], 0, s[88:89]
	s_mov_b32 m0, s15
	s_nop 0
	global_load_lds_dwordx4 v[168:169], off
	s_waitcnt vmcnt(6)
	s_barrier
	s_setprio 1
	v_mfma_f32_16x16x32_bf16 v[30:33], v[196:199], v[228:231], v[30:33]
	v_mfma_f32_16x16x32_bf16 v[26:29], v[196:199], v[236:239], v[26:29]
	v_mfma_f32_16x16x32_bf16 v[22:25], v[204:207], v[228:231], v[22:25]
	v_mfma_f32_16x16x32_bf16 v[18:21], v[204:207], v[236:239], v[18:21]
	v_mfma_f32_16x16x32_bf16 v[14:17], v[212:215], v[228:231], v[14:17]
	v_mfma_f32_16x16x32_bf16 v[10:13], v[212:215], v[236:239], v[10:13]
	v_mfma_f32_16x16x32_bf16 v[6:9], v[220:223], v[228:231], v[6:9]
	v_mfma_f32_16x16x32_bf16 v[2:5], v[220:223], v[236:239], v[2:5]
	v_mfma_f32_16x16x32_bf16 v[30:33], v[200:203], v[232:235], v[30:33]
	v_mfma_f32_16x16x32_bf16 v[26:29], v[200:203], v[240:243], v[26:29]
	v_mfma_f32_16x16x32_bf16 v[22:25], v[208:211], v[232:235], v[22:25]
	v_mfma_f32_16x16x32_bf16 v[18:21], v[208:211], v[240:243], v[18:21]
	v_mfma_f32_16x16x32_bf16 v[14:17], v[216:219], v[232:235], v[14:17]
	v_mfma_f32_16x16x32_bf16 v[10:13], v[216:219], v[240:243], v[10:13]
	v_mfma_f32_16x16x32_bf16 v[6:9], v[224:227], v[232:235], v[6:9]
	v_mfma_f32_16x16x32_bf16 v[2:5], v[224:227], v[240:243], v[2:5]
	s_setprio 0
	s_add_i32 s7, s7, 2
	v_lshl_add_u64 v[134:135], v[134:135], 0, s[90:91]
	v_lshl_add_u64 v[136:137], v[136:137], 0, s[90:91]
	v_lshl_add_u64 v[138:139], v[138:139], 0, s[90:91]
	s_cmp_lt_u32 s7, 12
	v_lshl_add_u64 v[140:141], v[140:141], 0, s[90:91]
	s_barrier
	s_cbranch_scc1 .LBB0_50
	s_add_u32 s22, s22, 0x40780
	s_addc_u32 s23, s23, 0
	v_readfirstlane_b32 s7, v166
	v_lshl_add_u64 v[130:131], v[130:131], 1, s[22:23]
	s_mov_b32 m0, s7
	v_readfirstlane_b32 s7, v167
	ds_read_b128 v[134:137], v165
	ds_read_b128 v[138:141], v165 offset:1024
	ds_read_b128 v[142:145], v165 offset:2048
	ds_read_b128 v[154:157], v165 offset:3072
	ds_read_b128 v[158:161], v149
	ds_read_b128 v[168:171], v149 offset:1024
	ds_read_b128 v[184:187], v148
	ds_read_b128 v[188:191], v148 offset:1024
	ds_read_b128 v[192:195], v147
	ds_read_b128 v[196:199], v147 offset:1024
	ds_read_b128 v[200:203], v146
	ds_read_b128 v[204:207], v146 offset:1024
	global_load_lds_dwordx4 v[130:131], off
	v_lshl_add_u64 v[130:131], v[132:133], 1, s[22:23]
	s_mov_b32 m0, s7
	s_nop 0
	global_load_lds_dwordx4 v[130:131], off
	s_barrier
	s_waitcnt lgkmcnt(0)
	s_setprio 1
	s_waitcnt lgkmcnt(0)
	v_mfma_f32_16x16x32_bf16 v[126:129], v[158:161], v[134:137], v[126:129]
	v_mfma_f32_16x16x32_bf16 v[122:125], v[158:161], v[142:145], v[122:125]
	v_mfma_f32_16x16x32_bf16 v[118:121], v[184:187], v[134:137], v[118:121]
	v_mfma_f32_16x16x32_bf16 v[114:117], v[184:187], v[142:145], v[114:117]
	v_mfma_f32_16x16x32_bf16 v[110:113], v[192:195], v[134:137], v[110:113]
	v_mfma_f32_16x16x32_bf16 v[106:109], v[192:195], v[142:145], v[106:109]
	v_mfma_f32_16x16x32_bf16 v[102:105], v[200:203], v[134:137], v[102:105]
	v_mfma_f32_16x16x32_bf16 v[98:101], v[200:203], v[142:145], v[98:101]
	v_mfma_f32_16x16x32_bf16 v[126:129], v[168:171], v[138:141], v[126:129]
	v_mfma_f32_16x16x32_bf16 v[122:125], v[168:171], v[154:157], v[122:125]
	v_mfma_f32_16x16x32_bf16 v[118:121], v[188:191], v[138:141], v[118:121]
	v_mfma_f32_16x16x32_bf16 v[114:117], v[188:191], v[154:157], v[114:117]
	v_mfma_f32_16x16x32_bf16 v[110:113], v[196:199], v[138:141], v[110:113]
	v_mfma_f32_16x16x32_bf16 v[106:109], v[196:199], v[154:157], v[106:109]
	v_mfma_f32_16x16x32_bf16 v[102:105], v[204:207], v[138:141], v[102:105]
	v_mfma_f32_16x16x32_bf16 v[98:101], v[204:207], v[154:157], v[98:101]
	s_setprio 0
	s_barrier
	ds_read_b128 v[130:133], v164
	ds_read_b128 v[208:211], v164 offset:1024
	ds_read_b128 v[212:215], v164 offset:2048
	ds_read_b128 v[164:167], v164 offset:3072
	s_barrier
; #define LDA(dst, b, hh) _Pragma("unroll") for (int m = 0; m < 4; ++m) _Pragma("unroll") for (int k = 0; k < 2; ++k) \
;         dst[m][k] = *(const bf16x8*)(SA(b, hh) + lds_byte(wr * 64 + m * 16 + fr, k * 32 + fq * 8))
; #define LDB(dst, b, hh) _Pragma("unroll") for (int n = 0; n < 2; ++n) _Pragma("unroll") for (int k = 0; k < 2; ++k) \
;         dst[n][k] = *(const bf16x8*)(SB(b, hh) + lds_byte(wc * 32 + n * 16 + fr, k * 32 + fq * 8))
; #define MMA(ai, bj, At_, Bt_) do { __builtin_amdgcn_s_setprio(1); \
;         _Pragma("unroll") for (int m = 0; m < 4; ++m) _Pragma("unroll") for (int n = 0; n < 2; ++n) _Pragma("unroll") for (int k = 0; k < 2; ++k) \
;             acc[ai][bj][m][n] = MFMA16(At_[m][k], Bt_[n][k], acc[ai][bj][m][n]); \
;         __builtin_amdgcn_s_setprio(0); } while (0)
; #define WAIT_V(n) asm volatile("s_waitcnt vmcnt(" #n ")" ::: "memory")
; #define WAIT_L(n) asm volatile("s_waitcnt lgkmcnt(" #n ")" ::: "memory")
; #define BAR __builtin_amdgcn_s_barrier()
; #define LDA(dst, b, hh) _Pragma("unroll") for (int m = 0; m < 4; ++m) _Pragma("unroll") for (int k = 0; k < 2; ++k) \
;         dst[m][k] = *(const bf16x8*)(SA(b, hh) + lds_byte(wr * 64 + m * 16 + fr, k * 32 + fq * 8))
; #define LDB(dst, b, hh) _Pragma("unroll") for (int n = 0; n < 2; ++n) _Pragma("unroll") for (int k = 0; k < 2; ++k) \
;         dst[n][k] = *(const bf16x8*)(SB(b, hh) + lds_byte(wc * 32 + n * 16 + fr, k * 32 + fq * 8))
; #define MMA(ai, bj, At_, Bt_) do { __builtin_amdgcn_s_setprio(1); \
;         _Pragma("unroll") for (int m = 0; m < 4; ++m) _Pragma("unroll") for (int n = 0; n < 2; ++n) _Pragma("unroll") for (int k = 0; k < 2; ++k) \
;             acc[ai][bj][m][n] = MFMA16(At_[m][k], Bt_[n][k], acc[ai][bj][m][n]); \
;         __builtin_amdgcn_s_setprio(0); } while (0)
; #define WAIT_V(n) asm volatile("s_waitcnt vmcnt(" #n ")" ::: "memory")
; #define WAIT_L(n) asm volatile("s_waitcnt lgkmcnt(" #n ")" ::: "memory")
; #define BAR __builtin_amdgcn_s_barrier()
; DI void gemm8(f32x4 (&acc)[2][2][4][2], const bf16_t* __restrict__ Rm, const bf16_t* __restrict__ Cm, int K, char* shm) {
;     ...
;       LDB(B1, 0, 1); BAR; WAIT_L(0); MMA(0, 1, At, B1); BAR;
;       LDA(At, 0, 1); WAIT_V(4); BAR; WAIT_L(0); MMA(1, 0, At, B0); MMA(1, 1, At, B1); BAR; }
;     { LDB(B0, 1, 0); LDA(At, 1, 0); WAIT_V(2); BAR; WAIT_L(0); MMA(0, 0, At, B0); BAR;
	s_waitcnt lgkmcnt(0)
	s_setprio 1
	s_waitcnt lgkmcnt(0)
	v_mfma_f32_16x16x32_bf16 v[66:69], v[200:203], v[212:215], v[66:69]
	v_mfma_f32_16x16x32_bf16 v[94:97], v[158:161], v[130:133], v[94:97]
	v_mfma_f32_16x16x32_bf16 v[90:93], v[158:161], v[212:215], v[90:93]
	v_mfma_f32_16x16x32_bf16 v[86:89], v[184:187], v[130:133], v[86:89]
	v_mfma_f32_16x16x32_bf16 v[82:85], v[184:187], v[212:215], v[82:85]
	v_mfma_f32_16x16x32_bf16 v[78:81], v[192:195], v[130:133], v[78:81]
	v_mfma_f32_16x16x32_bf16 v[74:77], v[192:195], v[212:215], v[74:77]
	v_mfma_f32_16x16x32_bf16 v[70:73], v[200:203], v[130:133], v[70:73]
	v_mfma_f32_16x16x32_bf16 v[66:69], v[204:207], v[164:167], v[66:69]
	v_mfma_f32_16x16x32_bf16 v[94:97], v[168:171], v[208:211], v[94:97]
	v_mfma_f32_16x16x32_bf16 v[90:93], v[168:171], v[164:167], v[90:93]
	v_mfma_f32_16x16x32_bf16 v[86:89], v[188:191], v[208:211], v[86:89]
	v_mfma_f32_16x16x32_bf16 v[82:85], v[188:191], v[164:167], v[82:85]
	v_mfma_f32_16x16x32_bf16 v[158:161], v[196:199], v[208:211], v[78:81]
	v_mfma_f32_16x16x32_bf16 v[168:171], v[196:199], v[164:167], v[74:77]
	v_mfma_f32_16x16x32_bf16 v[184:187], v[204:207], v[208:211], v[70:73]
	s_setprio 0
	s_barrier
	s_nop 0
	ds_read_b128 v[70:73], v149 offset:16384
	ds_read_b128 v[74:77], v149 offset:17408
	ds_read_b128 v[78:81], v148 offset:16384
	ds_read_b128 v[188:191], v148 offset:17408
	ds_read_b128 v[192:195], v147 offset:16384
	ds_read_b128 v[196:199], v147 offset:17408
	ds_read_b128 v[200:203], v146 offset:16384
	ds_read_b128 v[204:207], v146 offset:17408
	s_waitcnt vmcnt(4)
	s_barrier
	s_waitcnt lgkmcnt(0)
	s_setprio 1
	s_waitcnt lgkmcnt(0)
	v_mfma_f32_16x16x32_bf16 v[62:65], v[70:73], v[134:137], v[62:65]
	v_mfma_f32_16x16x32_bf16 v[58:61], v[70:73], v[142:145], v[58:61]
	v_mfma_f32_16x16x32_bf16 v[54:57], v[78:81], v[134:137], v[54:57]
	v_mfma_f32_16x16x32_bf16 v[50:53], v[78:81], v[142:145], v[50:53]
	v_mfma_f32_16x16x32_bf16 v[34:37], v[200:203], v[142:145], v[34:37]
	v_mfma_f32_16x16x32_bf16 v[62:65], v[74:77], v[138:141], v[62:65]
	v_mfma_f32_16x16x32_bf16 v[58:61], v[74:77], v[154:157], v[58:61]
	v_mfma_f32_16x16x32_bf16 v[54:57], v[188:191], v[138:141], v[54:57]
	v_mfma_f32_16x16x32_bf16 v[50:53], v[188:191], v[154:157], v[50:53]
	v_mfma_f32_16x16x32_bf16 v[46:49], v[192:195], v[134:137], v[46:49]
	v_mfma_f32_16x16x32_bf16 v[42:45], v[192:195], v[142:145], v[42:45]
	v_mfma_f32_16x16x32_bf16 v[38:41], v[200:203], v[134:137], v[38:41]
	v_mfma_f32_16x16x32_bf16 v[34:37], v[204:207], v[154:157], v[34:37]
	v_mfma_f32_16x16x32_bf16 v[216:219], v[196:199], v[138:141], v[46:49]
	v_mfma_f32_16x16x32_bf16 v[220:223], v[196:199], v[154:157], v[42:45]
	v_mfma_f32_16x16x32_bf16 v[224:227], v[204:207], v[138:141], v[38:41]
	s_setprio 0
	s_setprio 1
	v_mfma_f32_16x16x32_bf16 v[30:33], v[70:73], v[130:133], v[30:33]
	v_mfma_f32_16x16x32_bf16 v[26:29], v[70:73], v[212:215], v[26:29]
	v_mfma_f32_16x16x32_bf16 v[22:25], v[78:81], v[130:133], v[22:25]
	v_mfma_f32_16x16x32_bf16 v[18:21], v[78:81], v[212:215], v[18:21]
	v_mfma_f32_16x16x32_bf16 v[2:5], v[200:203], v[212:215], v[2:5]
	v_mfma_f32_16x16x32_bf16 v[30:33], v[74:77], v[208:211], v[30:33]
	v_mfma_f32_16x16x32_bf16 v[26:29], v[74:77], v[164:167], v[26:29]
	v_mfma_f32_16x16x32_bf16 v[22:25], v[188:191], v[208:211], v[22:25]
	v_mfma_f32_16x16x32_bf16 v[18:21], v[188:191], v[164:167], v[18:21]
	v_mfma_f32_16x16x32_bf16 v[14:17], v[192:195], v[130:133], v[14:17]
	v_mfma_f32_16x16x32_bf16 v[10:13], v[192:195], v[212:215], v[10:13]
	v_mfma_f32_16x16x32_bf16 v[6:9], v[200:203], v[130:133], v[6:9]
	v_mfma_f32_16x16x32_bf16 v[2:5], v[204:207], v[164:167], v[2:5]
	v_mfma_f32_16x16x32_bf16 v[154:157], v[196:199], v[208:211], v[14:17]
	v_mfma_f32_16x16x32_bf16 v[188:191], v[196:199], v[164:167], v[10:13]
	v_mfma_f32_16x16x32_bf16 v[192:195], v[204:207], v[208:211], v[6:9]
	s_setprio 0
	s_barrier
	s_nop 1
	ds_read_b128 v[6:9], v153
	ds_read_b128 v[10:13], v153 offset:1024
	ds_read_b128 v[14:17], v153 offset:2048
	ds_read_b128 v[164:167], v153 offset:3072
	ds_read_b128 v[38:41], v149 offset:32768
	ds_read_b128 v[42:45], v149 offset:33792
	ds_read_b128 v[46:49], v148 offset:32768
	ds_read_b128 v[70:73], v148 offset:33792
	ds_read_b128 v[196:199], v147 offset:32768
	ds_read_b128 v[200:203], v147 offset:33792
	ds_read_b128 v[204:207], v146 offset:32768
	ds_read_b128 v[208:211], v146 offset:33792
	s_waitcnt vmcnt(2)
	s_barrier
; #define LDA(dst, b, hh) _Pragma("unroll") for (int m = 0; m < 4; ++m) _Pragma("unroll") for (int k = 0; k < 2; ++k) \
;         dst[m][k] = *(const bf16x8*)(SA(b, hh) + lds_byte(wr * 64 + m * 16 + fr, k * 32 + fq * 8))
; #define LDB(dst, b, hh) _Pragma("unroll") for (int n = 0; n < 2; ++n) _Pragma("unroll") for (int k = 0; k < 2; ++k) \
;         dst[n][k] = *(const bf16x8*)(SB(b, hh) + lds_byte(wc * 32 + n * 16 + fr, k * 32 + fq * 8))
; #define MMA(ai, bj, At_, Bt_) do { __builtin_amdgcn_s_setprio(1); \
;         _Pragma("unroll") for (int m = 0; m < 4; ++m) _Pragma("unroll") for (int n = 0; n < 2; ++n) _Pragma("unroll") for (int k = 0; k < 2; ++k) \
;             acc[ai][bj][m][n] = MFMA16(At_[m][k], Bt_[n][k], acc[ai][bj][m][n]); \
;         __builtin_amdgcn_s_setprio(0); } while (0)
; #define WAIT_V(n) asm volatile("s_waitcnt vmcnt(" #n ")" ::: "memory")
; #define WAIT_L(n) asm volatile("s_waitcnt lgkmcnt(" #n ")" ::: "memory")
; #define BAR __builtin_amdgcn_s_barrier()
; #define LDA(dst, b, hh) _Pragma("unroll") for (int m = 0; m < 4; ++m) _Pragma("unroll") for (int k = 0; k < 2; ++k) \
;         dst[m][k] = *(const bf16x8*)(SA(b, hh) + lds_byte(wr * 64 + m * 16 + fr, k * 32 + fq * 8))
; #define LDB(dst, b, hh) _Pragma("unroll") for (int n = 0; n < 2; ++n) _Pragma("unroll") for (int k = 0; k < 2; ++k) \
;         dst[n][k] = *(const bf16x8*)(SB(b, hh) + lds_byte(wc * 32 + n * 16 + fr, k * 32 + fq * 8))
; #define MMA(ai, bj, At_, Bt_) do { __builtin_amdgcn_s_setprio(1); \
;         _Pragma("unroll") for (int m = 0; m < 4; ++m) _Pragma("unroll") for (int n = 0; n < 2; ++n) _Pragma("unroll") for (int k = 0; k < 2; ++k) \
;             acc[ai][bj][m][n] = MFMA16(At_[m][k], Bt_[n][k], acc[ai][bj][m][n]); \
;         __builtin_amdgcn_s_setprio(0); } while (0)
; #define WAIT_V(n) asm volatile("s_waitcnt vmcnt(" #n ")" ::: "memory")
; #define WAIT_L(n) asm volatile("s_waitcnt lgkmcnt(" #n ")" ::: "memory")
; #define BAR __builtin_amdgcn_s_barrier()
; DI void gemm8(f32x4 (&acc)[2][2][4][2], const bf16_t* __restrict__ Rm, const bf16_t* __restrict__ Cm, int K, char* shm) {
;     ...
;     { LDB(B0, 1, 0); LDA(At, 1, 0); WAIT_V(2); BAR; WAIT_L(0); MMA(0, 0, At, B0); BAR;
;       LDB(B1, 1, 1); WAIT_V(0); BAR; WAIT_L(0); MMA(0, 1, At, B1); BAR;
;       LDA(At, 1, 1); BAR; WAIT_L(0); MMA(1, 0, At, B0); MMA(1, 1, At, B1); BAR; }
;     if (wr == 0) BAR;
	s_waitcnt lgkmcnt(0)
	s_setprio 1
	s_waitcnt lgkmcnt(0)
	v_mfma_f32_16x16x32_bf16 v[74:77], v[38:41], v[6:9], v[126:129]
	v_mfma_f32_16x16x32_bf16 v[142:145], v[42:45], v[10:13], v[74:77]
	v_mfma_f32_16x16x32_bf16 v[74:77], v[38:41], v[14:17], v[122:125]
	v_mfma_f32_16x16x32_bf16 v[126:129], v[42:45], v[164:167], v[74:77]
	v_mfma_f32_16x16x32_bf16 v[74:77], v[46:49], v[6:9], v[118:121]
	v_mfma_f32_16x16x32_bf16 v[138:141], v[70:73], v[10:13], v[74:77]
	v_mfma_f32_16x16x32_bf16 v[74:77], v[46:49], v[14:17], v[114:117]
	v_mfma_f32_16x16x32_bf16 v[122:125], v[70:73], v[164:167], v[74:77]
	v_mfma_f32_16x16x32_bf16 v[74:77], v[196:199], v[6:9], v[110:113]
	v_mfma_f32_16x16x32_bf16 v[134:137], v[200:203], v[10:13], v[74:77]
	v_mfma_f32_16x16x32_bf16 v[74:77], v[196:199], v[14:17], v[106:109]
	v_mfma_f32_16x16x32_bf16 v[118:121], v[200:203], v[164:167], v[74:77]
	v_mfma_f32_16x16x32_bf16 v[74:77], v[204:207], v[6:9], v[102:105]
	v_mfma_f32_16x16x32_bf16 v[130:133], v[208:211], v[10:13], v[74:77]
	v_mfma_f32_16x16x32_bf16 v[74:77], v[204:207], v[14:17], v[98:101]
	v_mfma_f32_16x16x32_bf16 v[114:117], v[208:211], v[164:167], v[74:77]
	s_setprio 0
	s_barrier
	ds_read_b128 v[212:215], v150
	ds_read_b128 v[228:231], v150 offset:1024
	ds_read_b128 v[232:235], v150 offset:2048
	ds_read_b128 v[150:153], v150 offset:3072
	s_waitcnt vmcnt(0)
	s_barrier
	s_waitcnt lgkmcnt(0)
	s_setprio 1
	s_waitcnt lgkmcnt(0)
	v_mfma_f32_16x16x32_bf16 v[74:77], v[38:41], v[212:215], v[94:97]
	v_mfma_f32_16x16x32_bf16 v[38:41], v[38:41], v[232:235], v[90:93]
	v_mfma_f32_16x16x32_bf16 v[78:81], v[42:45], v[150:153], v[38:41]
	v_mfma_f32_16x16x32_bf16 v[38:41], v[46:49], v[212:215], v[86:89]
	v_mfma_f32_16x16x32_bf16 v[106:109], v[70:73], v[228:231], v[38:41]
	v_mfma_f32_16x16x32_bf16 v[38:41], v[46:49], v[232:235], v[82:85]
	v_mfma_f32_16x16x32_bf16 v[110:113], v[42:45], v[228:231], v[74:77]
	v_mfma_f32_16x16x32_bf16 v[74:77], v[70:73], v[150:153], v[38:41]
	v_mfma_f32_16x16x32_bf16 v[38:41], v[196:199], v[212:215], v[158:161]
	v_mfma_f32_16x16x32_bf16 v[102:105], v[200:203], v[228:231], v[38:41]
	v_mfma_f32_16x16x32_bf16 v[38:41], v[196:199], v[232:235], v[168:171]
	v_mfma_f32_16x16x32_bf16 v[70:73], v[200:203], v[150:153], v[38:41]
	v_mfma_f32_16x16x32_bf16 v[38:41], v[204:207], v[212:215], v[184:187]
	v_mfma_f32_16x16x32_bf16 v[98:101], v[208:211], v[228:231], v[38:41]
	v_mfma_f32_16x16x32_bf16 v[38:41], v[204:207], v[232:235], v[66:69]
	v_mfma_f32_16x16x32_bf16 v[66:69], v[208:211], v[150:153], v[38:41]
	s_setprio 0
	s_barrier
	ds_read_b128 v[82:85], v149 offset:49152
	ds_read_b128 v[86:89], v149 offset:50176
	ds_read_b128 v[90:93], v148 offset:49152
	ds_read_b128 v[94:97], v148 offset:50176
	ds_read_b128 v[158:161], v147 offset:49152
	ds_read_b128 v[168:171], v147 offset:50176
	ds_read_b128 v[184:187], v146 offset:49152
	ds_read_b128 v[146:149], v146 offset:50176
	s_barrier
	s_waitcnt lgkmcnt(0)
	s_setprio 1
	s_waitcnt lgkmcnt(0)
	v_mfma_f32_16x16x32_bf16 v[38:41], v[82:85], v[6:9], v[62:65]
	v_mfma_f32_16x16x32_bf16 v[62:65], v[86:89], v[10:13], v[38:41]
	v_mfma_f32_16x16x32_bf16 v[38:41], v[82:85], v[14:17], v[58:61]
	v_mfma_f32_16x16x32_bf16 v[46:49], v[86:89], v[164:167], v[38:41]
	v_mfma_f32_16x16x32_bf16 v[38:41], v[90:93], v[6:9], v[54:57]
	v_mfma_f32_16x16x32_bf16 v[58:61], v[94:97], v[10:13], v[38:41]
	v_mfma_f32_16x16x32_bf16 v[38:41], v[90:93], v[14:17], v[50:53]
	v_mfma_f32_16x16x32_bf16 v[42:45], v[94:97], v[164:167], v[38:41]
	v_mfma_f32_16x16x32_bf16 v[38:41], v[158:161], v[6:9], v[216:219]
	v_mfma_f32_16x16x32_bf16 v[6:9], v[184:187], v[6:9], v[224:227]
	v_mfma_f32_16x16x32_bf16 v[54:57], v[168:171], v[10:13], v[38:41]
	v_mfma_f32_16x16x32_bf16 v[38:41], v[158:161], v[14:17], v[220:223]
	v_mfma_f32_16x16x32_bf16 v[50:53], v[146:149], v[10:13], v[6:9]
	v_mfma_f32_16x16x32_bf16 v[6:9], v[184:187], v[14:17], v[34:37]
	v_mfma_f32_16x16x32_bf16 v[38:41], v[168:171], v[164:167], v[38:41]
	v_mfma_f32_16x16x32_bf16 v[34:37], v[146:149], v[164:167], v[6:9]
	s_setprio 0
	s_setprio 1
	v_mfma_f32_16x16x32_bf16 v[6:9], v[82:85], v[212:215], v[30:33]
	v_mfma_f32_16x16x32_bf16 v[30:33], v[86:89], v[228:231], v[6:9]
	v_mfma_f32_16x16x32_bf16 v[6:9], v[82:85], v[232:235], v[26:29]
	v_mfma_f32_16x16x32_bf16 v[14:17], v[86:89], v[150:153], v[6:9]
	v_mfma_f32_16x16x32_bf16 v[6:9], v[90:93], v[212:215], v[22:25]
	v_mfma_f32_16x16x32_bf16 v[26:29], v[94:97], v[228:231], v[6:9]
	v_mfma_f32_16x16x32_bf16 v[6:9], v[90:93], v[232:235], v[18:21]
	v_mfma_f32_16x16x32_bf16 v[10:13], v[94:97], v[150:153], v[6:9]
	v_mfma_f32_16x16x32_bf16 v[6:9], v[158:161], v[212:215], v[154:157]
	v_mfma_f32_16x16x32_bf16 v[22:25], v[168:171], v[228:231], v[6:9]
	v_mfma_f32_16x16x32_bf16 v[6:9], v[158:161], v[232:235], v[188:191]
	v_mfma_f32_16x16x32_bf16 v[18:21], v[184:187], v[212:215], v[192:195]
	v_mfma_f32_16x16x32_bf16 v[2:5], v[184:187], v[232:235], v[2:5]
	v_mfma_f32_16x16x32_bf16 v[6:9], v[168:171], v[150:153], v[6:9]
	v_mfma_f32_16x16x32_bf16 v[18:21], v[146:149], v[228:231], v[18:21]
	v_mfma_f32_16x16x32_bf16 v[2:5], v[146:149], v[150:153], v[2:5]
	s_setprio 0
	v_cmp_gt_u32_e32 vcc, s96, v0
	s_barrier
	s_and_saveexec_b64 s[22:23], vcc
	s_cbranch_execz .LBB0_46
	s_barrier
	s_branch .LBB0_46

; #define STAGE(P, BASE, br, kt) do { const bf16_t* g_ = (BASE) + (size_t)(br) * K + (size_t)(kt) * 64; \
;         _Pragma("unroll") for (int i_ = 0; i_ < 2; ++i_) \
;             __builtin_amdgcn_global_load_lds((const unsigned*)(g_ + gofs[i_]), (lds_ptr_t)((P) + wb + i_ * 8192), 16, 0, 0); } while (0)
; #define LDA(dst, b, hh) _Pragma("unroll") for (int m = 0; m < 4; ++m) _Pragma("unroll") for (int k = 0; k < 2; ++k) \
;         dst[m][k] = *(const bf16x8*)(SA(b, hh) + lds_byte(wr * 64 + m * 16 + fr, k * 32 + fq * 8))
; #define LDB(dst, b, hh) _Pragma("unroll") for (int n = 0; n < 2; ++n) _Pragma("unroll") for (int k = 0; k < 2; ++k) \
;         dst[n][k] = *(const bf16x8*)(SB(b, hh) + lds_byte(wc * 32 + n * 16 + fr, k * 32 + fq * 8))
; #define MMA(ai, bj, At_, Bt_) do { __builtin_amdgcn_s_setprio(1); \
;         _Pragma("unroll") for (int m = 0; m < 4; ++m) _Pragma("unroll") for (int n = 0; n < 2; ++n) _Pragma("unroll") for (int k = 0; k < 2; ++k) \
;             acc[ai][bj][m][n] = MFMA16(At_[m][k], Bt_[n][k], acc[ai][bj][m][n]); \
;         __builtin_amdgcn_s_setprio(0); } while (0)
; #define WAIT_L(n) asm volatile("s_waitcnt lgkmcnt(" #n ")" ::: "memory")
; #define BAR __builtin_amdgcn_s_barrier()
; #define SCHED __builtin_amdgcn_sched_barrier(0)
; #define STAGE(P, BASE, br, kt) do { const int sg_ = (kt) >> 3; const bf16_t* g_ = (sg_ == 0 ? BASE##0 : sg_ == 1 ? BASE##1 : BASE##2) + (size_t)(br) * K + (size_t)((kt) & 7) * 64; \
;         _Pragma("unroll") for (int i_ = 0; i_ < 2; ++i_) \
;             __builtin_amdgcn_global_load_lds((const unsigned*)(g_ + gofs[i_]), (lds_ptr_t)((P) + wb + i_ * 8192), 16, 0, 0); } while (0)
; #define WAIT_L(n) asm volatile("s_waitcnt lgkmcnt(" #n ")" ::: "memory")
; #define BAR __builtin_amdgcn_s_barrier()
; template <class Hook>
; DI void gemm8_cat3(f32x4 (&acc)[2][2][4][2], const bf16_t* R0, const bf16_t* R1, const bf16_t* R2, const bf16_t* C0, const bf16_t* C1, const bf16_t* C2, char* shm, Hook hook) {
;     ...
;         LDB(B0, 0, 0); SCHED; LDA(At, 0, 0); STAGE(SA(1, 1), R, 128, tt + 1);
;         WAIT_L(8); BAR; WAIT_L(0); MMA(0, 0, At, B0); BAR; SCHED;
;         LDB(B1, 0, 1); STAGE(SB(0, 0), C, 0, tt + 2);
;         BAR; WAIT_L(0); MMA(0, 1, At, B1); BAR;
;         LDA(At, 0, 1); STAGE(SA(0, 0), R, 0, tt + 2);
;         BAR; WAIT_L(0); MMA(1, 0, At, B0); BAR; SCHED;
;         STAGE(SB(0, 1), C, 128, tt + 2);
.LBB0_56:
	v_add_u32_e32 v190, 0xc000, v158
	v_add_u32_e32 v191, 0xe000, v158
	v_readfirstlane_b32 s7, v190
	s_mov_b32 m0, s7
	v_readfirstlane_b32 s7, v191
	global_load_lds_dwordx4 v[130:131], off
	s_mov_b32 m0, s7
	s_nop 0
	global_load_lds_dwordx4 v[132:133], off
	ds_read_b128 v[150:153], v189
	ds_read_b128 v[192:195], v189 offset:1024
	ds_read_b128 v[196:199], v189 offset:2048
	ds_read_b128 v[200:203], v189 offset:3072
	ds_read_b128 v[204:207], v157
	ds_read_b128 v[208:211], v157 offset:1024
	ds_read_b128 v[212:215], v156
	ds_read_b128 v[216:219], v156 offset:1024
	ds_read_b128 v[220:223], v155
	ds_read_b128 v[224:227], v155 offset:1024
	ds_read_b128 v[228:231], v154
	ds_read_b128 v[232:235], v154 offset:1024
	s_waitcnt lgkmcnt(8)
	s_barrier
	s_waitcnt lgkmcnt(0)
	s_setprio 1
	s_waitcnt lgkmcnt(0)
	v_mfma_f32_16x16x32_bf16 v[18:21], v[204:207], v[150:153], v[18:21]
	v_mfma_f32_16x16x32_bf16 v[58:61], v[204:207], v[196:199], v[58:61]
	v_mfma_f32_16x16x32_bf16 v[30:33], v[212:215], v[150:153], v[30:33]
	v_mfma_f32_16x16x32_bf16 v[54:57], v[212:215], v[196:199], v[54:57]
	v_mfma_f32_16x16x32_bf16 v[26:29], v[220:223], v[150:153], v[26:29]
	v_mfma_f32_16x16x32_bf16 v[50:53], v[220:223], v[196:199], v[50:53]
	v_mfma_f32_16x16x32_bf16 v[42:45], v[228:231], v[150:153], v[42:45]
	v_mfma_f32_16x16x32_bf16 v[46:49], v[228:231], v[196:199], v[46:49]
	v_mfma_f32_16x16x32_bf16 v[18:21], v[208:211], v[192:195], v[18:21]
	v_mfma_f32_16x16x32_bf16 v[58:61], v[208:211], v[200:203], v[58:61]
	v_mfma_f32_16x16x32_bf16 v[30:33], v[216:219], v[192:195], v[30:33]
	v_mfma_f32_16x16x32_bf16 v[54:57], v[216:219], v[200:203], v[54:57]
	v_mfma_f32_16x16x32_bf16 v[26:29], v[224:227], v[192:195], v[26:29]
	v_mfma_f32_16x16x32_bf16 v[50:53], v[224:227], v[200:203], v[50:53]
	v_mfma_f32_16x16x32_bf16 v[42:45], v[232:235], v[192:195], v[42:45]
	v_mfma_f32_16x16x32_bf16 v[46:49], v[232:235], v[200:203], v[46:49]
	s_setprio 0
	s_barrier
	s_add_i32 s7, s6, 2
	s_cmp_lt_u32 s6, 6
	s_cselect_b64 s[16:17], -1, 0
	s_and_b64 s[20:21], s[16:17], exec
	s_cselect_b32 s21, s11, s82
	s_cselect_b32 s20, s10, s25
	s_and_b32 s22, s2, 0x180
	s_lshl_b32 s22, s22, 1
	s_add_u32 s20, s20, s22
	s_addc_u32 s21, s21, 0
	v_readfirstlane_b32 s23, v159
	v_lshl_add_u64 v[172:173], s[20:21], 0, v[134:135]
	s_mov_b32 m0, s23
	v_readfirstlane_b32 s23, v160
	global_load_lds_dwordx4 v[172:173], off
	v_lshl_add_u64 v[172:173], s[20:21], 0, v[136:137]
	s_mov_b32 m0, s23
	s_nop 0
	global_load_lds_dwordx4 v[172:173], off
	ds_read_b128 v[236:239], v188
	ds_read_b128 v[240:243], v188 offset:1024
	ds_read_b128 v[244:247], v188 offset:2048
	ds_read_b128 v[248:251], v188 offset:3072
	s_barrier
	s_waitcnt lgkmcnt(0)
	s_setprio 1
	s_waitcnt lgkmcnt(0)
	v_mfma_f32_16x16x32_bf16 v[74:77], v[204:207], v[236:239], v[74:77]
	v_mfma_f32_16x16x32_bf16 v[90:93], v[204:207], v[244:247], v[90:93]
	v_mfma_f32_16x16x32_bf16 v[70:73], v[212:215], v[236:239], v[70:73]
	v_mfma_f32_16x16x32_bf16 v[86:89], v[212:215], v[244:247], v[86:89]
	v_mfma_f32_16x16x32_bf16 v[66:69], v[220:223], v[236:239], v[66:69]
	v_mfma_f32_16x16x32_bf16 v[82:85], v[220:223], v[244:247], v[82:85]
	v_mfma_f32_16x16x32_bf16 v[62:65], v[228:231], v[236:239], v[62:65]
	v_mfma_f32_16x16x32_bf16 v[78:81], v[228:231], v[244:247], v[78:81]
	v_mfma_f32_16x16x32_bf16 v[74:77], v[208:211], v[240:243], v[74:77]
	v_mfma_f32_16x16x32_bf16 v[90:93], v[208:211], v[248:251], v[90:93]
	v_mfma_f32_16x16x32_bf16 v[70:73], v[216:219], v[240:243], v[70:73]
	v_mfma_f32_16x16x32_bf16 v[86:89], v[216:219], v[248:251], v[86:89]
	v_mfma_f32_16x16x32_bf16 v[66:69], v[224:227], v[240:243], v[66:69]
	v_mfma_f32_16x16x32_bf16 v[82:85], v[224:227], v[248:251], v[82:85]
	v_mfma_f32_16x16x32_bf16 v[62:65], v[232:235], v[240:243], v[62:65]
	v_mfma_f32_16x16x32_bf16 v[78:81], v[232:235], v[248:251], v[78:81]
	s_setprio 0
	s_and_b64 vcc, s[16:17], exec
	s_cselect_b32 s16, s8, s15
	s_cselect_b32 s17, s9, s24
	s_add_u32 s16, s16, s22
	s_addc_u32 s17, s17, 0
	v_readfirstlane_b32 s22, v158
	v_lshl_add_u64 v[172:173], s[16:17], 0, v[134:135]
	s_mov_b32 m0, s22
	v_readfirstlane_b32 s22, v164
	s_barrier
	global_load_lds_dwordx4 v[172:173], off
	v_lshl_add_u64 v[172:173], s[16:17], 0, v[136:137]
	s_mov_b32 m0, s22
	s_nop 0
	global_load_lds_dwordx4 v[172:173], off
	ds_read_b128 v[204:207], v157 offset:16384
	ds_read_b128 v[208:211], v157 offset:17408
	ds_read_b128 v[212:215], v156 offset:16384
	ds_read_b128 v[216:219], v156 offset:17408
	ds_read_b128 v[220:223], v155 offset:16384
	ds_read_b128 v[224:227], v155 offset:17408
	ds_read_b128 v[228:231], v154 offset:16384
	ds_read_b128 v[232:235], v154 offset:17408
	s_barrier
	s_waitcnt lgkmcnt(0)
	s_setprio 1
	s_waitcnt lgkmcnt(0)
	v_mfma_f32_16x16x32_bf16 v[106:109], v[204:207], v[150:153], v[106:109]
	v_mfma_f32_16x16x32_bf16 v[122:125], v[204:207], v[196:199], v[122:125]
	v_mfma_f32_16x16x32_bf16 v[102:105], v[212:215], v[150:153], v[102:105]
	v_mfma_f32_16x16x32_bf16 v[118:121], v[212:215], v[196:199], v[118:121]
	v_mfma_f32_16x16x32_bf16 v[98:101], v[220:223], v[150:153], v[98:101]
	v_mfma_f32_16x16x32_bf16 v[114:117], v[220:223], v[196:199], v[114:117]
	v_mfma_f32_16x16x32_bf16 v[94:97], v[228:231], v[150:153], v[94:97]
	v_mfma_f32_16x16x32_bf16 v[110:113], v[228:231], v[196:199], v[110:113]
	v_mfma_f32_16x16x32_bf16 v[106:109], v[208:211], v[192:195], v[106:109]
	v_mfma_f32_16x16x32_bf16 v[122:125], v[208:211], v[200:203], v[122:125]
	v_mfma_f32_16x16x32_bf16 v[102:105], v[216:219], v[192:195], v[102:105]
	v_mfma_f32_16x16x32_bf16 v[118:121], v[216:219], v[200:203], v[118:121]
	v_mfma_f32_16x16x32_bf16 v[98:101], v[224:227], v[192:195], v[98:101]
	v_mfma_f32_16x16x32_bf16 v[114:117], v[224:227], v[200:203], v[114:117]
	v_mfma_f32_16x16x32_bf16 v[94:97], v[232:235], v[192:195], v[94:97]
	v_mfma_f32_16x16x32_bf16 v[110:113], v[232:235], v[200:203], v[110:113]
	s_setprio 0
	s_barrier
; #define STAGE(P, BASE, br, kt) do { const bf16_t* g_ = (BASE) + (size_t)(br) * K + (size_t)(kt) * 64; \
;         _Pragma("unroll") for (int i_ = 0; i_ < 2; ++i_) \
;             __builtin_amdgcn_global_load_lds((const unsigned*)(g_ + gofs[i_]), (lds_ptr_t)((P) + wb + i_ * 8192), 16, 0, 0); } while (0)
; #define LDA(dst, b, hh) _Pragma("unroll") for (int m = 0; m < 4; ++m) _Pragma("unroll") for (int k = 0; k < 2; ++k) \
;         dst[m][k] = *(const bf16x8*)(SA(b, hh) + lds_byte(wr * 64 + m * 16 + fr, k * 32 + fq * 8))
; #define LDB(dst, b, hh) _Pragma("unroll") for (int n = 0; n < 2; ++n) _Pragma("unroll") for (int k = 0; k < 2; ++k) \
;         dst[n][k] = *(const bf16x8*)(SB(b, hh) + lds_byte(wc * 32 + n * 16 + fr, k * 32 + fq * 8))
; #define MMA(ai, bj, At_, Bt_) do { __builtin_amdgcn_s_setprio(1); \
;         _Pragma("unroll") for (int m = 0; m < 4; ++m) _Pragma("unroll") for (int n = 0; n < 2; ++n) _Pragma("unroll") for (int k = 0; k < 2; ++k) \
;             acc[ai][bj][m][n] = MFMA16(At_[m][k], Bt_[n][k], acc[ai][bj][m][n]); \
;         __builtin_amdgcn_s_setprio(0); } while (0)
; #define WAIT_V(n) asm volatile("s_waitcnt vmcnt(" #n ")" ::: "memory")
; #define WAIT_L(n) asm volatile("s_waitcnt lgkmcnt(" #n ")" ::: "memory")
; #define BAR __builtin_amdgcn_s_barrier()
; #define SCHED __builtin_amdgcn_sched_barrier(0)
; #define STAGE(P, BASE, br, kt) do { const int sg_ = (kt) >> 3; const bf16_t* g_ = (sg_ == 0 ? BASE##0 : sg_ == 1 ? BASE##1 : BASE##2) + (size_t)(br) * K + (size_t)((kt) & 7) * 64; \
;         _Pragma("unroll") for (int i_ = 0; i_ < 2; ++i_) \
;             __builtin_amdgcn_global_load_lds((const unsigned*)(g_ + gofs[i_]), (lds_ptr_t)((P) + wb + i_ * 8192), 16, 0, 0); } while (0)
; #define BAR __builtin_amdgcn_s_barrier()
; template <class Hook>
; DI void gemm8_cat3(f32x4 (&acc)[2][2][4][2], const bf16_t* R0, const bf16_t* R1, const bf16_t* R2, const bf16_t* C0, const bf16_t* C1, const bf16_t* C2, char* shm, Hook hook) {
;     ...
;         STAGE(SB(0, 1), C, 128, tt + 2);
;         WAIT_V(6); BAR; MMA(1, 1, At, B1); BAR;
;         LDB(B0, 1, 0); SCHED; LDA(At, 1, 0); STAGE(SA(0, 1), R, 128, tt + 2);
;         WAIT_L(8); BAR; WAIT_L(0); MMA(0, 0, At, B0); BAR; SCHED;
;         LDB(B1, 1, 1); STAGE(SB(1, 0), C, 0, tt + 3);
;         BAR; WAIT_L(0); MMA(0, 1, At, B1); BAR;
;         LDA(At, 1, 1); STAGE(SA(1, 0), R, 0, tt + 3);
	s_add_u32 s20, s20, 0x20000
	s_addc_u32 s21, s21, 0
	v_readfirstlane_b32 s22, v165
	v_lshl_add_u64 v[150:151], s[20:21], 0, v[134:135]
	s_mov_b32 m0, s22
	s_nop 0
	global_load_lds_dwordx4 v[150:151], off
	v_lshl_add_u64 v[150:151], s[20:21], 0, v[136:137]
	v_readfirstlane_b32 s20, v166
	s_mov_b32 m0, s20
	s_nop 0
	global_load_lds_dwordx4 v[150:151], off
	s_waitcnt vmcnt(6)
	s_barrier
	s_setprio 1
	v_mfma_f32_16x16x32_bf16 v[126:129], v[204:207], v[236:239], v[126:129]
	v_mfma_f32_16x16x32_bf16 v[14:17], v[204:207], v[244:247], v[14:17]
	v_mfma_f32_16x16x32_bf16 v[34:37], v[212:215], v[236:239], v[34:37]
	v_mfma_f32_16x16x32_bf16 v[6:9], v[212:215], v[244:247], v[6:9]
	v_mfma_f32_16x16x32_bf16 v[38:41], v[220:223], v[236:239], v[38:41]
	v_mfma_f32_16x16x32_bf16 v[10:13], v[220:223], v[244:247], v[10:13]
	v_mfma_f32_16x16x32_bf16 v[22:25], v[228:231], v[236:239], v[22:25]
	v_mfma_f32_16x16x32_bf16 v[2:5], v[228:231], v[244:247], v[2:5]
	v_mfma_f32_16x16x32_bf16 v[126:129], v[208:211], v[240:243], v[126:129]
	v_mfma_f32_16x16x32_bf16 v[14:17], v[208:211], v[248:251], v[14:17]
	v_mfma_f32_16x16x32_bf16 v[34:37], v[216:219], v[240:243], v[34:37]
	v_mfma_f32_16x16x32_bf16 v[6:9], v[216:219], v[248:251], v[6:9]
	v_mfma_f32_16x16x32_bf16 v[38:41], v[224:227], v[240:243], v[38:41]
	v_mfma_f32_16x16x32_bf16 v[10:13], v[224:227], v[248:251], v[10:13]
	v_mfma_f32_16x16x32_bf16 v[22:25], v[232:235], v[240:243], v[22:25]
	v_mfma_f32_16x16x32_bf16 v[2:5], v[232:235], v[248:251], v[2:5]
	s_setprio 0
	s_barrier
	s_add_u32 s16, s16, 0x20000
	s_addc_u32 s17, s17, 0
	v_readfirstlane_b32 s20, v167
	v_lshl_add_u64 v[172:173], s[16:17], 0, v[134:135]
	s_mov_b32 m0, s20
	s_nop 0
	global_load_lds_dwordx4 v[172:173], off
	v_lshl_add_u64 v[172:173], s[16:17], 0, v[136:137]
	v_readfirstlane_b32 s16, v168
	s_mov_b32 m0, s16
	s_nop 0
	global_load_lds_dwordx4 v[172:173], off
	ds_read_b128 v[150:153], v169
	ds_read_b128 v[192:195], v169 offset:1024
	ds_read_b128 v[196:199], v169 offset:2048
	ds_read_b128 v[200:203], v169 offset:3072
	ds_read_b128 v[204:207], v157 offset:32768
	ds_read_b128 v[208:211], v157 offset:33792
	ds_read_b128 v[212:215], v156 offset:32768
	ds_read_b128 v[216:219], v156 offset:33792
	ds_read_b128 v[220:223], v155 offset:32768
	ds_read_b128 v[224:227], v155 offset:33792
	ds_read_b128 v[228:231], v154 offset:32768
	ds_read_b128 v[232:235], v154 offset:33792
	s_waitcnt lgkmcnt(8)
	s_barrier
	s_waitcnt lgkmcnt(0)
	s_setprio 1
	s_waitcnt lgkmcnt(0)
	v_mfma_f32_16x16x32_bf16 v[18:21], v[204:207], v[150:153], v[18:21]
	v_mfma_f32_16x16x32_bf16 v[58:61], v[204:207], v[196:199], v[58:61]
	v_mfma_f32_16x16x32_bf16 v[30:33], v[212:215], v[150:153], v[30:33]
	v_mfma_f32_16x16x32_bf16 v[54:57], v[212:215], v[196:199], v[54:57]
	v_mfma_f32_16x16x32_bf16 v[26:29], v[220:223], v[150:153], v[26:29]
	v_mfma_f32_16x16x32_bf16 v[50:53], v[220:223], v[196:199], v[50:53]
	v_mfma_f32_16x16x32_bf16 v[42:45], v[228:231], v[150:153], v[42:45]
	v_mfma_f32_16x16x32_bf16 v[46:49], v[228:231], v[196:199], v[46:49]
	v_mfma_f32_16x16x32_bf16 v[18:21], v[208:211], v[192:195], v[18:21]
	v_mfma_f32_16x16x32_bf16 v[58:61], v[208:211], v[200:203], v[58:61]
	v_mfma_f32_16x16x32_bf16 v[30:33], v[216:219], v[192:195], v[30:33]
	v_mfma_f32_16x16x32_bf16 v[54:57], v[216:219], v[200:203], v[54:57]
	v_mfma_f32_16x16x32_bf16 v[26:29], v[224:227], v[192:195], v[26:29]
	v_mfma_f32_16x16x32_bf16 v[50:53], v[224:227], v[200:203], v[50:53]
	v_mfma_f32_16x16x32_bf16 v[42:45], v[232:235], v[192:195], v[42:45]
	v_mfma_f32_16x16x32_bf16 v[46:49], v[232:235], v[200:203], v[46:49]
	s_setprio 0
	s_barrier
	s_add_i32 s16, s2, 64
	s_and_b32 s16, s16, 0x1c0
	s_lshl_b32 s20, s16, 1
	s_cmp_lt_u32 s6, 5
	s_cselect_b32 s16, s10, s25
	s_cselect_b32 s6, s11, s82
	s_cselect_b32 s21, s9, s24
	s_cselect_b32 s22, s8, s15
	s_add_u32 s16, s16, s20
	s_addc_u32 s17, s6, 0
	v_readfirstlane_b32 s6, v170
	v_lshl_add_u64 v[172:173], s[16:17], 0, v[134:135]
	s_mov_b32 m0, s6
	v_readfirstlane_b32 s6, v171
	global_load_lds_dwordx4 v[172:173], off
	v_lshl_add_u64 v[172:173], s[16:17], 0, v[136:137]
	s_mov_b32 m0, s6
	s_nop 0
	global_load_lds_dwordx4 v[172:173], off
	ds_read_b128 v[236:239], v161
	ds_read_b128 v[240:243], v161 offset:1024
	ds_read_b128 v[244:247], v161 offset:2048
	ds_read_b128 v[248:251], v161 offset:3072
	s_barrier
	s_waitcnt lgkmcnt(0)
	s_setprio 1
	s_waitcnt lgkmcnt(0)
	v_mfma_f32_16x16x32_bf16 v[74:77], v[204:207], v[236:239], v[74:77]
	v_mfma_f32_16x16x32_bf16 v[90:93], v[204:207], v[244:247], v[90:93]
	v_mfma_f32_16x16x32_bf16 v[70:73], v[212:215], v[236:239], v[70:73]
	v_mfma_f32_16x16x32_bf16 v[86:89], v[212:215], v[244:247], v[86:89]
	v_mfma_f32_16x16x32_bf16 v[66:69], v[220:223], v[236:239], v[66:69]
	v_mfma_f32_16x16x32_bf16 v[82:85], v[220:223], v[244:247], v[82:85]
	v_mfma_f32_16x16x32_bf16 v[62:65], v[228:231], v[236:239], v[62:65]
	v_mfma_f32_16x16x32_bf16 v[78:81], v[228:231], v[244:247], v[78:81]
	v_mfma_f32_16x16x32_bf16 v[74:77], v[208:211], v[240:243], v[74:77]
	v_mfma_f32_16x16x32_bf16 v[90:93], v[208:211], v[248:251], v[90:93]
	v_mfma_f32_16x16x32_bf16 v[70:73], v[216:219], v[240:243], v[70:73]
	v_mfma_f32_16x16x32_bf16 v[86:89], v[216:219], v[248:251], v[86:89]
	v_mfma_f32_16x16x32_bf16 v[66:69], v[224:227], v[240:243], v[66:69]
	v_mfma_f32_16x16x32_bf16 v[82:85], v[224:227], v[248:251], v[82:85]
	v_mfma_f32_16x16x32_bf16 v[62:65], v[232:235], v[240:243], v[62:65]
	v_mfma_f32_16x16x32_bf16 v[78:81], v[232:235], v[248:251], v[78:81]
	s_setprio 0
	s_add_u32 s20, s22, s20
	s_addc_u32 s21, s21, 0
	v_readfirstlane_b32 s6, v184
	v_lshl_add_u64 v[172:173], s[20:21], 0, v[134:135]
	s_mov_b32 m0, s6
	v_readfirstlane_b32 s6, v185
	s_barrier
; DI float frcp(float x) { return __builtin_amdgcn_rcpf(x); }
; #define STAGE(P, BASE, br, kt) do { const bf16_t* g_ = (BASE) + (size_t)(br) * K + (size_t)(kt) * 64; \
;         _Pragma("unroll") for (int i_ = 0; i_ < 2; ++i_) \
;             __builtin_amdgcn_global_load_lds((const unsigned*)(g_ + gofs[i_]), (lds_ptr_t)((P) + wb + i_ * 8192), 16, 0, 0); } while (0)
; #define LDA(dst, b, hh) _Pragma("unroll") for (int m = 0; m < 4; ++m) _Pragma("unroll") for (int k = 0; k < 2; ++k) \
;         dst[m][k] = *(const bf16x8*)(SA(b, hh) + lds_byte(wr * 64 + m * 16 + fr, k * 32 + fq * 8))
; #define MMA(ai, bj, At_, Bt_) do { __builtin_amdgcn_s_setprio(1); \
;         _Pragma("unroll") for (int m = 0; m < 4; ++m) _Pragma("unroll") for (int n = 0; n < 2; ++n) _Pragma("unroll") for (int k = 0; k < 2; ++k) \
;             acc[ai][bj][m][n] = MFMA16(At_[m][k], Bt_[n][k], acc[ai][bj][m][n]); \
;         __builtin_amdgcn_s_setprio(0); } while (0)
; #define WAIT_V(n) asm volatile("s_waitcnt vmcnt(" #n ")" ::: "memory")
; #define WAIT_L(n) asm volatile("s_waitcnt lgkmcnt(" #n ")" ::: "memory")
; #define BAR __builtin_amdgcn_s_barrier()
; #define SCHED __builtin_amdgcn_sched_barrier(0)
; template <class Hook>
; DI void gemm8_cat3(f32x4 (&acc)[2][2][4][2], const bf16_t* R0, const bf16_t* R1, const bf16_t* R2, const bf16_t* C0, const bf16_t* C1, const bf16_t* C2, char* shm, Hook hook) {
;     ...
;         LDA(At, 1, 1); STAGE(SA(1, 0), R, 0, tt + 3);
;         BAR; WAIT_L(0); MMA(1, 0, At, B0); BAR; SCHED;
;         STAGE(SB(1, 1), C, 128, tt + 3);
;         WAIT_V(6); BAR; MMA(1, 1, At, B1); BAR;
;     }
; DI void merge_scale(const Params& P, int tile, int seg, f32x4 (&acc)[2][2][4][2]) {
; #pragma unroll
;     for (int g8 = 0; g8 < 8; ++g8) {
;         const int ai = g8 >> 2, bj = (g8 >> 1) & 1, nn = g8 & 1;
;         const u32x4 ga = *gate_slot(P, tile, seg, g8), gb = *gate_slot(P, tile, seg + 1, g8);
; #pragma unroll
;         for (int e = 0; e < 8; ++e) {
;             const float rl = (float)((ga[e >> 2] >> (8 * (e & 3))) & 255u) * frcp((float)((gb[e >> 2] >> (8 * (e & 3))) & 255u));
;             const float rh = (float)((ga[2 + (e >> 2)] >> (8 * (e & 3))) & 255u) * frcp((float)((gb[2 + (e >> 2)] >> (8 * (e & 3))) & 255u));
;             acc[ai][bj][e >> 2][nn][e & 3] *= rl;
;             acc[ai][bj][2 + (e >> 2)][nn][e & 3] *= rh;
;         }
	global_load_lds_dwordx4 v[172:173], off
	v_lshl_add_u64 v[172:173], s[20:21], 0, v[136:137]
	s_mov_b32 m0, s6
	s_nop 0
	global_load_lds_dwordx4 v[172:173], off
	ds_read_b128 v[204:207], v157 offset:49152
	ds_read_b128 v[208:211], v157 offset:50176
	ds_read_b128 v[212:215], v156 offset:49152
	ds_read_b128 v[216:219], v156 offset:50176
	ds_read_b128 v[220:223], v155 offset:49152
	ds_read_b128 v[224:227], v155 offset:50176
	ds_read_b128 v[228:231], v154 offset:49152
	ds_read_b128 v[232:235], v154 offset:50176
	s_barrier
	s_waitcnt lgkmcnt(0)
	s_setprio 1
	s_waitcnt lgkmcnt(0)
	v_mfma_f32_16x16x32_bf16 v[106:109], v[204:207], v[150:153], v[106:109]
	v_mfma_f32_16x16x32_bf16 v[122:125], v[204:207], v[196:199], v[122:125]
	v_mfma_f32_16x16x32_bf16 v[102:105], v[212:215], v[150:153], v[102:105]
	v_mfma_f32_16x16x32_bf16 v[118:121], v[212:215], v[196:199], v[118:121]
	v_mfma_f32_16x16x32_bf16 v[98:101], v[220:223], v[150:153], v[98:101]
	v_mfma_f32_16x16x32_bf16 v[114:117], v[220:223], v[196:199], v[114:117]
	v_mfma_f32_16x16x32_bf16 v[94:97], v[228:231], v[150:153], v[94:97]
	v_mfma_f32_16x16x32_bf16 v[110:113], v[228:231], v[196:199], v[110:113]
	v_mfma_f32_16x16x32_bf16 v[106:109], v[208:211], v[192:195], v[106:109]
	v_mfma_f32_16x16x32_bf16 v[122:125], v[208:211], v[200:203], v[122:125]
	v_mfma_f32_16x16x32_bf16 v[102:105], v[216:219], v[192:195], v[102:105]
	v_mfma_f32_16x16x32_bf16 v[118:121], v[216:219], v[200:203], v[118:121]
	v_mfma_f32_16x16x32_bf16 v[98:101], v[224:227], v[192:195], v[98:101]
	v_mfma_f32_16x16x32_bf16 v[114:117], v[224:227], v[200:203], v[114:117]
	v_mfma_f32_16x16x32_bf16 v[94:97], v[232:235], v[192:195], v[94:97]
	v_mfma_f32_16x16x32_bf16 v[110:113], v[232:235], v[200:203], v[110:113]
	s_setprio 0
	s_barrier
	s_add_u32 s16, s16, 0x20000
	s_addc_u32 s17, s17, 0
	v_readfirstlane_b32 s6, v186
	v_lshl_add_u64 v[150:151], s[16:17], 0, v[134:135]
	s_mov_b32 m0, s6
	v_readfirstlane_b32 s6, v187
	global_load_lds_dwordx4 v[150:151], off
	v_lshl_add_u64 v[150:151], s[16:17], 0, v[136:137]
	s_mov_b32 m0, s6
	s_nop 0
	global_load_lds_dwordx4 v[150:151], off
	s_waitcnt vmcnt(6)
	s_barrier
	s_setprio 1
	v_mfma_f32_16x16x32_bf16 v[126:129], v[204:207], v[236:239], v[126:129]
	v_mfma_f32_16x16x32_bf16 v[14:17], v[204:207], v[244:247], v[14:17]
	v_mfma_f32_16x16x32_bf16 v[34:37], v[212:215], v[236:239], v[34:37]
	v_mfma_f32_16x16x32_bf16 v[6:9], v[212:215], v[244:247], v[6:9]
	v_mfma_f32_16x16x32_bf16 v[38:41], v[220:223], v[236:239], v[38:41]
	v_mfma_f32_16x16x32_bf16 v[10:13], v[220:223], v[244:247], v[10:13]
	v_mfma_f32_16x16x32_bf16 v[22:25], v[228:231], v[236:239], v[22:25]
	v_mfma_f32_16x16x32_bf16 v[2:5], v[228:231], v[244:247], v[2:5]
	v_mfma_f32_16x16x32_bf16 v[126:129], v[208:211], v[240:243], v[126:129]
	v_mfma_f32_16x16x32_bf16 v[14:17], v[208:211], v[248:251], v[14:17]
	v_mfma_f32_16x16x32_bf16 v[34:37], v[216:219], v[240:243], v[34:37]
	v_mfma_f32_16x16x32_bf16 v[6:9], v[216:219], v[248:251], v[6:9]
	v_mfma_f32_16x16x32_bf16 v[38:41], v[224:227], v[240:243], v[38:41]
	v_mfma_f32_16x16x32_bf16 v[10:13], v[224:227], v[248:251], v[10:13]
	v_mfma_f32_16x16x32_bf16 v[22:25], v[232:235], v[240:243], v[22:25]
	v_mfma_f32_16x16x32_bf16 v[2:5], v[232:235], v[248:251], v[2:5]
	s_setprio 0
	s_addk_i32 s2, 0x80
	v_lshl_add_u64 v[130:131], v[130:131], 0, s[90:91]
	v_lshl_add_u64 v[132:133], v[132:133], 0, s[90:91]
	s_mov_b32 s6, s7
	s_barrier
	s_cbranch_vccnz .LBB0_56
	v_readlane_b32 s2, v255, 38
	s_add_u32 s26, s2, s12
	v_readlane_b32 s2, v255, 39
	s_addc_u32 s2, s2, s13
	v_readlane_b32 s6, v253, 42
	s_add_u32 s3, s6, s3
	v_readlane_b32 s6, v253, 43
	s_addc_u32 s34, s6, 0
	s_ashr_i32 s59, s58, 31
	s_lshl_b64 s[6:7], s[58:59], 16
	s_add_u32 s10, s6, 0x10000
	s_addc_u32 s11, s7, 0
	s_add_u32 s8, s74, s6
	v_mov_b32_e32 v130, v162
	s_addc_u32 s9, s75, s7
	s_add_u32 s56, s74, s10
	v_ashrrev_i32_e32 v131, 31, v130
	v_lshl_add_u64 v[130:131], v[130:131], 4, s[8:9]
	v_mov_b32_e32 v150, v162
	v_mov_b64_e32 v[242:243], v[130:131]
	s_addc_u32 s57, s75, s11
	v_ashrrev_i32_e32 v151, 31, v150
	v_lshl_add_u64 v[150:151], v[150:151], 4, s[56:57]
	v_mov_b64_e32 v[244:245], v[150:151]
	s_mov_b64 s[0:1], 0x2000
	global_load_dwordx4 v[210:213], v[242:243], off
	v_lshl_add_u64 v[242:243], v[242:243], 0, s[0:1]
	global_load_dwordx4 v[226:229], v[244:245], off
	v_lshl_add_u64 v[244:245], v[244:245], 0, s[0:1]
	global_load_dwordx4 v[214:217], v[242:243], off
	v_lshl_add_u64 v[242:243], v[242:243], 0, s[0:1]
	global_load_dwordx4 v[230:233], v[244:245], off
	v_lshl_add_u64 v[244:245], v[244:245], 0, s[0:1]
	global_load_dwordx4 v[218:221], v[242:243], off
	v_lshl_add_u64 v[242:243], v[242:243], 0, s[0:1]
	global_load_dwordx4 v[234:237], v[244:245], off
	v_lshl_add_u64 v[244:245], v[244:245], 0, s[0:1]
	global_load_dwordx4 v[222:225], v[242:243], off
	v_lshl_add_u64 v[242:243], v[242:243], 0, s[0:1]
	global_load_dwordx4 v[238:241], v[244:245], off
	v_lshl_add_u64 v[244:245], v[244:245], 0, s[0:1]
	s_waitcnt vmcnt(7)
	s_nop 1
	v_mov_b64_e32 v[130:131], v[210:211]
	v_mov_b64_e32 v[132:133], v[212:213]
	v_cvt_f32_ubyte3_e32 v199, v130
	v_cvt_f32_ubyte2_e32 v198, v130
	v_cvt_f32_ubyte1_e32 v201, v130
	v_cvt_f32_ubyte0_e32 v200, v130
	s_waitcnt vmcnt(6)
; DI float frcp(float x) { return __builtin_amdgcn_rcpf(x); }
; DI u32x4* gate_slot(const Params& P, int tile, int j, int g8) { return (u32x4*)slotp(P, SL_SK) + ((size_t)(tile * 3 + j) * 8 + g8) * 512 + tid(); }
; DI void merge_scale(const Params& P, int tile, int seg, f32x4 (&acc)[2][2][4][2]) {
; #pragma unroll
;     for (int g8 = 0; g8 < 8; ++g8) {
;         const int ai = g8 >> 2, bj = (g8 >> 1) & 1, nn = g8 & 1;
;         const u32x4 ga = *gate_slot(P, tile, seg, g8), gb = *gate_slot(P, tile, seg + 1, g8);
; #pragma unroll
;         for (int e = 0; e < 8; ++e) {
;             const float rl = (float)((ga[e >> 2] >> (8 * (e & 3))) & 255u) * frcp((float)((gb[e >> 2] >> (8 * (e & 3))) & 255u));
;             const float rh = (float)((ga[2 + (e >> 2)] >> (8 * (e & 3))) & 255u) * frcp((float)((gb[2 + (e >> 2)] >> (8 * (e & 3))) & 255u));
;             acc[ai][bj][e >> 2][nn][e & 3] *= rl;
;             acc[ai][bj][2 + (e >> 2)][nn][e & 3] *= rh;
;         }
;         __builtin_amdgcn_sched_barrier(0);
;     }
	s_nop 1
	v_mov_b64_e32 v[192:193], v[226:227]
	v_mov_b64_e32 v[194:195], v[228:229]
	v_cvt_f32_ubyte0_e32 v151, v194
	v_cvt_f32_ubyte2_e32 v173, v194
	v_cvt_f32_ubyte0_e32 v150, v192
	v_rcp_iflag_f32_e32 v152, v151
	v_cvt_f32_ubyte1_e32 v151, v192
	v_cvt_f32_ubyte2_e32 v172, v192
	v_rcp_iflag_f32_e32 v196, v173
	v_cvt_f32_ubyte3_e32 v173, v192
	v_rcp_iflag_f32_e32 v150, v150
	v_rcp_iflag_f32_e32 v151, v151
	v_rcp_iflag_f32_e32 v172, v172
	v_rcp_iflag_f32_e32 v173, v173
	v_cvt_f32_ubyte1_e32 v153, v194
	v_cvt_f32_ubyte3_e32 v192, v194
	v_rcp_iflag_f32_e32 v153, v153
	v_rcp_iflag_f32_e32 v197, v192
	v_pk_mul_f32 v[150:151], v[150:151], v[200:201]
	v_pk_mul_f32 v[172:173], v[172:173], v[198:199]
	v_pk_mul_f32 v[18:19], v[18:19], v[150:151]
	v_pk_mul_f32 v[20:21], v[20:21], v[172:173]
	v_cvt_f32_ubyte3_e32 v151, v132
	v_cvt_f32_ubyte2_e32 v150, v132
	v_cvt_f32_ubyte1_e32 v173, v132
	v_cvt_f32_ubyte0_e32 v172, v132
	v_cvt_f32_ubyte0_e32 v130, v193
	v_pk_mul_f32 v[152:153], v[152:153], v[172:173]
	v_pk_mul_f32 v[150:151], v[196:197], v[150:151]
	v_rcp_iflag_f32_e32 v172, v130
	v_cvt_f32_ubyte0_e32 v130, v195
	v_pk_mul_f32 v[28:29], v[28:29], v[150:151]
	v_rcp_iflag_f32_e32 v150, v130
	v_cvt_f32_ubyte1_e32 v130, v193
	v_rcp_iflag_f32_e32 v173, v130
	v_cvt_f32_ubyte1_e32 v130, v195
	v_rcp_iflag_f32_e32 v151, v130
	v_cvt_f32_ubyte2_e32 v130, v193
	v_rcp_iflag_f32_e32 v192, v130
	v_cvt_f32_ubyte2_e32 v130, v195
	v_pk_mul_f32 v[26:27], v[26:27], v[152:153]
	v_rcp_iflag_f32_e32 v152, v130
	v_cvt_f32_ubyte3_e32 v130, v193
	v_rcp_iflag_f32_e32 v193, v130
	v_cvt_f32_ubyte3_e32 v130, v195
	v_rcp_iflag_f32_e32 v153, v130
	v_cvt_f32_ubyte3_e32 v195, v131
	v_cvt_f32_ubyte2_e32 v194, v131
	v_cvt_f32_ubyte1_e32 v197, v131
	v_cvt_f32_ubyte0_e32 v196, v131
	v_pk_mul_f32 v[130:131], v[172:173], v[196:197]
	v_pk_mul_f32 v[172:173], v[192:193], v[194:195]
	v_pk_mul_f32 v[30:31], v[30:31], v[130:131]
	v_pk_mul_f32 v[32:33], v[32:33], v[172:173]
	v_cvt_f32_ubyte3_e32 v131, v133
	v_cvt_f32_ubyte2_e32 v130, v133
	v_cvt_f32_ubyte1_e32 v173, v133
	v_cvt_f32_ubyte0_e32 v172, v133
	v_pk_mul_f32 v[132:133], v[150:151], v[172:173]
	v_pk_mul_f32 v[130:131], v[152:153], v[130:131]
	v_pk_mul_f32 v[42:43], v[42:43], v[132:133]
	v_pk_mul_f32 v[44:45], v[44:45], v[130:131]
	s_add_u32 s8, s62, s6
	v_mov_b32_e32 v130, v162
	s_addc_u32 s9, s63, s7
	s_mov_b32 s6, 0x13802000
	v_ashrrev_i32_e32 v131, 31, v130
	v_lshl_add_u64 v[130:131], v[130:131], 4, s[8:9]
	s_add_u32 s22, s62, s10
	v_add_co_u32_e32 v130, vcc, s6, v130
	s_addc_u32 s23, s63, s11
	s_nop 0
	v_addc_co_u32_e32 v131, vcc, 0, v131, vcc
	s_add_u32 s54, s22, 0x13802000
	v_mov_b32_e32 v150, v162
	s_addc_u32 s55, s23, 0
	v_ashrrev_i32_e32 v151, 31, v150
	v_lshl_add_u64 v[150:151], v[150:151], 4, s[54:55]
	s_waitcnt vmcnt(5)
	s_nop 1
	v_mov_b64_e32 v[130:131], v[214:215]
	v_mov_b64_e32 v[132:133], v[216:217]
	v_cvt_f32_ubyte3_e32 v199, v130
	v_cvt_f32_ubyte2_e32 v198, v130
	v_cvt_f32_ubyte1_e32 v201, v130
	v_cvt_f32_ubyte0_e32 v200, v130
	s_waitcnt vmcnt(4)
	s_nop 1
	v_mov_b64_e32 v[192:193], v[230:231]
	v_mov_b64_e32 v[194:195], v[232:233]
	v_cvt_f32_ubyte0_e32 v151, v194
	v_cvt_f32_ubyte2_e32 v173, v194
	v_cvt_f32_ubyte0_e32 v150, v192
	v_rcp_iflag_f32_e32 v152, v151
	v_cvt_f32_ubyte1_e32 v151, v192
	v_cvt_f32_ubyte2_e32 v172, v192
	v_rcp_iflag_f32_e32 v196, v173
	v_cvt_f32_ubyte3_e32 v173, v192
	v_rcp_iflag_f32_e32 v150, v150
	v_rcp_iflag_f32_e32 v151, v151
	v_rcp_iflag_f32_e32 v172, v172
	v_rcp_iflag_f32_e32 v173, v173
	v_cvt_f32_ubyte1_e32 v153, v194
	v_cvt_f32_ubyte3_e32 v192, v194
	v_rcp_iflag_f32_e32 v153, v153
	v_rcp_iflag_f32_e32 v197, v192
	v_pk_mul_f32 v[150:151], v[150:151], v[200:201]
	v_pk_mul_f32 v[172:173], v[172:173], v[198:199]
	v_pk_mul_f32 v[58:59], v[58:59], v[150:151]
	v_pk_mul_f32 v[60:61], v[60:61], v[172:173]
	v_cvt_f32_ubyte3_e32 v151, v132
	v_cvt_f32_ubyte2_e32 v150, v132
	v_cvt_f32_ubyte1_e32 v173, v132
	v_cvt_f32_ubyte0_e32 v172, v132
	v_cvt_f32_ubyte0_e32 v130, v193
	v_pk_mul_f32 v[152:153], v[152:153], v[172:173]
	v_pk_mul_f32 v[150:151], v[196:197], v[150:151]
	v_rcp_iflag_f32_e32 v172, v130
	v_cvt_f32_ubyte0_e32 v130, v195
	v_pk_mul_f32 v[52:53], v[52:53], v[150:151]
	v_rcp_iflag_f32_e32 v150, v130
	v_cvt_f32_ubyte1_e32 v130, v193
	v_rcp_iflag_f32_e32 v173, v130
	v_cvt_f32_ubyte1_e32 v130, v195
	v_rcp_iflag_f32_e32 v151, v130
	v_cvt_f32_ubyte2_e32 v130, v193
	v_rcp_iflag_f32_e32 v192, v130
	v_cvt_f32_ubyte2_e32 v130, v195
	v_pk_mul_f32 v[50:51], v[50:51], v[152:153]
	v_rcp_iflag_f32_e32 v152, v130
	v_cvt_f32_ubyte3_e32 v130, v193
	v_rcp_iflag_f32_e32 v193, v130
	v_cvt_f32_ubyte3_e32 v130, v195
	v_rcp_iflag_f32_e32 v153, v130
	v_cvt_f32_ubyte3_e32 v195, v131
	v_cvt_f32_ubyte2_e32 v194, v131
	v_cvt_f32_ubyte1_e32 v197, v131
	v_cvt_f32_ubyte0_e32 v196, v131
	v_pk_mul_f32 v[130:131], v[172:173], v[196:197]
	v_pk_mul_f32 v[172:173], v[192:193], v[194:195]
	v_pk_mul_f32 v[54:55], v[54:55], v[130:131]
	v_pk_mul_f32 v[56:57], v[56:57], v[172:173]
	v_cvt_f32_ubyte3_e32 v131, v133
	v_cvt_f32_ubyte2_e32 v130, v133
	v_cvt_f32_ubyte1_e32 v173, v133
	v_cvt_f32_ubyte0_e32 v172, v133
	v_pk_mul_f32 v[132:133], v[150:151], v[172:173]
	v_pk_mul_f32 v[130:131], v[152:153], v[130:131]
	v_pk_mul_f32 v[46:47], v[46:47], v[132:133]
	v_pk_mul_f32 v[48:49], v[48:49], v[130:131]
	v_mov_b32_e32 v130, v162
	s_mov_b32 s6, 0x13804000
	v_ashrrev_i32_e32 v131, 31, v130
	v_lshl_add_u64 v[130:131], v[130:131], 4, s[8:9]
	v_add_co_u32_e32 v130, vcc, s6, v130
	s_add_u32 s6, s22, 0x13804000
	s_nop 0
	v_addc_co_u32_e32 v131, vcc, 0, v131, vcc
	v_mov_b32_e32 v150, v162
	s_addc_u32 s7, s23, 0
	v_ashrrev_i32_e32 v151, 31, v150
	v_lshl_add_u64 v[150:151], v[150:151], 4, s[6:7]
	s_waitcnt vmcnt(3)
; DI float frcp(float x) { return __builtin_amdgcn_rcpf(x); }
; DI u32x4* gate_slot(const Params& P, int tile, int j, int g8) { return (u32x4*)slotp(P, SL_SK) + ((size_t)(tile * 3 + j) * 8 + g8) * 512 + tid(); }
; DI void merge_scale(const Params& P, int tile, int seg, f32x4 (&acc)[2][2][4][2]) {
; #pragma unroll
;     for (int g8 = 0; g8 < 8; ++g8) {
;         const int ai = g8 >> 2, bj = (g8 >> 1) & 1, nn = g8 & 1;
;         const u32x4 ga = *gate_slot(P, tile, seg, g8), gb = *gate_slot(P, tile, seg + 1, g8);
; #pragma unroll
;         for (int e = 0; e < 8; ++e) {
;             const float rl = (float)((ga[e >> 2] >> (8 * (e & 3))) & 255u) * frcp((float)((gb[e >> 2] >> (8 * (e & 3))) & 255u));
;             const float rh = (float)((ga[2 + (e >> 2)] >> (8 * (e & 3))) & 255u) * frcp((float)((gb[2 + (e >> 2)] >> (8 * (e & 3))) & 255u));
;             acc[ai][bj][e >> 2][nn][e & 3] *= rl;
;             acc[ai][bj][2 + (e >> 2)][nn][e & 3] *= rh;
;         }
;         __builtin_amdgcn_sched_barrier(0);
;     }
	s_nop 1
	v_mov_b64_e32 v[130:131], v[218:219]
	v_mov_b64_e32 v[132:133], v[220:221]
	v_cvt_f32_ubyte3_e32 v199, v130
	v_cvt_f32_ubyte2_e32 v198, v130
	v_cvt_f32_ubyte1_e32 v201, v130
	v_cvt_f32_ubyte0_e32 v200, v130
	s_waitcnt vmcnt(2)
	s_nop 1
	v_mov_b64_e32 v[192:193], v[234:235]
	v_mov_b64_e32 v[194:195], v[236:237]
	v_cvt_f32_ubyte0_e32 v151, v194
	v_cvt_f32_ubyte2_e32 v173, v194
	v_cvt_f32_ubyte0_e32 v150, v192
	v_rcp_iflag_f32_e32 v152, v151
	v_cvt_f32_ubyte1_e32 v151, v192
	v_cvt_f32_ubyte2_e32 v172, v192
	v_rcp_iflag_f32_e32 v196, v173
	v_cvt_f32_ubyte3_e32 v173, v192
	v_rcp_iflag_f32_e32 v150, v150
	v_rcp_iflag_f32_e32 v151, v151
	v_rcp_iflag_f32_e32 v172, v172
	v_rcp_iflag_f32_e32 v173, v173
	v_cvt_f32_ubyte1_e32 v153, v194
	v_cvt_f32_ubyte3_e32 v192, v194
	v_rcp_iflag_f32_e32 v153, v153
	v_rcp_iflag_f32_e32 v197, v192
	v_pk_mul_f32 v[150:151], v[150:151], v[200:201]
	v_pk_mul_f32 v[172:173], v[172:173], v[198:199]
	v_pk_mul_f32 v[74:75], v[74:75], v[150:151]
	v_pk_mul_f32 v[76:77], v[76:77], v[172:173]
	v_cvt_f32_ubyte3_e32 v151, v132
	v_cvt_f32_ubyte2_e32 v150, v132
	v_cvt_f32_ubyte1_e32 v173, v132
	v_cvt_f32_ubyte0_e32 v172, v132
	v_cvt_f32_ubyte0_e32 v130, v193
	v_pk_mul_f32 v[152:153], v[152:153], v[172:173]
	v_pk_mul_f32 v[150:151], v[196:197], v[150:151]
	v_rcp_iflag_f32_e32 v172, v130
	v_cvt_f32_ubyte0_e32 v130, v195
	v_pk_mul_f32 v[68:69], v[68:69], v[150:151]
	v_rcp_iflag_f32_e32 v150, v130
	v_cvt_f32_ubyte1_e32 v130, v193
	v_rcp_iflag_f32_e32 v173, v130
	v_cvt_f32_ubyte1_e32 v130, v195
	v_rcp_iflag_f32_e32 v151, v130
	v_cvt_f32_ubyte2_e32 v130, v193
	v_rcp_iflag_f32_e32 v192, v130
	v_cvt_f32_ubyte2_e32 v130, v195
	v_pk_mul_f32 v[66:67], v[66:67], v[152:153]
	v_rcp_iflag_f32_e32 v152, v130
	v_cvt_f32_ubyte3_e32 v130, v193
	v_rcp_iflag_f32_e32 v193, v130
	v_cvt_f32_ubyte3_e32 v130, v195
	v_rcp_iflag_f32_e32 v153, v130
	v_cvt_f32_ubyte3_e32 v195, v131
	v_cvt_f32_ubyte2_e32 v194, v131
	v_cvt_f32_ubyte1_e32 v197, v131
	v_cvt_f32_ubyte0_e32 v196, v131
	v_pk_mul_f32 v[130:131], v[172:173], v[196:197]
	v_pk_mul_f32 v[172:173], v[192:193], v[194:195]
	v_pk_mul_f32 v[70:71], v[70:71], v[130:131]
	v_pk_mul_f32 v[72:73], v[72:73], v[172:173]
	v_cvt_f32_ubyte3_e32 v131, v133
	v_cvt_f32_ubyte2_e32 v130, v133
	v_cvt_f32_ubyte1_e32 v173, v133
	v_cvt_f32_ubyte0_e32 v172, v133
	v_pk_mul_f32 v[132:133], v[150:151], v[172:173]
	v_pk_mul_f32 v[130:131], v[152:153], v[130:131]
	v_pk_mul_f32 v[62:63], v[62:63], v[132:133]
	v_pk_mul_f32 v[64:65], v[64:65], v[130:131]
	v_mov_b32_e32 v130, v162
	s_mov_b32 s10, 0x13806000
	v_ashrrev_i32_e32 v131, 31, v130
	v_lshl_add_u64 v[130:131], v[130:131], 4, s[8:9]
	v_add_co_u32_e32 v130, vcc, s10, v130
	s_add_u32 s10, s22, 0x13806000
	s_nop 0
	v_addc_co_u32_e32 v131, vcc, 0, v131, vcc
	v_mov_b32_e32 v150, v162
	s_addc_u32 s11, s23, 0
	v_ashrrev_i32_e32 v151, 31, v150
	v_lshl_add_u64 v[150:151], v[150:151], 4, s[10:11]
	s_waitcnt vmcnt(1)
	s_nop 1
	v_mov_b64_e32 v[130:131], v[222:223]
	v_mov_b64_e32 v[132:133], v[224:225]
	v_cvt_f32_ubyte3_e32 v199, v130
	v_cvt_f32_ubyte2_e32 v198, v130
	v_cvt_f32_ubyte1_e32 v201, v130
	v_cvt_f32_ubyte0_e32 v200, v130
	s_waitcnt vmcnt(0)
	s_nop 1
	v_mov_b64_e32 v[192:193], v[238:239]
	v_mov_b64_e32 v[194:195], v[240:241]
	global_load_dwordx4 v[210:213], v[242:243], off
	v_lshl_add_u64 v[242:243], v[242:243], 0, s[0:1]
	global_load_dwordx4 v[226:229], v[244:245], off
	v_lshl_add_u64 v[244:245], v[244:245], 0, s[0:1]
	global_load_dwordx4 v[214:217], v[242:243], off
	v_lshl_add_u64 v[242:243], v[242:243], 0, s[0:1]
	global_load_dwordx4 v[230:233], v[244:245], off
	v_lshl_add_u64 v[244:245], v[244:245], 0, s[0:1]
	global_load_dwordx4 v[218:221], v[242:243], off
	v_lshl_add_u64 v[242:243], v[242:243], 0, s[0:1]
	global_load_dwordx4 v[234:237], v[244:245], off
	v_lshl_add_u64 v[244:245], v[244:245], 0, s[0:1]
	global_load_dwordx4 v[222:225], v[242:243], off
	v_lshl_add_u64 v[242:243], v[242:243], 0, s[0:1]
	global_load_dwordx4 v[238:241], v[244:245], off
	v_lshl_add_u64 v[244:245], v[244:245], 0, s[0:1]
	v_cvt_f32_ubyte0_e32 v151, v194
	v_cvt_f32_ubyte2_e32 v173, v194
	v_cvt_f32_ubyte0_e32 v150, v192
	v_rcp_iflag_f32_e32 v152, v151
	v_cvt_f32_ubyte1_e32 v151, v192
	v_cvt_f32_ubyte2_e32 v172, v192
	v_rcp_iflag_f32_e32 v196, v173
	v_cvt_f32_ubyte3_e32 v173, v192
	v_rcp_iflag_f32_e32 v150, v150
	v_rcp_iflag_f32_e32 v151, v151
	v_rcp_iflag_f32_e32 v172, v172
	v_rcp_iflag_f32_e32 v173, v173
	v_cvt_f32_ubyte1_e32 v153, v194
	v_cvt_f32_ubyte3_e32 v192, v194
	v_rcp_iflag_f32_e32 v153, v153
	v_rcp_iflag_f32_e32 v197, v192
	v_pk_mul_f32 v[150:151], v[150:151], v[200:201]
	v_pk_mul_f32 v[172:173], v[172:173], v[198:199]
	v_pk_mul_f32 v[90:91], v[90:91], v[150:151]
	v_pk_mul_f32 v[92:93], v[92:93], v[172:173]
	v_cvt_f32_ubyte3_e32 v151, v132
	v_cvt_f32_ubyte2_e32 v150, v132
	v_cvt_f32_ubyte1_e32 v173, v132
	v_cvt_f32_ubyte0_e32 v172, v132
	v_cvt_f32_ubyte0_e32 v130, v193
	v_pk_mul_f32 v[152:153], v[152:153], v[172:173]
	v_pk_mul_f32 v[150:151], v[196:197], v[150:151]
	v_rcp_iflag_f32_e32 v172, v130
	v_cvt_f32_ubyte0_e32 v130, v195
	v_pk_mul_f32 v[84:85], v[84:85], v[150:151]
	v_rcp_iflag_f32_e32 v150, v130
	v_cvt_f32_ubyte1_e32 v130, v193
	v_rcp_iflag_f32_e32 v173, v130
	v_cvt_f32_ubyte1_e32 v130, v195
	v_rcp_iflag_f32_e32 v151, v130
	v_cvt_f32_ubyte2_e32 v130, v193
	v_rcp_iflag_f32_e32 v192, v130
	v_cvt_f32_ubyte2_e32 v130, v195
	v_pk_mul_f32 v[82:83], v[82:83], v[152:153]
	v_rcp_iflag_f32_e32 v152, v130
	v_cvt_f32_ubyte3_e32 v130, v193
	v_rcp_iflag_f32_e32 v193, v130
	v_cvt_f32_ubyte3_e32 v130, v195
	v_rcp_iflag_f32_e32 v153, v130
	v_cvt_f32_ubyte3_e32 v195, v131
	v_cvt_f32_ubyte2_e32 v194, v131
	v_cvt_f32_ubyte1_e32 v197, v131
	v_cvt_f32_ubyte0_e32 v196, v131
	v_pk_mul_f32 v[130:131], v[172:173], v[196:197]
	v_pk_mul_f32 v[172:173], v[192:193], v[194:195]
	v_pk_mul_f32 v[86:87], v[86:87], v[130:131]
	v_pk_mul_f32 v[88:89], v[88:89], v[172:173]
	v_cvt_f32_ubyte3_e32 v131, v133
	v_cvt_f32_ubyte2_e32 v130, v133
	v_cvt_f32_ubyte1_e32 v173, v133
	v_cvt_f32_ubyte0_e32 v172, v133
	v_pk_mul_f32 v[132:133], v[150:151], v[172:173]
	v_pk_mul_f32 v[130:131], v[152:153], v[130:131]
	v_pk_mul_f32 v[78:79], v[78:79], v[132:133]
	v_pk_mul_f32 v[80:81], v[80:81], v[130:131]
	v_mov_b32_e32 v130, v162
	s_mov_b32 s12, 0x13808000
	v_ashrrev_i32_e32 v131, 31, v130
	v_lshl_add_u64 v[130:131], v[130:131], 4, s[8:9]
	v_add_co_u32_e32 v130, vcc, s12, v130
	s_add_u32 s12, s22, 0x13808000
	s_nop 0
	v_addc_co_u32_e32 v131, vcc, 0, v131, vcc
	v_mov_b32_e32 v150, v162
	s_addc_u32 s13, s23, 0
	v_ashrrev_i32_e32 v151, 31, v150
	v_lshl_add_u64 v[150:151], v[150:151], 4, s[12:13]
	s_waitcnt vmcnt(7)
; DI float frcp(float x) { return __builtin_amdgcn_rcpf(x); }
; DI u32x4* gate_slot(const Params& P, int tile, int j, int g8) { return (u32x4*)slotp(P, SL_SK) + ((size_t)(tile * 3 + j) * 8 + g8) * 512 + tid(); }
; DI void merge_scale(const Params& P, int tile, int seg, f32x4 (&acc)[2][2][4][2]) {
; #pragma unroll
;     for (int g8 = 0; g8 < 8; ++g8) {
;         const int ai = g8 >> 2, bj = (g8 >> 1) & 1, nn = g8 & 1;
;         const u32x4 ga = *gate_slot(P, tile, seg, g8), gb = *gate_slot(P, tile, seg + 1, g8);
; #pragma unroll
;         for (int e = 0; e < 8; ++e) {
;             const float rl = (float)((ga[e >> 2] >> (8 * (e & 3))) & 255u) * frcp((float)((gb[e >> 2] >> (8 * (e & 3))) & 255u));
;             const float rh = (float)((ga[2 + (e >> 2)] >> (8 * (e & 3))) & 255u) * frcp((float)((gb[2 + (e >> 2)] >> (8 * (e & 3))) & 255u));
;             acc[ai][bj][e >> 2][nn][e & 3] *= rl;
;             acc[ai][bj][2 + (e >> 2)][nn][e & 3] *= rh;
;         }
;         __builtin_amdgcn_sched_barrier(0);
;     }
	s_nop 1
	v_mov_b64_e32 v[130:131], v[210:211]
	v_mov_b64_e32 v[132:133], v[212:213]
	v_cvt_f32_ubyte3_e32 v199, v130
	v_cvt_f32_ubyte2_e32 v198, v130
	v_cvt_f32_ubyte1_e32 v201, v130
	v_cvt_f32_ubyte0_e32 v200, v130
	s_waitcnt vmcnt(6)
	s_nop 1
	v_mov_b64_e32 v[192:193], v[226:227]
	v_mov_b64_e32 v[194:195], v[228:229]
	v_cvt_f32_ubyte0_e32 v151, v194
	v_cvt_f32_ubyte2_e32 v173, v194
	v_cvt_f32_ubyte0_e32 v150, v192
	v_rcp_iflag_f32_e32 v152, v151
	v_cvt_f32_ubyte1_e32 v151, v192
	v_cvt_f32_ubyte2_e32 v172, v192
	v_rcp_iflag_f32_e32 v196, v173
	v_cvt_f32_ubyte3_e32 v173, v192
	v_rcp_iflag_f32_e32 v150, v150
	v_rcp_iflag_f32_e32 v151, v151
	v_rcp_iflag_f32_e32 v172, v172
	v_rcp_iflag_f32_e32 v173, v173
	v_cvt_f32_ubyte1_e32 v153, v194
	v_cvt_f32_ubyte3_e32 v192, v194
	v_rcp_iflag_f32_e32 v153, v153
	v_rcp_iflag_f32_e32 v197, v192
	v_pk_mul_f32 v[150:151], v[150:151], v[200:201]
	v_pk_mul_f32 v[172:173], v[172:173], v[198:199]
	v_pk_mul_f32 v[106:107], v[106:107], v[150:151]
	v_pk_mul_f32 v[108:109], v[108:109], v[172:173]
	v_cvt_f32_ubyte3_e32 v151, v132
	v_cvt_f32_ubyte2_e32 v150, v132
	v_cvt_f32_ubyte1_e32 v173, v132
	v_cvt_f32_ubyte0_e32 v172, v132
	v_cvt_f32_ubyte0_e32 v130, v193
	v_pk_mul_f32 v[152:153], v[152:153], v[172:173]
	v_pk_mul_f32 v[150:151], v[196:197], v[150:151]
	v_rcp_iflag_f32_e32 v172, v130
	v_cvt_f32_ubyte0_e32 v130, v195
	v_pk_mul_f32 v[100:101], v[100:101], v[150:151]
	v_rcp_iflag_f32_e32 v150, v130
	v_cvt_f32_ubyte1_e32 v130, v193
	v_rcp_iflag_f32_e32 v173, v130
	v_cvt_f32_ubyte1_e32 v130, v195
	v_rcp_iflag_f32_e32 v151, v130
	v_cvt_f32_ubyte2_e32 v130, v193
	v_rcp_iflag_f32_e32 v192, v130
	v_cvt_f32_ubyte2_e32 v130, v195
	v_pk_mul_f32 v[98:99], v[98:99], v[152:153]
	v_rcp_iflag_f32_e32 v152, v130
	v_cvt_f32_ubyte3_e32 v130, v193
	v_rcp_iflag_f32_e32 v193, v130
	v_cvt_f32_ubyte3_e32 v130, v195
	v_rcp_iflag_f32_e32 v153, v130
	v_cvt_f32_ubyte3_e32 v195, v131
	v_cvt_f32_ubyte2_e32 v194, v131
	v_cvt_f32_ubyte1_e32 v197, v131
	v_cvt_f32_ubyte0_e32 v196, v131
	v_pk_mul_f32 v[130:131], v[172:173], v[196:197]
	v_pk_mul_f32 v[172:173], v[192:193], v[194:195]
	v_pk_mul_f32 v[102:103], v[102:103], v[130:131]
	v_pk_mul_f32 v[104:105], v[104:105], v[172:173]
	v_cvt_f32_ubyte3_e32 v131, v133
	v_cvt_f32_ubyte2_e32 v130, v133
	v_cvt_f32_ubyte1_e32 v173, v133
	v_cvt_f32_ubyte0_e32 v172, v133
	v_pk_mul_f32 v[132:133], v[150:151], v[172:173]
	v_pk_mul_f32 v[130:131], v[152:153], v[130:131]
	v_pk_mul_f32 v[94:95], v[94:95], v[132:133]
	v_pk_mul_f32 v[96:97], v[96:97], v[130:131]
	v_mov_b32_e32 v130, v162
	s_mov_b32 s16, 0x1380a000
	v_ashrrev_i32_e32 v131, 31, v130
	v_lshl_add_u64 v[130:131], v[130:131], 4, s[8:9]
	v_add_co_u32_e32 v130, vcc, s16, v130
	s_add_u32 s16, s22, 0x1380a000
	s_nop 0
	v_addc_co_u32_e32 v131, vcc, 0, v131, vcc
	v_mov_b32_e32 v150, v162
	s_addc_u32 s17, s23, 0
	v_ashrrev_i32_e32 v151, 31, v150
	v_lshl_add_u64 v[150:151], v[150:151], 4, s[16:17]
	s_waitcnt vmcnt(5)
	s_nop 1
	v_mov_b64_e32 v[130:131], v[214:215]
	v_mov_b64_e32 v[132:133], v[216:217]
	v_cvt_f32_ubyte3_e32 v199, v130
	v_cvt_f32_ubyte2_e32 v198, v130
	v_cvt_f32_ubyte1_e32 v201, v130
	v_cvt_f32_ubyte0_e32 v200, v130
	s_waitcnt vmcnt(4)
	s_nop 1
	v_mov_b64_e32 v[192:193], v[230:231]
	v_mov_b64_e32 v[194:195], v[232:233]
	v_cvt_f32_ubyte0_e32 v151, v194
	v_cvt_f32_ubyte2_e32 v173, v194
	v_cvt_f32_ubyte0_e32 v150, v192
	v_rcp_iflag_f32_e32 v152, v151
	v_cvt_f32_ubyte1_e32 v151, v192
	v_cvt_f32_ubyte2_e32 v172, v192
	v_rcp_iflag_f32_e32 v196, v173
	v_cvt_f32_ubyte3_e32 v173, v192
	v_rcp_iflag_f32_e32 v150, v150
	v_rcp_iflag_f32_e32 v151, v151
	v_rcp_iflag_f32_e32 v172, v172
	v_rcp_iflag_f32_e32 v173, v173
	v_cvt_f32_ubyte1_e32 v153, v194
	v_cvt_f32_ubyte3_e32 v192, v194
	v_rcp_iflag_f32_e32 v153, v153
	v_rcp_iflag_f32_e32 v197, v192
	v_pk_mul_f32 v[150:151], v[150:151], v[200:201]
	v_pk_mul_f32 v[172:173], v[172:173], v[198:199]
	v_pk_mul_f32 v[122:123], v[122:123], v[150:151]
	v_pk_mul_f32 v[124:125], v[124:125], v[172:173]
	v_cvt_f32_ubyte3_e32 v151, v132
	v_cvt_f32_ubyte2_e32 v150, v132
	v_cvt_f32_ubyte1_e32 v173, v132
	v_cvt_f32_ubyte0_e32 v172, v132
	v_cvt_f32_ubyte0_e32 v130, v193
	v_pk_mul_f32 v[152:153], v[152:153], v[172:173]
	v_pk_mul_f32 v[150:151], v[196:197], v[150:151]
	v_rcp_iflag_f32_e32 v172, v130
	v_cvt_f32_ubyte0_e32 v130, v195
	v_pk_mul_f32 v[116:117], v[116:117], v[150:151]
	v_rcp_iflag_f32_e32 v150, v130
	v_cvt_f32_ubyte1_e32 v130, v193
	v_rcp_iflag_f32_e32 v173, v130
	v_cvt_f32_ubyte1_e32 v130, v195
	v_rcp_iflag_f32_e32 v151, v130
	v_cvt_f32_ubyte2_e32 v130, v193
	v_rcp_iflag_f32_e32 v192, v130
	v_cvt_f32_ubyte2_e32 v130, v195
	v_pk_mul_f32 v[114:115], v[114:115], v[152:153]
	v_rcp_iflag_f32_e32 v152, v130
	v_cvt_f32_ubyte3_e32 v130, v193
	v_rcp_iflag_f32_e32 v193, v130
	v_cvt_f32_ubyte3_e32 v130, v195
	v_rcp_iflag_f32_e32 v153, v130
	v_cvt_f32_ubyte3_e32 v195, v131
	v_cvt_f32_ubyte2_e32 v194, v131
	v_cvt_f32_ubyte1_e32 v197, v131
	v_cvt_f32_ubyte0_e32 v196, v131
	v_pk_mul_f32 v[130:131], v[172:173], v[196:197]
	v_pk_mul_f32 v[172:173], v[192:193], v[194:195]
	v_pk_mul_f32 v[118:119], v[118:119], v[130:131]
	v_pk_mul_f32 v[120:121], v[120:121], v[172:173]
	v_cvt_f32_ubyte3_e32 v131, v133
	v_cvt_f32_ubyte2_e32 v130, v133
	v_cvt_f32_ubyte1_e32 v173, v133
	v_cvt_f32_ubyte0_e32 v172, v133
	v_pk_mul_f32 v[132:133], v[150:151], v[172:173]
	v_pk_mul_f32 v[130:131], v[152:153], v[130:131]
	v_pk_mul_f32 v[110:111], v[110:111], v[132:133]
	v_pk_mul_f32 v[112:113], v[112:113], v[130:131]
	v_mov_b32_e32 v130, v162
	s_mov_b32 s20, 0x1380c000
	v_ashrrev_i32_e32 v131, 31, v130
	v_lshl_add_u64 v[130:131], v[130:131], 4, s[8:9]
	v_add_co_u32_e32 v130, vcc, s20, v130
	s_add_u32 s20, s22, 0x1380c000
	s_nop 0
	v_addc_co_u32_e32 v131, vcc, 0, v131, vcc
	v_mov_b32_e32 v150, v162
	s_addc_u32 s21, s23, 0
	v_ashrrev_i32_e32 v151, 31, v150
	v_lshl_add_u64 v[150:151], v[150:151], 4, s[20:21]
	s_waitcnt vmcnt(3)
; DI float frcp(float x) { return __builtin_amdgcn_rcpf(x); }
; DI u32x4* gate_slot(const Params& P, int tile, int j, int g8) { return (u32x4*)slotp(P, SL_SK) + ((size_t)(tile * 3 + j) * 8 + g8) * 512 + tid(); }
; template <class Hook>
; DI void gemm8_cat3(f32x4 (&acc)[2][2][4][2], const bf16_t* R0, const bf16_t* R1, const bf16_t* R2, const bf16_t* C0, const bf16_t* C1, const bf16_t* C2, char* shm, Hook hook) {
;     ...
;     for (int tt = 8; tt < 16; tt += 2) {
; DI void merge_scale(const Params& P, int tile, int seg, f32x4 (&acc)[2][2][4][2]) {
; #pragma unroll
;     for (int g8 = 0; g8 < 8; ++g8) {
;         const int ai = g8 >> 2, bj = (g8 >> 1) & 1, nn = g8 & 1;
;         const u32x4 ga = *gate_slot(P, tile, seg, g8), gb = *gate_slot(P, tile, seg + 1, g8);
; #pragma unroll
;         for (int e = 0; e < 8; ++e) {
;             const float rl = (float)((ga[e >> 2] >> (8 * (e & 3))) & 255u) * frcp((float)((gb[e >> 2] >> (8 * (e & 3))) & 255u));
;             const float rh = (float)((ga[2 + (e >> 2)] >> (8 * (e & 3))) & 255u) * frcp((float)((gb[2 + (e >> 2)] >> (8 * (e & 3))) & 255u));
;             acc[ai][bj][e >> 2][nn][e & 3] *= rl;
;             acc[ai][bj][2 + (e >> 2)][nn][e & 3] *= rh;
;         }
;         __builtin_amdgcn_sched_barrier(0);
;     }
	s_nop 1
	v_mov_b64_e32 v[130:131], v[218:219]
	v_mov_b64_e32 v[132:133], v[220:221]
	v_cvt_f32_ubyte3_e32 v199, v130
	v_cvt_f32_ubyte2_e32 v198, v130
	v_cvt_f32_ubyte1_e32 v201, v130
	v_cvt_f32_ubyte0_e32 v200, v130
	s_waitcnt vmcnt(2)
	s_nop 1
	v_mov_b64_e32 v[192:193], v[234:235]
	v_mov_b64_e32 v[194:195], v[236:237]
	v_cvt_f32_ubyte0_e32 v151, v194
	v_cvt_f32_ubyte2_e32 v173, v194
	v_cvt_f32_ubyte0_e32 v150, v192
	v_rcp_iflag_f32_e32 v152, v151
	v_cvt_f32_ubyte1_e32 v151, v192
	v_cvt_f32_ubyte2_e32 v172, v192
	v_rcp_iflag_f32_e32 v196, v173
	v_cvt_f32_ubyte3_e32 v173, v192
	v_rcp_iflag_f32_e32 v150, v150
	v_rcp_iflag_f32_e32 v151, v151
	v_rcp_iflag_f32_e32 v172, v172
	v_rcp_iflag_f32_e32 v173, v173
	v_cvt_f32_ubyte1_e32 v153, v194
	v_cvt_f32_ubyte3_e32 v192, v194
	v_rcp_iflag_f32_e32 v153, v153
	v_rcp_iflag_f32_e32 v197, v192
	v_pk_mul_f32 v[150:151], v[150:151], v[200:201]
	v_pk_mul_f32 v[172:173], v[172:173], v[198:199]
	v_pk_mul_f32 v[126:127], v[126:127], v[150:151]
	v_pk_mul_f32 v[128:129], v[128:129], v[172:173]
	v_cvt_f32_ubyte3_e32 v151, v132
	v_cvt_f32_ubyte2_e32 v150, v132
	v_cvt_f32_ubyte1_e32 v173, v132
	v_cvt_f32_ubyte0_e32 v172, v132
	v_cvt_f32_ubyte0_e32 v130, v193
	v_pk_mul_f32 v[152:153], v[152:153], v[172:173]
	v_pk_mul_f32 v[150:151], v[196:197], v[150:151]
	v_rcp_iflag_f32_e32 v172, v130
	v_cvt_f32_ubyte0_e32 v130, v195
	v_pk_mul_f32 v[40:41], v[40:41], v[150:151]
	v_rcp_iflag_f32_e32 v150, v130
	v_cvt_f32_ubyte1_e32 v130, v193
	v_rcp_iflag_f32_e32 v173, v130
	v_cvt_f32_ubyte1_e32 v130, v195
	v_rcp_iflag_f32_e32 v151, v130
	v_cvt_f32_ubyte2_e32 v130, v193
	v_rcp_iflag_f32_e32 v192, v130
	v_cvt_f32_ubyte2_e32 v130, v195
	v_pk_mul_f32 v[38:39], v[38:39], v[152:153]
	v_rcp_iflag_f32_e32 v152, v130
	v_cvt_f32_ubyte3_e32 v130, v193
	v_rcp_iflag_f32_e32 v193, v130
	v_cvt_f32_ubyte3_e32 v130, v195
	v_rcp_iflag_f32_e32 v153, v130
	v_cvt_f32_ubyte3_e32 v195, v131
	v_cvt_f32_ubyte2_e32 v194, v131
	v_cvt_f32_ubyte1_e32 v197, v131
	v_cvt_f32_ubyte0_e32 v196, v131
	v_pk_mul_f32 v[130:131], v[172:173], v[196:197]
	v_pk_mul_f32 v[172:173], v[192:193], v[194:195]
	v_pk_mul_f32 v[34:35], v[34:35], v[130:131]
	v_pk_mul_f32 v[36:37], v[36:37], v[172:173]
	v_cvt_f32_ubyte3_e32 v131, v133
	v_cvt_f32_ubyte2_e32 v130, v133
	v_cvt_f32_ubyte1_e32 v173, v133
	v_cvt_f32_ubyte0_e32 v172, v133
	v_pk_mul_f32 v[132:133], v[150:151], v[172:173]
	v_pk_mul_f32 v[130:131], v[152:153], v[130:131]
	v_pk_mul_f32 v[22:23], v[22:23], v[132:133]
	v_pk_mul_f32 v[24:25], v[24:25], v[130:131]
	v_mov_b32_e32 v130, v162
	s_add_u32 s22, s22, 0x1380e000
	v_ashrrev_i32_e32 v131, 31, v130
	v_lshl_add_u64 v[130:131], v[130:131], 4, s[8:9]
	s_mov_b32 s8, 0x1380e000
	v_add_co_u32_e32 v130, vcc, s8, v130
	v_mov_b32_e32 v150, v162
	s_nop 0
	v_addc_co_u32_e32 v131, vcc, 0, v131, vcc
	s_addc_u32 s23, s23, 0
	v_ashrrev_i32_e32 v151, 31, v150
	v_lshl_add_u64 v[150:151], v[150:151], 4, s[22:23]
	s_waitcnt vmcnt(1)
	s_nop 1
	v_mov_b64_e32 v[130:131], v[222:223]
	v_mov_b64_e32 v[132:133], v[224:225]
	v_cvt_f32_ubyte3_e32 v199, v130
	v_cvt_f32_ubyte2_e32 v198, v130
	v_cvt_f32_ubyte1_e32 v201, v130
	v_cvt_f32_ubyte0_e32 v200, v130
	s_waitcnt vmcnt(0)
	s_nop 1
	v_mov_b64_e32 v[192:193], v[238:239]
	v_mov_b64_e32 v[194:195], v[240:241]
	v_cvt_f32_ubyte0_e32 v151, v194
	v_cvt_f32_ubyte2_e32 v173, v194
	v_cvt_f32_ubyte0_e32 v150, v192
	v_rcp_iflag_f32_e32 v152, v151
	v_cvt_f32_ubyte1_e32 v151, v192
	v_cvt_f32_ubyte2_e32 v172, v192
	v_rcp_iflag_f32_e32 v196, v173
	v_cvt_f32_ubyte3_e32 v173, v192
	v_rcp_iflag_f32_e32 v150, v150
	v_rcp_iflag_f32_e32 v151, v151
	v_rcp_iflag_f32_e32 v172, v172
	v_rcp_iflag_f32_e32 v173, v173
	v_cvt_f32_ubyte1_e32 v153, v194
	v_cvt_f32_ubyte3_e32 v192, v194
	v_rcp_iflag_f32_e32 v153, v153
	v_rcp_iflag_f32_e32 v197, v192
	v_pk_mul_f32 v[150:151], v[150:151], v[200:201]
	v_pk_mul_f32 v[172:173], v[172:173], v[198:199]
	v_pk_mul_f32 v[14:15], v[14:15], v[150:151]
	v_pk_mul_f32 v[16:17], v[16:17], v[172:173]
	v_cvt_f32_ubyte3_e32 v151, v132
	v_cvt_f32_ubyte2_e32 v150, v132
	v_cvt_f32_ubyte1_e32 v173, v132
	v_cvt_f32_ubyte0_e32 v172, v132
	v_cvt_f32_ubyte0_e32 v130, v193
	v_pk_mul_f32 v[152:153], v[152:153], v[172:173]
	v_pk_mul_f32 v[150:151], v[196:197], v[150:151]
	v_rcp_iflag_f32_e32 v172, v130
	v_cvt_f32_ubyte0_e32 v130, v195
	v_pk_mul_f32 v[12:13], v[12:13], v[150:151]
	v_rcp_iflag_f32_e32 v150, v130
	v_cvt_f32_ubyte1_e32 v130, v193
	v_rcp_iflag_f32_e32 v173, v130
	v_cvt_f32_ubyte1_e32 v130, v195
	v_rcp_iflag_f32_e32 v151, v130
	v_cvt_f32_ubyte2_e32 v130, v193
	v_rcp_iflag_f32_e32 v192, v130
	v_cvt_f32_ubyte2_e32 v130, v195
	v_pk_mul_f32 v[10:11], v[10:11], v[152:153]
	v_rcp_iflag_f32_e32 v152, v130
	v_cvt_f32_ubyte3_e32 v130, v193
	v_rcp_iflag_f32_e32 v193, v130
	v_cvt_f32_ubyte3_e32 v130, v195
	v_rcp_iflag_f32_e32 v153, v130
	v_cvt_f32_ubyte3_e32 v195, v131
	v_cvt_f32_ubyte2_e32 v194, v131
	v_cvt_f32_ubyte1_e32 v197, v131
	v_cvt_f32_ubyte0_e32 v196, v131
	v_pk_mul_f32 v[130:131], v[172:173], v[196:197]
	v_pk_mul_f32 v[172:173], v[192:193], v[194:195]
	v_pk_mul_f32 v[6:7], v[6:7], v[130:131]
	v_pk_mul_f32 v[8:9], v[8:9], v[172:173]
	v_cvt_f32_ubyte3_e32 v131, v133
	v_cvt_f32_ubyte2_e32 v130, v133
	v_cvt_f32_ubyte1_e32 v173, v133
	v_cvt_f32_ubyte0_e32 v172, v133
	v_pk_mul_f32 v[132:133], v[150:151], v[172:173]
	v_pk_mul_f32 v[130:131], v[152:153], v[130:131]
	v_pk_mul_f32 v[2:3], v[2:3], v[132:133]
	v_pk_mul_f32 v[4:5], v[4:5], v[130:131]
	s_mov_b64 s[8:9], s[50:51]
	v_lshl_add_u64 v[130:131], s[8:9], 0, v[146:147]
	v_lshl_add_u64 v[132:133], s[8:9], 0, v[148:149]
	s_mov_b32 s8, 6
	s_movk_i32 s9, 0x2c0
; #define STAGE(P, BASE, br, kt) do { const bf16_t* g_ = (BASE) + (size_t)(br) * K + (size_t)(kt) * 64; \
;         _Pragma("unroll") for (int i_ = 0; i_ < 2; ++i_) \
;             __builtin_amdgcn_global_load_lds((const unsigned*)(g_ + gofs[i_]), (lds_ptr_t)((P) + wb + i_ * 8192), 16, 0, 0); } while (0)
; #define LDA(dst, b, hh) _Pragma("unroll") for (int m = 0; m < 4; ++m) _Pragma("unroll") for (int k = 0; k < 2; ++k) \
;         dst[m][k] = *(const bf16x8*)(SA(b, hh) + lds_byte(wr * 64 + m * 16 + fr, k * 32 + fq * 8))
; #define LDB(dst, b, hh) _Pragma("unroll") for (int n = 0; n < 2; ++n) _Pragma("unroll") for (int k = 0; k < 2; ++k) \
;         dst[n][k] = *(const bf16x8*)(SB(b, hh) + lds_byte(wc * 32 + n * 16 + fr, k * 32 + fq * 8))
; #define MMA(ai, bj, At_, Bt_) do { __builtin_amdgcn_s_setprio(1); \
;         _Pragma("unroll") for (int m = 0; m < 4; ++m) _Pragma("unroll") for (int n = 0; n < 2; ++n) _Pragma("unroll") for (int k = 0; k < 2; ++k) \
;             acc[ai][bj][m][n] = MFMA16(At_[m][k], Bt_[n][k], acc[ai][bj][m][n]); \
;         __builtin_amdgcn_s_setprio(0); } while (0)
; #define WAIT_L(n) asm volatile("s_waitcnt lgkmcnt(" #n ")" ::: "memory")
; #define BAR __builtin_amdgcn_s_barrier()
; #define SCHED __builtin_amdgcn_sched_barrier(0)
; #define STAGE(P, BASE, br, kt) do { const int sg_ = (kt) >> 3; const bf16_t* g_ = (sg_ == 0 ? BASE##0 : sg_ == 1 ? BASE##1 : BASE##2) + (size_t)(br) * K + (size_t)((kt) & 7) * 64; \
;         _Pragma("unroll") for (int i_ = 0; i_ < 2; ++i_) \
;             __builtin_amdgcn_global_load_lds((const unsigned*)(g_ + gofs[i_]), (lds_ptr_t)((P) + wb + i_ * 8192), 16, 0, 0); } while (0)
; #define WAIT_L(n) asm volatile("s_waitcnt lgkmcnt(" #n ")" ::: "memory")
; #define BAR __builtin_amdgcn_s_barrier()
; template <class Hook>
; DI void gemm8_cat3(f32x4 (&acc)[2][2][4][2], const bf16_t* R0, const bf16_t* R1, const bf16_t* R2, const bf16_t* C0, const bf16_t* C1, const bf16_t* C2, char* shm, Hook hook) {
;     ...
;         LDB(B0, 0, 0); SCHED; LDA(At, 0, 0); STAGE(SA(1, 1), R, 128, tt + 1);
;         WAIT_L(8); BAR; WAIT_L(0); MMA(0, 0, At, B0); BAR; SCHED;
;         LDB(B1, 0, 1); STAGE(SB(0, 0), C, 0, tt + 2);
;         BAR; WAIT_L(0); MMA(0, 1, At, B1); BAR;
;         LDA(At, 0, 1); STAGE(SA(0, 0), R, 0, tt + 2);
;         BAR; WAIT_L(0); MMA(1, 0, At, B0); BAR; SCHED;
;         STAGE(SB(0, 1), C, 128, tt + 2);
.LBB0_58:
	v_readfirstlane_b32 s35, v190
	s_mov_b32 m0, s35
	v_readfirstlane_b32 s35, v191
	global_load_lds_dwordx4 v[130:131], off
	s_mov_b32 m0, s35
	s_nop 0
	global_load_lds_dwordx4 v[132:133], off
	ds_read_b128 v[146:149], v189
	ds_read_b128 v[150:153], v189 offset:1024
	ds_read_b128 v[192:195], v189 offset:2048
	ds_read_b128 v[196:199], v189 offset:3072
	ds_read_b128 v[200:203], v157
	ds_read_b128 v[204:207], v157 offset:1024
	ds_read_b128 v[208:211], v156
	ds_read_b128 v[212:215], v156 offset:1024
	ds_read_b128 v[216:219], v155
	ds_read_b128 v[220:223], v155 offset:1024
	ds_read_b128 v[224:227], v154
	ds_read_b128 v[228:231], v154 offset:1024
	s_waitcnt lgkmcnt(8)
	s_barrier
	s_waitcnt lgkmcnt(0)
	s_setprio 1
	s_waitcnt lgkmcnt(0)
	v_mfma_f32_16x16x32_bf16 v[18:21], v[200:203], v[146:149], v[18:21]
	v_mfma_f32_16x16x32_bf16 v[58:61], v[200:203], v[192:195], v[58:61]
	v_mfma_f32_16x16x32_bf16 v[30:33], v[208:211], v[146:149], v[30:33]
	v_mfma_f32_16x16x32_bf16 v[54:57], v[208:211], v[192:195], v[54:57]
	v_mfma_f32_16x16x32_bf16 v[26:29], v[216:219], v[146:149], v[26:29]
	v_mfma_f32_16x16x32_bf16 v[50:53], v[216:219], v[192:195], v[50:53]
	v_mfma_f32_16x16x32_bf16 v[42:45], v[224:227], v[146:149], v[42:45]
	v_mfma_f32_16x16x32_bf16 v[46:49], v[224:227], v[192:195], v[46:49]
	v_mfma_f32_16x16x32_bf16 v[18:21], v[204:207], v[150:153], v[18:21]
	v_mfma_f32_16x16x32_bf16 v[58:61], v[204:207], v[196:199], v[58:61]
	v_mfma_f32_16x16x32_bf16 v[30:33], v[212:215], v[150:153], v[30:33]
	v_mfma_f32_16x16x32_bf16 v[54:57], v[212:215], v[196:199], v[54:57]
	v_mfma_f32_16x16x32_bf16 v[26:29], v[220:223], v[150:153], v[26:29]
	v_mfma_f32_16x16x32_bf16 v[50:53], v[220:223], v[196:199], v[50:53]
	v_mfma_f32_16x16x32_bf16 v[42:45], v[228:231], v[150:153], v[42:45]
	v_mfma_f32_16x16x32_bf16 v[46:49], v[228:231], v[196:199], v[46:49]
	s_setprio 0
	s_barrier
	s_sub_i32 s96, s9, 64
	s_add_i32 s35, s8, 4
	s_and_b32 s96, s96, 0x180
	s_and_b32 s35, s35, 24
	s_lshl_b32 vcc_lo, s96, 1
	s_cmp_eq_u32 s35, 8
	s_cselect_b32 s96, s25, s3
	s_cselect_b32 s35, s82, s34
	s_cselect_b32 vcc_hi, s24, s2
	s_cselect_b32 s44, s15, s26
	s_add_u32 s96, s96, vcc_lo
	s_addc_u32 s97, s35, 0
	v_readfirstlane_b32 s35, v159
	v_lshl_add_u64 v[172:173], s[96:97], 0, v[134:135]
	s_mov_b32 m0, s35
	v_readfirstlane_b32 s35, v160
	global_load_lds_dwordx4 v[172:173], off
	v_lshl_add_u64 v[172:173], s[96:97], 0, v[136:137]
	s_mov_b32 m0, s35
	s_nop 0
	global_load_lds_dwordx4 v[172:173], off
	ds_read_b128 v[232:235], v188
	ds_read_b128 v[236:239], v188 offset:1024
	ds_read_b128 v[240:243], v188 offset:2048
	ds_read_b128 v[244:247], v188 offset:3072
	s_barrier
	s_waitcnt lgkmcnt(0)
	s_setprio 1
	s_waitcnt lgkmcnt(0)
	v_mfma_f32_16x16x32_bf16 v[74:77], v[200:203], v[232:235], v[74:77]
	v_mfma_f32_16x16x32_bf16 v[90:93], v[200:203], v[240:243], v[90:93]
	v_mfma_f32_16x16x32_bf16 v[70:73], v[208:211], v[232:235], v[70:73]
	v_mfma_f32_16x16x32_bf16 v[86:89], v[208:211], v[240:243], v[86:89]
	v_mfma_f32_16x16x32_bf16 v[66:69], v[216:219], v[232:235], v[66:69]
	v_mfma_f32_16x16x32_bf16 v[82:85], v[216:219], v[240:243], v[82:85]
	v_mfma_f32_16x16x32_bf16 v[62:65], v[224:227], v[232:235], v[62:65]
	v_mfma_f32_16x16x32_bf16 v[78:81], v[224:227], v[240:243], v[78:81]
	v_mfma_f32_16x16x32_bf16 v[74:77], v[204:207], v[236:239], v[74:77]
	v_mfma_f32_16x16x32_bf16 v[90:93], v[204:207], v[244:247], v[90:93]
	v_mfma_f32_16x16x32_bf16 v[70:73], v[212:215], v[236:239], v[70:73]
	v_mfma_f32_16x16x32_bf16 v[86:89], v[212:215], v[244:247], v[86:89]
	v_mfma_f32_16x16x32_bf16 v[66:69], v[220:223], v[236:239], v[66:69]
	v_mfma_f32_16x16x32_bf16 v[82:85], v[220:223], v[244:247], v[82:85]
	v_mfma_f32_16x16x32_bf16 v[62:65], v[228:231], v[236:239], v[62:65]
	v_mfma_f32_16x16x32_bf16 v[78:81], v[228:231], v[244:247], v[78:81]
	s_setprio 0
	s_add_u32 vcc_lo, s44, vcc_lo
	s_addc_u32 vcc_hi, vcc_hi, 0
	v_readfirstlane_b32 s35, v158
	v_lshl_add_u64 v[172:173], vcc, 0, v[134:135]
	s_mov_b32 m0, s35
	v_readfirstlane_b32 s35, v164
	s_barrier
	global_load_lds_dwordx4 v[172:173], off
	v_lshl_add_u64 v[172:173], vcc, 0, v[136:137]
	s_mov_b32 m0, s35
	s_nop 0
	global_load_lds_dwordx4 v[172:173], off
	ds_read_b128 v[200:203], v157 offset:16384
	ds_read_b128 v[204:207], v157 offset:17408
	ds_read_b128 v[208:211], v156 offset:16384
	ds_read_b128 v[212:215], v156 offset:17408
	ds_read_b128 v[216:219], v155 offset:16384
	ds_read_b128 v[220:223], v155 offset:17408
	ds_read_b128 v[224:227], v154 offset:16384
	ds_read_b128 v[228:231], v154 offset:17408
	s_barrier
	s_waitcnt lgkmcnt(0)
	s_setprio 1
	s_waitcnt lgkmcnt(0)
	v_mfma_f32_16x16x32_bf16 v[106:109], v[200:203], v[146:149], v[106:109]
	v_mfma_f32_16x16x32_bf16 v[122:125], v[200:203], v[192:195], v[122:125]
	v_mfma_f32_16x16x32_bf16 v[102:105], v[208:211], v[146:149], v[102:105]
	v_mfma_f32_16x16x32_bf16 v[118:121], v[208:211], v[192:195], v[118:121]
	v_mfma_f32_16x16x32_bf16 v[98:101], v[216:219], v[146:149], v[98:101]
	v_mfma_f32_16x16x32_bf16 v[114:117], v[216:219], v[192:195], v[114:117]
	v_mfma_f32_16x16x32_bf16 v[94:97], v[224:227], v[146:149], v[94:97]
	v_mfma_f32_16x16x32_bf16 v[110:113], v[224:227], v[192:195], v[110:113]
	v_mfma_f32_16x16x32_bf16 v[106:109], v[204:207], v[150:153], v[106:109]
	v_mfma_f32_16x16x32_bf16 v[122:125], v[204:207], v[196:199], v[122:125]
	v_mfma_f32_16x16x32_bf16 v[102:105], v[212:215], v[150:153], v[102:105]
	v_mfma_f32_16x16x32_bf16 v[118:121], v[212:215], v[196:199], v[118:121]
	v_mfma_f32_16x16x32_bf16 v[98:101], v[220:223], v[150:153], v[98:101]
	v_mfma_f32_16x16x32_bf16 v[114:117], v[220:223], v[196:199], v[114:117]
	v_mfma_f32_16x16x32_bf16 v[94:97], v[228:231], v[150:153], v[94:97]
	v_mfma_f32_16x16x32_bf16 v[110:113], v[228:231], v[196:199], v[110:113]
	s_setprio 0
	s_barrier
; #define STAGE(P, BASE, br, kt) do { const bf16_t* g_ = (BASE) + (size_t)(br) * K + (size_t)(kt) * 64; \
;         _Pragma("unroll") for (int i_ = 0; i_ < 2; ++i_) \
;             __builtin_amdgcn_global_load_lds((const unsigned*)(g_ + gofs[i_]), (lds_ptr_t)((P) + wb + i_ * 8192), 16, 0, 0); } while (0)
; #define LDA(dst, b, hh) _Pragma("unroll") for (int m = 0; m < 4; ++m) _Pragma("unroll") for (int k = 0; k < 2; ++k) \
;         dst[m][k] = *(const bf16x8*)(SA(b, hh) + lds_byte(wr * 64 + m * 16 + fr, k * 32 + fq * 8))
; #define LDB(dst, b, hh) _Pragma("unroll") for (int n = 0; n < 2; ++n) _Pragma("unroll") for (int k = 0; k < 2; ++k) \
;         dst[n][k] = *(const bf16x8*)(SB(b, hh) + lds_byte(wc * 32 + n * 16 + fr, k * 32 + fq * 8))
; #define MMA(ai, bj, At_, Bt_) do { __builtin_amdgcn_s_setprio(1); \
;         _Pragma("unroll") for (int m = 0; m < 4; ++m) _Pragma("unroll") for (int n = 0; n < 2; ++n) _Pragma("unroll") for (int k = 0; k < 2; ++k) \
;             acc[ai][bj][m][n] = MFMA16(At_[m][k], Bt_[n][k], acc[ai][bj][m][n]); \
;         __builtin_amdgcn_s_setprio(0); } while (0)
; #define WAIT_V(n) asm volatile("s_waitcnt vmcnt(" #n ")" ::: "memory")
; #define WAIT_L(n) asm volatile("s_waitcnt lgkmcnt(" #n ")" ::: "memory")
; #define BAR __builtin_amdgcn_s_barrier()
; #define SCHED __builtin_amdgcn_sched_barrier(0)
; #define STAGE(P, BASE, br, kt) do { const int sg_ = (kt) >> 3; const bf16_t* g_ = (sg_ == 0 ? BASE##0 : sg_ == 1 ? BASE##1 : BASE##2) + (size_t)(br) * K + (size_t)((kt) & 7) * 64; \
;         _Pragma("unroll") for (int i_ = 0; i_ < 2; ++i_) \
;             __builtin_amdgcn_global_load_lds((const unsigned*)(g_ + gofs[i_]), (lds_ptr_t)((P) + wb + i_ * 8192), 16, 0, 0); } while (0)
; #define BAR __builtin_amdgcn_s_barrier()
; template <class Hook>
; DI void gemm8_cat3(f32x4 (&acc)[2][2][4][2], const bf16_t* R0, const bf16_t* R1, const bf16_t* R2, const bf16_t* C0, const bf16_t* C1, const bf16_t* C2, char* shm, Hook hook) {
;     ...
;         STAGE(SB(0, 1), C, 128, tt + 2);
;         WAIT_V(6); BAR; MMA(1, 1, At, B1); BAR;
;         LDB(B0, 1, 0); SCHED; LDA(At, 1, 0); STAGE(SA(0, 1), R, 128, tt + 2);
;         WAIT_L(8); BAR; WAIT_L(0); MMA(0, 0, At, B0); BAR; SCHED;
;         LDB(B1, 1, 1); STAGE(SB(1, 0), C, 0, tt + 3);
;         BAR; WAIT_L(0); MMA(0, 1, At, B1); BAR;
;         LDA(At, 1, 1); STAGE(SA(1, 0), R, 0, tt + 3);
	s_add_u32 s96, s96, 0x20000
	s_addc_u32 s97, s97, 0
	v_readfirstlane_b32 s35, v165
	v_lshl_add_u64 v[146:147], s[96:97], 0, v[134:135]
	s_mov_b32 m0, s35
	v_readfirstlane_b32 s35, v166
	global_load_lds_dwordx4 v[146:147], off
	v_lshl_add_u64 v[146:147], s[96:97], 0, v[136:137]
	s_mov_b32 m0, s35
	s_nop 0
	global_load_lds_dwordx4 v[146:147], off
	s_waitcnt vmcnt(6)
	s_barrier
	s_setprio 1
	v_mfma_f32_16x16x32_bf16 v[126:129], v[200:203], v[232:235], v[126:129]
	v_mfma_f32_16x16x32_bf16 v[14:17], v[200:203], v[240:243], v[14:17]
	v_mfma_f32_16x16x32_bf16 v[34:37], v[208:211], v[232:235], v[34:37]
	v_mfma_f32_16x16x32_bf16 v[6:9], v[208:211], v[240:243], v[6:9]
	v_mfma_f32_16x16x32_bf16 v[38:41], v[216:219], v[232:235], v[38:41]
	v_mfma_f32_16x16x32_bf16 v[10:13], v[216:219], v[240:243], v[10:13]
	v_mfma_f32_16x16x32_bf16 v[22:25], v[224:227], v[232:235], v[22:25]
	v_mfma_f32_16x16x32_bf16 v[2:5], v[224:227], v[240:243], v[2:5]
	v_mfma_f32_16x16x32_bf16 v[126:129], v[204:207], v[236:239], v[126:129]
	v_mfma_f32_16x16x32_bf16 v[14:17], v[204:207], v[244:247], v[14:17]
	v_mfma_f32_16x16x32_bf16 v[34:37], v[212:215], v[236:239], v[34:37]
	v_mfma_f32_16x16x32_bf16 v[6:9], v[212:215], v[244:247], v[6:9]
	v_mfma_f32_16x16x32_bf16 v[38:41], v[220:223], v[236:239], v[38:41]
	v_mfma_f32_16x16x32_bf16 v[10:13], v[220:223], v[244:247], v[10:13]
	v_mfma_f32_16x16x32_bf16 v[22:25], v[228:231], v[236:239], v[22:25]
	v_mfma_f32_16x16x32_bf16 v[2:5], v[228:231], v[244:247], v[2:5]
	s_setprio 0
	s_barrier
	s_add_u32 s96, vcc_lo, 0x20000
	s_addc_u32 s97, vcc_hi, 0
	v_readfirstlane_b32 s35, v167
	v_lshl_add_u64 v[172:173], s[96:97], 0, v[134:135]
	s_mov_b32 m0, s35
	v_readfirstlane_b32 s35, v168
	global_load_lds_dwordx4 v[172:173], off
	v_lshl_add_u64 v[172:173], s[96:97], 0, v[136:137]
	s_mov_b32 m0, s35
	s_nop 0
	global_load_lds_dwordx4 v[172:173], off
	ds_read_b128 v[146:149], v169
	ds_read_b128 v[150:153], v169 offset:1024
	ds_read_b128 v[192:195], v169 offset:2048
	ds_read_b128 v[196:199], v169 offset:3072
	ds_read_b128 v[200:203], v157 offset:32768
	ds_read_b128 v[204:207], v157 offset:33792
	ds_read_b128 v[208:211], v156 offset:32768
	ds_read_b128 v[212:215], v156 offset:33792
	ds_read_b128 v[216:219], v155 offset:32768
	ds_read_b128 v[220:223], v155 offset:33792
	ds_read_b128 v[224:227], v154 offset:32768
	ds_read_b128 v[228:231], v154 offset:33792
	s_waitcnt lgkmcnt(8)
	s_barrier
	s_waitcnt lgkmcnt(0)
	s_setprio 1
	s_waitcnt lgkmcnt(0)
	v_mfma_f32_16x16x32_bf16 v[18:21], v[200:203], v[146:149], v[18:21]
	v_mfma_f32_16x16x32_bf16 v[58:61], v[200:203], v[192:195], v[58:61]
	v_mfma_f32_16x16x32_bf16 v[30:33], v[208:211], v[146:149], v[30:33]
	v_mfma_f32_16x16x32_bf16 v[54:57], v[208:211], v[192:195], v[54:57]
	v_mfma_f32_16x16x32_bf16 v[26:29], v[216:219], v[146:149], v[26:29]
	v_mfma_f32_16x16x32_bf16 v[50:53], v[216:219], v[192:195], v[50:53]
	v_mfma_f32_16x16x32_bf16 v[42:45], v[224:227], v[146:149], v[42:45]
	v_mfma_f32_16x16x32_bf16 v[46:49], v[224:227], v[192:195], v[46:49]
	v_mfma_f32_16x16x32_bf16 v[18:21], v[204:207], v[150:153], v[18:21]
	v_mfma_f32_16x16x32_bf16 v[58:61], v[204:207], v[196:199], v[58:61]
	v_mfma_f32_16x16x32_bf16 v[30:33], v[212:215], v[150:153], v[30:33]
	v_mfma_f32_16x16x32_bf16 v[54:57], v[212:215], v[196:199], v[54:57]
	v_mfma_f32_16x16x32_bf16 v[26:29], v[220:223], v[150:153], v[26:29]
	v_mfma_f32_16x16x32_bf16 v[50:53], v[220:223], v[196:199], v[50:53]
	v_mfma_f32_16x16x32_bf16 v[42:45], v[228:231], v[150:153], v[42:45]
	v_mfma_f32_16x16x32_bf16 v[46:49], v[228:231], v[196:199], v[46:49]
	s_setprio 0
	s_barrier
	s_add_i32 s35, s8, 5
	s_and_b32 s44, s9, 0x1c0
	s_and_b32 s35, s35, 24
	s_lshl_b32 s44, s44, 1
	s_cmp_eq_u32 s35, 8
	s_cselect_b32 s45, s25, s3
	s_cselect_b32 s35, s82, s34
	s_cselect_b32 vcc_hi, s24, s2
	s_cselect_b32 vcc_lo, s15, s26
	s_add_u32 s96, s45, s44
	s_addc_u32 s97, s35, 0
	v_readfirstlane_b32 s35, v170
	v_lshl_add_u64 v[172:173], s[96:97], 0, v[134:135]
	s_mov_b32 m0, s35
	v_readfirstlane_b32 s35, v171
	global_load_lds_dwordx4 v[172:173], off
	v_lshl_add_u64 v[172:173], s[96:97], 0, v[136:137]
	s_mov_b32 m0, s35
	s_nop 0
	global_load_lds_dwordx4 v[172:173], off
	ds_read_b128 v[232:235], v161
	ds_read_b128 v[236:239], v161 offset:1024
	ds_read_b128 v[240:243], v161 offset:2048
	ds_read_b128 v[244:247], v161 offset:3072
	s_barrier
	s_waitcnt lgkmcnt(0)
	s_setprio 1
	s_waitcnt lgkmcnt(0)
	v_mfma_f32_16x16x32_bf16 v[74:77], v[200:203], v[232:235], v[74:77]
	v_mfma_f32_16x16x32_bf16 v[90:93], v[200:203], v[240:243], v[90:93]
	v_mfma_f32_16x16x32_bf16 v[70:73], v[208:211], v[232:235], v[70:73]
	v_mfma_f32_16x16x32_bf16 v[86:89], v[208:211], v[240:243], v[86:89]
	v_mfma_f32_16x16x32_bf16 v[66:69], v[216:219], v[232:235], v[66:69]
	v_mfma_f32_16x16x32_bf16 v[82:85], v[216:219], v[240:243], v[82:85]
	v_mfma_f32_16x16x32_bf16 v[62:65], v[224:227], v[232:235], v[62:65]
	v_mfma_f32_16x16x32_bf16 v[78:81], v[224:227], v[240:243], v[78:81]
	v_mfma_f32_16x16x32_bf16 v[74:77], v[204:207], v[236:239], v[74:77]
	v_mfma_f32_16x16x32_bf16 v[90:93], v[204:207], v[244:247], v[90:93]
	v_mfma_f32_16x16x32_bf16 v[70:73], v[212:215], v[236:239], v[70:73]
	v_mfma_f32_16x16x32_bf16 v[86:89], v[212:215], v[244:247], v[86:89]
	v_mfma_f32_16x16x32_bf16 v[66:69], v[220:223], v[236:239], v[66:69]
	v_mfma_f32_16x16x32_bf16 v[82:85], v[220:223], v[244:247], v[82:85]
	v_mfma_f32_16x16x32_bf16 v[62:65], v[228:231], v[236:239], v[62:65]
	v_mfma_f32_16x16x32_bf16 v[78:81], v[228:231], v[244:247], v[78:81]
	s_setprio 0
	s_add_u32 vcc_lo, vcc_lo, s44
	s_addc_u32 vcc_hi, vcc_hi, 0
	v_readfirstlane_b32 s35, v184
	v_lshl_add_u64 v[172:173], vcc, 0, v[134:135]
	s_mov_b32 m0, s35
	v_readfirstlane_b32 s35, v185
	s_barrier
; DI float frcp(float x) { return __builtin_amdgcn_rcpf(x); }
; #define STAGE(P, BASE, br, kt) do { const bf16_t* g_ = (BASE) + (size_t)(br) * K + (size_t)(kt) * 64; \
;         _Pragma("unroll") for (int i_ = 0; i_ < 2; ++i_) \
;             __builtin_amdgcn_global_load_lds((const unsigned*)(g_ + gofs[i_]), (lds_ptr_t)((P) + wb + i_ * 8192), 16, 0, 0); } while (0)
; #define LDA(dst, b, hh) _Pragma("unroll") for (int m = 0; m < 4; ++m) _Pragma("unroll") for (int k = 0; k < 2; ++k) \
;         dst[m][k] = *(const bf16x8*)(SA(b, hh) + lds_byte(wr * 64 + m * 16 + fr, k * 32 + fq * 8))
; #define MMA(ai, bj, At_, Bt_) do { __builtin_amdgcn_s_setprio(1); \
;         _Pragma("unroll") for (int m = 0; m < 4; ++m) _Pragma("unroll") for (int n = 0; n < 2; ++n) _Pragma("unroll") for (int k = 0; k < 2; ++k) \
;             acc[ai][bj][m][n] = MFMA16(At_[m][k], Bt_[n][k], acc[ai][bj][m][n]); \
;         __builtin_amdgcn_s_setprio(0); } while (0)
; #define WAIT_V(n) asm volatile("s_waitcnt vmcnt(" #n ")" ::: "memory")
; #define WAIT_L(n) asm volatile("s_waitcnt lgkmcnt(" #n ")" ::: "memory")
; #define BAR __builtin_amdgcn_s_barrier()
; template <class Hook>
; DI void gemm8_cat3(f32x4 (&acc)[2][2][4][2], const bf16_t* R0, const bf16_t* R1, const bf16_t* R2, const bf16_t* C0, const bf16_t* C1, const bf16_t* C2, char* shm, Hook hook) {
;     ...
;         LDA(At, 1, 1); STAGE(SA(1, 0), R, 0, tt + 3);
;         BAR; WAIT_L(0); MMA(1, 0, At, B0); BAR; SCHED;
;         STAGE(SB(1, 1), C, 128, tt + 3);
;         WAIT_V(6); BAR; MMA(1, 1, At, B1); BAR;
;     }
; DI void merge_scale(const Params& P, int tile, int seg, f32x4 (&acc)[2][2][4][2]) {
; #pragma unroll
;     for (int g8 = 0; g8 < 8; ++g8) {
;         const int ai = g8 >> 2, bj = (g8 >> 1) & 1, nn = g8 & 1;
;         const u32x4 ga = *gate_slot(P, tile, seg, g8), gb = *gate_slot(P, tile, seg + 1, g8);
; #pragma unroll
;         for (int e = 0; e < 8; ++e) {
;             const float rl = (float)((ga[e >> 2] >> (8 * (e & 3))) & 255u) * frcp((float)((gb[e >> 2] >> (8 * (e & 3))) & 255u));
;             const float rh = (float)((ga[2 + (e >> 2)] >> (8 * (e & 3))) & 255u) * frcp((float)((gb[2 + (e >> 2)] >> (8 * (e & 3))) & 255u));
;             acc[ai][bj][e >> 2][nn][e & 3] *= rl;
;             acc[ai][bj][2 + (e >> 2)][nn][e & 3] *= rh;
;         }
;         __builtin_amdgcn_sched_barrier(0);
;     }
	global_load_lds_dwordx4 v[172:173], off
	v_lshl_add_u64 v[172:173], vcc, 0, v[136:137]
	s_mov_b32 m0, s35
	s_nop 0
	global_load_lds_dwordx4 v[172:173], off
	ds_read_b128 v[200:203], v157 offset:49152
	ds_read_b128 v[204:207], v157 offset:50176
	ds_read_b128 v[208:211], v156 offset:49152
	ds_read_b128 v[212:215], v156 offset:50176
	ds_read_b128 v[216:219], v155 offset:49152
	ds_read_b128 v[220:223], v155 offset:50176
	ds_read_b128 v[224:227], v154 offset:49152
	ds_read_b128 v[228:231], v154 offset:50176
	s_barrier
	s_waitcnt lgkmcnt(0)
	s_setprio 1
	s_waitcnt lgkmcnt(0)
	v_mfma_f32_16x16x32_bf16 v[106:109], v[200:203], v[146:149], v[106:109]
	v_mfma_f32_16x16x32_bf16 v[122:125], v[200:203], v[192:195], v[122:125]
	v_mfma_f32_16x16x32_bf16 v[102:105], v[208:211], v[146:149], v[102:105]
	v_mfma_f32_16x16x32_bf16 v[118:121], v[208:211], v[192:195], v[118:121]
	v_mfma_f32_16x16x32_bf16 v[98:101], v[216:219], v[146:149], v[98:101]
	v_mfma_f32_16x16x32_bf16 v[114:117], v[216:219], v[192:195], v[114:117]
	v_mfma_f32_16x16x32_bf16 v[94:97], v[224:227], v[146:149], v[94:97]
	v_mfma_f32_16x16x32_bf16 v[110:113], v[224:227], v[192:195], v[110:113]
	v_mfma_f32_16x16x32_bf16 v[106:109], v[204:207], v[150:153], v[106:109]
	v_mfma_f32_16x16x32_bf16 v[122:125], v[204:207], v[196:199], v[122:125]
	v_mfma_f32_16x16x32_bf16 v[102:105], v[212:215], v[150:153], v[102:105]
	v_mfma_f32_16x16x32_bf16 v[118:121], v[212:215], v[196:199], v[118:121]
	v_mfma_f32_16x16x32_bf16 v[98:101], v[220:223], v[150:153], v[98:101]
	v_mfma_f32_16x16x32_bf16 v[114:117], v[220:223], v[196:199], v[114:117]
	v_mfma_f32_16x16x32_bf16 v[94:97], v[228:231], v[150:153], v[94:97]
	v_mfma_f32_16x16x32_bf16 v[110:113], v[228:231], v[196:199], v[110:113]
	s_setprio 0
	s_barrier
	s_add_u32 s96, s96, 0x20000
	s_addc_u32 s97, s97, 0
	v_readfirstlane_b32 s35, v186
	v_lshl_add_u64 v[146:147], s[96:97], 0, v[134:135]
	s_mov_b32 m0, s35
	v_readfirstlane_b32 s35, v187
	global_load_lds_dwordx4 v[146:147], off
	v_lshl_add_u64 v[146:147], s[96:97], 0, v[136:137]
	s_mov_b32 m0, s35
	s_nop 0
	global_load_lds_dwordx4 v[146:147], off
	s_waitcnt vmcnt(6)
	s_barrier
	s_setprio 1
	v_mfma_f32_16x16x32_bf16 v[126:129], v[200:203], v[232:235], v[126:129]
	v_mfma_f32_16x16x32_bf16 v[14:17], v[200:203], v[240:243], v[14:17]
	v_mfma_f32_16x16x32_bf16 v[34:37], v[208:211], v[232:235], v[34:37]
	v_mfma_f32_16x16x32_bf16 v[6:9], v[208:211], v[240:243], v[6:9]
	v_mfma_f32_16x16x32_bf16 v[38:41], v[216:219], v[232:235], v[38:41]
	v_mfma_f32_16x16x32_bf16 v[10:13], v[216:219], v[240:243], v[10:13]
	v_mfma_f32_16x16x32_bf16 v[22:25], v[224:227], v[232:235], v[22:25]
	v_mfma_f32_16x16x32_bf16 v[2:5], v[224:227], v[240:243], v[2:5]
	v_mfma_f32_16x16x32_bf16 v[126:129], v[204:207], v[236:239], v[126:129]
	v_mfma_f32_16x16x32_bf16 v[14:17], v[204:207], v[244:247], v[14:17]
	v_mfma_f32_16x16x32_bf16 v[34:37], v[212:215], v[236:239], v[34:37]
	v_mfma_f32_16x16x32_bf16 v[6:9], v[212:215], v[244:247], v[6:9]
	v_mfma_f32_16x16x32_bf16 v[38:41], v[220:223], v[236:239], v[38:41]
	v_mfma_f32_16x16x32_bf16 v[10:13], v[220:223], v[244:247], v[10:13]
	v_mfma_f32_16x16x32_bf16 v[22:25], v[228:231], v[236:239], v[22:25]
	v_mfma_f32_16x16x32_bf16 v[2:5], v[228:231], v[244:247], v[2:5]
	s_setprio 0
	s_add_i32 s8, s8, 2
	s_addk_i32 s9, 0x80
	v_lshl_add_u64 v[130:131], v[130:131], 0, s[90:91]
	s_cmp_lt_u32 s8, 14
	v_lshl_add_u64 v[132:133], v[132:133], 0, s[90:91]
	s_barrier
	s_cbranch_scc1 .LBB0_58
	s_lshl_b64 s[8:9], s[58:59], 16
	v_mov_b32_e32 v130, v162
	s_add_u32 s35, s8, 0x20000
	s_addc_u32 s44, s9, 0
	v_ashrrev_i32_e32 v131, 31, v130
	v_lshl_add_u64 v[130:131], v[130:131], 4, s[56:57]
	v_mov_b32_e32 v134, v162
	s_add_u32 s8, s74, s35
	v_mov_b64_e32 v[242:243], v[130:131]
	s_addc_u32 s9, s75, s44
	v_ashrrev_i32_e32 v135, 31, v134
	v_lshl_add_u64 v[134:135], v[134:135], 4, s[8:9]
	v_mov_b64_e32 v[244:245], v[134:135]
	s_mov_b64 s[0:1], 0x2000
	global_load_dwordx4 v[210:213], v[242:243], off
	v_lshl_add_u64 v[242:243], v[242:243], 0, s[0:1]
	global_load_dwordx4 v[226:229], v[244:245], off
	v_lshl_add_u64 v[244:245], v[244:245], 0, s[0:1]
	global_load_dwordx4 v[214:217], v[242:243], off
	v_lshl_add_u64 v[242:243], v[242:243], 0, s[0:1]
	global_load_dwordx4 v[230:233], v[244:245], off
	v_lshl_add_u64 v[244:245], v[244:245], 0, s[0:1]
	global_load_dwordx4 v[218:221], v[242:243], off
	v_lshl_add_u64 v[242:243], v[242:243], 0, s[0:1]
	global_load_dwordx4 v[234:237], v[244:245], off
	v_lshl_add_u64 v[244:245], v[244:245], 0, s[0:1]
	global_load_dwordx4 v[222:225], v[242:243], off
	v_lshl_add_u64 v[242:243], v[242:243], 0, s[0:1]
	global_load_dwordx4 v[238:241], v[244:245], off
	v_lshl_add_u64 v[244:245], v[244:245], 0, s[0:1]
	s_waitcnt vmcnt(7)
	s_nop 1
	v_mov_b64_e32 v[130:131], v[210:211]
	v_mov_b64_e32 v[132:133], v[212:213]
	v_cvt_f32_ubyte3_e32 v147, v130
	v_cvt_f32_ubyte2_e32 v146, v130
	v_cvt_f32_ubyte1_e32 v149, v130
	v_cvt_f32_ubyte0_e32 v148, v130
	v_cvt_f32_ubyte3_e32 v151, v132
	v_cvt_f32_ubyte2_e32 v150, v132
	v_cvt_f32_ubyte1_e32 v153, v132
	v_cvt_f32_ubyte0_e32 v152, v132
	v_cvt_f32_ubyte3_e32 v173, v131
	v_cvt_f32_ubyte2_e32 v172, v131
	v_cvt_f32_ubyte1_e32 v193, v131
	v_cvt_f32_ubyte0_e32 v192, v131
	v_cvt_f32_ubyte3_e32 v131, v133
	v_cvt_f32_ubyte2_e32 v130, v133
	v_cvt_f32_ubyte1_e32 v195, v133
	v_cvt_f32_ubyte0_e32 v194, v133
	s_waitcnt vmcnt(6)
; DI float frcp(float x) { return __builtin_amdgcn_rcpf(x); }
; DI u32x4* gate_slot(const Params& P, int tile, int j, int g8) { return (u32x4*)slotp(P, SL_SK) + ((size_t)(tile * 3 + j) * 8 + g8) * 512 + tid(); }
; DI void merge_scale(const Params& P, int tile, int seg, f32x4 (&acc)[2][2][4][2]) {
; #pragma unroll
;     for (int g8 = 0; g8 < 8; ++g8) {
;         const int ai = g8 >> 2, bj = (g8 >> 1) & 1, nn = g8 & 1;
;         const u32x4 ga = *gate_slot(P, tile, seg, g8), gb = *gate_slot(P, tile, seg + 1, g8);
; #pragma unroll
;         for (int e = 0; e < 8; ++e) {
;             const float rl = (float)((ga[e >> 2] >> (8 * (e & 3))) & 255u) * frcp((float)((gb[e >> 2] >> (8 * (e & 3))) & 255u));
;             const float rh = (float)((ga[2 + (e >> 2)] >> (8 * (e & 3))) & 255u) * frcp((float)((gb[2 + (e >> 2)] >> (8 * (e & 3))) & 255u));
;             acc[ai][bj][e >> 2][nn][e & 3] *= rl;
;             acc[ai][bj][2 + (e >> 2)][nn][e & 3] *= rh;
;         }
;         __builtin_amdgcn_sched_barrier(0);
;     }
	s_nop 1
	v_mov_b64_e32 v[134:135], v[226:227]
	v_mov_b64_e32 v[136:137], v[228:229]
	v_cvt_f32_ubyte0_e32 v132, v134
	v_cvt_f32_ubyte0_e32 v133, v136
	v_cvt_f32_ubyte1_e32 v196, v134
	v_cvt_f32_ubyte1_e32 v197, v136
	v_cvt_f32_ubyte2_e32 v198, v134
	v_cvt_f32_ubyte2_e32 v199, v136
	v_cvt_f32_ubyte3_e32 v200, v134
	v_cvt_f32_ubyte3_e32 v201, v136
	v_cvt_f32_ubyte0_e32 v202, v135
	v_cvt_f32_ubyte0_e32 v203, v137
	v_cvt_f32_ubyte1_e32 v204, v135
	v_cvt_f32_ubyte1_e32 v205, v137
	v_cvt_f32_ubyte2_e32 v206, v135
	v_cvt_f32_ubyte2_e32 v207, v137
	v_cvt_f32_ubyte3_e32 v208, v135
	v_cvt_f32_ubyte3_e32 v209, v137
	v_rcp_iflag_f32_e32 v132, v132
	v_rcp_iflag_f32_e32 v134, v133
	v_rcp_iflag_f32_e32 v133, v196
	v_rcp_iflag_f32_e32 v135, v197
	v_rcp_iflag_f32_e32 v136, v198
	v_rcp_iflag_f32_e32 v196, v199
	v_rcp_iflag_f32_e32 v137, v200
	v_rcp_iflag_f32_e32 v197, v201
	v_rcp_iflag_f32_e32 v198, v202
	v_rcp_iflag_f32_e32 v200, v203
	v_rcp_iflag_f32_e32 v199, v204
	v_rcp_iflag_f32_e32 v201, v205
	v_rcp_iflag_f32_e32 v202, v206
	v_rcp_iflag_f32_e32 v204, v207
	v_rcp_iflag_f32_e32 v203, v208
	v_rcp_iflag_f32_e32 v205, v209
	v_pk_mul_f32 v[148:149], v[132:133], v[148:149]
	v_pk_mul_f32 v[132:133], v[136:137], v[146:147]
	v_pk_mul_f32 v[134:135], v[134:135], v[152:153]
	v_pk_mul_f32 v[136:137], v[196:197], v[150:151]
	v_pk_mul_f32 v[146:147], v[198:199], v[192:193]
	v_pk_mul_f32 v[150:151], v[202:203], v[172:173]
	v_pk_mul_f32 v[152:153], v[200:201], v[194:195]
	v_pk_mul_f32 v[172:173], v[204:205], v[130:131]
	v_pk_mul_f32 v[132:133], v[20:21], v[132:133]
	v_pk_mul_f32 v[130:131], v[18:19], v[148:149]
	v_pk_mul_f32 v[20:21], v[28:29], v[136:137]
	v_pk_mul_f32 v[18:19], v[26:27], v[134:135]
	v_pk_mul_f32 v[32:33], v[32:33], v[150:151]
	v_pk_mul_f32 v[30:31], v[30:31], v[146:147]
	v_pk_mul_f32 v[28:29], v[44:45], v[172:173]
	v_pk_mul_f32 v[26:27], v[42:43], v[152:153]
	v_mov_b32_e32 v42, v162
	s_add_u32 s35, s62, s35
	v_ashrrev_i32_e32 v43, 31, v42
	v_lshl_add_u64 v[42:43], v[42:43], 4, s[54:55]
	s_addc_u32 vcc_lo, s63, s44
	s_add_u32 s58, s35, 0x13802000
	v_mov_b32_e32 v42, v162
	s_addc_u32 s59, vcc_lo, 0
	v_ashrrev_i32_e32 v43, 31, v42
	v_lshl_add_u64 v[42:43], v[42:43], 4, s[58:59]
	s_waitcnt vmcnt(5)
	s_nop 1
	v_mov_b64_e32 v[134:135], v[214:215]
	v_mov_b64_e32 v[136:137], v[216:217]
	v_cvt_f32_ubyte3_e32 v173, v134
	v_cvt_f32_ubyte2_e32 v172, v134
	v_cvt_f32_ubyte1_e32 v193, v134
	v_cvt_f32_ubyte0_e32 v192, v134
	s_waitcnt vmcnt(4)
	s_nop 1
	v_mov_b64_e32 v[146:147], v[230:231]
	v_mov_b64_e32 v[148:149], v[232:233]
	v_cvt_f32_ubyte0_e32 v43, v148
	v_cvt_f32_ubyte1_e32 v44, v148
	v_cvt_f32_ubyte2_e32 v45, v148
	v_cvt_f32_ubyte0_e32 v42, v146
	v_rcp_iflag_f32_e32 v150, v43
	v_cvt_f32_ubyte1_e32 v43, v146
	v_rcp_iflag_f32_e32 v151, v44
	v_cvt_f32_ubyte2_e32 v44, v146
	v_rcp_iflag_f32_e32 v152, v45
	v_cvt_f32_ubyte3_e32 v45, v146
	v_rcp_iflag_f32_e32 v42, v42
	v_rcp_iflag_f32_e32 v43, v43
	v_rcp_iflag_f32_e32 v44, v44
	v_rcp_iflag_f32_e32 v45, v45
	v_cvt_f32_ubyte3_e32 v146, v148
	v_rcp_iflag_f32_e32 v153, v146
	v_pk_mul_f32 v[42:43], v[42:43], v[192:193]
	v_pk_mul_f32 v[44:45], v[44:45], v[172:173]
	v_pk_mul_f32 v[42:43], v[58:59], v[42:43]
	v_pk_mul_f32 v[44:45], v[60:61], v[44:45]
	v_cvt_f32_ubyte3_e32 v59, v136
	v_cvt_f32_ubyte2_e32 v58, v136
	v_cvt_f32_ubyte1_e32 v61, v136
	v_cvt_f32_ubyte0_e32 v60, v136
	v_pk_mul_f32 v[60:61], v[150:151], v[60:61]
	v_pk_mul_f32 v[58:59], v[152:153], v[58:59]
	v_pk_mul_f32 v[50:51], v[50:51], v[60:61]
	v_pk_mul_f32 v[52:53], v[52:53], v[58:59]
	v_cvt_f32_ubyte0_e32 v58, v147
	v_cvt_f32_ubyte1_e32 v59, v147
	v_cvt_f32_ubyte2_e32 v60, v147
	v_cvt_f32_ubyte3_e32 v61, v147
	v_rcp_iflag_f32_e32 v150, v58
	v_rcp_iflag_f32_e32 v151, v59
	v_rcp_iflag_f32_e32 v146, v60
	v_rcp_iflag_f32_e32 v147, v61
	v_cvt_f32_ubyte0_e32 v58, v149
	v_cvt_f32_ubyte1_e32 v59, v149
	v_cvt_f32_ubyte2_e32 v60, v149
	v_cvt_f32_ubyte3_e32 v61, v149
	v_rcp_iflag_f32_e32 v58, v58
	v_rcp_iflag_f32_e32 v59, v59
	v_rcp_iflag_f32_e32 v60, v60
	v_rcp_iflag_f32_e32 v61, v61
	v_cvt_f32_ubyte3_e32 v149, v135
	v_cvt_f32_ubyte2_e32 v148, v135
	v_cvt_f32_ubyte1_e32 v153, v135
	v_cvt_f32_ubyte0_e32 v152, v135
	v_pk_mul_f32 v[134:135], v[150:151], v[152:153]
	v_pk_mul_f32 v[146:147], v[146:147], v[148:149]
	v_pk_mul_f32 v[54:55], v[54:55], v[134:135]
	v_pk_mul_f32 v[56:57], v[56:57], v[146:147]
	v_cvt_f32_ubyte3_e32 v135, v137
	v_cvt_f32_ubyte2_e32 v134, v137
	v_cvt_f32_ubyte1_e32 v147, v137
	v_cvt_f32_ubyte0_e32 v146, v137
	v_pk_mul_f32 v[58:59], v[58:59], v[146:147]
	v_pk_mul_f32 v[60:61], v[60:61], v[134:135]
	v_pk_mul_f32 v[46:47], v[46:47], v[58:59]
	v_pk_mul_f32 v[48:49], v[48:49], v[60:61]
	v_mov_b32_e32 v58, v162
	s_add_u32 s56, s35, 0x13804000
	v_ashrrev_i32_e32 v59, 31, v58
	v_lshl_add_u64 v[58:59], v[58:59], 4, s[6:7]
	v_mov_b32_e32 v58, v162
	s_addc_u32 s57, vcc_lo, 0
	v_ashrrev_i32_e32 v59, 31, v58
	v_lshl_add_u64 v[58:59], v[58:59], 4, s[56:57]
	s_waitcnt vmcnt(3)
	s_nop 1
	v_mov_b64_e32 v[134:135], v[218:219]
	v_mov_b64_e32 v[136:137], v[220:221]
	v_cvt_f32_ubyte3_e32 v173, v134
	v_cvt_f32_ubyte2_e32 v172, v134
	v_cvt_f32_ubyte1_e32 v193, v134
	v_cvt_f32_ubyte0_e32 v192, v134
	s_waitcnt vmcnt(2)
; DI float frcp(float x) { return __builtin_amdgcn_rcpf(x); }
; DI u32x4* gate_slot(const Params& P, int tile, int j, int g8) { return (u32x4*)slotp(P, SL_SK) + ((size_t)(tile * 3 + j) * 8 + g8) * 512 + tid(); }
; DI void merge_scale(const Params& P, int tile, int seg, f32x4 (&acc)[2][2][4][2]) {
; #pragma unroll
;     for (int g8 = 0; g8 < 8; ++g8) {
;         const int ai = g8 >> 2, bj = (g8 >> 1) & 1, nn = g8 & 1;
;         const u32x4 ga = *gate_slot(P, tile, seg, g8), gb = *gate_slot(P, tile, seg + 1, g8);
; #pragma unroll
;         for (int e = 0; e < 8; ++e) {
;             const float rl = (float)((ga[e >> 2] >> (8 * (e & 3))) & 255u) * frcp((float)((gb[e >> 2] >> (8 * (e & 3))) & 255u));
;             const float rh = (float)((ga[2 + (e >> 2)] >> (8 * (e & 3))) & 255u) * frcp((float)((gb[2 + (e >> 2)] >> (8 * (e & 3))) & 255u));
;             acc[ai][bj][e >> 2][nn][e & 3] *= rl;
;             acc[ai][bj][2 + (e >> 2)][nn][e & 3] *= rh;
;         }
;         __builtin_amdgcn_sched_barrier(0);
;     }
	s_nop 1
	v_mov_b64_e32 v[146:147], v[234:235]
	v_mov_b64_e32 v[148:149], v[236:237]
	v_cvt_f32_ubyte0_e32 v59, v148
	v_cvt_f32_ubyte1_e32 v60, v148
	v_cvt_f32_ubyte2_e32 v61, v148
	v_cvt_f32_ubyte0_e32 v58, v146
	v_rcp_iflag_f32_e32 v150, v59
	v_cvt_f32_ubyte1_e32 v59, v146
	v_rcp_iflag_f32_e32 v151, v60
	v_cvt_f32_ubyte2_e32 v60, v146
	v_rcp_iflag_f32_e32 v152, v61
	v_cvt_f32_ubyte3_e32 v61, v146
	v_rcp_iflag_f32_e32 v58, v58
	v_rcp_iflag_f32_e32 v59, v59
	v_rcp_iflag_f32_e32 v60, v60
	v_rcp_iflag_f32_e32 v61, v61
	v_cvt_f32_ubyte3_e32 v146, v148
	v_rcp_iflag_f32_e32 v153, v146
	v_pk_mul_f32 v[58:59], v[58:59], v[192:193]
	v_pk_mul_f32 v[60:61], v[60:61], v[172:173]
	v_pk_mul_f32 v[58:59], v[74:75], v[58:59]
	v_pk_mul_f32 v[60:61], v[76:77], v[60:61]
	v_cvt_f32_ubyte3_e32 v75, v136
	v_cvt_f32_ubyte2_e32 v74, v136
	v_cvt_f32_ubyte1_e32 v77, v136
	v_cvt_f32_ubyte0_e32 v76, v136
	v_pk_mul_f32 v[76:77], v[150:151], v[76:77]
	v_pk_mul_f32 v[74:75], v[152:153], v[74:75]
	v_pk_mul_f32 v[66:67], v[66:67], v[76:77]
	v_pk_mul_f32 v[68:69], v[68:69], v[74:75]
	v_cvt_f32_ubyte0_e32 v74, v147
	v_cvt_f32_ubyte1_e32 v75, v147
	v_cvt_f32_ubyte2_e32 v76, v147
	v_cvt_f32_ubyte3_e32 v77, v147
	v_rcp_iflag_f32_e32 v150, v74
	v_rcp_iflag_f32_e32 v151, v75
	v_rcp_iflag_f32_e32 v146, v76
	v_rcp_iflag_f32_e32 v147, v77
	v_cvt_f32_ubyte0_e32 v74, v149
	v_cvt_f32_ubyte1_e32 v75, v149
	v_cvt_f32_ubyte2_e32 v76, v149
	v_cvt_f32_ubyte3_e32 v77, v149
	v_rcp_iflag_f32_e32 v74, v74
	v_rcp_iflag_f32_e32 v75, v75
	v_rcp_iflag_f32_e32 v76, v76
	v_rcp_iflag_f32_e32 v77, v77
	v_cvt_f32_ubyte3_e32 v149, v135
	v_cvt_f32_ubyte2_e32 v148, v135
	v_cvt_f32_ubyte1_e32 v153, v135
	v_cvt_f32_ubyte0_e32 v152, v135
	v_pk_mul_f32 v[134:135], v[150:151], v[152:153]
	v_pk_mul_f32 v[146:147], v[146:147], v[148:149]
	v_pk_mul_f32 v[70:71], v[70:71], v[134:135]
	v_pk_mul_f32 v[72:73], v[72:73], v[146:147]
	v_cvt_f32_ubyte3_e32 v135, v137
	v_cvt_f32_ubyte2_e32 v134, v137
	v_cvt_f32_ubyte1_e32 v147, v137
	v_cvt_f32_ubyte0_e32 v146, v137
	v_pk_mul_f32 v[74:75], v[74:75], v[146:147]
	v_pk_mul_f32 v[76:77], v[76:77], v[134:135]
	v_pk_mul_f32 v[62:63], v[62:63], v[74:75]
	v_pk_mul_f32 v[64:65], v[64:65], v[76:77]
	v_mov_b32_e32 v74, v162
	s_add_u32 s54, s35, 0x13806000
	v_ashrrev_i32_e32 v75, 31, v74
	v_lshl_add_u64 v[74:75], v[74:75], 4, s[10:11]
	v_mov_b32_e32 v74, v162
	s_addc_u32 s55, vcc_lo, 0
	v_ashrrev_i32_e32 v75, 31, v74
	v_lshl_add_u64 v[74:75], v[74:75], 4, s[54:55]
	s_waitcnt vmcnt(1)
	s_nop 1
	v_mov_b64_e32 v[134:135], v[222:223]
	v_mov_b64_e32 v[136:137], v[224:225]
	v_cvt_f32_ubyte3_e32 v173, v134
	v_cvt_f32_ubyte2_e32 v172, v134
	v_cvt_f32_ubyte1_e32 v193, v134
	v_cvt_f32_ubyte0_e32 v192, v134
	s_waitcnt vmcnt(0)
	s_nop 1
	v_mov_b64_e32 v[146:147], v[238:239]
	v_mov_b64_e32 v[148:149], v[240:241]
	global_load_dwordx4 v[210:213], v[242:243], off
	v_lshl_add_u64 v[242:243], v[242:243], 0, s[0:1]
	global_load_dwordx4 v[226:229], v[244:245], off
	v_lshl_add_u64 v[244:245], v[244:245], 0, s[0:1]
	global_load_dwordx4 v[214:217], v[242:243], off
	v_lshl_add_u64 v[242:243], v[242:243], 0, s[0:1]
	global_load_dwordx4 v[230:233], v[244:245], off
	v_lshl_add_u64 v[244:245], v[244:245], 0, s[0:1]
	global_load_dwordx4 v[218:221], v[242:243], off
	v_lshl_add_u64 v[242:243], v[242:243], 0, s[0:1]
	global_load_dwordx4 v[234:237], v[244:245], off
	v_lshl_add_u64 v[244:245], v[244:245], 0, s[0:1]
	global_load_dwordx4 v[222:225], v[242:243], off
	v_lshl_add_u64 v[242:243], v[242:243], 0, s[0:1]
	global_load_dwordx4 v[238:241], v[244:245], off
	v_lshl_add_u64 v[244:245], v[244:245], 0, s[0:1]
	v_cvt_f32_ubyte0_e32 v75, v148
	v_cvt_f32_ubyte1_e32 v76, v148
	v_cvt_f32_ubyte2_e32 v77, v148
	v_cvt_f32_ubyte0_e32 v74, v146
	v_rcp_iflag_f32_e32 v150, v75
	v_cvt_f32_ubyte1_e32 v75, v146
	v_rcp_iflag_f32_e32 v151, v76
	v_cvt_f32_ubyte2_e32 v76, v146
	v_rcp_iflag_f32_e32 v152, v77
	v_cvt_f32_ubyte3_e32 v77, v146
	v_rcp_iflag_f32_e32 v74, v74
	v_rcp_iflag_f32_e32 v75, v75
	v_rcp_iflag_f32_e32 v76, v76
	v_rcp_iflag_f32_e32 v77, v77
	v_cvt_f32_ubyte3_e32 v146, v148
	v_rcp_iflag_f32_e32 v153, v146
	v_pk_mul_f32 v[74:75], v[74:75], v[192:193]
	v_pk_mul_f32 v[76:77], v[76:77], v[172:173]
	v_pk_mul_f32 v[74:75], v[90:91], v[74:75]
	v_pk_mul_f32 v[76:77], v[92:93], v[76:77]
	v_cvt_f32_ubyte3_e32 v91, v136
	v_cvt_f32_ubyte2_e32 v90, v136
	v_cvt_f32_ubyte1_e32 v93, v136
	v_cvt_f32_ubyte0_e32 v92, v136
	v_pk_mul_f32 v[92:93], v[150:151], v[92:93]
	v_pk_mul_f32 v[90:91], v[152:153], v[90:91]
	v_pk_mul_f32 v[82:83], v[82:83], v[92:93]
	v_pk_mul_f32 v[84:85], v[84:85], v[90:91]
	v_cvt_f32_ubyte0_e32 v90, v147
	v_cvt_f32_ubyte1_e32 v91, v147
	v_cvt_f32_ubyte2_e32 v92, v147
	v_cvt_f32_ubyte3_e32 v93, v147
	v_rcp_iflag_f32_e32 v150, v90
	v_rcp_iflag_f32_e32 v151, v91
	v_rcp_iflag_f32_e32 v146, v92
	v_rcp_iflag_f32_e32 v147, v93
	v_cvt_f32_ubyte0_e32 v90, v149
	v_cvt_f32_ubyte1_e32 v91, v149
	v_cvt_f32_ubyte2_e32 v92, v149
	v_cvt_f32_ubyte3_e32 v93, v149
	v_rcp_iflag_f32_e32 v90, v90
	v_rcp_iflag_f32_e32 v91, v91
	v_rcp_iflag_f32_e32 v92, v92
	v_rcp_iflag_f32_e32 v93, v93
	v_cvt_f32_ubyte3_e32 v149, v135
	v_cvt_f32_ubyte2_e32 v148, v135
	v_cvt_f32_ubyte1_e32 v153, v135
	v_cvt_f32_ubyte0_e32 v152, v135
	v_pk_mul_f32 v[134:135], v[150:151], v[152:153]
	v_pk_mul_f32 v[146:147], v[146:147], v[148:149]
	v_pk_mul_f32 v[86:87], v[86:87], v[134:135]
	v_pk_mul_f32 v[88:89], v[88:89], v[146:147]
	v_cvt_f32_ubyte3_e32 v135, v137
	v_cvt_f32_ubyte2_e32 v134, v137
	v_cvt_f32_ubyte1_e32 v147, v137
	v_cvt_f32_ubyte0_e32 v146, v137
	v_pk_mul_f32 v[90:91], v[90:91], v[146:147]
	v_pk_mul_f32 v[92:93], v[92:93], v[134:135]
	v_pk_mul_f32 v[78:79], v[78:79], v[90:91]
	v_pk_mul_f32 v[80:81], v[80:81], v[92:93]
	v_mov_b32_e32 v90, v162
	s_add_u32 s6, s35, 0x13808000
	v_ashrrev_i32_e32 v91, 31, v90
	v_lshl_add_u64 v[90:91], v[90:91], 4, s[12:13]
	v_mov_b32_e32 v90, v162
	s_addc_u32 s7, vcc_lo, 0
	v_ashrrev_i32_e32 v91, 31, v90
	v_lshl_add_u64 v[90:91], v[90:91], 4, s[6:7]
	s_waitcnt vmcnt(7)
; DI float frcp(float x) { return __builtin_amdgcn_rcpf(x); }
; DI u32x4* gate_slot(const Params& P, int tile, int j, int g8) { return (u32x4*)slotp(P, SL_SK) + ((size_t)(tile * 3 + j) * 8 + g8) * 512 + tid(); }
; DI void merge_scale(const Params& P, int tile, int seg, f32x4 (&acc)[2][2][4][2]) {
; #pragma unroll
;     for (int g8 = 0; g8 < 8; ++g8) {
;         const int ai = g8 >> 2, bj = (g8 >> 1) & 1, nn = g8 & 1;
;         const u32x4 ga = *gate_slot(P, tile, seg, g8), gb = *gate_slot(P, tile, seg + 1, g8);
; #pragma unroll
;         for (int e = 0; e < 8; ++e) {
;             const float rl = (float)((ga[e >> 2] >> (8 * (e & 3))) & 255u) * frcp((float)((gb[e >> 2] >> (8 * (e & 3))) & 255u));
;             const float rh = (float)((ga[2 + (e >> 2)] >> (8 * (e & 3))) & 255u) * frcp((float)((gb[2 + (e >> 2)] >> (8 * (e & 3))) & 255u));
;             acc[ai][bj][e >> 2][nn][e & 3] *= rl;
;             acc[ai][bj][2 + (e >> 2)][nn][e & 3] *= rh;
;         }
;         __builtin_amdgcn_sched_barrier(0);
;     }
	s_nop 1
	v_mov_b64_e32 v[134:135], v[210:211]
	v_mov_b64_e32 v[136:137], v[212:213]
	v_cvt_f32_ubyte3_e32 v173, v134
	v_cvt_f32_ubyte2_e32 v172, v134
	v_cvt_f32_ubyte1_e32 v193, v134
	v_cvt_f32_ubyte0_e32 v192, v134
	s_waitcnt vmcnt(6)
	s_nop 1
	v_mov_b64_e32 v[146:147], v[226:227]
	v_mov_b64_e32 v[148:149], v[228:229]
	v_cvt_f32_ubyte0_e32 v91, v148
	v_cvt_f32_ubyte1_e32 v92, v148
	v_cvt_f32_ubyte2_e32 v93, v148
	v_cvt_f32_ubyte0_e32 v90, v146
	v_rcp_iflag_f32_e32 v150, v91
	v_cvt_f32_ubyte1_e32 v91, v146
	v_rcp_iflag_f32_e32 v151, v92
	v_cvt_f32_ubyte2_e32 v92, v146
	v_rcp_iflag_f32_e32 v152, v93
	v_cvt_f32_ubyte3_e32 v93, v146
	v_rcp_iflag_f32_e32 v90, v90
	v_rcp_iflag_f32_e32 v91, v91
	v_rcp_iflag_f32_e32 v92, v92
	v_rcp_iflag_f32_e32 v93, v93
	v_cvt_f32_ubyte3_e32 v146, v148
	v_rcp_iflag_f32_e32 v153, v146
	v_pk_mul_f32 v[90:91], v[90:91], v[192:193]
	v_pk_mul_f32 v[92:93], v[92:93], v[172:173]
	v_pk_mul_f32 v[90:91], v[106:107], v[90:91]
	v_pk_mul_f32 v[92:93], v[108:109], v[92:93]
	v_cvt_f32_ubyte3_e32 v107, v136
	v_cvt_f32_ubyte2_e32 v106, v136
	v_cvt_f32_ubyte1_e32 v109, v136
	v_cvt_f32_ubyte0_e32 v108, v136
	v_pk_mul_f32 v[108:109], v[150:151], v[108:109]
	v_pk_mul_f32 v[106:107], v[152:153], v[106:107]
	v_pk_mul_f32 v[98:99], v[98:99], v[108:109]
	v_pk_mul_f32 v[100:101], v[100:101], v[106:107]
	v_cvt_f32_ubyte0_e32 v106, v147
	v_cvt_f32_ubyte1_e32 v107, v147
	v_cvt_f32_ubyte2_e32 v108, v147
	v_cvt_f32_ubyte3_e32 v109, v147
	v_rcp_iflag_f32_e32 v150, v106
	v_rcp_iflag_f32_e32 v151, v107
	v_rcp_iflag_f32_e32 v146, v108
	v_rcp_iflag_f32_e32 v147, v109
	v_cvt_f32_ubyte0_e32 v106, v149
	v_cvt_f32_ubyte1_e32 v107, v149
	v_cvt_f32_ubyte2_e32 v108, v149
	v_cvt_f32_ubyte3_e32 v109, v149
	v_rcp_iflag_f32_e32 v106, v106
	v_rcp_iflag_f32_e32 v107, v107
	v_rcp_iflag_f32_e32 v108, v108
	v_rcp_iflag_f32_e32 v109, v109
	v_cvt_f32_ubyte3_e32 v149, v135
	v_cvt_f32_ubyte2_e32 v148, v135
	v_cvt_f32_ubyte1_e32 v153, v135
	v_cvt_f32_ubyte0_e32 v152, v135
	v_pk_mul_f32 v[134:135], v[150:151], v[152:153]
	v_pk_mul_f32 v[146:147], v[146:147], v[148:149]
	v_pk_mul_f32 v[102:103], v[102:103], v[134:135]
	v_pk_mul_f32 v[104:105], v[104:105], v[146:147]
	v_cvt_f32_ubyte3_e32 v135, v137
	v_cvt_f32_ubyte2_e32 v134, v137
	v_cvt_f32_ubyte1_e32 v147, v137
	v_cvt_f32_ubyte0_e32 v146, v137
	v_pk_mul_f32 v[106:107], v[106:107], v[146:147]
	v_pk_mul_f32 v[108:109], v[108:109], v[134:135]
	v_pk_mul_f32 v[94:95], v[94:95], v[106:107]
	v_pk_mul_f32 v[96:97], v[96:97], v[108:109]
	v_mov_b32_e32 v106, v162
	s_add_u32 s10, s35, 0x1380a000
	v_ashrrev_i32_e32 v107, 31, v106
	v_lshl_add_u64 v[106:107], v[106:107], 4, s[16:17]
	v_mov_b32_e32 v106, v162
	s_addc_u32 s11, vcc_lo, 0
	v_ashrrev_i32_e32 v107, 31, v106
	v_lshl_add_u64 v[106:107], v[106:107], 4, s[10:11]
	s_waitcnt vmcnt(5)
	s_nop 1
	v_mov_b64_e32 v[134:135], v[214:215]
	v_mov_b64_e32 v[136:137], v[216:217]
	v_cvt_f32_ubyte3_e32 v173, v134
	v_cvt_f32_ubyte2_e32 v172, v134
	v_cvt_f32_ubyte1_e32 v193, v134
	v_cvt_f32_ubyte0_e32 v192, v134
	s_waitcnt vmcnt(4)
	s_nop 1
	v_mov_b64_e32 v[146:147], v[230:231]
	v_mov_b64_e32 v[148:149], v[232:233]
	v_cvt_f32_ubyte0_e32 v107, v148
	v_cvt_f32_ubyte1_e32 v108, v148
	v_cvt_f32_ubyte2_e32 v109, v148
	v_cvt_f32_ubyte0_e32 v106, v146
	v_rcp_iflag_f32_e32 v150, v107
	v_cvt_f32_ubyte1_e32 v107, v146
	v_rcp_iflag_f32_e32 v151, v108
	v_cvt_f32_ubyte2_e32 v108, v146
	v_rcp_iflag_f32_e32 v152, v109
	v_cvt_f32_ubyte3_e32 v109, v146
	v_rcp_iflag_f32_e32 v106, v106
	v_rcp_iflag_f32_e32 v107, v107
	v_rcp_iflag_f32_e32 v108, v108
	v_rcp_iflag_f32_e32 v109, v109
	v_cvt_f32_ubyte3_e32 v146, v148
	v_rcp_iflag_f32_e32 v153, v146
	v_pk_mul_f32 v[106:107], v[106:107], v[192:193]
	v_pk_mul_f32 v[108:109], v[108:109], v[172:173]
	v_pk_mul_f32 v[106:107], v[122:123], v[106:107]
	v_pk_mul_f32 v[108:109], v[124:125], v[108:109]
	v_cvt_f32_ubyte3_e32 v123, v136
	v_cvt_f32_ubyte2_e32 v122, v136
	v_cvt_f32_ubyte1_e32 v125, v136
	v_cvt_f32_ubyte0_e32 v124, v136
	v_pk_mul_f32 v[124:125], v[150:151], v[124:125]
	v_pk_mul_f32 v[122:123], v[152:153], v[122:123]
	v_pk_mul_f32 v[114:115], v[114:115], v[124:125]
	v_pk_mul_f32 v[116:117], v[116:117], v[122:123]
	v_cvt_f32_ubyte0_e32 v122, v147
	v_cvt_f32_ubyte1_e32 v123, v147
	v_cvt_f32_ubyte2_e32 v124, v147
	v_cvt_f32_ubyte3_e32 v125, v147
	v_rcp_iflag_f32_e32 v150, v122
	v_rcp_iflag_f32_e32 v151, v123
	v_rcp_iflag_f32_e32 v146, v124
	v_rcp_iflag_f32_e32 v147, v125
	v_cvt_f32_ubyte0_e32 v122, v149
	v_cvt_f32_ubyte1_e32 v123, v149
	v_cvt_f32_ubyte2_e32 v124, v149
	v_cvt_f32_ubyte3_e32 v125, v149
	v_rcp_iflag_f32_e32 v122, v122
	v_rcp_iflag_f32_e32 v123, v123
	v_rcp_iflag_f32_e32 v124, v124
	v_rcp_iflag_f32_e32 v125, v125
	v_cvt_f32_ubyte3_e32 v149, v135
	v_cvt_f32_ubyte2_e32 v148, v135
	v_cvt_f32_ubyte1_e32 v153, v135
	v_cvt_f32_ubyte0_e32 v152, v135
	v_pk_mul_f32 v[134:135], v[150:151], v[152:153]
	v_pk_mul_f32 v[146:147], v[146:147], v[148:149]
	v_pk_mul_f32 v[118:119], v[118:119], v[134:135]
	v_pk_mul_f32 v[120:121], v[120:121], v[146:147]
	v_cvt_f32_ubyte3_e32 v135, v137
	v_cvt_f32_ubyte2_e32 v134, v137
	v_cvt_f32_ubyte1_e32 v147, v137
	v_cvt_f32_ubyte0_e32 v146, v137
	v_pk_mul_f32 v[122:123], v[122:123], v[146:147]
	v_pk_mul_f32 v[124:125], v[124:125], v[134:135]
	v_pk_mul_f32 v[110:111], v[110:111], v[122:123]
	v_pk_mul_f32 v[112:113], v[112:113], v[124:125]
	v_mov_b32_e32 v122, v162
	s_add_u32 s12, s35, 0x1380c000
	v_ashrrev_i32_e32 v123, 31, v122
	v_lshl_add_u64 v[122:123], v[122:123], 4, s[20:21]
	v_mov_b32_e32 v122, v162
	s_addc_u32 s13, vcc_lo, 0
	v_ashrrev_i32_e32 v123, 31, v122
	v_lshl_add_u64 v[122:123], v[122:123], 4, s[12:13]
	s_waitcnt vmcnt(3)
; DI float frcp(float x) { return __builtin_amdgcn_rcpf(x); }
; DI u32x4* gate_slot(const Params& P, int tile, int j, int g8) { return (u32x4*)slotp(P, SL_SK) + ((size_t)(tile * 3 + j) * 8 + g8) * 512 + tid(); }
; template <class Hook>
; DI void gemm8_cat3(f32x4 (&acc)[2][2][4][2], const bf16_t* R0, const bf16_t* R1, const bf16_t* R2, const bf16_t* C0, const bf16_t* C1, const bf16_t* C2, char* shm, Hook hook) {
;     ...
;     for (int tt = 16; tt < nt - 2; tt += 2) {
; DI void merge_scale(const Params& P, int tile, int seg, f32x4 (&acc)[2][2][4][2]) {
; #pragma unroll
;     for (int g8 = 0; g8 < 8; ++g8) {
;         const int ai = g8 >> 2, bj = (g8 >> 1) & 1, nn = g8 & 1;
;         const u32x4 ga = *gate_slot(P, tile, seg, g8), gb = *gate_slot(P, tile, seg + 1, g8);
; #pragma unroll
;         for (int e = 0; e < 8; ++e) {
;             const float rl = (float)((ga[e >> 2] >> (8 * (e & 3))) & 255u) * frcp((float)((gb[e >> 2] >> (8 * (e & 3))) & 255u));
;             const float rh = (float)((ga[2 + (e >> 2)] >> (8 * (e & 3))) & 255u) * frcp((float)((gb[2 + (e >> 2)] >> (8 * (e & 3))) & 255u));
;             acc[ai][bj][e >> 2][nn][e & 3] *= rl;
;             acc[ai][bj][2 + (e >> 2)][nn][e & 3] *= rh;
;         }
;         __builtin_amdgcn_sched_barrier(0);
;     }
	s_nop 1
	v_mov_b64_e32 v[134:135], v[218:219]
	v_mov_b64_e32 v[136:137], v[220:221]
	v_cvt_f32_ubyte3_e32 v173, v134
	v_cvt_f32_ubyte2_e32 v172, v134
	v_cvt_f32_ubyte1_e32 v193, v134
	v_cvt_f32_ubyte0_e32 v192, v134
	s_waitcnt vmcnt(2)
	s_nop 1
	v_mov_b64_e32 v[146:147], v[234:235]
	v_mov_b64_e32 v[148:149], v[236:237]
	v_cvt_f32_ubyte0_e32 v123, v148
	v_cvt_f32_ubyte1_e32 v124, v148
	v_cvt_f32_ubyte2_e32 v125, v148
	v_cvt_f32_ubyte0_e32 v122, v146
	v_rcp_iflag_f32_e32 v150, v123
	v_cvt_f32_ubyte1_e32 v123, v146
	v_rcp_iflag_f32_e32 v151, v124
	v_cvt_f32_ubyte2_e32 v124, v146
	v_rcp_iflag_f32_e32 v152, v125
	v_cvt_f32_ubyte3_e32 v125, v146
	v_rcp_iflag_f32_e32 v122, v122
	v_rcp_iflag_f32_e32 v123, v123
	v_rcp_iflag_f32_e32 v124, v124
	v_rcp_iflag_f32_e32 v125, v125
	v_cvt_f32_ubyte3_e32 v146, v148
	v_rcp_iflag_f32_e32 v153, v146
	v_pk_mul_f32 v[122:123], v[122:123], v[192:193]
	v_pk_mul_f32 v[124:125], v[124:125], v[172:173]
	v_pk_mul_f32 v[122:123], v[126:127], v[122:123]
	v_pk_mul_f32 v[124:125], v[128:129], v[124:125]
	v_cvt_f32_ubyte3_e32 v127, v136
	v_cvt_f32_ubyte2_e32 v126, v136
	v_cvt_f32_ubyte1_e32 v129, v136
	v_cvt_f32_ubyte0_e32 v128, v136
	v_pk_mul_f32 v[128:129], v[150:151], v[128:129]
	v_pk_mul_f32 v[126:127], v[152:153], v[126:127]
	v_pk_mul_f32 v[38:39], v[38:39], v[128:129]
	v_pk_mul_f32 v[40:41], v[40:41], v[126:127]
	v_cvt_f32_ubyte0_e32 v126, v147
	v_cvt_f32_ubyte1_e32 v127, v147
	v_cvt_f32_ubyte2_e32 v128, v147
	v_cvt_f32_ubyte3_e32 v129, v147
	v_rcp_iflag_f32_e32 v150, v126
	v_rcp_iflag_f32_e32 v151, v127
	v_rcp_iflag_f32_e32 v146, v128
	v_rcp_iflag_f32_e32 v147, v129
	v_cvt_f32_ubyte0_e32 v126, v149
	v_cvt_f32_ubyte1_e32 v127, v149
	v_cvt_f32_ubyte2_e32 v128, v149
	v_cvt_f32_ubyte3_e32 v129, v149
	v_rcp_iflag_f32_e32 v126, v126
	v_rcp_iflag_f32_e32 v127, v127
	v_rcp_iflag_f32_e32 v128, v128
	v_rcp_iflag_f32_e32 v129, v129
	v_cvt_f32_ubyte3_e32 v149, v135
	v_cvt_f32_ubyte2_e32 v148, v135
	v_cvt_f32_ubyte1_e32 v153, v135
	v_cvt_f32_ubyte0_e32 v152, v135
	v_pk_mul_f32 v[134:135], v[150:151], v[152:153]
	v_pk_mul_f32 v[146:147], v[146:147], v[148:149]
	v_pk_mul_f32 v[34:35], v[34:35], v[134:135]
	v_pk_mul_f32 v[36:37], v[36:37], v[146:147]
	v_cvt_f32_ubyte3_e32 v135, v137
	v_cvt_f32_ubyte2_e32 v134, v137
	v_cvt_f32_ubyte1_e32 v147, v137
	v_cvt_f32_ubyte0_e32 v146, v137
	v_pk_mul_f32 v[126:127], v[126:127], v[146:147]
	v_pk_mul_f32 v[128:129], v[128:129], v[134:135]
	v_pk_mul_f32 v[22:23], v[22:23], v[126:127]
	v_pk_mul_f32 v[24:25], v[24:25], v[128:129]
	v_mov_b32_e32 v126, v162
	s_add_u32 s16, s35, 0x1380e000
	v_ashrrev_i32_e32 v127, 31, v126
	v_lshl_add_u64 v[126:127], v[126:127], 4, s[22:23]
	v_mov_b32_e32 v134, v162
	s_addc_u32 s17, vcc_lo, 0
	v_ashrrev_i32_e32 v135, 31, v134
	v_lshl_add_u64 v[134:135], v[134:135], 4, s[16:17]
	s_waitcnt vmcnt(1)
	s_nop 1
	v_mov_b64_e32 v[126:127], v[222:223]
	v_mov_b64_e32 v[128:129], v[224:225]
	v_cvt_f32_ubyte3_e32 v173, v126
	v_cvt_f32_ubyte2_e32 v172, v126
	v_cvt_f32_ubyte1_e32 v193, v126
	v_cvt_f32_ubyte0_e32 v192, v126
	s_waitcnt vmcnt(0)
	s_nop 1
	v_mov_b64_e32 v[146:147], v[238:239]
	v_mov_b64_e32 v[148:149], v[240:241]
	v_cvt_f32_ubyte0_e32 v135, v148
	v_cvt_f32_ubyte0_e32 v134, v146
	v_rcp_iflag_f32_e32 v136, v135
	v_cvt_f32_ubyte1_e32 v135, v146
	v_cvt_f32_ubyte2_e32 v150, v146
	v_cvt_f32_ubyte2_e32 v151, v148
	v_cvt_f32_ubyte3_e32 v146, v146
	v_rcp_iflag_f32_e32 v134, v134
	v_rcp_iflag_f32_e32 v135, v135
	v_rcp_iflag_f32_e32 v150, v150
	v_rcp_iflag_f32_e32 v152, v151
	v_rcp_iflag_f32_e32 v151, v146
	v_cvt_f32_ubyte1_e32 v137, v148
	v_cvt_f32_ubyte3_e32 v146, v148
	v_rcp_iflag_f32_e32 v137, v137
	v_rcp_iflag_f32_e32 v153, v146
	v_pk_mul_f32 v[134:135], v[134:135], v[192:193]
	v_pk_mul_f32 v[150:151], v[150:151], v[172:173]
	v_pk_mul_f32 v[14:15], v[14:15], v[134:135]
	v_pk_mul_f32 v[16:17], v[16:17], v[150:151]
	v_cvt_f32_ubyte3_e32 v135, v128
	v_cvt_f32_ubyte2_e32 v134, v128
	v_cvt_f32_ubyte1_e32 v151, v128
	v_cvt_f32_ubyte0_e32 v150, v128
	v_cvt_f32_ubyte0_e32 v126, v147
	v_pk_mul_f32 v[136:137], v[136:137], v[150:151]
	v_pk_mul_f32 v[134:135], v[152:153], v[134:135]
	v_rcp_iflag_f32_e32 v150, v126
	v_cvt_f32_ubyte0_e32 v126, v149
	v_pk_mul_f32 v[12:13], v[12:13], v[134:135]
	v_rcp_iflag_f32_e32 v134, v126
	v_cvt_f32_ubyte1_e32 v126, v147
	v_rcp_iflag_f32_e32 v151, v126
	v_cvt_f32_ubyte1_e32 v126, v149
	v_rcp_iflag_f32_e32 v135, v126
	v_cvt_f32_ubyte2_e32 v126, v147
	v_rcp_iflag_f32_e32 v146, v126
	v_cvt_f32_ubyte2_e32 v126, v149
	v_pk_mul_f32 v[10:11], v[10:11], v[136:137]
	v_rcp_iflag_f32_e32 v136, v126
	v_cvt_f32_ubyte3_e32 v126, v147
	v_rcp_iflag_f32_e32 v147, v126
	v_cvt_f32_ubyte3_e32 v126, v149
	v_rcp_iflag_f32_e32 v137, v126
	v_cvt_f32_ubyte3_e32 v149, v127
	v_cvt_f32_ubyte2_e32 v148, v127
	v_cvt_f32_ubyte1_e32 v153, v127
	v_cvt_f32_ubyte0_e32 v152, v127
	v_pk_mul_f32 v[126:127], v[150:151], v[152:153]
	v_pk_mul_f32 v[146:147], v[146:147], v[148:149]
	v_pk_mul_f32 v[6:7], v[6:7], v[126:127]
	v_pk_mul_f32 v[8:9], v[8:9], v[146:147]
	v_cvt_f32_ubyte3_e32 v127, v129
	v_cvt_f32_ubyte2_e32 v126, v129
	v_cvt_f32_ubyte1_e32 v147, v129
	v_cvt_f32_ubyte0_e32 v146, v129
	v_pk_mul_f32 v[128:129], v[134:135], v[146:147]
	v_pk_mul_f32 v[126:127], v[136:137], v[126:127]
	v_pk_mul_f32 v[2:3], v[2:3], v[128:129]
	v_pk_mul_f32 v[4:5], v[4:5], v[126:127]
	s_mov_b32 s23, 14
	s_mov_b64 s[20:21], 0
	s_mov_b64 s[36:37], 0x20080
	s_mov_b64 s[42:43], 0x20100
	s_mov_b64 s[44:45], 0x20180
; #define STAGE(P, BASE, br, kt) do { const bf16_t* g_ = (BASE) + (size_t)(br) * K + (size_t)(kt) * 64; \
;         _Pragma("unroll") for (int i_ = 0; i_ < 2; ++i_) \
;             __builtin_amdgcn_global_load_lds((const unsigned*)(g_ + gofs[i_]), (lds_ptr_t)((P) + wb + i_ * 8192), 16, 0, 0); } while (0)
; #define LDA(dst, b, hh) _Pragma("unroll") for (int m = 0; m < 4; ++m) _Pragma("unroll") for (int k = 0; k < 2; ++k) \
;         dst[m][k] = *(const bf16x8*)(SA(b, hh) + lds_byte(wr * 64 + m * 16 + fr, k * 32 + fq * 8))
; #define LDB(dst, b, hh) _Pragma("unroll") for (int n = 0; n < 2; ++n) _Pragma("unroll") for (int k = 0; k < 2; ++k) \
;         dst[n][k] = *(const bf16x8*)(SB(b, hh) + lds_byte(wc * 32 + n * 16 + fr, k * 32 + fq * 8))
; #define MMA(ai, bj, At_, Bt_) do { __builtin_amdgcn_s_setprio(1); \
;         _Pragma("unroll") for (int m = 0; m < 4; ++m) _Pragma("unroll") for (int n = 0; n < 2; ++n) _Pragma("unroll") for (int k = 0; k < 2; ++k) \
;             acc[ai][bj][m][n] = MFMA16(At_[m][k], Bt_[n][k], acc[ai][bj][m][n]); \
;         __builtin_amdgcn_s_setprio(0); } while (0)
; #define WAIT_V(n) asm volatile("s_waitcnt vmcnt(" #n ")" ::: "memory")
; #define WAIT_L(n) asm volatile("s_waitcnt lgkmcnt(" #n ")" ::: "memory")
; #define BAR __builtin_amdgcn_s_barrier()
; #define SCHED __builtin_amdgcn_sched_barrier(0)
; #define LDA(dst, b, hh) _Pragma("unroll") for (int m = 0; m < 4; ++m) _Pragma("unroll") for (int k = 0; k < 2; ++k) \
;         dst[m][k] = *(const bf16x8*)(SA(b, hh) + lds_byte(wr * 64 + m * 16 + fr, k * 32 + fq * 8))
; #define WAIT_V(n) asm volatile("s_waitcnt vmcnt(" #n ")" ::: "memory")
; #define BAR __builtin_amdgcn_s_barrier()
; template <class Hook>
; DI void gemm8_cat3(f32x4 (&acc)[2][2][4][2], const bf16_t* R0, const bf16_t* R1, const bf16_t* R2, const bf16_t* C0, const bf16_t* C1, const bf16_t* C2, char* shm, Hook hook) {
;     ...
;     for (int tt = 16; tt < nt - 2; tt += 2) {
;         LDB(B0, 0, 0); SCHED; LDA(At, 0, 0); STAGE(SA(1, 1), R, 128, tt + 1);
;         WAIT_L(8); BAR; WAIT_L(0); MMA(0, 0, At, B0); BAR; SCHED;
;         LDB(B1, 0, 1); STAGE(SB(0, 0), C, 0, tt + 2);
;         BAR; WAIT_L(0); MMA(0, 1, At, B1); BAR;
;         LDA(At, 0, 1); STAGE(SA(0, 0), R, 0, tt + 2);
;         BAR; WAIT_L(0); MMA(1, 0, At, B0); BAR; SCHED;
;         STAGE(SB(0, 1), C, 128, tt + 2);
;         WAIT_V(6); BAR; MMA(1, 1, At, B1); BAR;
.LBB0_60:
	s_add_i32 s22, s23, 2
	s_and_b32 s35, s22, 24
	s_cmp_eq_u32 s35, 8
	s_cselect_b32 s97, s24, s2
	s_cselect_b32 s96, s15, s26
	v_lshl_add_u64 v[172:173], s[96:97], 0, v[142:143]
	v_lshl_add_u64 v[172:173], v[172:173], 0, s[20:21]
	v_readfirstlane_b32 s35, v190
	v_lshl_add_u64 v[172:173], v[172:173], 0, s[36:37]
	s_mov_b32 m0, s35
	s_nop 0
	global_load_lds_dwordx4 v[172:173], off
	v_lshl_add_u64 v[172:173], s[96:97], 0, v[144:145]
	v_lshl_add_u64 v[172:173], v[172:173], 0, s[20:21]
	v_readfirstlane_b32 s35, v191
	v_lshl_add_u64 v[172:173], v[172:173], 0, s[36:37]
	s_mov_b32 m0, s35
	s_nop 0
	global_load_lds_dwordx4 v[172:173], off
	ds_read_b128 v[126:129], v189
	ds_read_b128 v[134:137], v189 offset:1024
	ds_read_b128 v[146:149], v189 offset:2048
	ds_read_b128 v[150:153], v189 offset:3072
	ds_read_b128 v[192:195], v157
	ds_read_b128 v[196:199], v157 offset:1024
	ds_read_b128 v[200:203], v156
	ds_read_b128 v[204:207], v156 offset:1024
	ds_read_b128 v[208:211], v155
	ds_read_b128 v[212:215], v155 offset:1024
	ds_read_b128 v[216:219], v154
	ds_read_b128 v[220:223], v154 offset:1024
	s_waitcnt lgkmcnt(8)
	s_barrier
	s_waitcnt lgkmcnt(0)
	s_setprio 1
	s_waitcnt lgkmcnt(0)
	v_mfma_f32_16x16x32_bf16 v[130:133], v[192:195], v[126:129], v[130:133]
	v_mfma_f32_16x16x32_bf16 v[42:45], v[192:195], v[146:149], v[42:45]
	v_mfma_f32_16x16x32_bf16 v[30:33], v[200:203], v[126:129], v[30:33]
	v_mfma_f32_16x16x32_bf16 v[54:57], v[200:203], v[146:149], v[54:57]
	v_mfma_f32_16x16x32_bf16 v[18:21], v[208:211], v[126:129], v[18:21]
	v_mfma_f32_16x16x32_bf16 v[50:53], v[208:211], v[146:149], v[50:53]
	v_mfma_f32_16x16x32_bf16 v[26:29], v[216:219], v[126:129], v[26:29]
	v_mfma_f32_16x16x32_bf16 v[46:49], v[216:219], v[146:149], v[46:49]
	v_mfma_f32_16x16x32_bf16 v[130:133], v[196:199], v[134:137], v[130:133]
	v_mfma_f32_16x16x32_bf16 v[42:45], v[196:199], v[150:153], v[42:45]
	v_mfma_f32_16x16x32_bf16 v[30:33], v[204:207], v[134:137], v[30:33]
	v_mfma_f32_16x16x32_bf16 v[54:57], v[204:207], v[150:153], v[54:57]
	v_mfma_f32_16x16x32_bf16 v[18:21], v[212:215], v[134:137], v[18:21]
	v_mfma_f32_16x16x32_bf16 v[50:53], v[212:215], v[150:153], v[50:53]
	v_mfma_f32_16x16x32_bf16 v[26:29], v[220:223], v[134:137], v[26:29]
	v_mfma_f32_16x16x32_bf16 v[46:49], v[220:223], v[150:153], v[46:49]
	s_setprio 0
	s_barrier
	s_add_i32 s35, s23, 4
	s_and_b32 s35, s35, 56
	s_cmp_eq_u32 s35, 8
	s_cselect_b32 s97, s82, s34
	s_cselect_b32 s96, s25, s3
	v_lshl_add_u64 v[172:173], s[96:97], 0, v[142:143]
	v_lshl_add_u64 v[172:173], v[172:173], 0, s[20:21]
	v_readfirstlane_b32 s35, v159
	v_lshl_add_u64 v[240:241], v[172:173], 0, s[90:91]
	s_mov_b32 m0, s35
	s_nop 0
	global_load_lds_dwordx4 v[240:241], off
	v_lshl_add_u64 v[240:241], s[96:97], 0, v[144:145]
	v_lshl_add_u64 v[240:241], v[240:241], 0, s[20:21]
	v_readfirstlane_b32 s35, v160
	v_lshl_add_u64 v[242:243], v[240:241], 0, s[90:91]
	s_mov_b32 m0, s35
	s_nop 0
	global_load_lds_dwordx4 v[242:243], off
	ds_read_b128 v[224:227], v188
	ds_read_b128 v[228:231], v188 offset:1024
	ds_read_b128 v[232:235], v188 offset:2048
	ds_read_b128 v[236:239], v188 offset:3072
	s_barrier
	s_waitcnt lgkmcnt(0)
	s_setprio 1
	s_waitcnt lgkmcnt(0)
	v_mfma_f32_16x16x32_bf16 v[58:61], v[192:195], v[224:227], v[58:61]
	v_mfma_f32_16x16x32_bf16 v[74:77], v[192:195], v[232:235], v[74:77]
	v_mfma_f32_16x16x32_bf16 v[70:73], v[200:203], v[224:227], v[70:73]
	v_mfma_f32_16x16x32_bf16 v[86:89], v[200:203], v[232:235], v[86:89]
	v_mfma_f32_16x16x32_bf16 v[66:69], v[208:211], v[224:227], v[66:69]
	v_mfma_f32_16x16x32_bf16 v[82:85], v[208:211], v[232:235], v[82:85]
	v_mfma_f32_16x16x32_bf16 v[62:65], v[216:219], v[224:227], v[62:65]
	v_mfma_f32_16x16x32_bf16 v[78:81], v[216:219], v[232:235], v[78:81]
	v_mfma_f32_16x16x32_bf16 v[58:61], v[196:199], v[228:231], v[58:61]
	v_mfma_f32_16x16x32_bf16 v[74:77], v[196:199], v[236:239], v[74:77]
	v_mfma_f32_16x16x32_bf16 v[70:73], v[204:207], v[228:231], v[70:73]
	v_mfma_f32_16x16x32_bf16 v[86:89], v[204:207], v[236:239], v[86:89]
	v_mfma_f32_16x16x32_bf16 v[66:69], v[212:215], v[228:231], v[66:69]
	v_mfma_f32_16x16x32_bf16 v[82:85], v[212:215], v[236:239], v[82:85]
	v_mfma_f32_16x16x32_bf16 v[62:65], v[220:223], v[228:231], v[62:65]
	v_mfma_f32_16x16x32_bf16 v[78:81], v[220:223], v[236:239], v[78:81]
	s_setprio 0
	s_cselect_b32 s97, s24, s2
	s_cselect_b32 s96, s15, s26
	v_lshl_add_u64 v[242:243], s[96:97], 0, v[142:143]
	v_lshl_add_u64 v[242:243], v[242:243], 0, s[20:21]
	v_readfirstlane_b32 s35, v158
	v_lshl_add_u64 v[244:245], v[242:243], 0, s[90:91]
	s_mov_b32 m0, s35
	s_barrier
	global_load_lds_dwordx4 v[244:245], off
	v_lshl_add_u64 v[244:245], s[96:97], 0, v[144:145]
	v_lshl_add_u64 v[244:245], v[244:245], 0, s[20:21]
	v_readfirstlane_b32 s35, v164
	v_lshl_add_u64 v[246:247], v[244:245], 0, s[90:91]
	s_mov_b32 m0, s35
	s_nop 0
	global_load_lds_dwordx4 v[246:247], off
	ds_read_b128 v[192:195], v157 offset:16384
	ds_read_b128 v[196:199], v157 offset:17408
	ds_read_b128 v[200:203], v156 offset:16384
	ds_read_b128 v[204:207], v156 offset:17408
	ds_read_b128 v[208:211], v155 offset:16384
	ds_read_b128 v[212:215], v155 offset:17408
	ds_read_b128 v[216:219], v154 offset:16384
	ds_read_b128 v[220:223], v154 offset:17408
	s_barrier
; #define STAGE(P, BASE, br, kt) do { const bf16_t* g_ = (BASE) + (size_t)(br) * K + (size_t)(kt) * 64; \
;         _Pragma("unroll") for (int i_ = 0; i_ < 2; ++i_) \
;             __builtin_amdgcn_global_load_lds((const unsigned*)(g_ + gofs[i_]), (lds_ptr_t)((P) + wb + i_ * 8192), 16, 0, 0); } while (0)
; #define LDA(dst, b, hh) _Pragma("unroll") for (int m = 0; m < 4; ++m) _Pragma("unroll") for (int k = 0; k < 2; ++k) \
;         dst[m][k] = *(const bf16x8*)(SA(b, hh) + lds_byte(wr * 64 + m * 16 + fr, k * 32 + fq * 8))
; #define LDB(dst, b, hh) _Pragma("unroll") for (int n = 0; n < 2; ++n) _Pragma("unroll") for (int k = 0; k < 2; ++k) \
;         dst[n][k] = *(const bf16x8*)(SB(b, hh) + lds_byte(wc * 32 + n * 16 + fr, k * 32 + fq * 8))
; #define MMA(ai, bj, At_, Bt_) do { __builtin_amdgcn_s_setprio(1); \
;         _Pragma("unroll") for (int m = 0; m < 4; ++m) _Pragma("unroll") for (int n = 0; n < 2; ++n) _Pragma("unroll") for (int k = 0; k < 2; ++k) \
;             acc[ai][bj][m][n] = MFMA16(At_[m][k], Bt_[n][k], acc[ai][bj][m][n]); \
;         __builtin_amdgcn_s_setprio(0); } while (0)
; #define WAIT_V(n) asm volatile("s_waitcnt vmcnt(" #n ")" ::: "memory")
; #define WAIT_L(n) asm volatile("s_waitcnt lgkmcnt(" #n ")" ::: "memory")
; #define BAR __builtin_amdgcn_s_barrier()
; #define SCHED __builtin_amdgcn_sched_barrier(0)
; #define STAGE(P, BASE, br, kt) do { const int sg_ = (kt) >> 3; const bf16_t* g_ = (sg_ == 0 ? BASE##0 : sg_ == 1 ? BASE##1 : BASE##2) + (size_t)(br) * K + (size_t)((kt) & 7) * 64; \
;         _Pragma("unroll") for (int i_ = 0; i_ < 2; ++i_) \
;             __builtin_amdgcn_global_load_lds((const unsigned*)(g_ + gofs[i_]), (lds_ptr_t)((P) + wb + i_ * 8192), 16, 0, 0); } while (0)
; template <class Hook>
; DI void gemm8_cat3(f32x4 (&acc)[2][2][4][2], const bf16_t* R0, const bf16_t* R1, const bf16_t* R2, const bf16_t* C0, const bf16_t* C1, const bf16_t* C2, char* shm, Hook hook) {
;     ...
;         BAR; WAIT_L(0); MMA(1, 0, At, B0); BAR; SCHED;
;         STAGE(SB(0, 1), C, 128, tt + 2);
;         WAIT_V(6); BAR; MMA(1, 1, At, B1); BAR;
;         LDB(B0, 1, 0); SCHED; LDA(At, 1, 0); STAGE(SA(0, 1), R, 128, tt + 2);
;         WAIT_L(8); BAR; WAIT_L(0); MMA(0, 0, At, B0); BAR; SCHED;
;         LDB(B1, 1, 1); STAGE(SB(1, 0), C, 0, tt + 3);
;         BAR; WAIT_L(0); MMA(0, 1, At, B1); BAR;
;         LDA(At, 1, 1); STAGE(SA(1, 0), R, 0, tt + 3);
	s_waitcnt lgkmcnt(0)
	s_setprio 1
	s_waitcnt lgkmcnt(0)
	v_mfma_f32_16x16x32_bf16 v[90:93], v[192:195], v[126:129], v[90:93]
	v_mfma_f32_16x16x32_bf16 v[106:109], v[192:195], v[146:149], v[106:109]
	v_mfma_f32_16x16x32_bf16 v[102:105], v[200:203], v[126:129], v[102:105]
	v_mfma_f32_16x16x32_bf16 v[118:121], v[200:203], v[146:149], v[118:121]
	v_mfma_f32_16x16x32_bf16 v[98:101], v[208:211], v[126:129], v[98:101]
	v_mfma_f32_16x16x32_bf16 v[114:117], v[208:211], v[146:149], v[114:117]
	v_mfma_f32_16x16x32_bf16 v[94:97], v[216:219], v[126:129], v[94:97]
	v_mfma_f32_16x16x32_bf16 v[110:113], v[216:219], v[146:149], v[110:113]
	v_mfma_f32_16x16x32_bf16 v[90:93], v[196:199], v[134:137], v[90:93]
	v_mfma_f32_16x16x32_bf16 v[106:109], v[196:199], v[150:153], v[106:109]
	v_mfma_f32_16x16x32_bf16 v[102:105], v[204:207], v[134:137], v[102:105]
	v_mfma_f32_16x16x32_bf16 v[118:121], v[204:207], v[150:153], v[118:121]
	v_mfma_f32_16x16x32_bf16 v[98:101], v[212:215], v[134:137], v[98:101]
	v_mfma_f32_16x16x32_bf16 v[114:117], v[212:215], v[150:153], v[114:117]
	v_mfma_f32_16x16x32_bf16 v[94:97], v[220:223], v[134:137], v[94:97]
	v_mfma_f32_16x16x32_bf16 v[110:113], v[220:223], v[150:153], v[110:113]
	s_setprio 0
	s_barrier
	v_readfirstlane_b32 s35, v165
	v_lshl_add_u64 v[126:127], v[172:173], 0, s[42:43]
	s_mov_b32 m0, s35
	v_readfirstlane_b32 s35, v166
	global_load_lds_dwordx4 v[126:127], off
	v_lshl_add_u64 v[126:127], v[240:241], 0, s[42:43]
	s_mov_b32 m0, s35
	s_nop 0
	global_load_lds_dwordx4 v[126:127], off
	s_waitcnt vmcnt(6)
	s_barrier
	s_setprio 1
	v_mfma_f32_16x16x32_bf16 v[122:125], v[192:195], v[224:227], v[122:125]
	v_mfma_f32_16x16x32_bf16 v[14:17], v[192:195], v[232:235], v[14:17]
	v_mfma_f32_16x16x32_bf16 v[34:37], v[200:203], v[224:227], v[34:37]
	v_mfma_f32_16x16x32_bf16 v[6:9], v[200:203], v[232:235], v[6:9]
	v_mfma_f32_16x16x32_bf16 v[38:41], v[208:211], v[224:227], v[38:41]
	v_mfma_f32_16x16x32_bf16 v[10:13], v[208:211], v[232:235], v[10:13]
	v_mfma_f32_16x16x32_bf16 v[22:25], v[216:219], v[224:227], v[22:25]
	v_mfma_f32_16x16x32_bf16 v[2:5], v[216:219], v[232:235], v[2:5]
	v_mfma_f32_16x16x32_bf16 v[122:125], v[196:199], v[228:231], v[122:125]
	v_mfma_f32_16x16x32_bf16 v[14:17], v[196:199], v[236:239], v[14:17]
	v_mfma_f32_16x16x32_bf16 v[34:37], v[204:207], v[228:231], v[34:37]
	v_mfma_f32_16x16x32_bf16 v[6:9], v[204:207], v[236:239], v[6:9]
	v_mfma_f32_16x16x32_bf16 v[38:41], v[212:215], v[228:231], v[38:41]
	v_mfma_f32_16x16x32_bf16 v[10:13], v[212:215], v[236:239], v[10:13]
	v_mfma_f32_16x16x32_bf16 v[22:25], v[220:223], v[228:231], v[22:25]
	v_mfma_f32_16x16x32_bf16 v[2:5], v[220:223], v[236:239], v[2:5]
	s_setprio 0
	s_barrier
	v_readfirstlane_b32 s35, v167
	v_lshl_add_u64 v[172:173], v[242:243], 0, s[42:43]
	s_mov_b32 m0, s35
	v_readfirstlane_b32 s35, v168
	global_load_lds_dwordx4 v[172:173], off
	v_lshl_add_u64 v[172:173], v[244:245], 0, s[42:43]
	s_mov_b32 m0, s35
	s_nop 0
	global_load_lds_dwordx4 v[172:173], off
	ds_read_b128 v[126:129], v169
	ds_read_b128 v[134:137], v169 offset:1024
	ds_read_b128 v[146:149], v169 offset:2048
	ds_read_b128 v[150:153], v169 offset:3072
	ds_read_b128 v[192:195], v157 offset:32768
	ds_read_b128 v[196:199], v157 offset:33792
	ds_read_b128 v[200:203], v156 offset:32768
	ds_read_b128 v[204:207], v156 offset:33792
	ds_read_b128 v[208:211], v155 offset:32768
	ds_read_b128 v[212:215], v155 offset:33792
	ds_read_b128 v[216:219], v154 offset:32768
	ds_read_b128 v[220:223], v154 offset:33792
	s_waitcnt lgkmcnt(8)
	s_barrier
	s_waitcnt lgkmcnt(0)
	s_setprio 1
	s_waitcnt lgkmcnt(0)
	v_mfma_f32_16x16x32_bf16 v[130:133], v[192:195], v[126:129], v[130:133]
	v_mfma_f32_16x16x32_bf16 v[42:45], v[192:195], v[146:149], v[42:45]
	v_mfma_f32_16x16x32_bf16 v[30:33], v[200:203], v[126:129], v[30:33]
	v_mfma_f32_16x16x32_bf16 v[54:57], v[200:203], v[146:149], v[54:57]
	v_mfma_f32_16x16x32_bf16 v[18:21], v[208:211], v[126:129], v[18:21]
	v_mfma_f32_16x16x32_bf16 v[50:53], v[208:211], v[146:149], v[50:53]
	v_mfma_f32_16x16x32_bf16 v[26:29], v[216:219], v[126:129], v[26:29]
	v_mfma_f32_16x16x32_bf16 v[46:49], v[216:219], v[146:149], v[46:49]
	v_mfma_f32_16x16x32_bf16 v[130:133], v[196:199], v[134:137], v[130:133]
	v_mfma_f32_16x16x32_bf16 v[42:45], v[196:199], v[150:153], v[42:45]
	v_mfma_f32_16x16x32_bf16 v[30:33], v[204:207], v[134:137], v[30:33]
	v_mfma_f32_16x16x32_bf16 v[54:57], v[204:207], v[150:153], v[54:57]
	v_mfma_f32_16x16x32_bf16 v[18:21], v[212:215], v[134:137], v[18:21]
	v_mfma_f32_16x16x32_bf16 v[50:53], v[212:215], v[150:153], v[50:53]
	v_mfma_f32_16x16x32_bf16 v[26:29], v[220:223], v[134:137], v[26:29]
	v_mfma_f32_16x16x32_bf16 v[46:49], v[220:223], v[150:153], v[46:49]
	s_setprio 0
	s_barrier
	s_add_i32 s23, s23, 5
	s_and_b32 s23, s23, 56
	s_cmp_eq_u32 s23, 8
	s_cselect_b32 s97, s82, s34
	s_cselect_b32 s96, s25, s3
	v_lshl_add_u64 v[172:173], s[96:97], 0, v[142:143]
	v_lshl_add_u64 v[172:173], v[172:173], 0, s[20:21]
	v_readfirstlane_b32 s23, v170
	v_lshl_add_u64 v[240:241], v[172:173], 0, s[72:73]
	s_mov_b32 m0, s23
	s_nop 0
	global_load_lds_dwordx4 v[240:241], off
	v_lshl_add_u64 v[240:241], s[96:97], 0, v[144:145]
	v_lshl_add_u64 v[240:241], v[240:241], 0, s[20:21]
	v_readfirstlane_b32 s23, v171
	v_lshl_add_u64 v[242:243], v[240:241], 0, s[72:73]
	s_mov_b32 m0, s23
	s_nop 0
	global_load_lds_dwordx4 v[242:243], off
	ds_read_b128 v[224:227], v161
	ds_read_b128 v[228:231], v161 offset:1024
	ds_read_b128 v[232:235], v161 offset:2048
	ds_read_b128 v[236:239], v161 offset:3072
	s_barrier
; #define STAGE(P, BASE, br, kt) do { const bf16_t* g_ = (BASE) + (size_t)(br) * K + (size_t)(kt) * 64; \
;         _Pragma("unroll") for (int i_ = 0; i_ < 2; ++i_) \
;             __builtin_amdgcn_global_load_lds((const unsigned*)(g_ + gofs[i_]), (lds_ptr_t)((P) + wb + i_ * 8192), 16, 0, 0); } while (0)
; #define LDA(dst, b, hh) _Pragma("unroll") for (int m = 0; m < 4; ++m) _Pragma("unroll") for (int k = 0; k < 2; ++k) \
;         dst[m][k] = *(const bf16x8*)(SA(b, hh) + lds_byte(wr * 64 + m * 16 + fr, k * 32 + fq * 8))
; #define LDB(dst, b, hh) _Pragma("unroll") for (int n = 0; n < 2; ++n) _Pragma("unroll") for (int k = 0; k < 2; ++k) \
;         dst[n][k] = *(const bf16x8*)(SB(b, hh) + lds_byte(wc * 32 + n * 16 + fr, k * 32 + fq * 8))
; #define MMA(ai, bj, At_, Bt_) do { __builtin_amdgcn_s_setprio(1); \
;         _Pragma("unroll") for (int m = 0; m < 4; ++m) _Pragma("unroll") for (int n = 0; n < 2; ++n) _Pragma("unroll") for (int k = 0; k < 2; ++k) \
;             acc[ai][bj][m][n] = MFMA16(At_[m][k], Bt_[n][k], acc[ai][bj][m][n]); \
;         __builtin_amdgcn_s_setprio(0); } while (0)
; #define WAIT_V(n) asm volatile("s_waitcnt vmcnt(" #n ")" ::: "memory")
; #define WAIT_L(n) asm volatile("s_waitcnt lgkmcnt(" #n ")" ::: "memory")
; #define BAR __builtin_amdgcn_s_barrier()
; #define SCHED __builtin_amdgcn_sched_barrier(0)
; #define LDA(dst, b, hh) _Pragma("unroll") for (int m = 0; m < 4; ++m) _Pragma("unroll") for (int k = 0; k < 2; ++k) \
;         dst[m][k] = *(const bf16x8*)(SA(b, hh) + lds_byte(wr * 64 + m * 16 + fr, k * 32 + fq * 8))
; #define WAIT_V(n) asm volatile("s_waitcnt vmcnt(" #n ")" ::: "memory")
; template <class Hook>
; DI void gemm8_cat3(f32x4 (&acc)[2][2][4][2], const bf16_t* R0, const bf16_t* R1, const bf16_t* R2, const bf16_t* C0, const bf16_t* C1, const bf16_t* C2, char* shm, Hook hook) {
;     ...
;         LDB(B0, 1, 0); SCHED; LDA(At, 1, 0); STAGE(SA(0, 1), R, 128, tt + 2);
;         WAIT_L(8); BAR; WAIT_L(0); MMA(0, 0, At, B0); BAR; SCHED;
;         LDB(B1, 1, 1); STAGE(SB(1, 0), C, 0, tt + 3);
;         BAR; WAIT_L(0); MMA(0, 1, At, B1); BAR;
;         LDA(At, 1, 1); STAGE(SA(1, 0), R, 0, tt + 3);
;         BAR; WAIT_L(0); MMA(1, 0, At, B0); BAR; SCHED;
;         STAGE(SB(1, 1), C, 128, tt + 3);
;         WAIT_V(6); BAR; MMA(1, 1, At, B1); BAR;
;     }
;     { LDB(B0, 0, 0); LDA(At, 0, 0); STAGE(SA(1, 1), R, 128, nt - 1);
	s_waitcnt lgkmcnt(0)
	s_setprio 1
	s_waitcnt lgkmcnt(0)
	v_mfma_f32_16x16x32_bf16 v[58:61], v[192:195], v[224:227], v[58:61]
	v_mfma_f32_16x16x32_bf16 v[74:77], v[192:195], v[232:235], v[74:77]
	v_mfma_f32_16x16x32_bf16 v[70:73], v[200:203], v[224:227], v[70:73]
	v_mfma_f32_16x16x32_bf16 v[86:89], v[200:203], v[232:235], v[86:89]
	v_mfma_f32_16x16x32_bf16 v[66:69], v[208:211], v[224:227], v[66:69]
	v_mfma_f32_16x16x32_bf16 v[82:85], v[208:211], v[232:235], v[82:85]
	v_mfma_f32_16x16x32_bf16 v[62:65], v[216:219], v[224:227], v[62:65]
	v_mfma_f32_16x16x32_bf16 v[78:81], v[216:219], v[232:235], v[78:81]
	v_mfma_f32_16x16x32_bf16 v[58:61], v[196:199], v[228:231], v[58:61]
	v_mfma_f32_16x16x32_bf16 v[74:77], v[196:199], v[236:239], v[74:77]
	v_mfma_f32_16x16x32_bf16 v[70:73], v[204:207], v[228:231], v[70:73]
	v_mfma_f32_16x16x32_bf16 v[86:89], v[204:207], v[236:239], v[86:89]
	v_mfma_f32_16x16x32_bf16 v[66:69], v[212:215], v[228:231], v[66:69]
	v_mfma_f32_16x16x32_bf16 v[82:85], v[212:215], v[236:239], v[82:85]
	v_mfma_f32_16x16x32_bf16 v[62:65], v[220:223], v[228:231], v[62:65]
	v_mfma_f32_16x16x32_bf16 v[78:81], v[220:223], v[236:239], v[78:81]
	s_setprio 0
	s_cselect_b32 s97, s24, s2
	s_cselect_b32 s96, s15, s26
	v_lshl_add_u64 v[242:243], s[96:97], 0, v[142:143]
	v_lshl_add_u64 v[242:243], v[242:243], 0, s[20:21]
	v_readfirstlane_b32 s23, v184
	v_lshl_add_u64 v[242:243], v[242:243], 0, s[72:73]
	s_mov_b32 m0, s23
	s_barrier
	global_load_lds_dwordx4 v[242:243], off
	v_lshl_add_u64 v[242:243], s[96:97], 0, v[144:145]
	v_lshl_add_u64 v[242:243], v[242:243], 0, s[20:21]
	v_readfirstlane_b32 s23, v185
	v_lshl_add_u64 v[242:243], v[242:243], 0, s[72:73]
	s_mov_b32 m0, s23
	s_nop 0
	global_load_lds_dwordx4 v[242:243], off
	ds_read_b128 v[192:195], v157 offset:49152
	ds_read_b128 v[196:199], v157 offset:50176
	ds_read_b128 v[200:203], v156 offset:49152
	ds_read_b128 v[204:207], v156 offset:50176
	ds_read_b128 v[208:211], v155 offset:49152
	ds_read_b128 v[212:215], v155 offset:50176
	ds_read_b128 v[216:219], v154 offset:49152
	ds_read_b128 v[220:223], v154 offset:50176
	s_barrier
	s_waitcnt lgkmcnt(0)
	s_setprio 1
	s_waitcnt lgkmcnt(0)
	v_mfma_f32_16x16x32_bf16 v[90:93], v[192:195], v[126:129], v[90:93]
	v_mfma_f32_16x16x32_bf16 v[106:109], v[192:195], v[146:149], v[106:109]
	v_mfma_f32_16x16x32_bf16 v[102:105], v[200:203], v[126:129], v[102:105]
	v_mfma_f32_16x16x32_bf16 v[118:121], v[200:203], v[146:149], v[118:121]
	v_mfma_f32_16x16x32_bf16 v[98:101], v[208:211], v[126:129], v[98:101]
	v_mfma_f32_16x16x32_bf16 v[114:117], v[208:211], v[146:149], v[114:117]
	v_mfma_f32_16x16x32_bf16 v[94:97], v[216:219], v[126:129], v[94:97]
	v_mfma_f32_16x16x32_bf16 v[110:113], v[216:219], v[146:149], v[110:113]
	v_mfma_f32_16x16x32_bf16 v[90:93], v[196:199], v[134:137], v[90:93]
	v_mfma_f32_16x16x32_bf16 v[106:109], v[196:199], v[150:153], v[106:109]
	v_mfma_f32_16x16x32_bf16 v[102:105], v[204:207], v[134:137], v[102:105]
	v_mfma_f32_16x16x32_bf16 v[118:121], v[204:207], v[150:153], v[118:121]
	v_mfma_f32_16x16x32_bf16 v[98:101], v[212:215], v[134:137], v[98:101]
	v_mfma_f32_16x16x32_bf16 v[114:117], v[212:215], v[150:153], v[114:117]
	v_mfma_f32_16x16x32_bf16 v[94:97], v[220:223], v[134:137], v[94:97]
	v_mfma_f32_16x16x32_bf16 v[110:113], v[220:223], v[150:153], v[110:113]
	s_setprio 0
	s_barrier
	v_readfirstlane_b32 s23, v186
	v_lshl_add_u64 v[126:127], v[172:173], 0, s[44:45]
	s_mov_b32 m0, s23
	v_readfirstlane_b32 s23, v187
	global_load_lds_dwordx4 v[126:127], off
	v_lshl_add_u64 v[126:127], v[240:241], 0, s[44:45]
	s_mov_b32 m0, s23
	s_nop 0
	global_load_lds_dwordx4 v[126:127], off
	s_waitcnt vmcnt(6)
	s_barrier
	s_setprio 1
	v_mfma_f32_16x16x32_bf16 v[122:125], v[192:195], v[224:227], v[122:125]
	v_mfma_f32_16x16x32_bf16 v[14:17], v[192:195], v[232:235], v[14:17]
	v_mfma_f32_16x16x32_bf16 v[34:37], v[200:203], v[224:227], v[34:37]
	v_mfma_f32_16x16x32_bf16 v[6:9], v[200:203], v[232:235], v[6:9]
	v_mfma_f32_16x16x32_bf16 v[38:41], v[208:211], v[224:227], v[38:41]
	v_mfma_f32_16x16x32_bf16 v[10:13], v[208:211], v[232:235], v[10:13]
	v_mfma_f32_16x16x32_bf16 v[22:25], v[216:219], v[224:227], v[22:25]
	v_mfma_f32_16x16x32_bf16 v[2:5], v[216:219], v[232:235], v[2:5]
	v_mfma_f32_16x16x32_bf16 v[122:125], v[196:199], v[228:231], v[122:125]
	v_mfma_f32_16x16x32_bf16 v[14:17], v[196:199], v[236:239], v[14:17]
	v_mfma_f32_16x16x32_bf16 v[34:37], v[204:207], v[228:231], v[34:37]
	v_mfma_f32_16x16x32_bf16 v[6:9], v[204:207], v[236:239], v[6:9]
	v_mfma_f32_16x16x32_bf16 v[38:41], v[212:215], v[228:231], v[38:41]
	v_mfma_f32_16x16x32_bf16 v[10:13], v[212:215], v[236:239], v[10:13]
	v_mfma_f32_16x16x32_bf16 v[22:25], v[220:223], v[228:231], v[22:25]
	v_mfma_f32_16x16x32_bf16 v[2:5], v[220:223], v[236:239], v[2:5]
	s_setprio 0
	s_add_u32 s20, s20, 0x100
	s_addc_u32 s21, s21, 0
	s_cmp_lt_u32 s22, 20
	s_mov_b32 s23, s22
	s_barrier
	s_cbranch_scc1 .LBB0_60
	s_add_u32 s20, s26, 0x20380
	s_addc_u32 s21, s2, 0
	v_readfirstlane_b32 s2, v190
	v_lshl_add_u64 v[138:139], v[138:139], 1, s[20:21]
	s_mov_b32 m0, s2
	v_readfirstlane_b32 s2, v191
	ds_read_b128 v[126:129], v189
	ds_read_b128 v[134:137], v189 offset:1024
	ds_read_b128 v[142:145], v189 offset:2048
	ds_read_b128 v[146:149], v189 offset:3072
	ds_read_b128 v[150:153], v157
	ds_read_b128 v[164:167], v157 offset:1024
	ds_read_b128 v[184:187], v156
	ds_read_b128 v[192:195], v156 offset:1024
	ds_read_b128 v[196:199], v155
	ds_read_b128 v[200:203], v155 offset:1024
	ds_read_b128 v[204:207], v154
	ds_read_b128 v[208:211], v154 offset:1024
	global_load_lds_dwordx4 v[138:139], off
	v_lshl_add_u64 v[138:139], v[140:141], 1, s[20:21]
	s_mov_b32 m0, s2
	s_nop 0
	global_load_lds_dwordx4 v[138:139], off
	s_barrier
; #define STAGE(P, BASE, br, kt) do { const bf16_t* g_ = (BASE) + (size_t)(br) * K + (size_t)(kt) * 64; \
;         _Pragma("unroll") for (int i_ = 0; i_ < 2; ++i_) \
;             __builtin_amdgcn_global_load_lds((const unsigned*)(g_ + gofs[i_]), (lds_ptr_t)((P) + wb + i_ * 8192), 16, 0, 0); } while (0)
; #define LDA(dst, b, hh) _Pragma("unroll") for (int m = 0; m < 4; ++m) _Pragma("unroll") for (int k = 0; k < 2; ++k) \
;         dst[m][k] = *(const bf16x8*)(SA(b, hh) + lds_byte(wr * 64 + m * 16 + fr, k * 32 + fq * 8))
; #define LDB(dst, b, hh) _Pragma("unroll") for (int n = 0; n < 2; ++n) _Pragma("unroll") for (int k = 0; k < 2; ++k) \
;         dst[n][k] = *(const bf16x8*)(SB(b, hh) + lds_byte(wc * 32 + n * 16 + fr, k * 32 + fq * 8))
; #define MMA(ai, bj, At_, Bt_) do { __builtin_amdgcn_s_setprio(1); \
;         _Pragma("unroll") for (int m = 0; m < 4; ++m) _Pragma("unroll") for (int n = 0; n < 2; ++n) _Pragma("unroll") for (int k = 0; k < 2; ++k) \
;             acc[ai][bj][m][n] = MFMA16(At_[m][k], Bt_[n][k], acc[ai][bj][m][n]); \
;         __builtin_amdgcn_s_setprio(0); } while (0)
; #define WAIT_V(n) asm volatile("s_waitcnt vmcnt(" #n ")" ::: "memory")
; #define WAIT_L(n) asm volatile("s_waitcnt lgkmcnt(" #n ")" ::: "memory")
; #define BAR __builtin_amdgcn_s_barrier()
; #define STAGE(P, BASE, br, kt) do { const int sg_ = (kt) >> 3; const bf16_t* g_ = (sg_ == 0 ? BASE##0 : sg_ == 1 ? BASE##1 : BASE##2) + (size_t)(br) * K + (size_t)((kt) & 7) * 64; \
;         _Pragma("unroll") for (int i_ = 0; i_ < 2; ++i_) \
;             __builtin_amdgcn_global_load_lds((const unsigned*)(g_ + gofs[i_]), (lds_ptr_t)((P) + wb + i_ * 8192), 16, 0, 0); } while (0)
; #define WAIT_V(n) asm volatile("s_waitcnt vmcnt(" #n ")" ::: "memory")
; #define WAIT_L(n) asm volatile("s_waitcnt lgkmcnt(" #n ")" ::: "memory")
; template <class Hook>
; DI void gemm8_cat3(f32x4 (&acc)[2][2][4][2], const bf16_t* R0, const bf16_t* R1, const bf16_t* R2, const bf16_t* C0, const bf16_t* C1, const bf16_t* C2, char* shm, Hook hook) {
;     ...
;     { LDB(B0, 0, 0); LDA(At, 0, 0); STAGE(SA(1, 1), R, 128, nt - 1);
;       BAR; WAIT_L(0); MMA(0, 0, At, B0); BAR;
;       LDB(B1, 0, 1); BAR; WAIT_L(0); MMA(0, 1, At, B1); BAR;
;       LDA(At, 0, 1); WAIT_V(4); BAR; WAIT_L(0); MMA(1, 0, At, B0); MMA(1, 1, At, B1); BAR; }
;     { LDB(B0, 1, 0); LDA(At, 1, 0); WAIT_V(2); BAR; WAIT_L(0); MMA(0, 0, At, B0); BAR;
	s_waitcnt lgkmcnt(0)
	s_setprio 1
	s_waitcnt lgkmcnt(0)
	v_mfma_f32_16x16x32_bf16 v[42:45], v[150:153], v[142:145], v[42:45]
	v_mfma_f32_16x16x32_bf16 v[30:33], v[184:187], v[126:129], v[30:33]
	v_mfma_f32_16x16x32_bf16 v[54:57], v[184:187], v[142:145], v[54:57]
	v_mfma_f32_16x16x32_bf16 v[18:21], v[196:199], v[126:129], v[18:21]
	v_mfma_f32_16x16x32_bf16 v[50:53], v[196:199], v[142:145], v[50:53]
	v_mfma_f32_16x16x32_bf16 v[26:29], v[204:207], v[126:129], v[26:29]
	v_mfma_f32_16x16x32_bf16 v[46:49], v[204:207], v[142:145], v[46:49]
	v_mfma_f32_16x16x32_bf16 v[130:133], v[150:153], v[126:129], v[130:133]
	v_mfma_f32_16x16x32_bf16 v[42:45], v[164:167], v[146:149], v[42:45]
	v_mfma_f32_16x16x32_bf16 v[30:33], v[192:195], v[134:137], v[30:33]
	v_mfma_f32_16x16x32_bf16 v[54:57], v[192:195], v[146:149], v[54:57]
	v_mfma_f32_16x16x32_bf16 v[18:21], v[200:203], v[134:137], v[18:21]
	v_mfma_f32_16x16x32_bf16 v[50:53], v[200:203], v[146:149], v[50:53]
	v_mfma_f32_16x16x32_bf16 v[26:29], v[208:211], v[134:137], v[26:29]
	v_mfma_f32_16x16x32_bf16 v[46:49], v[208:211], v[146:149], v[46:49]
	v_mfma_f32_16x16x32_bf16 v[130:133], v[164:167], v[134:137], v[130:133]
	s_setprio 0
	s_barrier
	ds_read_b128 v[138:141], v188
	ds_read_b128 v[212:215], v188 offset:1024
	ds_read_b128 v[216:219], v188 offset:2048
	ds_read_b128 v[188:191], v188 offset:3072
	s_barrier
	s_waitcnt lgkmcnt(0)
	s_setprio 1
	s_waitcnt lgkmcnt(0)
	v_mfma_f32_16x16x32_bf16 v[66:69], v[196:199], v[138:141], v[66:69]
	v_mfma_f32_16x16x32_bf16 v[58:61], v[150:153], v[138:141], v[58:61]
	v_mfma_f32_16x16x32_bf16 v[74:77], v[150:153], v[216:219], v[74:77]
	v_mfma_f32_16x16x32_bf16 v[70:73], v[184:187], v[138:141], v[70:73]
	v_mfma_f32_16x16x32_bf16 v[86:89], v[184:187], v[216:219], v[86:89]
	v_mfma_f32_16x16x32_bf16 v[150:153], v[200:203], v[212:215], v[66:69]
	v_mfma_f32_16x16x32_bf16 v[66:69], v[196:199], v[216:219], v[82:85]
	v_mfma_f32_16x16x32_bf16 v[62:65], v[204:207], v[138:141], v[62:65]
	v_mfma_f32_16x16x32_bf16 v[58:61], v[164:167], v[212:215], v[58:61]
	v_mfma_f32_16x16x32_bf16 v[74:77], v[164:167], v[188:191], v[74:77]
	v_mfma_f32_16x16x32_bf16 v[70:73], v[192:195], v[212:215], v[70:73]
	v_mfma_f32_16x16x32_bf16 v[86:89], v[192:195], v[188:191], v[86:89]
	v_mfma_f32_16x16x32_bf16 v[164:167], v[200:203], v[188:191], v[66:69]
	v_mfma_f32_16x16x32_bf16 v[62:65], v[208:211], v[212:215], v[62:65]
	v_mfma_f32_16x16x32_bf16 v[66:69], v[204:207], v[216:219], v[78:81]
	v_mfma_f32_16x16x32_bf16 v[184:187], v[208:211], v[188:191], v[66:69]
	s_setprio 0
	s_barrier
	s_nop 4
	ds_read_b128 v[66:69], v157 offset:16384
	ds_read_b128 v[78:81], v157 offset:17408
	ds_read_b128 v[82:85], v156 offset:16384
	ds_read_b128 v[192:195], v156 offset:17408
	ds_read_b128 v[196:199], v155 offset:16384
	ds_read_b128 v[200:203], v155 offset:17408
	ds_read_b128 v[204:207], v154 offset:16384
	ds_read_b128 v[208:211], v154 offset:17408
	s_waitcnt vmcnt(4)
	s_barrier
	s_waitcnt lgkmcnt(0)
	s_setprio 1
	s_waitcnt lgkmcnt(0)
	v_mfma_f32_16x16x32_bf16 v[90:93], v[66:69], v[126:129], v[90:93]
	v_mfma_f32_16x16x32_bf16 v[220:223], v[78:81], v[134:137], v[90:93]
	v_mfma_f32_16x16x32_bf16 v[90:93], v[66:69], v[142:145], v[106:109]
	v_mfma_f32_16x16x32_bf16 v[224:227], v[78:81], v[146:149], v[90:93]
	v_mfma_f32_16x16x32_bf16 v[90:93], v[82:85], v[126:129], v[102:105]
	v_mfma_f32_16x16x32_bf16 v[228:231], v[192:195], v[134:137], v[90:93]
	v_mfma_f32_16x16x32_bf16 v[90:93], v[82:85], v[142:145], v[118:121]
	v_mfma_f32_16x16x32_bf16 v[232:235], v[192:195], v[146:149], v[90:93]
	v_mfma_f32_16x16x32_bf16 v[90:93], v[196:199], v[126:129], v[98:101]
	v_mfma_f32_16x16x32_bf16 v[236:239], v[200:203], v[134:137], v[90:93]
	v_mfma_f32_16x16x32_bf16 v[90:93], v[196:199], v[142:145], v[114:117]
	v_mfma_f32_16x16x32_bf16 v[240:243], v[200:203], v[146:149], v[90:93]
	v_mfma_f32_16x16x32_bf16 v[90:93], v[204:207], v[126:129], v[94:97]
	v_mfma_f32_16x16x32_bf16 v[134:137], v[208:211], v[134:137], v[90:93]
	v_mfma_f32_16x16x32_bf16 v[90:93], v[204:207], v[142:145], v[110:113]
	v_mfma_f32_16x16x32_bf16 v[142:145], v[208:211], v[146:149], v[90:93]
	s_setprio 0
	s_setprio 1
	v_mfma_f32_16x16x32_bf16 v[34:37], v[82:85], v[138:141], v[34:37]
	v_mfma_f32_16x16x32_bf16 v[10:13], v[196:199], v[216:219], v[10:13]
	v_mfma_f32_16x16x32_bf16 v[14:17], v[66:69], v[216:219], v[14:17]
	v_mfma_f32_16x16x32_bf16 v[244:247], v[192:195], v[212:215], v[34:37]
	v_mfma_f32_16x16x32_bf16 v[6:9], v[82:85], v[216:219], v[6:9]
	v_mfma_f32_16x16x32_bf16 v[34:37], v[196:199], v[138:141], v[38:41]
	v_mfma_f32_16x16x32_bf16 v[196:199], v[200:203], v[188:191], v[10:13]
	v_mfma_f32_16x16x32_bf16 v[10:13], v[204:207], v[138:141], v[22:25]
	v_mfma_f32_16x16x32_bf16 v[90:93], v[66:69], v[138:141], v[122:125]
	v_mfma_f32_16x16x32_bf16 v[14:17], v[78:81], v[188:191], v[14:17]
	v_mfma_f32_16x16x32_bf16 v[6:9], v[192:195], v[188:191], v[6:9]
	v_mfma_f32_16x16x32_bf16 v[22:25], v[208:211], v[212:215], v[10:13]
	v_mfma_f32_16x16x32_bf16 v[2:5], v[204:207], v[216:219], v[2:5]
	v_mfma_f32_16x16x32_bf16 v[146:149], v[78:81], v[212:215], v[90:93]
	v_mfma_f32_16x16x32_bf16 v[192:195], v[200:203], v[212:215], v[34:37]
	v_mfma_f32_16x16x32_bf16 v[138:141], v[208:211], v[188:191], v[2:5]
	s_setprio 0
	s_barrier
	s_nop 2
	ds_read_b128 v[2:5], v169
	ds_read_b128 v[10:13], v169 offset:1024
	ds_read_b128 v[38:41], v169 offset:2048
	ds_read_b128 v[168:171], v169 offset:3072
	ds_read_b128 v[34:37], v157 offset:32768
	ds_read_b128 v[66:69], v157 offset:33792
	ds_read_b128 v[78:81], v156 offset:32768
	ds_read_b128 v[94:97], v156 offset:33792
	ds_read_b128 v[188:191], v155 offset:32768
	ds_read_b128 v[200:203], v155 offset:33792
	ds_read_b128 v[204:207], v154 offset:32768
	ds_read_b128 v[208:211], v154 offset:33792
	s_waitcnt vmcnt(2)
	s_barrier
; #define LDA(dst, b, hh) _Pragma("unroll") for (int m = 0; m < 4; ++m) _Pragma("unroll") for (int k = 0; k < 2; ++k) \
;         dst[m][k] = *(const bf16x8*)(SA(b, hh) + lds_byte(wr * 64 + m * 16 + fr, k * 32 + fq * 8))
; #define LDB(dst, b, hh) _Pragma("unroll") for (int n = 0; n < 2; ++n) _Pragma("unroll") for (int k = 0; k < 2; ++k) \
;         dst[n][k] = *(const bf16x8*)(SB(b, hh) + lds_byte(wc * 32 + n * 16 + fr, k * 32 + fq * 8))
; #define MMA(ai, bj, At_, Bt_) do { __builtin_amdgcn_s_setprio(1); \
;         _Pragma("unroll") for (int m = 0; m < 4; ++m) _Pragma("unroll") for (int n = 0; n < 2; ++n) _Pragma("unroll") for (int k = 0; k < 2; ++k) \
;             acc[ai][bj][m][n] = MFMA16(At_[m][k], Bt_[n][k], acc[ai][bj][m][n]); \
;         __builtin_amdgcn_s_setprio(0); } while (0)
; #define WAIT_V(n) asm volatile("s_waitcnt vmcnt(" #n ")" ::: "memory")
; #define WAIT_L(n) asm volatile("s_waitcnt lgkmcnt(" #n ")" ::: "memory")
; #define BAR __builtin_amdgcn_s_barrier()
; #define LDA(dst, b, hh) _Pragma("unroll") for (int m = 0; m < 4; ++m) _Pragma("unroll") for (int k = 0; k < 2; ++k) \
;         dst[m][k] = *(const bf16x8*)(SA(b, hh) + lds_byte(wr * 64 + m * 16 + fr, k * 32 + fq * 8))
; #define LDB(dst, b, hh) _Pragma("unroll") for (int n = 0; n < 2; ++n) _Pragma("unroll") for (int k = 0; k < 2; ++k) \
;         dst[n][k] = *(const bf16x8*)(SB(b, hh) + lds_byte(wc * 32 + n * 16 + fr, k * 32 + fq * 8))
; #define MMA(ai, bj, At_, Bt_) do { __builtin_amdgcn_s_setprio(1); \
;         _Pragma("unroll") for (int m = 0; m < 4; ++m) _Pragma("unroll") for (int n = 0; n < 2; ++n) _Pragma("unroll") for (int k = 0; k < 2; ++k) \
;             acc[ai][bj][m][n] = MFMA16(At_[m][k], Bt_[n][k], acc[ai][bj][m][n]); \
;         __builtin_amdgcn_s_setprio(0); } while (0)
; #define WAIT_V(n) asm volatile("s_waitcnt vmcnt(" #n ")" ::: "memory")
; #define BAR __builtin_amdgcn_s_barrier()
; template <class Hook>
; DI void gemm8_cat3(f32x4 (&acc)[2][2][4][2], const bf16_t* R0, const bf16_t* R1, const bf16_t* R2, const bf16_t* C0, const bf16_t* C1, const bf16_t* C2, char* shm, Hook hook) {
;     ...
;     { LDB(B0, 1, 0); LDA(At, 1, 0); WAIT_V(2); BAR; WAIT_L(0); MMA(0, 0, At, B0); BAR;
;       LDB(B1, 1, 1); WAIT_V(0); BAR; WAIT_L(0); MMA(0, 1, At, B1); BAR;
;       LDA(At, 1, 1); BAR; WAIT_L(0); MMA(1, 0, At, B0); MMA(1, 1, At, B1); BAR; }
;     if (wr == 0) BAR;
	s_waitcnt lgkmcnt(0)
	s_setprio 1
	s_waitcnt lgkmcnt(0)
	v_mfma_f32_16x16x32_bf16 v[18:21], v[188:191], v[2:5], v[18:21]
	v_mfma_f32_16x16x32_bf16 v[126:129], v[200:203], v[10:13], v[18:21]
	v_mfma_f32_16x16x32_bf16 v[18:21], v[188:191], v[38:41], v[50:53]
	v_mfma_f32_16x16x32_bf16 v[30:33], v[78:81], v[2:5], v[30:33]
	v_mfma_f32_16x16x32_bf16 v[110:113], v[200:203], v[168:171], v[18:21]
	v_mfma_f32_16x16x32_bf16 v[18:21], v[204:207], v[2:5], v[26:29]
	v_mfma_f32_16x16x32_bf16 v[82:85], v[34:37], v[2:5], v[130:133]
	v_mfma_f32_16x16x32_bf16 v[42:45], v[34:37], v[38:41], v[42:45]
	v_mfma_f32_16x16x32_bf16 v[114:117], v[94:97], v[10:13], v[30:33]
	v_mfma_f32_16x16x32_bf16 v[30:33], v[78:81], v[38:41], v[54:57]
	v_mfma_f32_16x16x32_bf16 v[118:121], v[208:211], v[10:13], v[18:21]
	v_mfma_f32_16x16x32_bf16 v[18:21], v[204:207], v[38:41], v[46:49]
	v_mfma_f32_16x16x32_bf16 v[122:125], v[66:69], v[10:13], v[82:85]
	v_mfma_f32_16x16x32_bf16 v[106:109], v[66:69], v[168:171], v[42:45]
	v_mfma_f32_16x16x32_bf16 v[98:101], v[94:97], v[168:171], v[30:33]
	v_mfma_f32_16x16x32_bf16 v[102:105], v[208:211], v[168:171], v[18:21]
	s_setprio 0
	s_barrier
	ds_read_b128 v[130:133], v161
	ds_read_b128 v[212:215], v161 offset:1024
	ds_read_b128 v[216:219], v161 offset:2048
	ds_read_b128 v[158:161], v161 offset:3072
	s_waitcnt vmcnt(0)
	s_barrier
	s_waitcnt lgkmcnt(0)
	s_setprio 1
	s_waitcnt lgkmcnt(0)
	v_mfma_f32_16x16x32_bf16 v[18:21], v[34:37], v[130:133], v[58:61]
	v_mfma_f32_16x16x32_bf16 v[90:93], v[66:69], v[212:215], v[18:21]
	v_mfma_f32_16x16x32_bf16 v[18:21], v[34:37], v[216:219], v[74:77]
	v_mfma_f32_16x16x32_bf16 v[74:77], v[66:69], v[158:161], v[18:21]
	v_mfma_f32_16x16x32_bf16 v[18:21], v[78:81], v[130:133], v[70:73]
	v_mfma_f32_16x16x32_bf16 v[82:85], v[94:97], v[212:215], v[18:21]
	v_mfma_f32_16x16x32_bf16 v[18:21], v[78:81], v[216:219], v[86:89]
	v_mfma_f32_16x16x32_bf16 v[66:69], v[94:97], v[158:161], v[18:21]
	v_mfma_f32_16x16x32_bf16 v[18:21], v[188:191], v[130:133], v[150:153]
	v_mfma_f32_16x16x32_bf16 v[94:97], v[200:203], v[212:215], v[18:21]
	v_mfma_f32_16x16x32_bf16 v[18:21], v[188:191], v[216:219], v[164:167]
	v_mfma_f32_16x16x32_bf16 v[78:81], v[200:203], v[158:161], v[18:21]
	v_mfma_f32_16x16x32_bf16 v[18:21], v[204:207], v[130:133], v[62:65]
	v_mfma_f32_16x16x32_bf16 v[86:89], v[208:211], v[212:215], v[18:21]
	v_mfma_f32_16x16x32_bf16 v[18:21], v[204:207], v[216:219], v[184:187]
	v_mfma_f32_16x16x32_bf16 v[70:73], v[208:211], v[158:161], v[18:21]
	s_setprio 0
	s_barrier
	s_nop 4
	ds_read_b128 v[18:21], v157 offset:49152
	ds_read_b128 v[30:33], v157 offset:50176
	ds_read_b128 v[150:153], v156 offset:49152
	ds_read_b128 v[164:167], v156 offset:50176
	ds_read_b128 v[184:187], v155 offset:49152
	ds_read_b128 v[188:191], v155 offset:50176
	ds_read_b128 v[200:203], v154 offset:49152
	ds_read_b128 v[154:157], v154 offset:50176
	s_barrier
	s_waitcnt lgkmcnt(0)
	s_setprio 1
	s_waitcnt lgkmcnt(0)
	v_mfma_f32_16x16x32_bf16 v[26:29], v[18:21], v[2:5], v[220:223]
	v_mfma_f32_16x16x32_bf16 v[58:61], v[30:33], v[10:13], v[26:29]
	v_mfma_f32_16x16x32_bf16 v[26:29], v[18:21], v[38:41], v[224:227]
	v_mfma_f32_16x16x32_bf16 v[42:45], v[30:33], v[168:171], v[26:29]
	v_mfma_f32_16x16x32_bf16 v[26:29], v[150:153], v[2:5], v[228:231]
	v_mfma_f32_16x16x32_bf16 v[50:53], v[164:167], v[10:13], v[26:29]
	v_mfma_f32_16x16x32_bf16 v[26:29], v[150:153], v[38:41], v[232:235]
	v_mfma_f32_16x16x32_bf16 v[34:37], v[164:167], v[168:171], v[26:29]
	v_mfma_f32_16x16x32_bf16 v[26:29], v[184:187], v[2:5], v[236:239]
	v_mfma_f32_16x16x32_bf16 v[2:5], v[200:203], v[2:5], v[134:137]
	v_mfma_f32_16x16x32_bf16 v[62:65], v[188:191], v[10:13], v[26:29]
	v_mfma_f32_16x16x32_bf16 v[26:29], v[184:187], v[38:41], v[240:243]
	v_mfma_f32_16x16x32_bf16 v[54:57], v[154:157], v[10:13], v[2:5]
	v_mfma_f32_16x16x32_bf16 v[2:5], v[200:203], v[38:41], v[142:145]
	v_mfma_f32_16x16x32_bf16 v[46:49], v[188:191], v[168:171], v[26:29]
	v_mfma_f32_16x16x32_bf16 v[38:41], v[154:157], v[168:171], v[2:5]
	s_setprio 0
	s_setprio 1
	v_mfma_f32_16x16x32_bf16 v[2:5], v[18:21], v[130:133], v[146:149]
	v_mfma_f32_16x16x32_bf16 v[26:29], v[30:33], v[212:215], v[2:5]
	v_mfma_f32_16x16x32_bf16 v[2:5], v[18:21], v[216:219], v[14:17]
	v_mfma_f32_16x16x32_bf16 v[10:13], v[30:33], v[158:161], v[2:5]
	v_mfma_f32_16x16x32_bf16 v[2:5], v[150:153], v[130:133], v[244:247]
	v_mfma_f32_16x16x32_bf16 v[18:21], v[164:167], v[212:215], v[2:5]
	v_mfma_f32_16x16x32_bf16 v[2:5], v[150:153], v[216:219], v[6:9]
	v_mfma_f32_16x16x32_bf16 v[6:9], v[184:187], v[130:133], v[192:195]
	v_mfma_f32_16x16x32_bf16 v[30:33], v[188:191], v[212:215], v[6:9]
	v_mfma_f32_16x16x32_bf16 v[6:9], v[184:187], v[216:219], v[196:199]
	v_mfma_f32_16x16x32_bf16 v[14:17], v[188:191], v[158:161], v[6:9]
	v_mfma_f32_16x16x32_bf16 v[6:9], v[200:203], v[130:133], v[22:25]
	v_mfma_f32_16x16x32_bf16 v[22:25], v[154:157], v[212:215], v[6:9]
	v_mfma_f32_16x16x32_bf16 v[6:9], v[200:203], v[216:219], v[138:141]
	v_mfma_f32_16x16x32_bf16 v[2:5], v[164:167], v[158:161], v[2:5]
	v_mfma_f32_16x16x32_bf16 v[6:9], v[154:157], v[158:161], v[6:9]
	s_setprio 0
	s_movk_i32 s96, 0x100
	v_cmp_gt_u32_e32 vcc, s96, v0
	s_barrier
	s_and_saveexec_b64 s[20:21], vcc
	s_cbranch_execz .LBB0_42
	s_barrier
	s_branch .LBB0_42

; #define STAGE(P, BASE, br, kt) do { const bf16_t* g_ = (BASE) + (size_t)(br) * K + (size_t)(kt) * 64; \
;         _Pragma("unroll") for (int i_ = 0; i_ < 2; ++i_) \
;             __builtin_amdgcn_global_load_lds((const unsigned*)(g_ + gofs[i_]), (lds_ptr_t)((P) + wb + i_ * 8192), 16, 0, 0); } while (0)
; #define LDA(dst, b, hh) _Pragma("unroll") for (int m = 0; m < 4; ++m) _Pragma("unroll") for (int k = 0; k < 2; ++k) \
;         dst[m][k] = *(const bf16x8*)(SA(b, hh) + lds_byte(wr * 64 + m * 16 + fr, k * 32 + fq * 8))
; #define LDB(dst, b, hh) _Pragma("unroll") for (int n = 0; n < 2; ++n) _Pragma("unroll") for (int k = 0; k < 2; ++k) \
;         dst[n][k] = *(const bf16x8*)(SB(b, hh) + lds_byte(wc * 32 + n * 16 + fr, k * 32 + fq * 8))
; #define MMA(ai, bj, At_, Bt_) do { __builtin_amdgcn_s_setprio(1); \
;         _Pragma("unroll") for (int m = 0; m < 4; ++m) _Pragma("unroll") for (int n = 0; n < 2; ++n) _Pragma("unroll") for (int k = 0; k < 2; ++k) \
;             acc[ai][bj][m][n] = MFMA16(At_[m][k], Bt_[n][k], acc[ai][bj][m][n]); \
;         __builtin_amdgcn_s_setprio(0); } while (0)
; #define WAIT_L(n) asm volatile("s_waitcnt lgkmcnt(" #n ")" ::: "memory")
; #define BAR __builtin_amdgcn_s_barrier()
; #define SCHED __builtin_amdgcn_sched_barrier(0)
; #define STAGE(P, BASE, br, kt) do { const int sg_ = (kt) >> 3; const bf16_t* g_ = (sg_ == 0 ? BASE##0 : sg_ == 1 ? BASE##1 : BASE##2) + (size_t)(br) * K + (size_t)((kt) & 7) * 64; \
;         _Pragma("unroll") for (int i_ = 0; i_ < 2; ++i_) \
;             __builtin_amdgcn_global_load_lds((const unsigned*)(g_ + gofs[i_]), (lds_ptr_t)((P) + wb + i_ * 8192), 16, 0, 0); } while (0)
; #define WAIT_L(n) asm volatile("s_waitcnt lgkmcnt(" #n ")" ::: "memory")
; #define BAR __builtin_amdgcn_s_barrier()
; #define SCHED __builtin_amdgcn_sched_barrier(0)
; DI void gemm8(f32x4 (&acc)[2][2][4][2], const bf16_t* __restrict__ Rm, const bf16_t* __restrict__ Cm, int K, char* shm) {
;     ...
;     for (int tt = 0; tt < nt - 2; tt += 2) {
;         LDB(B0, 0, 0); SCHED; LDA(At, 0, 0); STAGE(SA(1, 1), Rm, 128, tt + 1);
;         WAIT_L(8); BAR; WAIT_L(0); MMA(0, 0, At, B0); BAR; SCHED;
;         LDB(B1, 0, 1); STAGE(SB(0, 0), Cm, 0, tt + 2);
;         BAR; WAIT_L(0); MMA(0, 1, At, B1); BAR;
;         LDA(At, 0, 1); STAGE(SA(0, 0), Rm, 0, tt + 2);
;         BAR; WAIT_L(0); MMA(1, 0, At, B0); BAR; SCHED;
.LBB0_114:
	v_add_u32_e32 v166, 0xc000, v146
	v_lshl_add_u64 v[172:173], s[62:63], 0, v[138:139]
	v_readfirstlane_b32 s2, v166
	v_add_u32_e32 v167, 0xe000, v146
	v_lshl_add_u64 v[228:229], v[172:173], 0, s[52:53]
	s_mov_b32 m0, s2
	v_lshl_add_u64 v[244:245], s[62:63], 0, v[140:141]
	v_readfirstlane_b32 s2, v167
	global_load_lds_dwordx4 v[228:229], off
	v_lshl_add_u64 v[228:229], v[244:245], 0, s[52:53]
	s_mov_b32 m0, s2
	s_nop 0
	global_load_lds_dwordx4 v[228:229], off
	ds_read_b128 v[168:171], v165
	ds_read_b128 v[184:187], v165 offset:1024
	ds_read_b128 v[188:191], v165 offset:2048
	ds_read_b128 v[192:195], v165 offset:3072
	ds_read_b128 v[196:199], v145
	ds_read_b128 v[200:203], v145 offset:1024
	ds_read_b128 v[204:207], v144
	ds_read_b128 v[208:211], v144 offset:1024
	ds_read_b128 v[212:215], v143
	ds_read_b128 v[216:219], v143 offset:1024
	ds_read_b128 v[220:223], v142
	ds_read_b128 v[224:227], v142 offset:1024
	s_waitcnt lgkmcnt(8)
	s_barrier
	s_waitcnt lgkmcnt(0)
	s_setprio 1
	s_waitcnt lgkmcnt(0)
	v_mfma_f32_16x16x32_bf16 v[126:129], v[196:199], v[168:171], v[126:129]
	v_mfma_f32_16x16x32_bf16 v[122:125], v[196:199], v[188:191], v[122:125]
	v_mfma_f32_16x16x32_bf16 v[118:121], v[204:207], v[168:171], v[118:121]
	v_mfma_f32_16x16x32_bf16 v[114:117], v[204:207], v[188:191], v[114:117]
	v_mfma_f32_16x16x32_bf16 v[110:113], v[212:215], v[168:171], v[110:113]
	v_mfma_f32_16x16x32_bf16 v[106:109], v[212:215], v[188:191], v[106:109]
	v_mfma_f32_16x16x32_bf16 v[102:105], v[220:223], v[168:171], v[102:105]
	v_mfma_f32_16x16x32_bf16 v[98:101], v[220:223], v[188:191], v[98:101]
	v_mfma_f32_16x16x32_bf16 v[126:129], v[200:203], v[184:187], v[126:129]
	v_mfma_f32_16x16x32_bf16 v[122:125], v[200:203], v[192:195], v[122:125]
	v_mfma_f32_16x16x32_bf16 v[118:121], v[208:211], v[184:187], v[118:121]
	v_mfma_f32_16x16x32_bf16 v[114:117], v[208:211], v[192:195], v[114:117]
	v_mfma_f32_16x16x32_bf16 v[110:113], v[216:219], v[184:187], v[110:113]
	v_mfma_f32_16x16x32_bf16 v[106:109], v[216:219], v[192:195], v[106:109]
	v_mfma_f32_16x16x32_bf16 v[102:105], v[224:227], v[184:187], v[102:105]
	v_mfma_f32_16x16x32_bf16 v[98:101], v[224:227], v[192:195], v[98:101]
	s_setprio 0
	s_barrier
	v_lshl_add_u64 v[246:247], s[62:63], 0, v[134:135]
	v_readfirstlane_b32 s2, v147
	v_lshl_add_u64 v[248:249], v[246:247], 0, s[90:91]
	s_mov_b32 m0, s2
	s_nop 0
	global_load_lds_dwordx4 v[248:249], off
	v_lshl_add_u64 v[248:249], s[62:63], 0, v[136:137]
	v_readfirstlane_b32 s2, v148
	v_lshl_add_u64 v[250:251], v[248:249], 0, s[90:91]
	s_mov_b32 m0, s2
	s_nop 0
	global_load_lds_dwordx4 v[250:251], off
	ds_read_b128 v[228:231], v164
	ds_read_b128 v[232:235], v164 offset:1024
	ds_read_b128 v[236:239], v164 offset:2048
	ds_read_b128 v[240:243], v164 offset:3072
	s_barrier
	s_waitcnt lgkmcnt(0)
	s_setprio 1
	s_waitcnt lgkmcnt(0)
	v_mfma_f32_16x16x32_bf16 v[94:97], v[196:199], v[228:231], v[94:97]
	v_mfma_f32_16x16x32_bf16 v[90:93], v[196:199], v[236:239], v[90:93]
	v_mfma_f32_16x16x32_bf16 v[86:89], v[204:207], v[228:231], v[86:89]
	v_mfma_f32_16x16x32_bf16 v[82:85], v[204:207], v[236:239], v[82:85]
	v_mfma_f32_16x16x32_bf16 v[78:81], v[212:215], v[228:231], v[78:81]
	v_mfma_f32_16x16x32_bf16 v[74:77], v[212:215], v[236:239], v[74:77]
	v_mfma_f32_16x16x32_bf16 v[70:73], v[220:223], v[228:231], v[70:73]
	v_mfma_f32_16x16x32_bf16 v[66:69], v[220:223], v[236:239], v[66:69]
	v_mfma_f32_16x16x32_bf16 v[94:97], v[200:203], v[232:235], v[94:97]
	v_mfma_f32_16x16x32_bf16 v[90:93], v[200:203], v[240:243], v[90:93]
	v_mfma_f32_16x16x32_bf16 v[86:89], v[208:211], v[232:235], v[86:89]
	v_mfma_f32_16x16x32_bf16 v[82:85], v[208:211], v[240:243], v[82:85]
	v_mfma_f32_16x16x32_bf16 v[78:81], v[216:219], v[232:235], v[78:81]
	v_mfma_f32_16x16x32_bf16 v[74:77], v[216:219], v[240:243], v[74:77]
	v_mfma_f32_16x16x32_bf16 v[70:73], v[224:227], v[232:235], v[70:73]
	v_mfma_f32_16x16x32_bf16 v[66:69], v[224:227], v[240:243], v[66:69]
	s_setprio 0
	v_readfirstlane_b32 s2, v146
	v_lshl_add_u64 v[250:251], v[172:173], 0, s[68:69]
	s_mov_b32 m0, s2
	v_readfirstlane_b32 s2, v150
	s_barrier
	global_load_lds_dwordx4 v[250:251], off
	v_lshl_add_u64 v[250:251], v[244:245], 0, s[68:69]
	s_mov_b32 m0, s2
	s_nop 0
	global_load_lds_dwordx4 v[250:251], off
	ds_read_b128 v[196:199], v145 offset:16384
	ds_read_b128 v[200:203], v145 offset:17408
	ds_read_b128 v[204:207], v144 offset:16384
	ds_read_b128 v[208:211], v144 offset:17408
	ds_read_b128 v[212:215], v143 offset:16384
	ds_read_b128 v[216:219], v143 offset:17408
	ds_read_b128 v[220:223], v142 offset:16384
	ds_read_b128 v[224:227], v142 offset:17408
	s_barrier
	s_waitcnt lgkmcnt(0)
	s_setprio 1
	s_waitcnt lgkmcnt(0)
	v_mfma_f32_16x16x32_bf16 v[62:65], v[196:199], v[168:171], v[62:65]
	v_mfma_f32_16x16x32_bf16 v[58:61], v[196:199], v[188:191], v[58:61]
	v_mfma_f32_16x16x32_bf16 v[54:57], v[204:207], v[168:171], v[54:57]
	v_mfma_f32_16x16x32_bf16 v[50:53], v[204:207], v[188:191], v[50:53]
	v_mfma_f32_16x16x32_bf16 v[46:49], v[212:215], v[168:171], v[46:49]
	v_mfma_f32_16x16x32_bf16 v[42:45], v[212:215], v[188:191], v[42:45]
	v_mfma_f32_16x16x32_bf16 v[38:41], v[220:223], v[168:171], v[38:41]
	v_mfma_f32_16x16x32_bf16 v[34:37], v[220:223], v[188:191], v[34:37]
	v_mfma_f32_16x16x32_bf16 v[62:65], v[200:203], v[184:187], v[62:65]
	v_mfma_f32_16x16x32_bf16 v[58:61], v[200:203], v[192:195], v[58:61]
	v_mfma_f32_16x16x32_bf16 v[54:57], v[208:211], v[184:187], v[54:57]
	v_mfma_f32_16x16x32_bf16 v[50:53], v[208:211], v[192:195], v[50:53]
	v_mfma_f32_16x16x32_bf16 v[46:49], v[216:219], v[184:187], v[46:49]
	v_mfma_f32_16x16x32_bf16 v[42:45], v[216:219], v[192:195], v[42:45]
	v_mfma_f32_16x16x32_bf16 v[38:41], v[224:227], v[184:187], v[38:41]
	v_mfma_f32_16x16x32_bf16 v[34:37], v[224:227], v[192:195], v[34:37]
	s_setprio 0
	s_barrier
; #define STAGE(P, BASE, br, kt) do { const bf16_t* g_ = (BASE) + (size_t)(br) * K + (size_t)(kt) * 64; \
;         _Pragma("unroll") for (int i_ = 0; i_ < 2; ++i_) \
;             __builtin_amdgcn_global_load_lds((const unsigned*)(g_ + gofs[i_]), (lds_ptr_t)((P) + wb + i_ * 8192), 16, 0, 0); } while (0)
; #define LDA(dst, b, hh) _Pragma("unroll") for (int m = 0; m < 4; ++m) _Pragma("unroll") for (int k = 0; k < 2; ++k) \
;         dst[m][k] = *(const bf16x8*)(SA(b, hh) + lds_byte(wr * 64 + m * 16 + fr, k * 32 + fq * 8))
; #define LDB(dst, b, hh) _Pragma("unroll") for (int n = 0; n < 2; ++n) _Pragma("unroll") for (int k = 0; k < 2; ++k) \
;         dst[n][k] = *(const bf16x8*)(SB(b, hh) + lds_byte(wc * 32 + n * 16 + fr, k * 32 + fq * 8))
; #define MMA(ai, bj, At_, Bt_) do { __builtin_amdgcn_s_setprio(1); \
;         _Pragma("unroll") for (int m = 0; m < 4; ++m) _Pragma("unroll") for (int n = 0; n < 2; ++n) _Pragma("unroll") for (int k = 0; k < 2; ++k) \
;             acc[ai][bj][m][n] = MFMA16(At_[m][k], Bt_[n][k], acc[ai][bj][m][n]); \
;         __builtin_amdgcn_s_setprio(0); } while (0)
; #define WAIT_V(n) asm volatile("s_waitcnt vmcnt(" #n ")" ::: "memory")
; #define WAIT_L(n) asm volatile("s_waitcnt lgkmcnt(" #n ")" ::: "memory")
; #define BAR __builtin_amdgcn_s_barrier()
; #define SCHED __builtin_amdgcn_sched_barrier(0)
; #define STAGE(P, BASE, br, kt) do { const int sg_ = (kt) >> 3; const bf16_t* g_ = (sg_ == 0 ? BASE##0 : sg_ == 1 ? BASE##1 : BASE##2) + (size_t)(br) * K + (size_t)((kt) & 7) * 64; \
;         _Pragma("unroll") for (int i_ = 0; i_ < 2; ++i_) \
;             __builtin_amdgcn_global_load_lds((const unsigned*)(g_ + gofs[i_]), (lds_ptr_t)((P) + wb + i_ * 8192), 16, 0, 0); } while (0)
; DI void gemm8(f32x4 (&acc)[2][2][4][2], const bf16_t* __restrict__ Rm, const bf16_t* __restrict__ Cm, int K, char* shm) {
;     ...
;         BAR; WAIT_L(0); MMA(1, 0, At, B0); BAR; SCHED;
;         STAGE(SB(0, 1), Cm, 128, tt + 2);
;         WAIT_V(6); BAR; MMA(1, 1, At, B1); BAR;
;         LDB(B0, 1, 0); SCHED; LDA(At, 1, 0); STAGE(SA(0, 1), Rm, 128, tt + 2);
;         WAIT_L(8); BAR; WAIT_L(0); MMA(0, 0, At, B0); BAR; SCHED;
;         LDB(B1, 1, 1); STAGE(SB(1, 0), Cm, 0, tt + 3);
;         BAR; WAIT_L(0); MMA(0, 1, At, B1); BAR;
;         LDA(At, 1, 1); STAGE(SA(1, 0), Rm, 0, tt + 3);
;         BAR; WAIT_L(0); MMA(1, 0, At, B0); BAR; SCHED;
	v_readfirstlane_b32 s2, v151
	v_lshl_add_u64 v[168:169], v[246:247], 0, s[76:77]
	s_mov_b32 m0, s2
	v_readfirstlane_b32 s2, v152
	global_load_lds_dwordx4 v[168:169], off
	v_lshl_add_u64 v[168:169], v[248:249], 0, s[76:77]
	s_mov_b32 m0, s2
	s_nop 0
	global_load_lds_dwordx4 v[168:169], off
	s_waitcnt vmcnt(6)
	s_barrier
	s_setprio 1
	v_mfma_f32_16x16x32_bf16 v[30:33], v[196:199], v[228:231], v[30:33]
	v_mfma_f32_16x16x32_bf16 v[26:29], v[196:199], v[236:239], v[26:29]
	v_mfma_f32_16x16x32_bf16 v[22:25], v[204:207], v[228:231], v[22:25]
	v_mfma_f32_16x16x32_bf16 v[18:21], v[204:207], v[236:239], v[18:21]
	v_mfma_f32_16x16x32_bf16 v[14:17], v[212:215], v[228:231], v[14:17]
	v_mfma_f32_16x16x32_bf16 v[10:13], v[212:215], v[236:239], v[10:13]
	v_mfma_f32_16x16x32_bf16 v[6:9], v[220:223], v[228:231], v[6:9]
	v_mfma_f32_16x16x32_bf16 v[2:5], v[220:223], v[236:239], v[2:5]
	v_mfma_f32_16x16x32_bf16 v[30:33], v[200:203], v[232:235], v[30:33]
	v_mfma_f32_16x16x32_bf16 v[26:29], v[200:203], v[240:243], v[26:29]
	v_mfma_f32_16x16x32_bf16 v[22:25], v[208:211], v[232:235], v[22:25]
	v_mfma_f32_16x16x32_bf16 v[18:21], v[208:211], v[240:243], v[18:21]
	v_mfma_f32_16x16x32_bf16 v[14:17], v[216:219], v[232:235], v[14:17]
	v_mfma_f32_16x16x32_bf16 v[10:13], v[216:219], v[240:243], v[10:13]
	v_mfma_f32_16x16x32_bf16 v[6:9], v[224:227], v[232:235], v[6:9]
	v_mfma_f32_16x16x32_bf16 v[2:5], v[224:227], v[240:243], v[2:5]
	s_setprio 0
	s_barrier
	v_readfirstlane_b32 s2, v153
	v_lshl_add_u64 v[228:229], v[172:173], 0, s[70:71]
	s_mov_b32 m0, s2
	v_readfirstlane_b32 s2, v154
	global_load_lds_dwordx4 v[228:229], off
	v_lshl_add_u64 v[228:229], v[244:245], 0, s[70:71]
	s_mov_b32 m0, s2
	s_nop 0
	global_load_lds_dwordx4 v[228:229], off
	ds_read_b128 v[168:171], v155
	ds_read_b128 v[184:187], v155 offset:1024
	ds_read_b128 v[188:191], v155 offset:2048
	ds_read_b128 v[192:195], v155 offset:3072
	ds_read_b128 v[196:199], v145 offset:32768
	ds_read_b128 v[200:203], v145 offset:33792
	ds_read_b128 v[204:207], v144 offset:32768
	ds_read_b128 v[208:211], v144 offset:33792
	ds_read_b128 v[212:215], v143 offset:32768
	ds_read_b128 v[216:219], v143 offset:33792
	ds_read_b128 v[220:223], v142 offset:32768
	ds_read_b128 v[224:227], v142 offset:33792
	s_waitcnt lgkmcnt(8)
	s_barrier
	s_waitcnt lgkmcnt(0)
	s_setprio 1
	s_waitcnt lgkmcnt(0)
	v_mfma_f32_16x16x32_bf16 v[126:129], v[196:199], v[168:171], v[126:129]
	v_mfma_f32_16x16x32_bf16 v[122:125], v[196:199], v[188:191], v[122:125]
	v_mfma_f32_16x16x32_bf16 v[118:121], v[204:207], v[168:171], v[118:121]
	v_mfma_f32_16x16x32_bf16 v[114:117], v[204:207], v[188:191], v[114:117]
	v_mfma_f32_16x16x32_bf16 v[110:113], v[212:215], v[168:171], v[110:113]
	v_mfma_f32_16x16x32_bf16 v[106:109], v[212:215], v[188:191], v[106:109]
	v_mfma_f32_16x16x32_bf16 v[102:105], v[220:223], v[168:171], v[102:105]
	v_mfma_f32_16x16x32_bf16 v[98:101], v[220:223], v[188:191], v[98:101]
	v_mfma_f32_16x16x32_bf16 v[126:129], v[200:203], v[184:187], v[126:129]
	v_mfma_f32_16x16x32_bf16 v[122:125], v[200:203], v[192:195], v[122:125]
	v_mfma_f32_16x16x32_bf16 v[118:121], v[208:211], v[184:187], v[118:121]
	v_mfma_f32_16x16x32_bf16 v[114:117], v[208:211], v[192:195], v[114:117]
	v_mfma_f32_16x16x32_bf16 v[110:113], v[216:219], v[184:187], v[110:113]
	v_mfma_f32_16x16x32_bf16 v[106:109], v[216:219], v[192:195], v[106:109]
	v_mfma_f32_16x16x32_bf16 v[102:105], v[224:227], v[184:187], v[102:105]
	v_mfma_f32_16x16x32_bf16 v[98:101], v[224:227], v[192:195], v[98:101]
	s_setprio 0
	s_barrier
	v_readfirstlane_b32 s2, v156
	v_lshl_add_u64 v[250:251], v[246:247], 0, s[72:73]
	s_mov_b32 m0, s2
	v_readfirstlane_b32 s2, v157
	global_load_lds_dwordx4 v[250:251], off
	v_lshl_add_u64 v[250:251], v[248:249], 0, s[72:73]
	s_mov_b32 m0, s2
	s_nop 0
	global_load_lds_dwordx4 v[250:251], off
	ds_read_b128 v[228:231], v149
	ds_read_b128 v[232:235], v149 offset:1024
	ds_read_b128 v[236:239], v149 offset:2048
	ds_read_b128 v[240:243], v149 offset:3072
	s_barrier
	s_waitcnt lgkmcnt(0)
	s_setprio 1
	s_waitcnt lgkmcnt(0)
	v_mfma_f32_16x16x32_bf16 v[94:97], v[196:199], v[228:231], v[94:97]
	v_mfma_f32_16x16x32_bf16 v[90:93], v[196:199], v[236:239], v[90:93]
	v_mfma_f32_16x16x32_bf16 v[86:89], v[204:207], v[228:231], v[86:89]
	v_mfma_f32_16x16x32_bf16 v[82:85], v[204:207], v[236:239], v[82:85]
	v_mfma_f32_16x16x32_bf16 v[78:81], v[212:215], v[228:231], v[78:81]
	v_mfma_f32_16x16x32_bf16 v[74:77], v[212:215], v[236:239], v[74:77]
	v_mfma_f32_16x16x32_bf16 v[70:73], v[220:223], v[228:231], v[70:73]
	v_mfma_f32_16x16x32_bf16 v[66:69], v[220:223], v[236:239], v[66:69]
	v_mfma_f32_16x16x32_bf16 v[94:97], v[200:203], v[232:235], v[94:97]
	v_mfma_f32_16x16x32_bf16 v[90:93], v[200:203], v[240:243], v[90:93]
	v_mfma_f32_16x16x32_bf16 v[86:89], v[208:211], v[232:235], v[86:89]
	v_mfma_f32_16x16x32_bf16 v[82:85], v[208:211], v[240:243], v[82:85]
	v_mfma_f32_16x16x32_bf16 v[78:81], v[216:219], v[232:235], v[78:81]
	v_mfma_f32_16x16x32_bf16 v[74:77], v[216:219], v[240:243], v[74:77]
	v_mfma_f32_16x16x32_bf16 v[70:73], v[224:227], v[232:235], v[70:73]
	v_mfma_f32_16x16x32_bf16 v[66:69], v[224:227], v[240:243], v[66:69]
	s_setprio 0
	v_readfirstlane_b32 s2, v158
	v_lshl_add_u64 v[172:173], v[172:173], 0, s[46:47]
	s_mov_b32 m0, s2
	v_readfirstlane_b32 s2, v159
	s_barrier
	global_load_lds_dwordx4 v[172:173], off
	v_lshl_add_u64 v[172:173], v[244:245], 0, s[46:47]
	s_mov_b32 m0, s2
	s_nop 0
	global_load_lds_dwordx4 v[172:173], off
	ds_read_b128 v[196:199], v145 offset:49152
	ds_read_b128 v[200:203], v145 offset:50176
	ds_read_b128 v[204:207], v144 offset:49152
	ds_read_b128 v[208:211], v144 offset:50176
	ds_read_b128 v[212:215], v143 offset:49152
	ds_read_b128 v[216:219], v143 offset:50176
	ds_read_b128 v[220:223], v142 offset:49152
	ds_read_b128 v[224:227], v142 offset:50176
	s_barrier
; #define STAGE(P, BASE, br, kt) do { const bf16_t* g_ = (BASE) + (size_t)(br) * K + (size_t)(kt) * 64; \
;         _Pragma("unroll") for (int i_ = 0; i_ < 2; ++i_) \
;             __builtin_amdgcn_global_load_lds((const unsigned*)(g_ + gofs[i_]), (lds_ptr_t)((P) + wb + i_ * 8192), 16, 0, 0); } while (0)
; #define LDA(dst, b, hh) _Pragma("unroll") for (int m = 0; m < 4; ++m) _Pragma("unroll") for (int k = 0; k < 2; ++k) \
;         dst[m][k] = *(const bf16x8*)(SA(b, hh) + lds_byte(wr * 64 + m * 16 + fr, k * 32 + fq * 8))
; #define LDB(dst, b, hh) _Pragma("unroll") for (int n = 0; n < 2; ++n) _Pragma("unroll") for (int k = 0; k < 2; ++k) \
;         dst[n][k] = *(const bf16x8*)(SB(b, hh) + lds_byte(wc * 32 + n * 16 + fr, k * 32 + fq * 8))
; #define MMA(ai, bj, At_, Bt_) do { __builtin_amdgcn_s_setprio(1); \
;         _Pragma("unroll") for (int m = 0; m < 4; ++m) _Pragma("unroll") for (int n = 0; n < 2; ++n) _Pragma("unroll") for (int k = 0; k < 2; ++k) \
;             acc[ai][bj][m][n] = MFMA16(At_[m][k], Bt_[n][k], acc[ai][bj][m][n]); \
;         __builtin_amdgcn_s_setprio(0); } while (0)
; #define WAIT_V(n) asm volatile("s_waitcnt vmcnt(" #n ")" ::: "memory")
; #define WAIT_L(n) asm volatile("s_waitcnt lgkmcnt(" #n ")" ::: "memory")
; #define BAR __builtin_amdgcn_s_barrier()
; #define SCHED __builtin_amdgcn_sched_barrier(0)
; #define STAGE(P, BASE, br, kt) do { const int sg_ = (kt) >> 3; const bf16_t* g_ = (sg_ == 0 ? BASE##0 : sg_ == 1 ? BASE##1 : BASE##2) + (size_t)(br) * K + (size_t)((kt) & 7) * 64; \
;         _Pragma("unroll") for (int i_ = 0; i_ < 2; ++i_) \
;             __builtin_amdgcn_global_load_lds((const unsigned*)(g_ + gofs[i_]), (lds_ptr_t)((P) + wb + i_ * 8192), 16, 0, 0); } while (0)
; #define LDA(dst, b, hh) _Pragma("unroll") for (int m = 0; m < 4; ++m) _Pragma("unroll") for (int k = 0; k < 2; ++k) \
;         dst[m][k] = *(const bf16x8*)(SA(b, hh) + lds_byte(wr * 64 + m * 16 + fr, k * 32 + fq * 8))
; #define BAR __builtin_amdgcn_s_barrier()
; DI void gemm8(f32x4 (&acc)[2][2][4][2], const bf16_t* __restrict__ Rm, const bf16_t* __restrict__ Cm, int K, char* shm) {
;     ...
;         BAR; WAIT_L(0); MMA(1, 0, At, B0); BAR; SCHED;
;         STAGE(SB(1, 1), Cm, 128, tt + 3);
;         WAIT_V(6); BAR; MMA(1, 1, At, B1); BAR;
;     }
;     { LDB(B0, 0, 0); LDA(At, 0, 0); STAGE(SA(1, 1), Rm, 128, nt - 1);
;       BAR; WAIT_L(0); MMA(0, 0, At, B0); BAR;
	s_waitcnt lgkmcnt(0)
	s_setprio 1
	s_waitcnt lgkmcnt(0)
	v_mfma_f32_16x16x32_bf16 v[62:65], v[196:199], v[168:171], v[62:65]
	v_mfma_f32_16x16x32_bf16 v[58:61], v[196:199], v[188:191], v[58:61]
	v_mfma_f32_16x16x32_bf16 v[54:57], v[204:207], v[168:171], v[54:57]
	v_mfma_f32_16x16x32_bf16 v[50:53], v[204:207], v[188:191], v[50:53]
	v_mfma_f32_16x16x32_bf16 v[46:49], v[212:215], v[168:171], v[46:49]
	v_mfma_f32_16x16x32_bf16 v[42:45], v[212:215], v[188:191], v[42:45]
	v_mfma_f32_16x16x32_bf16 v[38:41], v[220:223], v[168:171], v[38:41]
	v_mfma_f32_16x16x32_bf16 v[34:37], v[220:223], v[188:191], v[34:37]
	v_mfma_f32_16x16x32_bf16 v[62:65], v[200:203], v[184:187], v[62:65]
	v_mfma_f32_16x16x32_bf16 v[58:61], v[200:203], v[192:195], v[58:61]
	v_mfma_f32_16x16x32_bf16 v[54:57], v[208:211], v[184:187], v[54:57]
	v_mfma_f32_16x16x32_bf16 v[50:53], v[208:211], v[192:195], v[50:53]
	v_mfma_f32_16x16x32_bf16 v[46:49], v[216:219], v[184:187], v[46:49]
	v_mfma_f32_16x16x32_bf16 v[42:45], v[216:219], v[192:195], v[42:45]
	v_mfma_f32_16x16x32_bf16 v[38:41], v[224:227], v[184:187], v[38:41]
	v_mfma_f32_16x16x32_bf16 v[34:37], v[224:227], v[192:195], v[34:37]
	s_setprio 0
	s_barrier
	v_readfirstlane_b32 s2, v160
	v_lshl_add_u64 v[168:169], v[246:247], 0, s[88:89]
	s_mov_b32 m0, s2
	v_readfirstlane_b32 s2, v161
	global_load_lds_dwordx4 v[168:169], off
	v_lshl_add_u64 v[168:169], v[248:249], 0, s[88:89]
	s_mov_b32 m0, s2
	s_nop 0
	global_load_lds_dwordx4 v[168:169], off
	s_waitcnt vmcnt(6)
	s_barrier
	s_setprio 1
	v_mfma_f32_16x16x32_bf16 v[30:33], v[196:199], v[228:231], v[30:33]
	v_mfma_f32_16x16x32_bf16 v[26:29], v[196:199], v[236:239], v[26:29]
	v_mfma_f32_16x16x32_bf16 v[22:25], v[204:207], v[228:231], v[22:25]
	v_mfma_f32_16x16x32_bf16 v[18:21], v[204:207], v[236:239], v[18:21]
	v_mfma_f32_16x16x32_bf16 v[14:17], v[212:215], v[228:231], v[14:17]
	v_mfma_f32_16x16x32_bf16 v[10:13], v[212:215], v[236:239], v[10:13]
	v_mfma_f32_16x16x32_bf16 v[6:9], v[220:223], v[228:231], v[6:9]
	v_mfma_f32_16x16x32_bf16 v[2:5], v[220:223], v[236:239], v[2:5]
	v_mfma_f32_16x16x32_bf16 v[30:33], v[200:203], v[232:235], v[30:33]
	v_mfma_f32_16x16x32_bf16 v[26:29], v[200:203], v[240:243], v[26:29]
	v_mfma_f32_16x16x32_bf16 v[22:25], v[208:211], v[232:235], v[22:25]
	v_mfma_f32_16x16x32_bf16 v[18:21], v[208:211], v[240:243], v[18:21]
	v_mfma_f32_16x16x32_bf16 v[14:17], v[216:219], v[232:235], v[14:17]
	v_mfma_f32_16x16x32_bf16 v[10:13], v[216:219], v[240:243], v[10:13]
	v_mfma_f32_16x16x32_bf16 v[6:9], v[224:227], v[232:235], v[6:9]
	v_mfma_f32_16x16x32_bf16 v[2:5], v[224:227], v[240:243], v[2:5]
	s_setprio 0
	s_add_i32 s16, s16, 2
	v_lshl_add_u64 v[134:135], v[134:135], 0, s[90:91]
	v_lshl_add_u64 v[136:137], v[136:137], 0, s[90:91]
	v_lshl_add_u64 v[138:139], v[138:139], 0, s[90:91]
	s_cmp_lt_u32 s16, 12
	v_lshl_add_u64 v[140:141], v[140:141], 0, s[90:91]
	s_barrier
	s_cbranch_scc1 .LBB0_114
	s_add_u32 s2, s8, 0x40780
	s_addc_u32 s3, s9, 0
	v_readfirstlane_b32 s8, v166
	v_lshl_add_u64 v[130:131], v[130:131], 1, s[2:3]
	s_mov_b32 m0, s8
	ds_read_b128 v[134:137], v165
	ds_read_b128 v[138:141], v165 offset:1024
	ds_read_b128 v[150:153], v165 offset:2048
	ds_read_b128 v[156:159], v165 offset:3072
	ds_read_b128 v[168:171], v145
	ds_read_b128 v[184:187], v145 offset:1024
	ds_read_b128 v[188:191], v144
	ds_read_b128 v[192:195], v144 offset:1024
	ds_read_b128 v[196:199], v143
	ds_read_b128 v[200:203], v143 offset:1024
	ds_read_b128 v[204:207], v142
	ds_read_b128 v[208:211], v142 offset:1024
	global_load_lds_dwordx4 v[130:131], off
	v_lshl_add_u64 v[130:131], v[132:133], 1, s[2:3]
	v_readfirstlane_b32 s2, v167
	s_mov_b32 m0, s2
	s_nop 0
	global_load_lds_dwordx4 v[130:131], off
	s_barrier
	s_waitcnt lgkmcnt(0)
	s_setprio 1
	s_waitcnt lgkmcnt(0)
	v_mfma_f32_16x16x32_bf16 v[126:129], v[168:171], v[134:137], v[126:129]
	v_mfma_f32_16x16x32_bf16 v[122:125], v[168:171], v[150:153], v[122:125]
	v_mfma_f32_16x16x32_bf16 v[118:121], v[188:191], v[134:137], v[118:121]
	v_mfma_f32_16x16x32_bf16 v[110:113], v[196:199], v[134:137], v[110:113]
	v_mfma_f32_16x16x32_bf16 v[102:105], v[204:207], v[134:137], v[102:105]
	v_mfma_f32_16x16x32_bf16 v[126:129], v[184:187], v[138:141], v[126:129]
	v_mfma_f32_16x16x32_bf16 v[122:125], v[184:187], v[156:159], v[122:125]
	v_mfma_f32_16x16x32_bf16 v[118:121], v[192:195], v[138:141], v[118:121]
	v_mfma_f32_16x16x32_bf16 v[114:117], v[188:191], v[150:153], v[114:117]
	v_mfma_f32_16x16x32_bf16 v[110:113], v[200:203], v[138:141], v[110:113]
	v_mfma_f32_16x16x32_bf16 v[106:109], v[196:199], v[150:153], v[106:109]
	v_mfma_f32_16x16x32_bf16 v[102:105], v[208:211], v[138:141], v[102:105]
	v_mfma_f32_16x16x32_bf16 v[98:101], v[204:207], v[150:153], v[98:101]
	v_mfma_f32_16x16x32_bf16 v[130:133], v[192:195], v[156:159], v[114:117]
	v_mfma_f32_16x16x32_bf16 v[212:215], v[200:203], v[156:159], v[106:109]
	v_mfma_f32_16x16x32_bf16 v[216:219], v[208:211], v[156:159], v[98:101]
	s_setprio 0
	s_barrier
	s_nop 2
	ds_read_b128 v[98:101], v164
	ds_read_b128 v[106:109], v164 offset:1024
	ds_read_b128 v[114:117], v164 offset:2048
	ds_read_b128 v[164:167], v164 offset:3072
	s_barrier
; #define LDA(dst, b, hh) _Pragma("unroll") for (int m = 0; m < 4; ++m) _Pragma("unroll") for (int k = 0; k < 2; ++k) \
;         dst[m][k] = *(const bf16x8*)(SA(b, hh) + lds_byte(wr * 64 + m * 16 + fr, k * 32 + fq * 8))
; #define LDB(dst, b, hh) _Pragma("unroll") for (int n = 0; n < 2; ++n) _Pragma("unroll") for (int k = 0; k < 2; ++k) \
;         dst[n][k] = *(const bf16x8*)(SB(b, hh) + lds_byte(wc * 32 + n * 16 + fr, k * 32 + fq * 8))
; #define MMA(ai, bj, At_, Bt_) do { __builtin_amdgcn_s_setprio(1); \
;         _Pragma("unroll") for (int m = 0; m < 4; ++m) _Pragma("unroll") for (int n = 0; n < 2; ++n) _Pragma("unroll") for (int k = 0; k < 2; ++k) \
;             acc[ai][bj][m][n] = MFMA16(At_[m][k], Bt_[n][k], acc[ai][bj][m][n]); \
;         __builtin_amdgcn_s_setprio(0); } while (0)
; #define WAIT_V(n) asm volatile("s_waitcnt vmcnt(" #n ")" ::: "memory")
; #define WAIT_L(n) asm volatile("s_waitcnt lgkmcnt(" #n ")" ::: "memory")
; #define BAR __builtin_amdgcn_s_barrier()
; #define LDA(dst, b, hh) _Pragma("unroll") for (int m = 0; m < 4; ++m) _Pragma("unroll") for (int k = 0; k < 2; ++k) \
;         dst[m][k] = *(const bf16x8*)(SA(b, hh) + lds_byte(wr * 64 + m * 16 + fr, k * 32 + fq * 8))
; #define LDB(dst, b, hh) _Pragma("unroll") for (int n = 0; n < 2; ++n) _Pragma("unroll") for (int k = 0; k < 2; ++k) \
;         dst[n][k] = *(const bf16x8*)(SB(b, hh) + lds_byte(wc * 32 + n * 16 + fr, k * 32 + fq * 8))
; #define MMA(ai, bj, At_, Bt_) do { __builtin_amdgcn_s_setprio(1); \
;         _Pragma("unroll") for (int m = 0; m < 4; ++m) _Pragma("unroll") for (int n = 0; n < 2; ++n) _Pragma("unroll") for (int k = 0; k < 2; ++k) \
;             acc[ai][bj][m][n] = MFMA16(At_[m][k], Bt_[n][k], acc[ai][bj][m][n]); \
;         __builtin_amdgcn_s_setprio(0); } while (0)
; #define WAIT_V(n) asm volatile("s_waitcnt vmcnt(" #n ")" ::: "memory")
; #define WAIT_L(n) asm volatile("s_waitcnt lgkmcnt(" #n ")" ::: "memory")
; DI void gemm8(f32x4 (&acc)[2][2][4][2], const bf16_t* __restrict__ Rm, const bf16_t* __restrict__ Cm, int K, char* shm) {
;     ...
;       BAR; WAIT_L(0); MMA(0, 0, At, B0); BAR;
;       LDB(B1, 0, 1); BAR; WAIT_L(0); MMA(0, 1, At, B1); BAR;
;       LDA(At, 0, 1); WAIT_V(4); BAR; WAIT_L(0); MMA(1, 0, At, B0); MMA(1, 1, At, B1); BAR; }
;     { LDB(B0, 1, 0); LDA(At, 1, 0); WAIT_V(2); BAR; WAIT_L(0); MMA(0, 0, At, B0); BAR;
	s_waitcnt lgkmcnt(0)
	s_setprio 1
	s_waitcnt lgkmcnt(0)
	v_mfma_f32_16x16x32_bf16 v[94:97], v[168:171], v[98:101], v[94:97]
	v_mfma_f32_16x16x32_bf16 v[90:93], v[168:171], v[114:117], v[90:93]
	v_mfma_f32_16x16x32_bf16 v[86:89], v[188:191], v[98:101], v[86:89]
	v_mfma_f32_16x16x32_bf16 v[78:81], v[196:199], v[98:101], v[78:81]
	v_mfma_f32_16x16x32_bf16 v[70:73], v[204:207], v[98:101], v[70:73]
	v_mfma_f32_16x16x32_bf16 v[94:97], v[184:187], v[106:109], v[94:97]
	v_mfma_f32_16x16x32_bf16 v[90:93], v[184:187], v[164:167], v[90:93]
	v_mfma_f32_16x16x32_bf16 v[86:89], v[192:195], v[106:109], v[86:89]
	v_mfma_f32_16x16x32_bf16 v[82:85], v[188:191], v[114:117], v[82:85]
	v_mfma_f32_16x16x32_bf16 v[78:81], v[200:203], v[106:109], v[78:81]
	v_mfma_f32_16x16x32_bf16 v[74:77], v[196:199], v[114:117], v[74:77]
	v_mfma_f32_16x16x32_bf16 v[70:73], v[208:211], v[106:109], v[70:73]
	v_mfma_f32_16x16x32_bf16 v[66:69], v[204:207], v[114:117], v[66:69]
	v_mfma_f32_16x16x32_bf16 v[168:171], v[192:195], v[164:167], v[82:85]
	v_mfma_f32_16x16x32_bf16 v[184:187], v[200:203], v[164:167], v[74:77]
	v_mfma_f32_16x16x32_bf16 v[188:191], v[208:211], v[164:167], v[66:69]
	s_setprio 0
	s_barrier
	s_nop 2
	ds_read_b128 v[66:69], v145 offset:16384
	ds_read_b128 v[74:77], v145 offset:17408
	ds_read_b128 v[82:85], v144 offset:16384
	ds_read_b128 v[192:195], v144 offset:17408
	ds_read_b128 v[196:199], v143 offset:16384
	ds_read_b128 v[200:203], v143 offset:17408
	ds_read_b128 v[204:207], v142 offset:16384
	ds_read_b128 v[208:211], v142 offset:17408
	s_waitcnt vmcnt(4)
	s_barrier
	s_waitcnt lgkmcnt(0)
	s_setprio 1
	s_waitcnt lgkmcnt(0)
	v_mfma_f32_16x16x32_bf16 v[62:65], v[66:69], v[134:137], v[62:65]
	v_mfma_f32_16x16x32_bf16 v[58:61], v[66:69], v[150:153], v[58:61]
	v_mfma_f32_16x16x32_bf16 v[54:57], v[82:85], v[134:137], v[54:57]
	v_mfma_f32_16x16x32_bf16 v[46:49], v[196:199], v[134:137], v[46:49]
	v_mfma_f32_16x16x32_bf16 v[38:41], v[204:207], v[134:137], v[38:41]
	v_mfma_f32_16x16x32_bf16 v[62:65], v[74:77], v[138:141], v[62:65]
	v_mfma_f32_16x16x32_bf16 v[58:61], v[74:77], v[156:159], v[58:61]
	v_mfma_f32_16x16x32_bf16 v[54:57], v[192:195], v[138:141], v[54:57]
	v_mfma_f32_16x16x32_bf16 v[50:53], v[82:85], v[150:153], v[50:53]
	v_mfma_f32_16x16x32_bf16 v[46:49], v[200:203], v[138:141], v[46:49]
	v_mfma_f32_16x16x32_bf16 v[42:45], v[196:199], v[150:153], v[42:45]
	v_mfma_f32_16x16x32_bf16 v[38:41], v[208:211], v[138:141], v[38:41]
	v_mfma_f32_16x16x32_bf16 v[34:37], v[204:207], v[150:153], v[34:37]
	v_mfma_f32_16x16x32_bf16 v[220:223], v[192:195], v[156:159], v[50:53]
	v_mfma_f32_16x16x32_bf16 v[224:227], v[200:203], v[156:159], v[42:45]
	v_mfma_f32_16x16x32_bf16 v[134:137], v[208:211], v[156:159], v[34:37]
	s_setprio 0
	s_setprio 1
	v_mfma_f32_16x16x32_bf16 v[30:33], v[66:69], v[98:101], v[30:33]
	v_mfma_f32_16x16x32_bf16 v[26:29], v[66:69], v[114:117], v[26:29]
	v_mfma_f32_16x16x32_bf16 v[22:25], v[82:85], v[98:101], v[22:25]
	v_mfma_f32_16x16x32_bf16 v[14:17], v[196:199], v[98:101], v[14:17]
	v_mfma_f32_16x16x32_bf16 v[6:9], v[204:207], v[98:101], v[6:9]
	v_mfma_f32_16x16x32_bf16 v[30:33], v[74:77], v[106:109], v[30:33]
	v_mfma_f32_16x16x32_bf16 v[26:29], v[74:77], v[164:167], v[26:29]
	v_mfma_f32_16x16x32_bf16 v[22:25], v[192:195], v[106:109], v[22:25]
	v_mfma_f32_16x16x32_bf16 v[18:21], v[82:85], v[114:117], v[18:21]
	v_mfma_f32_16x16x32_bf16 v[14:17], v[200:203], v[106:109], v[14:17]
	v_mfma_f32_16x16x32_bf16 v[10:13], v[196:199], v[114:117], v[10:13]
	v_mfma_f32_16x16x32_bf16 v[6:9], v[208:211], v[106:109], v[6:9]
	v_mfma_f32_16x16x32_bf16 v[2:5], v[204:207], v[114:117], v[2:5]
	v_mfma_f32_16x16x32_bf16 v[138:141], v[192:195], v[164:167], v[18:21]
	v_mfma_f32_16x16x32_bf16 v[150:153], v[200:203], v[164:167], v[10:13]
	v_mfma_f32_16x16x32_bf16 v[156:159], v[208:211], v[164:167], v[2:5]
	s_setprio 0
	s_barrier
	s_nop 2
	ds_read_b128 v[2:5], v155
	ds_read_b128 v[10:13], v155 offset:1024
	ds_read_b128 v[18:21], v155 offset:2048
	ds_read_b128 v[164:167], v155 offset:3072
	ds_read_b128 v[34:37], v145 offset:32768
	ds_read_b128 v[42:45], v145 offset:33792
	ds_read_b128 v[50:53], v144 offset:32768
	ds_read_b128 v[74:77], v144 offset:33792
	ds_read_b128 v[192:195], v143 offset:32768
	ds_read_b128 v[196:199], v143 offset:33792
	ds_read_b128 v[200:203], v142 offset:32768
	ds_read_b128 v[204:207], v142 offset:33792
	s_waitcnt vmcnt(2)
	s_barrier
; #define LDA(dst, b, hh) _Pragma("unroll") for (int m = 0; m < 4; ++m) _Pragma("unroll") for (int k = 0; k < 2; ++k) \
;         dst[m][k] = *(const bf16x8*)(SA(b, hh) + lds_byte(wr * 64 + m * 16 + fr, k * 32 + fq * 8))
; #define LDB(dst, b, hh) _Pragma("unroll") for (int n = 0; n < 2; ++n) _Pragma("unroll") for (int k = 0; k < 2; ++k) \
;         dst[n][k] = *(const bf16x8*)(SB(b, hh) + lds_byte(wc * 32 + n * 16 + fr, k * 32 + fq * 8))
; #define MMA(ai, bj, At_, Bt_) do { __builtin_amdgcn_s_setprio(1); \
;         _Pragma("unroll") for (int m = 0; m < 4; ++m) _Pragma("unroll") for (int n = 0; n < 2; ++n) _Pragma("unroll") for (int k = 0; k < 2; ++k) \
;             acc[ai][bj][m][n] = MFMA16(At_[m][k], Bt_[n][k], acc[ai][bj][m][n]); \
;         __builtin_amdgcn_s_setprio(0); } while (0)
; #define WAIT_V(n) asm volatile("s_waitcnt vmcnt(" #n ")" ::: "memory")
; #define WAIT_L(n) asm volatile("s_waitcnt lgkmcnt(" #n ")" ::: "memory")
; #define BAR __builtin_amdgcn_s_barrier()
; #define LDA(dst, b, hh) _Pragma("unroll") for (int m = 0; m < 4; ++m) _Pragma("unroll") for (int k = 0; k < 2; ++k) \
;         dst[m][k] = *(const bf16x8*)(SA(b, hh) + lds_byte(wr * 64 + m * 16 + fr, k * 32 + fq * 8))
; #define LDB(dst, b, hh) _Pragma("unroll") for (int n = 0; n < 2; ++n) _Pragma("unroll") for (int k = 0; k < 2; ++k) \
;         dst[n][k] = *(const bf16x8*)(SB(b, hh) + lds_byte(wc * 32 + n * 16 + fr, k * 32 + fq * 8))
; #define MMA(ai, bj, At_, Bt_) do { __builtin_amdgcn_s_setprio(1); \
;         _Pragma("unroll") for (int m = 0; m < 4; ++m) _Pragma("unroll") for (int n = 0; n < 2; ++n) _Pragma("unroll") for (int k = 0; k < 2; ++k) \
;             acc[ai][bj][m][n] = MFMA16(At_[m][k], Bt_[n][k], acc[ai][bj][m][n]); \
;         __builtin_amdgcn_s_setprio(0); } while (0)
; #define WAIT_V(n) asm volatile("s_waitcnt vmcnt(" #n ")" ::: "memory")
; #define WAIT_L(n) asm volatile("s_waitcnt lgkmcnt(" #n ")" ::: "memory")
; #define BAR __builtin_amdgcn_s_barrier()
; DI void gemm8(f32x4 (&acc)[2][2][4][2], const bf16_t* __restrict__ Rm, const bf16_t* __restrict__ Cm, int K, char* shm) {
;     ...
;     { LDB(B0, 1, 0); LDA(At, 1, 0); WAIT_V(2); BAR; WAIT_L(0); MMA(0, 0, At, B0); BAR;
;       LDB(B1, 1, 1); WAIT_V(0); BAR; WAIT_L(0); MMA(0, 1, At, B1); BAR;
;       LDA(At, 1, 1); BAR; WAIT_L(0); MMA(1, 0, At, B0); MMA(1, 1, At, B1); BAR; }
;     if (wr == 0) BAR;
	s_waitcnt lgkmcnt(0)
	s_setprio 1
	s_waitcnt lgkmcnt(0)
	v_mfma_f32_16x16x32_bf16 v[66:69], v[34:37], v[2:5], v[126:129]
	v_mfma_f32_16x16x32_bf16 v[114:117], v[42:45], v[10:13], v[66:69]
	v_mfma_f32_16x16x32_bf16 v[66:69], v[34:37], v[18:21], v[122:125]
	v_mfma_f32_16x16x32_bf16 v[98:101], v[42:45], v[164:167], v[66:69]
	v_mfma_f32_16x16x32_bf16 v[66:69], v[50:53], v[2:5], v[118:121]
	v_mfma_f32_16x16x32_bf16 v[122:125], v[74:77], v[10:13], v[66:69]
	v_mfma_f32_16x16x32_bf16 v[66:69], v[50:53], v[18:21], v[130:133]
	v_mfma_f32_16x16x32_bf16 v[106:109], v[74:77], v[164:167], v[66:69]
	v_mfma_f32_16x16x32_bf16 v[66:69], v[192:195], v[2:5], v[110:113]
	v_mfma_f32_16x16x32_bf16 v[126:129], v[196:199], v[10:13], v[66:69]
	v_mfma_f32_16x16x32_bf16 v[66:69], v[192:195], v[18:21], v[212:215]
	v_mfma_f32_16x16x32_bf16 v[110:113], v[196:199], v[164:167], v[66:69]
	v_mfma_f32_16x16x32_bf16 v[66:69], v[200:203], v[2:5], v[102:105]
	v_mfma_f32_16x16x32_bf16 v[118:121], v[204:207], v[10:13], v[66:69]
	v_mfma_f32_16x16x32_bf16 v[66:69], v[200:203], v[18:21], v[216:219]
	v_mfma_f32_16x16x32_bf16 v[102:105], v[204:207], v[164:167], v[66:69]
	s_setprio 0
	s_barrier
	ds_read_b128 v[130:133], v149
	ds_read_b128 v[208:211], v149 offset:1024
	ds_read_b128 v[212:215], v149 offset:2048
	ds_read_b128 v[146:149], v149 offset:3072
	s_waitcnt vmcnt(0)
	s_barrier
	s_waitcnt lgkmcnt(0)
	s_setprio 1
	s_waitcnt lgkmcnt(0)
	v_mfma_f32_16x16x32_bf16 v[66:69], v[34:37], v[130:133], v[94:97]
	v_mfma_f32_16x16x32_bf16 v[34:37], v[34:37], v[212:215], v[90:93]
	v_mfma_f32_16x16x32_bf16 v[82:85], v[42:45], v[208:211], v[66:69]
	v_mfma_f32_16x16x32_bf16 v[66:69], v[42:45], v[146:149], v[34:37]
	v_mfma_f32_16x16x32_bf16 v[34:37], v[50:53], v[130:133], v[86:89]
	v_mfma_f32_16x16x32_bf16 v[90:93], v[74:77], v[208:211], v[34:37]
	v_mfma_f32_16x16x32_bf16 v[34:37], v[50:53], v[212:215], v[168:171]
	v_mfma_f32_16x16x32_bf16 v[74:77], v[74:77], v[146:149], v[34:37]
	v_mfma_f32_16x16x32_bf16 v[34:37], v[192:195], v[130:133], v[78:81]
	v_mfma_f32_16x16x32_bf16 v[94:97], v[196:199], v[208:211], v[34:37]
	v_mfma_f32_16x16x32_bf16 v[34:37], v[192:195], v[212:215], v[184:187]
	v_mfma_f32_16x16x32_bf16 v[78:81], v[196:199], v[146:149], v[34:37]
	v_mfma_f32_16x16x32_bf16 v[34:37], v[200:203], v[130:133], v[70:73]
	v_mfma_f32_16x16x32_bf16 v[86:89], v[204:207], v[208:211], v[34:37]
	v_mfma_f32_16x16x32_bf16 v[34:37], v[200:203], v[212:215], v[188:191]
	v_mfma_f32_16x16x32_bf16 v[70:73], v[204:207], v[146:149], v[34:37]
	s_setprio 0
	s_barrier
	ds_read_b128 v[168:171], v145 offset:49152
	ds_read_b128 v[184:187], v145 offset:50176
	ds_read_b128 v[188:191], v144 offset:49152
	ds_read_b128 v[192:195], v144 offset:50176
	ds_read_b128 v[196:199], v143 offset:49152
	ds_read_b128 v[200:203], v143 offset:50176
	ds_read_b128 v[204:207], v142 offset:49152
	ds_read_b128 v[142:145], v142 offset:50176
	s_barrier
	s_waitcnt lgkmcnt(0)
	s_setprio 1
	s_waitcnt lgkmcnt(0)
	v_mfma_f32_16x16x32_bf16 v[34:37], v[168:171], v[2:5], v[62:65]
	v_mfma_f32_16x16x32_bf16 v[42:45], v[188:191], v[2:5], v[54:57]
	v_mfma_f32_16x16x32_bf16 v[46:49], v[196:199], v[2:5], v[46:49]
	v_mfma_f32_16x16x32_bf16 v[2:5], v[204:207], v[2:5], v[38:41]
	v_mfma_f32_16x16x32_bf16 v[50:53], v[184:187], v[10:13], v[34:37]
	v_mfma_f32_16x16x32_bf16 v[34:37], v[168:171], v[18:21], v[58:61]
	v_mfma_f32_16x16x32_bf16 v[58:61], v[192:195], v[10:13], v[42:45]
	v_mfma_f32_16x16x32_bf16 v[42:45], v[188:191], v[18:21], v[220:223]
	v_mfma_f32_16x16x32_bf16 v[62:65], v[200:203], v[10:13], v[46:49]
	v_mfma_f32_16x16x32_bf16 v[46:49], v[196:199], v[18:21], v[224:227]
	v_mfma_f32_16x16x32_bf16 v[54:57], v[142:145], v[10:13], v[2:5]
	v_mfma_f32_16x16x32_bf16 v[2:5], v[204:207], v[18:21], v[134:137]
	v_mfma_f32_16x16x32_bf16 v[34:37], v[184:187], v[164:167], v[34:37]
	v_mfma_f32_16x16x32_bf16 v[42:45], v[192:195], v[164:167], v[42:45]
	v_mfma_f32_16x16x32_bf16 v[46:49], v[200:203], v[164:167], v[46:49]
	v_mfma_f32_16x16x32_bf16 v[38:41], v[142:145], v[164:167], v[2:5]
	s_setprio 0
	s_setprio 1
	v_mfma_f32_16x16x32_bf16 v[2:5], v[168:171], v[130:133], v[30:33]
	v_mfma_f32_16x16x32_bf16 v[10:13], v[188:191], v[130:133], v[22:25]
	v_mfma_f32_16x16x32_bf16 v[14:17], v[196:199], v[130:133], v[14:17]
	v_mfma_f32_16x16x32_bf16 v[6:9], v[204:207], v[130:133], v[6:9]
	v_mfma_f32_16x16x32_bf16 v[18:21], v[184:187], v[208:211], v[2:5]
	v_mfma_f32_16x16x32_bf16 v[2:5], v[168:171], v[212:215], v[26:29]
	v_mfma_f32_16x16x32_bf16 v[26:29], v[192:195], v[208:211], v[10:13]
	v_mfma_f32_16x16x32_bf16 v[10:13], v[188:191], v[212:215], v[138:141]
	v_mfma_f32_16x16x32_bf16 v[30:33], v[200:203], v[208:211], v[14:17]
	v_mfma_f32_16x16x32_bf16 v[14:17], v[196:199], v[212:215], v[150:153]
	v_mfma_f32_16x16x32_bf16 v[22:25], v[142:145], v[208:211], v[6:9]
	v_mfma_f32_16x16x32_bf16 v[6:9], v[204:207], v[212:215], v[156:159]
	v_mfma_f32_16x16x32_bf16 v[2:5], v[184:187], v[146:149], v[2:5]
	v_mfma_f32_16x16x32_bf16 v[10:13], v[192:195], v[146:149], v[10:13]
	v_mfma_f32_16x16x32_bf16 v[14:17], v[200:203], v[146:149], v[14:17]
	v_mfma_f32_16x16x32_bf16 v[6:9], v[142:145], v[146:149], v[6:9]
	s_setprio 0
	v_cmp_gt_u32_e32 vcc, s96, v0
	s_barrier
	s_and_saveexec_b64 s[8:9], vcc
	s_cbranch_execz .LBB0_117
	s_barrier

; #define STAGE(P, BASE, br, kt) do { const bf16_t* g_ = (BASE) + (size_t)(br) * K + (size_t)(kt) * 64; \
;         _Pragma("unroll") for (int i_ = 0; i_ < 2; ++i_) \
;             __builtin_amdgcn_global_load_lds((const unsigned*)(g_ + gofs[i_]), (lds_ptr_t)((P) + wb + i_ * 8192), 16, 0, 0); } while (0)
; #define LDA(dst, b, hh) _Pragma("unroll") for (int m = 0; m < 4; ++m) _Pragma("unroll") for (int k = 0; k < 2; ++k) \
;         dst[m][k] = *(const bf16x8*)(SA(b, hh) + lds_byte(wr * 64 + m * 16 + fr, k * 32 + fq * 8))
; #define LDB(dst, b, hh) _Pragma("unroll") for (int n = 0; n < 2; ++n) _Pragma("unroll") for (int k = 0; k < 2; ++k) \
;         dst[n][k] = *(const bf16x8*)(SB(b, hh) + lds_byte(wc * 32 + n * 16 + fr, k * 32 + fq * 8))
; #define MMA(ai, bj, At_, Bt_) do { __builtin_amdgcn_s_setprio(1); \
;         _Pragma("unroll") for (int m = 0; m < 4; ++m) _Pragma("unroll") for (int n = 0; n < 2; ++n) _Pragma("unroll") for (int k = 0; k < 2; ++k) \
;             acc[ai][bj][m][n] = MFMA16(At_[m][k], Bt_[n][k], acc[ai][bj][m][n]); \
;         __builtin_amdgcn_s_setprio(0); } while (0)
; #define WAIT_L(n) asm volatile("s_waitcnt lgkmcnt(" #n ")" ::: "memory")
; #define BAR __builtin_amdgcn_s_barrier()
; #define SCHED __builtin_amdgcn_sched_barrier(0)
; #define STAGE(P, BASE, br, kt) do { const int sg_ = (kt) >> 3; const bf16_t* g_ = (sg_ == 0 ? BASE##0 : sg_ == 1 ? BASE##1 : BASE##2) + (size_t)(br) * K + (size_t)((kt) & 7) * 64; \
;         _Pragma("unroll") for (int i_ = 0; i_ < 2; ++i_) \
;             __builtin_amdgcn_global_load_lds((const unsigned*)(g_ + gofs[i_]), (lds_ptr_t)((P) + wb + i_ * 8192), 16, 0, 0); } while (0)
; #define WAIT_L(n) asm volatile("s_waitcnt lgkmcnt(" #n ")" ::: "memory")
; #define BAR __builtin_amdgcn_s_barrier()
; #define SCHED __builtin_amdgcn_sched_barrier(0)
; DI void gemm8(f32x4 (&acc)[2][2][4][2], const bf16_t* __restrict__ Rm, const bf16_t* __restrict__ Cm, int K, char* shm) {
;     ...
;     for (int tt = 0; tt < nt - 2; tt += 2) {
;         LDB(B0, 0, 0); SCHED; LDA(At, 0, 0); STAGE(SA(1, 1), Rm, 128, tt + 1);
;         WAIT_L(8); BAR; WAIT_L(0); MMA(0, 0, At, B0); BAR; SCHED;
;         LDB(B1, 0, 1); STAGE(SB(0, 0), Cm, 0, tt + 2);
;         BAR; WAIT_L(0); MMA(0, 1, At, B1); BAR;
;         LDA(At, 0, 1); STAGE(SA(0, 0), Rm, 0, tt + 2);
;         BAR; WAIT_L(0); MMA(1, 0, At, B0); BAR; SCHED;
.LBB0_178:
	v_add_u32_e32 v166, 0xc000, v146
	v_lshl_add_u64 v[172:173], s[62:63], 0, v[138:139]
	v_readfirstlane_b32 s3, v166
	v_add_u32_e32 v167, 0xe000, v146
	v_lshl_add_u64 v[228:229], v[172:173], 0, s[8:9]
	s_mov_b32 m0, s3
	v_lshl_add_u64 v[244:245], s[62:63], 0, v[140:141]
	v_readfirstlane_b32 s3, v167
	global_load_lds_dwordx4 v[228:229], off
	v_lshl_add_u64 v[228:229], v[244:245], 0, s[8:9]
	s_mov_b32 m0, s3
	s_nop 0
	global_load_lds_dwordx4 v[228:229], off
	ds_read_b128 v[168:171], v165
	ds_read_b128 v[184:187], v165 offset:1024
	ds_read_b128 v[188:191], v165 offset:2048
	ds_read_b128 v[192:195], v165 offset:3072
	ds_read_b128 v[196:199], v145
	ds_read_b128 v[200:203], v145 offset:1024
	ds_read_b128 v[204:207], v144
	ds_read_b128 v[208:211], v144 offset:1024
	ds_read_b128 v[212:215], v143
	ds_read_b128 v[216:219], v143 offset:1024
	ds_read_b128 v[220:223], v142
	ds_read_b128 v[224:227], v142 offset:1024
	s_waitcnt lgkmcnt(8)
	s_barrier
	s_waitcnt lgkmcnt(0)
	s_setprio 1
	s_waitcnt lgkmcnt(0)
	v_mfma_f32_16x16x32_bf16 v[126:129], v[196:199], v[168:171], v[126:129]
	v_mfma_f32_16x16x32_bf16 v[122:125], v[196:199], v[188:191], v[122:125]
	v_mfma_f32_16x16x32_bf16 v[118:121], v[204:207], v[168:171], v[118:121]
	v_mfma_f32_16x16x32_bf16 v[114:117], v[204:207], v[188:191], v[114:117]
	v_mfma_f32_16x16x32_bf16 v[110:113], v[212:215], v[168:171], v[110:113]
	v_mfma_f32_16x16x32_bf16 v[106:109], v[212:215], v[188:191], v[106:109]
	v_mfma_f32_16x16x32_bf16 v[102:105], v[220:223], v[168:171], v[102:105]
	v_mfma_f32_16x16x32_bf16 v[98:101], v[220:223], v[188:191], v[98:101]
	v_mfma_f32_16x16x32_bf16 v[126:129], v[200:203], v[184:187], v[126:129]
	v_mfma_f32_16x16x32_bf16 v[122:125], v[200:203], v[192:195], v[122:125]
	v_mfma_f32_16x16x32_bf16 v[118:121], v[208:211], v[184:187], v[118:121]
	v_mfma_f32_16x16x32_bf16 v[114:117], v[208:211], v[192:195], v[114:117]
	v_mfma_f32_16x16x32_bf16 v[110:113], v[216:219], v[184:187], v[110:113]
	v_mfma_f32_16x16x32_bf16 v[106:109], v[216:219], v[192:195], v[106:109]
	v_mfma_f32_16x16x32_bf16 v[102:105], v[224:227], v[184:187], v[102:105]
	v_mfma_f32_16x16x32_bf16 v[98:101], v[224:227], v[192:195], v[98:101]
	s_setprio 0
	s_barrier
	v_lshl_add_u64 v[246:247], s[62:63], 0, v[134:135]
	v_readfirstlane_b32 s3, v147
	v_lshl_add_u64 v[248:249], v[246:247], 0, s[90:91]
	s_mov_b32 m0, s3
	s_nop 0
	global_load_lds_dwordx4 v[248:249], off
	v_lshl_add_u64 v[248:249], s[62:63], 0, v[136:137]
	v_readfirstlane_b32 s3, v148
	v_lshl_add_u64 v[250:251], v[248:249], 0, s[90:91]
	s_mov_b32 m0, s3
	s_nop 0
	global_load_lds_dwordx4 v[250:251], off
	ds_read_b128 v[228:231], v164
	ds_read_b128 v[232:235], v164 offset:1024
	ds_read_b128 v[236:239], v164 offset:2048
	ds_read_b128 v[240:243], v164 offset:3072
	s_barrier
	s_waitcnt lgkmcnt(0)
	s_setprio 1
	s_waitcnt lgkmcnt(0)
	v_mfma_f32_16x16x32_bf16 v[94:97], v[196:199], v[228:231], v[94:97]
	v_mfma_f32_16x16x32_bf16 v[90:93], v[196:199], v[236:239], v[90:93]
	v_mfma_f32_16x16x32_bf16 v[86:89], v[204:207], v[228:231], v[86:89]
	v_mfma_f32_16x16x32_bf16 v[82:85], v[204:207], v[236:239], v[82:85]
	v_mfma_f32_16x16x32_bf16 v[78:81], v[212:215], v[228:231], v[78:81]
	v_mfma_f32_16x16x32_bf16 v[74:77], v[212:215], v[236:239], v[74:77]
	v_mfma_f32_16x16x32_bf16 v[70:73], v[220:223], v[228:231], v[70:73]
	v_mfma_f32_16x16x32_bf16 v[66:69], v[220:223], v[236:239], v[66:69]
	v_mfma_f32_16x16x32_bf16 v[94:97], v[200:203], v[232:235], v[94:97]
	v_mfma_f32_16x16x32_bf16 v[90:93], v[200:203], v[240:243], v[90:93]
	v_mfma_f32_16x16x32_bf16 v[86:89], v[208:211], v[232:235], v[86:89]
	v_mfma_f32_16x16x32_bf16 v[82:85], v[208:211], v[240:243], v[82:85]
	v_mfma_f32_16x16x32_bf16 v[78:81], v[216:219], v[232:235], v[78:81]
	v_mfma_f32_16x16x32_bf16 v[74:77], v[216:219], v[240:243], v[74:77]
	v_mfma_f32_16x16x32_bf16 v[70:73], v[224:227], v[232:235], v[70:73]
	v_mfma_f32_16x16x32_bf16 v[66:69], v[224:227], v[240:243], v[66:69]
	s_setprio 0
	v_readfirstlane_b32 s3, v146
	v_lshl_add_u64 v[250:251], v[172:173], 0, s[10:11]
	s_mov_b32 m0, s3
	v_readfirstlane_b32 s3, v150
	s_barrier
	global_load_lds_dwordx4 v[250:251], off
	v_lshl_add_u64 v[250:251], v[244:245], 0, s[10:11]
	s_mov_b32 m0, s3
	s_nop 0
	global_load_lds_dwordx4 v[250:251], off
	ds_read_b128 v[196:199], v145 offset:16384
	ds_read_b128 v[200:203], v145 offset:17408
	ds_read_b128 v[204:207], v144 offset:16384
	ds_read_b128 v[208:211], v144 offset:17408
	ds_read_b128 v[212:215], v143 offset:16384
	ds_read_b128 v[216:219], v143 offset:17408
	ds_read_b128 v[220:223], v142 offset:16384
	ds_read_b128 v[224:227], v142 offset:17408
	s_barrier
	s_waitcnt lgkmcnt(0)
	s_setprio 1
	s_waitcnt lgkmcnt(0)
	v_mfma_f32_16x16x32_bf16 v[62:65], v[196:199], v[168:171], v[62:65]
	v_mfma_f32_16x16x32_bf16 v[58:61], v[196:199], v[188:191], v[58:61]
	v_mfma_f32_16x16x32_bf16 v[54:57], v[204:207], v[168:171], v[54:57]
	v_mfma_f32_16x16x32_bf16 v[50:53], v[204:207], v[188:191], v[50:53]
	v_mfma_f32_16x16x32_bf16 v[46:49], v[212:215], v[168:171], v[46:49]
	v_mfma_f32_16x16x32_bf16 v[42:45], v[212:215], v[188:191], v[42:45]
	v_mfma_f32_16x16x32_bf16 v[38:41], v[220:223], v[168:171], v[38:41]
	v_mfma_f32_16x16x32_bf16 v[34:37], v[220:223], v[188:191], v[34:37]
	v_mfma_f32_16x16x32_bf16 v[62:65], v[200:203], v[184:187], v[62:65]
	v_mfma_f32_16x16x32_bf16 v[58:61], v[200:203], v[192:195], v[58:61]
	v_mfma_f32_16x16x32_bf16 v[54:57], v[208:211], v[184:187], v[54:57]
	v_mfma_f32_16x16x32_bf16 v[50:53], v[208:211], v[192:195], v[50:53]
	v_mfma_f32_16x16x32_bf16 v[46:49], v[216:219], v[184:187], v[46:49]
	v_mfma_f32_16x16x32_bf16 v[42:45], v[216:219], v[192:195], v[42:45]
	v_mfma_f32_16x16x32_bf16 v[38:41], v[224:227], v[184:187], v[38:41]
	v_mfma_f32_16x16x32_bf16 v[34:37], v[224:227], v[192:195], v[34:37]
	s_setprio 0
	s_barrier
; #define STAGE(P, BASE, br, kt) do { const bf16_t* g_ = (BASE) + (size_t)(br) * K + (size_t)(kt) * 64; \
;         _Pragma("unroll") for (int i_ = 0; i_ < 2; ++i_) \
;             __builtin_amdgcn_global_load_lds((const unsigned*)(g_ + gofs[i_]), (lds_ptr_t)((P) + wb + i_ * 8192), 16, 0, 0); } while (0)
; #define LDA(dst, b, hh) _Pragma("unroll") for (int m = 0; m < 4; ++m) _Pragma("unroll") for (int k = 0; k < 2; ++k) \
;         dst[m][k] = *(const bf16x8*)(SA(b, hh) + lds_byte(wr * 64 + m * 16 + fr, k * 32 + fq * 8))
; #define LDB(dst, b, hh) _Pragma("unroll") for (int n = 0; n < 2; ++n) _Pragma("unroll") for (int k = 0; k < 2; ++k) \
;         dst[n][k] = *(const bf16x8*)(SB(b, hh) + lds_byte(wc * 32 + n * 16 + fr, k * 32 + fq * 8))
; #define MMA(ai, bj, At_, Bt_) do { __builtin_amdgcn_s_setprio(1); \
;         _Pragma("unroll") for (int m = 0; m < 4; ++m) _Pragma("unroll") for (int n = 0; n < 2; ++n) _Pragma("unroll") for (int k = 0; k < 2; ++k) \
;             acc[ai][bj][m][n] = MFMA16(At_[m][k], Bt_[n][k], acc[ai][bj][m][n]); \
;         __builtin_amdgcn_s_setprio(0); } while (0)
; #define WAIT_V(n) asm volatile("s_waitcnt vmcnt(" #n ")" ::: "memory")
; #define WAIT_L(n) asm volatile("s_waitcnt lgkmcnt(" #n ")" ::: "memory")
; #define BAR __builtin_amdgcn_s_barrier()
; #define SCHED __builtin_amdgcn_sched_barrier(0)
; #define STAGE(P, BASE, br, kt) do { const int sg_ = (kt) >> 3; const bf16_t* g_ = (sg_ == 0 ? BASE##0 : sg_ == 1 ? BASE##1 : BASE##2) + (size_t)(br) * K + (size_t)((kt) & 7) * 64; \
;         _Pragma("unroll") for (int i_ = 0; i_ < 2; ++i_) \
;             __builtin_amdgcn_global_load_lds((const unsigned*)(g_ + gofs[i_]), (lds_ptr_t)((P) + wb + i_ * 8192), 16, 0, 0); } while (0)
; DI void gemm8(f32x4 (&acc)[2][2][4][2], const bf16_t* __restrict__ Rm, const bf16_t* __restrict__ Cm, int K, char* shm) {
;     ...
;         BAR; WAIT_L(0); MMA(1, 0, At, B0); BAR; SCHED;
;         STAGE(SB(0, 1), Cm, 128, tt + 2);
;         WAIT_V(6); BAR; MMA(1, 1, At, B1); BAR;
;         LDB(B0, 1, 0); SCHED; LDA(At, 1, 0); STAGE(SA(0, 1), Rm, 128, tt + 2);
;         WAIT_L(8); BAR; WAIT_L(0); MMA(0, 0, At, B0); BAR; SCHED;
;         LDB(B1, 1, 1); STAGE(SB(1, 0), Cm, 0, tt + 3);
;         BAR; WAIT_L(0); MMA(0, 1, At, B1); BAR;
;         LDA(At, 1, 1); STAGE(SA(1, 0), Rm, 0, tt + 3);
;         BAR; WAIT_L(0); MMA(1, 0, At, B0); BAR; SCHED;
	v_readfirstlane_b32 s3, v151
	v_lshl_add_u64 v[168:169], v[246:247], 0, s[76:77]
	s_mov_b32 m0, s3
	v_readfirstlane_b32 s3, v152
	global_load_lds_dwordx4 v[168:169], off
	v_lshl_add_u64 v[168:169], v[248:249], 0, s[76:77]
	s_mov_b32 m0, s3
	s_nop 0
	global_load_lds_dwordx4 v[168:169], off
	s_waitcnt vmcnt(6)
	s_barrier
	s_setprio 1
	v_mfma_f32_16x16x32_bf16 v[30:33], v[196:199], v[228:231], v[30:33]
	v_mfma_f32_16x16x32_bf16 v[26:29], v[196:199], v[236:239], v[26:29]
	v_mfma_f32_16x16x32_bf16 v[22:25], v[204:207], v[228:231], v[22:25]
	v_mfma_f32_16x16x32_bf16 v[18:21], v[204:207], v[236:239], v[18:21]
	v_mfma_f32_16x16x32_bf16 v[14:17], v[212:215], v[228:231], v[14:17]
	v_mfma_f32_16x16x32_bf16 v[10:13], v[212:215], v[236:239], v[10:13]
	v_mfma_f32_16x16x32_bf16 v[6:9], v[220:223], v[228:231], v[6:9]
	v_mfma_f32_16x16x32_bf16 v[2:5], v[220:223], v[236:239], v[2:5]
	v_mfma_f32_16x16x32_bf16 v[30:33], v[200:203], v[232:235], v[30:33]
	v_mfma_f32_16x16x32_bf16 v[26:29], v[200:203], v[240:243], v[26:29]
	v_mfma_f32_16x16x32_bf16 v[22:25], v[208:211], v[232:235], v[22:25]
	v_mfma_f32_16x16x32_bf16 v[18:21], v[208:211], v[240:243], v[18:21]
	v_mfma_f32_16x16x32_bf16 v[14:17], v[216:219], v[232:235], v[14:17]
	v_mfma_f32_16x16x32_bf16 v[10:13], v[216:219], v[240:243], v[10:13]
	v_mfma_f32_16x16x32_bf16 v[6:9], v[224:227], v[232:235], v[6:9]
	v_mfma_f32_16x16x32_bf16 v[2:5], v[224:227], v[240:243], v[2:5]
	s_setprio 0
	s_barrier
	v_readfirstlane_b32 s3, v153
	v_lshl_add_u64 v[228:229], v[172:173], 0, s[12:13]
	s_mov_b32 m0, s3
	v_readfirstlane_b32 s3, v155
	global_load_lds_dwordx4 v[228:229], off
	v_lshl_add_u64 v[228:229], v[244:245], 0, s[12:13]
	s_mov_b32 m0, s3
	s_nop 0
	global_load_lds_dwordx4 v[228:229], off
	ds_read_b128 v[168:171], v154
	ds_read_b128 v[184:187], v154 offset:1024
	ds_read_b128 v[188:191], v154 offset:2048
	ds_read_b128 v[192:195], v154 offset:3072
	ds_read_b128 v[196:199], v145 offset:32768
	ds_read_b128 v[200:203], v145 offset:33792
	ds_read_b128 v[204:207], v144 offset:32768
	ds_read_b128 v[208:211], v144 offset:33792
	ds_read_b128 v[212:215], v143 offset:32768
	ds_read_b128 v[216:219], v143 offset:33792
	ds_read_b128 v[220:223], v142 offset:32768
	ds_read_b128 v[224:227], v142 offset:33792
	s_waitcnt lgkmcnt(8)
	s_barrier
	s_waitcnt lgkmcnt(0)
	s_setprio 1
	s_waitcnt lgkmcnt(0)
	v_mfma_f32_16x16x32_bf16 v[126:129], v[196:199], v[168:171], v[126:129]
	v_mfma_f32_16x16x32_bf16 v[122:125], v[196:199], v[188:191], v[122:125]
	v_mfma_f32_16x16x32_bf16 v[118:121], v[204:207], v[168:171], v[118:121]
	v_mfma_f32_16x16x32_bf16 v[114:117], v[204:207], v[188:191], v[114:117]
	v_mfma_f32_16x16x32_bf16 v[110:113], v[212:215], v[168:171], v[110:113]
	v_mfma_f32_16x16x32_bf16 v[106:109], v[212:215], v[188:191], v[106:109]
	v_mfma_f32_16x16x32_bf16 v[102:105], v[220:223], v[168:171], v[102:105]
	v_mfma_f32_16x16x32_bf16 v[98:101], v[220:223], v[188:191], v[98:101]
	v_mfma_f32_16x16x32_bf16 v[126:129], v[200:203], v[184:187], v[126:129]
	v_mfma_f32_16x16x32_bf16 v[122:125], v[200:203], v[192:195], v[122:125]
	v_mfma_f32_16x16x32_bf16 v[118:121], v[208:211], v[184:187], v[118:121]
	v_mfma_f32_16x16x32_bf16 v[114:117], v[208:211], v[192:195], v[114:117]
	v_mfma_f32_16x16x32_bf16 v[110:113], v[216:219], v[184:187], v[110:113]
	v_mfma_f32_16x16x32_bf16 v[106:109], v[216:219], v[192:195], v[106:109]
	v_mfma_f32_16x16x32_bf16 v[102:105], v[224:227], v[184:187], v[102:105]
	v_mfma_f32_16x16x32_bf16 v[98:101], v[224:227], v[192:195], v[98:101]
	s_setprio 0
	s_barrier
	v_readfirstlane_b32 s3, v156
	v_lshl_add_u64 v[250:251], v[246:247], 0, s[72:73]
	s_mov_b32 m0, s3
	v_readfirstlane_b32 s3, v157
	global_load_lds_dwordx4 v[250:251], off
	v_lshl_add_u64 v[250:251], v[248:249], 0, s[72:73]
	s_mov_b32 m0, s3
	s_nop 0
	global_load_lds_dwordx4 v[250:251], off
	ds_read_b128 v[228:231], v149
	ds_read_b128 v[232:235], v149 offset:1024
	ds_read_b128 v[236:239], v149 offset:2048
	ds_read_b128 v[240:243], v149 offset:3072
	s_barrier
	s_waitcnt lgkmcnt(0)
	s_setprio 1
	s_waitcnt lgkmcnt(0)
	v_mfma_f32_16x16x32_bf16 v[94:97], v[196:199], v[228:231], v[94:97]
	v_mfma_f32_16x16x32_bf16 v[90:93], v[196:199], v[236:239], v[90:93]
	v_mfma_f32_16x16x32_bf16 v[86:89], v[204:207], v[228:231], v[86:89]
	v_mfma_f32_16x16x32_bf16 v[82:85], v[204:207], v[236:239], v[82:85]
	v_mfma_f32_16x16x32_bf16 v[78:81], v[212:215], v[228:231], v[78:81]
	v_mfma_f32_16x16x32_bf16 v[74:77], v[212:215], v[236:239], v[74:77]
	v_mfma_f32_16x16x32_bf16 v[70:73], v[220:223], v[228:231], v[70:73]
	v_mfma_f32_16x16x32_bf16 v[66:69], v[220:223], v[236:239], v[66:69]
	v_mfma_f32_16x16x32_bf16 v[94:97], v[200:203], v[232:235], v[94:97]
	v_mfma_f32_16x16x32_bf16 v[90:93], v[200:203], v[240:243], v[90:93]
	v_mfma_f32_16x16x32_bf16 v[86:89], v[208:211], v[232:235], v[86:89]
	v_mfma_f32_16x16x32_bf16 v[82:85], v[208:211], v[240:243], v[82:85]
	v_mfma_f32_16x16x32_bf16 v[78:81], v[216:219], v[232:235], v[78:81]
	v_mfma_f32_16x16x32_bf16 v[74:77], v[216:219], v[240:243], v[74:77]
	v_mfma_f32_16x16x32_bf16 v[70:73], v[224:227], v[232:235], v[70:73]
	v_mfma_f32_16x16x32_bf16 v[66:69], v[224:227], v[240:243], v[66:69]
	s_setprio 0
	v_readfirstlane_b32 s3, v158
	v_lshl_add_u64 v[172:173], v[172:173], 0, s[16:17]
	s_mov_b32 m0, s3
	v_readfirstlane_b32 s3, v159
	s_barrier
	global_load_lds_dwordx4 v[172:173], off
	v_lshl_add_u64 v[172:173], v[244:245], 0, s[16:17]
	s_mov_b32 m0, s3
	s_nop 0
	global_load_lds_dwordx4 v[172:173], off
	ds_read_b128 v[196:199], v145 offset:49152
	ds_read_b128 v[200:203], v145 offset:50176
	ds_read_b128 v[204:207], v144 offset:49152
	ds_read_b128 v[208:211], v144 offset:50176
	ds_read_b128 v[212:215], v143 offset:49152
	ds_read_b128 v[216:219], v143 offset:50176
	ds_read_b128 v[220:223], v142 offset:49152
	ds_read_b128 v[224:227], v142 offset:50176
	s_barrier
; #define STAGE(P, BASE, br, kt) do { const bf16_t* g_ = (BASE) + (size_t)(br) * K + (size_t)(kt) * 64; \
;         _Pragma("unroll") for (int i_ = 0; i_ < 2; ++i_) \
;             __builtin_amdgcn_global_load_lds((const unsigned*)(g_ + gofs[i_]), (lds_ptr_t)((P) + wb + i_ * 8192), 16, 0, 0); } while (0)
; #define LDA(dst, b, hh) _Pragma("unroll") for (int m = 0; m < 4; ++m) _Pragma("unroll") for (int k = 0; k < 2; ++k) \
;         dst[m][k] = *(const bf16x8*)(SA(b, hh) + lds_byte(wr * 64 + m * 16 + fr, k * 32 + fq * 8))
; #define LDB(dst, b, hh) _Pragma("unroll") for (int n = 0; n < 2; ++n) _Pragma("unroll") for (int k = 0; k < 2; ++k) \
;         dst[n][k] = *(const bf16x8*)(SB(b, hh) + lds_byte(wc * 32 + n * 16 + fr, k * 32 + fq * 8))
; #define MMA(ai, bj, At_, Bt_) do { __builtin_amdgcn_s_setprio(1); \
;         _Pragma("unroll") for (int m = 0; m < 4; ++m) _Pragma("unroll") for (int n = 0; n < 2; ++n) _Pragma("unroll") for (int k = 0; k < 2; ++k) \
;             acc[ai][bj][m][n] = MFMA16(At_[m][k], Bt_[n][k], acc[ai][bj][m][n]); \
;         __builtin_amdgcn_s_setprio(0); } while (0)
; #define WAIT_V(n) asm volatile("s_waitcnt vmcnt(" #n ")" ::: "memory")
; #define WAIT_L(n) asm volatile("s_waitcnt lgkmcnt(" #n ")" ::: "memory")
; #define BAR __builtin_amdgcn_s_barrier()
; #define SCHED __builtin_amdgcn_sched_barrier(0)
; #define STAGE(P, BASE, br, kt) do { const int sg_ = (kt) >> 3; const bf16_t* g_ = (sg_ == 0 ? BASE##0 : sg_ == 1 ? BASE##1 : BASE##2) + (size_t)(br) * K + (size_t)((kt) & 7) * 64; \
;         _Pragma("unroll") for (int i_ = 0; i_ < 2; ++i_) \
;             __builtin_amdgcn_global_load_lds((const unsigned*)(g_ + gofs[i_]), (lds_ptr_t)((P) + wb + i_ * 8192), 16, 0, 0); } while (0)
; #define LDA(dst, b, hh) _Pragma("unroll") for (int m = 0; m < 4; ++m) _Pragma("unroll") for (int k = 0; k < 2; ++k) \
;         dst[m][k] = *(const bf16x8*)(SA(b, hh) + lds_byte(wr * 64 + m * 16 + fr, k * 32 + fq * 8))
; #define BAR __builtin_amdgcn_s_barrier()
; DI void gemm8(f32x4 (&acc)[2][2][4][2], const bf16_t* __restrict__ Rm, const bf16_t* __restrict__ Cm, int K, char* shm) {
;     ...
;         BAR; WAIT_L(0); MMA(1, 0, At, B0); BAR; SCHED;
;         STAGE(SB(1, 1), Cm, 128, tt + 3);
;         WAIT_V(6); BAR; MMA(1, 1, At, B1); BAR;
;     }
;     { LDB(B0, 0, 0); LDA(At, 0, 0); STAGE(SA(1, 1), Rm, 128, nt - 1);
;       BAR; WAIT_L(0); MMA(0, 0, At, B0); BAR;
	s_waitcnt lgkmcnt(0)
	s_setprio 1
	s_waitcnt lgkmcnt(0)
	v_mfma_f32_16x16x32_bf16 v[62:65], v[196:199], v[168:171], v[62:65]
	v_mfma_f32_16x16x32_bf16 v[58:61], v[196:199], v[188:191], v[58:61]
	v_mfma_f32_16x16x32_bf16 v[54:57], v[204:207], v[168:171], v[54:57]
	v_mfma_f32_16x16x32_bf16 v[50:53], v[204:207], v[188:191], v[50:53]
	v_mfma_f32_16x16x32_bf16 v[46:49], v[212:215], v[168:171], v[46:49]
	v_mfma_f32_16x16x32_bf16 v[42:45], v[212:215], v[188:191], v[42:45]
	v_mfma_f32_16x16x32_bf16 v[38:41], v[220:223], v[168:171], v[38:41]
	v_mfma_f32_16x16x32_bf16 v[34:37], v[220:223], v[188:191], v[34:37]
	v_mfma_f32_16x16x32_bf16 v[62:65], v[200:203], v[184:187], v[62:65]
	v_mfma_f32_16x16x32_bf16 v[58:61], v[200:203], v[192:195], v[58:61]
	v_mfma_f32_16x16x32_bf16 v[54:57], v[208:211], v[184:187], v[54:57]
	v_mfma_f32_16x16x32_bf16 v[50:53], v[208:211], v[192:195], v[50:53]
	v_mfma_f32_16x16x32_bf16 v[46:49], v[216:219], v[184:187], v[46:49]
	v_mfma_f32_16x16x32_bf16 v[42:45], v[216:219], v[192:195], v[42:45]
	v_mfma_f32_16x16x32_bf16 v[38:41], v[224:227], v[184:187], v[38:41]
	v_mfma_f32_16x16x32_bf16 v[34:37], v[224:227], v[192:195], v[34:37]
	s_setprio 0
	s_barrier
	v_readfirstlane_b32 s3, v160
	v_lshl_add_u64 v[168:169], v[246:247], 0, s[88:89]
	s_mov_b32 m0, s3
	v_readfirstlane_b32 s3, v161
	global_load_lds_dwordx4 v[168:169], off
	v_lshl_add_u64 v[168:169], v[248:249], 0, s[88:89]
	s_mov_b32 m0, s3
	s_nop 0
	global_load_lds_dwordx4 v[168:169], off
	s_waitcnt vmcnt(6)
	s_barrier
	s_setprio 1
	v_mfma_f32_16x16x32_bf16 v[30:33], v[196:199], v[228:231], v[30:33]
	v_mfma_f32_16x16x32_bf16 v[26:29], v[196:199], v[236:239], v[26:29]
	v_mfma_f32_16x16x32_bf16 v[22:25], v[204:207], v[228:231], v[22:25]
	v_mfma_f32_16x16x32_bf16 v[18:21], v[204:207], v[236:239], v[18:21]
	v_mfma_f32_16x16x32_bf16 v[14:17], v[212:215], v[228:231], v[14:17]
	v_mfma_f32_16x16x32_bf16 v[10:13], v[212:215], v[236:239], v[10:13]
	v_mfma_f32_16x16x32_bf16 v[6:9], v[220:223], v[228:231], v[6:9]
	v_mfma_f32_16x16x32_bf16 v[2:5], v[220:223], v[236:239], v[2:5]
	v_mfma_f32_16x16x32_bf16 v[30:33], v[200:203], v[232:235], v[30:33]
	v_mfma_f32_16x16x32_bf16 v[26:29], v[200:203], v[240:243], v[26:29]
	v_mfma_f32_16x16x32_bf16 v[22:25], v[208:211], v[232:235], v[22:25]
	v_mfma_f32_16x16x32_bf16 v[18:21], v[208:211], v[240:243], v[18:21]
	v_mfma_f32_16x16x32_bf16 v[14:17], v[216:219], v[232:235], v[14:17]
	v_mfma_f32_16x16x32_bf16 v[10:13], v[216:219], v[240:243], v[10:13]
	v_mfma_f32_16x16x32_bf16 v[6:9], v[224:227], v[232:235], v[6:9]
	v_mfma_f32_16x16x32_bf16 v[2:5], v[224:227], v[240:243], v[2:5]
	s_setprio 0
	s_add_i32 s2, s2, 2
	v_lshl_add_u64 v[134:135], v[134:135], 0, s[90:91]
	v_lshl_add_u64 v[136:137], v[136:137], 0, s[90:91]
	v_lshl_add_u64 v[138:139], v[138:139], 0, s[90:91]
	s_cmp_lt_u32 s2, 12
	v_lshl_add_u64 v[140:141], v[140:141], 0, s[90:91]
	s_barrier
	s_cbranch_scc1 .LBB0_178
	s_add_u32 s2, s6, 0x40780
	s_addc_u32 s3, s7, 0
	v_readfirstlane_b32 s6, v166
	v_lshl_add_u64 v[130:131], v[130:131], 1, s[2:3]
	s_mov_b32 m0, s6
	ds_read_b128 v[134:137], v165
	ds_read_b128 v[138:141], v165 offset:1024
	ds_read_b128 v[150:153], v165 offset:2048
	ds_read_b128 v[156:159], v165 offset:3072
	ds_read_b128 v[168:171], v145
	ds_read_b128 v[184:187], v145 offset:1024
	ds_read_b128 v[188:191], v144
	ds_read_b128 v[192:195], v144 offset:1024
	ds_read_b128 v[196:199], v143
	ds_read_b128 v[200:203], v143 offset:1024
	ds_read_b128 v[204:207], v142
	ds_read_b128 v[208:211], v142 offset:1024
	global_load_lds_dwordx4 v[130:131], off
	v_lshl_add_u64 v[130:131], v[132:133], 1, s[2:3]
	v_readfirstlane_b32 s2, v167
	s_mov_b32 m0, s2
	s_nop 0
	global_load_lds_dwordx4 v[130:131], off
	s_barrier
	s_waitcnt lgkmcnt(0)
	s_setprio 1
	s_waitcnt lgkmcnt(0)
	v_mfma_f32_16x16x32_bf16 v[126:129], v[168:171], v[134:137], v[126:129]
	v_mfma_f32_16x16x32_bf16 v[122:125], v[168:171], v[150:153], v[122:125]
	v_mfma_f32_16x16x32_bf16 v[118:121], v[188:191], v[134:137], v[118:121]
	v_mfma_f32_16x16x32_bf16 v[114:117], v[188:191], v[150:153], v[114:117]
	v_mfma_f32_16x16x32_bf16 v[110:113], v[196:199], v[134:137], v[110:113]
	v_mfma_f32_16x16x32_bf16 v[126:129], v[184:187], v[138:141], v[126:129]
	v_mfma_f32_16x16x32_bf16 v[122:125], v[184:187], v[156:159], v[122:125]
	v_mfma_f32_16x16x32_bf16 v[118:121], v[192:195], v[138:141], v[118:121]
	v_mfma_f32_16x16x32_bf16 v[114:117], v[192:195], v[156:159], v[114:117]
	v_mfma_f32_16x16x32_bf16 v[110:113], v[200:203], v[138:141], v[110:113]
	v_mfma_f32_16x16x32_bf16 v[106:109], v[196:199], v[150:153], v[106:109]
	v_mfma_f32_16x16x32_bf16 v[102:105], v[204:207], v[134:137], v[102:105]
	v_mfma_f32_16x16x32_bf16 v[98:101], v[204:207], v[150:153], v[98:101]
	v_mfma_f32_16x16x32_bf16 v[130:133], v[200:203], v[156:159], v[106:109]
	v_mfma_f32_16x16x32_bf16 v[212:215], v[208:211], v[138:141], v[102:105]
	v_mfma_f32_16x16x32_bf16 v[216:219], v[208:211], v[156:159], v[98:101]
	s_setprio 0
	s_barrier
	s_nop 2
	ds_read_b128 v[98:101], v164
	ds_read_b128 v[102:105], v164 offset:1024
	ds_read_b128 v[106:109], v164 offset:2048
	ds_read_b128 v[164:167], v164 offset:3072
	s_barrier
; #define LDA(dst, b, hh) _Pragma("unroll") for (int m = 0; m < 4; ++m) _Pragma("unroll") for (int k = 0; k < 2; ++k) \
;         dst[m][k] = *(const bf16x8*)(SA(b, hh) + lds_byte(wr * 64 + m * 16 + fr, k * 32 + fq * 8))
; #define LDB(dst, b, hh) _Pragma("unroll") for (int n = 0; n < 2; ++n) _Pragma("unroll") for (int k = 0; k < 2; ++k) \
;         dst[n][k] = *(const bf16x8*)(SB(b, hh) + lds_byte(wc * 32 + n * 16 + fr, k * 32 + fq * 8))
; #define MMA(ai, bj, At_, Bt_) do { __builtin_amdgcn_s_setprio(1); \
;         _Pragma("unroll") for (int m = 0; m < 4; ++m) _Pragma("unroll") for (int n = 0; n < 2; ++n) _Pragma("unroll") for (int k = 0; k < 2; ++k) \
;             acc[ai][bj][m][n] = MFMA16(At_[m][k], Bt_[n][k], acc[ai][bj][m][n]); \
;         __builtin_amdgcn_s_setprio(0); } while (0)
; #define WAIT_V(n) asm volatile("s_waitcnt vmcnt(" #n ")" ::: "memory")
; #define WAIT_L(n) asm volatile("s_waitcnt lgkmcnt(" #n ")" ::: "memory")
; #define BAR __builtin_amdgcn_s_barrier()
; #define LDA(dst, b, hh) _Pragma("unroll") for (int m = 0; m < 4; ++m) _Pragma("unroll") for (int k = 0; k < 2; ++k) \
;         dst[m][k] = *(const bf16x8*)(SA(b, hh) + lds_byte(wr * 64 + m * 16 + fr, k * 32 + fq * 8))
; #define LDB(dst, b, hh) _Pragma("unroll") for (int n = 0; n < 2; ++n) _Pragma("unroll") for (int k = 0; k < 2; ++k) \
;         dst[n][k] = *(const bf16x8*)(SB(b, hh) + lds_byte(wc * 32 + n * 16 + fr, k * 32 + fq * 8))
; #define MMA(ai, bj, At_, Bt_) do { __builtin_amdgcn_s_setprio(1); \
;         _Pragma("unroll") for (int m = 0; m < 4; ++m) _Pragma("unroll") for (int n = 0; n < 2; ++n) _Pragma("unroll") for (int k = 0; k < 2; ++k) \
;             acc[ai][bj][m][n] = MFMA16(At_[m][k], Bt_[n][k], acc[ai][bj][m][n]); \
;         __builtin_amdgcn_s_setprio(0); } while (0)
; #define WAIT_V(n) asm volatile("s_waitcnt vmcnt(" #n ")" ::: "memory")
; #define WAIT_L(n) asm volatile("s_waitcnt lgkmcnt(" #n ")" ::: "memory")
; DI void gemm8(f32x4 (&acc)[2][2][4][2], const bf16_t* __restrict__ Rm, const bf16_t* __restrict__ Cm, int K, char* shm) {
;     ...
;       BAR; WAIT_L(0); MMA(0, 0, At, B0); BAR;
;       LDB(B1, 0, 1); BAR; WAIT_L(0); MMA(0, 1, At, B1); BAR;
;       LDA(At, 0, 1); WAIT_V(4); BAR; WAIT_L(0); MMA(1, 0, At, B0); MMA(1, 1, At, B1); BAR; }
;     { LDB(B0, 1, 0); LDA(At, 1, 0); WAIT_V(2); BAR; WAIT_L(0); MMA(0, 0, At, B0); BAR;
	s_waitcnt lgkmcnt(0)
	s_setprio 1
	s_waitcnt lgkmcnt(0)
	v_mfma_f32_16x16x32_bf16 v[94:97], v[168:171], v[98:101], v[94:97]
	v_mfma_f32_16x16x32_bf16 v[90:93], v[168:171], v[106:109], v[90:93]
	v_mfma_f32_16x16x32_bf16 v[86:89], v[188:191], v[98:101], v[86:89]
	v_mfma_f32_16x16x32_bf16 v[82:85], v[188:191], v[106:109], v[82:85]
	v_mfma_f32_16x16x32_bf16 v[94:97], v[184:187], v[102:105], v[94:97]
	v_mfma_f32_16x16x32_bf16 v[90:93], v[184:187], v[164:167], v[90:93]
	v_mfma_f32_16x16x32_bf16 v[86:89], v[192:195], v[102:105], v[86:89]
	v_mfma_f32_16x16x32_bf16 v[82:85], v[192:195], v[164:167], v[82:85]
	v_mfma_f32_16x16x32_bf16 v[78:81], v[196:199], v[98:101], v[78:81]
	v_mfma_f32_16x16x32_bf16 v[74:77], v[196:199], v[106:109], v[74:77]
	v_mfma_f32_16x16x32_bf16 v[70:73], v[204:207], v[98:101], v[70:73]
	v_mfma_f32_16x16x32_bf16 v[66:69], v[204:207], v[106:109], v[66:69]
	v_mfma_f32_16x16x32_bf16 v[168:171], v[200:203], v[102:105], v[78:81]
	v_mfma_f32_16x16x32_bf16 v[184:187], v[200:203], v[164:167], v[74:77]
	v_mfma_f32_16x16x32_bf16 v[188:191], v[208:211], v[102:105], v[70:73]
	v_mfma_f32_16x16x32_bf16 v[192:195], v[208:211], v[164:167], v[66:69]
	s_setprio 0
	s_barrier
	s_nop 1
	ds_read_b128 v[66:69], v145 offset:16384
	ds_read_b128 v[70:73], v145 offset:17408
	ds_read_b128 v[74:77], v144 offset:16384
	ds_read_b128 v[78:81], v144 offset:17408
	ds_read_b128 v[196:199], v143 offset:16384
	ds_read_b128 v[200:203], v143 offset:17408
	ds_read_b128 v[204:207], v142 offset:16384
	ds_read_b128 v[208:211], v142 offset:17408
	s_waitcnt vmcnt(4)
	s_barrier
	s_waitcnt lgkmcnt(0)
	s_setprio 1
	s_waitcnt lgkmcnt(0)
	v_mfma_f32_16x16x32_bf16 v[62:65], v[66:69], v[134:137], v[62:65]
	v_mfma_f32_16x16x32_bf16 v[58:61], v[66:69], v[150:153], v[58:61]
	v_mfma_f32_16x16x32_bf16 v[54:57], v[74:77], v[134:137], v[54:57]
	v_mfma_f32_16x16x32_bf16 v[50:53], v[74:77], v[150:153], v[50:53]
	v_mfma_f32_16x16x32_bf16 v[62:65], v[70:73], v[138:141], v[62:65]
	v_mfma_f32_16x16x32_bf16 v[58:61], v[70:73], v[156:159], v[58:61]
	v_mfma_f32_16x16x32_bf16 v[54:57], v[78:81], v[138:141], v[54:57]
	v_mfma_f32_16x16x32_bf16 v[50:53], v[78:81], v[156:159], v[50:53]
	v_mfma_f32_16x16x32_bf16 v[46:49], v[196:199], v[134:137], v[46:49]
	v_mfma_f32_16x16x32_bf16 v[42:45], v[196:199], v[150:153], v[42:45]
	v_mfma_f32_16x16x32_bf16 v[38:41], v[204:207], v[134:137], v[38:41]
	v_mfma_f32_16x16x32_bf16 v[34:37], v[204:207], v[150:153], v[34:37]
	v_mfma_f32_16x16x32_bf16 v[220:223], v[200:203], v[138:141], v[46:49]
	v_mfma_f32_16x16x32_bf16 v[224:227], v[200:203], v[156:159], v[42:45]
	v_mfma_f32_16x16x32_bf16 v[134:137], v[208:211], v[138:141], v[38:41]
	v_mfma_f32_16x16x32_bf16 v[138:141], v[208:211], v[156:159], v[34:37]
	s_setprio 0
	s_setprio 1
	v_mfma_f32_16x16x32_bf16 v[30:33], v[66:69], v[98:101], v[30:33]
	v_mfma_f32_16x16x32_bf16 v[26:29], v[66:69], v[106:109], v[26:29]
	v_mfma_f32_16x16x32_bf16 v[22:25], v[74:77], v[98:101], v[22:25]
	v_mfma_f32_16x16x32_bf16 v[30:33], v[70:73], v[102:105], v[30:33]
	v_mfma_f32_16x16x32_bf16 v[26:29], v[70:73], v[164:167], v[26:29]
	v_mfma_f32_16x16x32_bf16 v[22:25], v[78:81], v[102:105], v[22:25]
	v_mfma_f32_16x16x32_bf16 v[18:21], v[74:77], v[106:109], v[18:21]
	v_mfma_f32_16x16x32_bf16 v[14:17], v[196:199], v[98:101], v[14:17]
	v_mfma_f32_16x16x32_bf16 v[10:13], v[196:199], v[106:109], v[10:13]
	v_mfma_f32_16x16x32_bf16 v[6:9], v[204:207], v[98:101], v[6:9]
	v_mfma_f32_16x16x32_bf16 v[2:5], v[204:207], v[106:109], v[2:5]
	v_mfma_f32_16x16x32_bf16 v[150:153], v[78:81], v[164:167], v[18:21]
	v_mfma_f32_16x16x32_bf16 v[156:159], v[200:203], v[102:105], v[14:17]
	v_mfma_f32_16x16x32_bf16 v[196:199], v[200:203], v[164:167], v[10:13]
	v_mfma_f32_16x16x32_bf16 v[200:203], v[208:211], v[102:105], v[6:9]
	v_mfma_f32_16x16x32_bf16 v[164:167], v[208:211], v[164:167], v[2:5]
	s_setprio 0
	s_barrier
	ds_read_b128 v[18:21], v154
	ds_read_b128 v[204:207], v154 offset:1024
	ds_read_b128 v[208:211], v154 offset:2048
	ds_read_b128 v[228:231], v154 offset:3072
	ds_read_b128 v[2:5], v145 offset:32768
	ds_read_b128 v[6:9], v145 offset:33792
	ds_read_b128 v[10:13], v144 offset:32768
	ds_read_b128 v[14:17], v144 offset:33792
	ds_read_b128 v[46:49], v143 offset:32768
	ds_read_b128 v[232:235], v143 offset:33792
	ds_read_b128 v[236:239], v142 offset:32768
	ds_read_b128 v[240:243], v142 offset:33792
	s_waitcnt vmcnt(2)
	s_barrier
; #define LDA(dst, b, hh) _Pragma("unroll") for (int m = 0; m < 4; ++m) _Pragma("unroll") for (int k = 0; k < 2; ++k) \
;         dst[m][k] = *(const bf16x8*)(SA(b, hh) + lds_byte(wr * 64 + m * 16 + fr, k * 32 + fq * 8))
; #define LDB(dst, b, hh) _Pragma("unroll") for (int n = 0; n < 2; ++n) _Pragma("unroll") for (int k = 0; k < 2; ++k) \
;         dst[n][k] = *(const bf16x8*)(SB(b, hh) + lds_byte(wc * 32 + n * 16 + fr, k * 32 + fq * 8))
; #define MMA(ai, bj, At_, Bt_) do { __builtin_amdgcn_s_setprio(1); \
;         _Pragma("unroll") for (int m = 0; m < 4; ++m) _Pragma("unroll") for (int n = 0; n < 2; ++n) _Pragma("unroll") for (int k = 0; k < 2; ++k) \
;             acc[ai][bj][m][n] = MFMA16(At_[m][k], Bt_[n][k], acc[ai][bj][m][n]); \
;         __builtin_amdgcn_s_setprio(0); } while (0)
; #define WAIT_V(n) asm volatile("s_waitcnt vmcnt(" #n ")" ::: "memory")
; #define WAIT_L(n) asm volatile("s_waitcnt lgkmcnt(" #n ")" ::: "memory")
; #define BAR __builtin_amdgcn_s_barrier()
; #define LDA(dst, b, hh) _Pragma("unroll") for (int m = 0; m < 4; ++m) _Pragma("unroll") for (int k = 0; k < 2; ++k) \
;         dst[m][k] = *(const bf16x8*)(SA(b, hh) + lds_byte(wr * 64 + m * 16 + fr, k * 32 + fq * 8))
; #define LDB(dst, b, hh) _Pragma("unroll") for (int n = 0; n < 2; ++n) _Pragma("unroll") for (int k = 0; k < 2; ++k) \
;         dst[n][k] = *(const bf16x8*)(SB(b, hh) + lds_byte(wc * 32 + n * 16 + fr, k * 32 + fq * 8))
; #define MMA(ai, bj, At_, Bt_) do { __builtin_amdgcn_s_setprio(1); \
;         _Pragma("unroll") for (int m = 0; m < 4; ++m) _Pragma("unroll") for (int n = 0; n < 2; ++n) _Pragma("unroll") for (int k = 0; k < 2; ++k) \
;             acc[ai][bj][m][n] = MFMA16(At_[m][k], Bt_[n][k], acc[ai][bj][m][n]); \
;         __builtin_amdgcn_s_setprio(0); } while (0)
; #define WAIT_V(n) asm volatile("s_waitcnt vmcnt(" #n ")" ::: "memory")
; #define WAIT_L(n) asm volatile("s_waitcnt lgkmcnt(" #n ")" ::: "memory")
; #define BAR __builtin_amdgcn_s_barrier()
; DI void gemm8(f32x4 (&acc)[2][2][4][2], const bf16_t* __restrict__ Rm, const bf16_t* __restrict__ Cm, int K, char* shm) {
;     ...
;     { LDB(B0, 1, 0); LDA(At, 1, 0); WAIT_V(2); BAR; WAIT_L(0); MMA(0, 0, At, B0); BAR;
;       LDB(B1, 1, 1); WAIT_V(0); BAR; WAIT_L(0); MMA(0, 1, At, B1); BAR;
;       LDA(At, 1, 1); BAR; WAIT_L(0); MMA(1, 0, At, B0); MMA(1, 1, At, B1); BAR; }
;     if (wr == 0) BAR;
	s_waitcnt lgkmcnt(0)
	s_setprio 1
	s_waitcnt lgkmcnt(0)
	v_mfma_f32_16x16x32_bf16 v[34:37], v[2:5], v[18:21], v[126:129]
	v_mfma_f32_16x16x32_bf16 v[98:101], v[6:9], v[204:207], v[34:37]
	v_mfma_f32_16x16x32_bf16 v[34:37], v[2:5], v[208:211], v[122:125]
	v_mfma_f32_16x16x32_bf16 v[66:69], v[6:9], v[228:231], v[34:37]
	v_mfma_f32_16x16x32_bf16 v[34:37], v[10:13], v[18:21], v[118:121]
	v_mfma_f32_16x16x32_bf16 v[102:105], v[14:17], v[204:207], v[34:37]
	v_mfma_f32_16x16x32_bf16 v[34:37], v[10:13], v[208:211], v[114:117]
	v_mfma_f32_16x16x32_bf16 v[70:73], v[14:17], v[228:231], v[34:37]
	v_mfma_f32_16x16x32_bf16 v[34:37], v[46:49], v[18:21], v[110:113]
	v_mfma_f32_16x16x32_bf16 v[106:109], v[232:235], v[204:207], v[34:37]
	v_mfma_f32_16x16x32_bf16 v[34:37], v[46:49], v[208:211], v[130:133]
	v_mfma_f32_16x16x32_bf16 v[74:77], v[232:235], v[228:231], v[34:37]
	v_mfma_f32_16x16x32_bf16 v[34:37], v[236:239], v[18:21], v[212:215]
	v_mfma_f32_16x16x32_bf16 v[110:113], v[240:243], v[204:207], v[34:37]
	v_mfma_f32_16x16x32_bf16 v[34:37], v[236:239], v[208:211], v[216:219]
	v_mfma_f32_16x16x32_bf16 v[78:81], v[240:243], v[228:231], v[34:37]
	s_setprio 0
	s_barrier
	ds_read_b128 v[130:133], v149
	ds_read_b128 v[212:215], v149 offset:1024
	ds_read_b128 v[216:219], v149 offset:2048
	ds_read_b128 v[146:149], v149 offset:3072
	s_waitcnt vmcnt(0)
	s_barrier
	s_waitcnt lgkmcnt(0)
	s_setprio 1
	s_waitcnt lgkmcnt(0)
	v_mfma_f32_16x16x32_bf16 v[34:37], v[2:5], v[130:133], v[94:97]
	v_mfma_f32_16x16x32_bf16 v[2:5], v[2:5], v[216:219], v[90:93]
	v_mfma_f32_16x16x32_bf16 v[34:37], v[6:9], v[212:215], v[34:37]
	v_mfma_f32_16x16x32_bf16 v[2:5], v[6:9], v[146:149], v[2:5]
	v_mfma_f32_16x16x32_bf16 v[6:9], v[10:13], v[130:133], v[86:89]
	v_mfma_f32_16x16x32_bf16 v[38:41], v[14:17], v[212:215], v[6:9]
	v_mfma_f32_16x16x32_bf16 v[6:9], v[10:13], v[216:219], v[82:85]
	v_mfma_f32_16x16x32_bf16 v[6:9], v[14:17], v[146:149], v[6:9]
	v_mfma_f32_16x16x32_bf16 v[10:13], v[46:49], v[130:133], v[168:171]
	v_mfma_f32_16x16x32_bf16 v[14:17], v[236:239], v[130:133], v[188:191]
	v_mfma_f32_16x16x32_bf16 v[42:45], v[232:235], v[212:215], v[10:13]
	v_mfma_f32_16x16x32_bf16 v[10:13], v[46:49], v[216:219], v[184:187]
	v_mfma_f32_16x16x32_bf16 v[46:49], v[240:243], v[212:215], v[14:17]
	v_mfma_f32_16x16x32_bf16 v[14:17], v[236:239], v[216:219], v[192:195]
	v_mfma_f32_16x16x32_bf16 v[10:13], v[232:235], v[146:149], v[10:13]
	v_mfma_f32_16x16x32_bf16 v[14:17], v[240:243], v[146:149], v[14:17]
	s_setprio 0
	s_barrier
	ds_read_b128 v[168:171], v145 offset:49152
	ds_read_b128 v[184:187], v145 offset:50176
	ds_read_b128 v[188:191], v144 offset:49152
	ds_read_b128 v[192:195], v144 offset:50176
	ds_read_b128 v[232:235], v143 offset:49152
	ds_read_b128 v[236:239], v143 offset:50176
	ds_read_b128 v[240:243], v142 offset:49152
	ds_read_b128 v[142:145], v142 offset:50176
	s_barrier
	s_waitcnt lgkmcnt(0)
	s_setprio 1
	s_waitcnt lgkmcnt(0)
	v_mfma_f32_16x16x32_bf16 v[50:53], v[188:191], v[208:211], v[50:53]
	v_mfma_f32_16x16x32_bf16 v[62:65], v[168:171], v[18:21], v[62:65]
	v_mfma_f32_16x16x32_bf16 v[54:57], v[188:191], v[18:21], v[54:57]
	v_mfma_f32_16x16x32_bf16 v[86:89], v[192:195], v[228:231], v[50:53]
	v_mfma_f32_16x16x32_bf16 v[50:53], v[232:235], v[18:21], v[220:223]
	v_mfma_f32_16x16x32_bf16 v[18:21], v[240:243], v[18:21], v[134:137]
	v_mfma_f32_16x16x32_bf16 v[58:61], v[168:171], v[208:211], v[58:61]
	v_mfma_f32_16x16x32_bf16 v[122:125], v[236:239], v[204:207], v[50:53]
	v_mfma_f32_16x16x32_bf16 v[50:53], v[232:235], v[208:211], v[224:227]
	v_mfma_f32_16x16x32_bf16 v[126:129], v[142:145], v[204:207], v[18:21]
	v_mfma_f32_16x16x32_bf16 v[18:21], v[240:243], v[208:211], v[138:141]
	v_mfma_f32_16x16x32_bf16 v[114:117], v[184:187], v[204:207], v[62:65]
	v_mfma_f32_16x16x32_bf16 v[82:85], v[184:187], v[228:231], v[58:61]
	v_mfma_f32_16x16x32_bf16 v[118:121], v[192:195], v[204:207], v[54:57]
	v_mfma_f32_16x16x32_bf16 v[90:93], v[236:239], v[228:231], v[50:53]
	v_mfma_f32_16x16x32_bf16 v[94:97], v[142:145], v[228:231], v[18:21]
	s_setprio 0
	s_setprio 1
	v_mfma_f32_16x16x32_bf16 v[18:21], v[168:171], v[130:133], v[30:33]
	v_mfma_f32_16x16x32_bf16 v[50:53], v[184:187], v[212:215], v[18:21]
	v_mfma_f32_16x16x32_bf16 v[18:21], v[168:171], v[216:219], v[26:29]
	v_mfma_f32_16x16x32_bf16 v[22:25], v[188:191], v[130:133], v[22:25]
	v_mfma_f32_16x16x32_bf16 v[26:29], v[232:235], v[130:133], v[156:159]
	v_mfma_f32_16x16x32_bf16 v[30:33], v[240:243], v[130:133], v[200:203]
	v_mfma_f32_16x16x32_bf16 v[54:57], v[192:195], v[212:215], v[22:25]
	v_mfma_f32_16x16x32_bf16 v[22:25], v[188:191], v[216:219], v[150:153]
	v_mfma_f32_16x16x32_bf16 v[58:61], v[236:239], v[212:215], v[26:29]
	v_mfma_f32_16x16x32_bf16 v[26:29], v[232:235], v[216:219], v[196:199]
	v_mfma_f32_16x16x32_bf16 v[62:65], v[142:145], v[212:215], v[30:33]
	v_mfma_f32_16x16x32_bf16 v[30:33], v[240:243], v[216:219], v[164:167]
	v_mfma_f32_16x16x32_bf16 v[18:21], v[184:187], v[146:149], v[18:21]
	v_mfma_f32_16x16x32_bf16 v[22:25], v[192:195], v[146:149], v[22:25]
	v_mfma_f32_16x16x32_bf16 v[26:29], v[236:239], v[146:149], v[26:29]
	v_mfma_f32_16x16x32_bf16 v[30:33], v[142:145], v[146:149], v[30:33]
	s_setprio 0
	v_cmp_gt_u32_e32 vcc, s96, v0
	s_barrier
	s_and_saveexec_b64 s[6:7], vcc
	s_cbranch_execz .LBB0_181
	s_barrier

; #define STAGE(P, BASE, br, kt) do { const bf16_t* g_ = (BASE) + (size_t)(br) * K + (size_t)(kt) * 64; \
;         _Pragma("unroll") for (int i_ = 0; i_ < 2; ++i_) \
;             __builtin_amdgcn_global_load_lds((const unsigned*)(g_ + gofs[i_]), (lds_ptr_t)((P) + wb + i_ * 8192), 16, 0, 0); } while (0)
; #define LDA(dst, b, hh) _Pragma("unroll") for (int m = 0; m < 4; ++m) _Pragma("unroll") for (int k = 0; k < 2; ++k) \
;         dst[m][k] = *(const bf16x8*)(SA(b, hh) + lds_byte(wr * 64 + m * 16 + fr, k * 32 + fq * 8))
; #define LDB(dst, b, hh) _Pragma("unroll") for (int n = 0; n < 2; ++n) _Pragma("unroll") for (int k = 0; k < 2; ++k) \
;         dst[n][k] = *(const bf16x8*)(SB(b, hh) + lds_byte(wc * 32 + n * 16 + fr, k * 32 + fq * 8))
; #define MMA(ai, bj, At_, Bt_) do { __builtin_amdgcn_s_setprio(1); \
;         _Pragma("unroll") for (int m = 0; m < 4; ++m) _Pragma("unroll") for (int n = 0; n < 2; ++n) _Pragma("unroll") for (int k = 0; k < 2; ++k) \
;             acc[ai][bj][m][n] = MFMA16(At_[m][k], Bt_[n][k], acc[ai][bj][m][n]); \
;         __builtin_amdgcn_s_setprio(0); } while (0)
; #define WAIT_L(n) asm volatile("s_waitcnt lgkmcnt(" #n ")" ::: "memory")
; #define BAR __builtin_amdgcn_s_barrier()
; #define SCHED __builtin_amdgcn_sched_barrier(0)
; #define STAGE(P, BASE, br, kt) do { const int sg_ = (kt) >> 3; const bf16_t* g_ = (sg_ == 0 ? BASE##0 : sg_ == 1 ? BASE##1 : BASE##2) + (size_t)(br) * K + (size_t)((kt) & 7) * 64; \
;         _Pragma("unroll") for (int i_ = 0; i_ < 2; ++i_) \
;             __builtin_amdgcn_global_load_lds((const unsigned*)(g_ + gofs[i_]), (lds_ptr_t)((P) + wb + i_ * 8192), 16, 0, 0); } while (0)
; #define WAIT_L(n) asm volatile("s_waitcnt lgkmcnt(" #n ")" ::: "memory")
; #define BAR __builtin_amdgcn_s_barrier()
; #define SCHED __builtin_amdgcn_sched_barrier(0)
; DI void gemm8(f32x4 (&acc)[2][2][4][2], const bf16_t* __restrict__ Rm, const bf16_t* __restrict__ Cm, int K, char* shm) {
;     ...
;     for (int tt = 0; tt < nt - 2; tt += 2) {
;         LDB(B0, 0, 0); SCHED; LDA(At, 0, 0); STAGE(SA(1, 1), Rm, 128, tt + 1);
;         WAIT_L(8); BAR; WAIT_L(0); MMA(0, 0, At, B0); BAR; SCHED;
;         LDB(B1, 0, 1); STAGE(SB(0, 0), Cm, 0, tt + 2);
;         BAR; WAIT_L(0); MMA(0, 1, At, B1); BAR;
;         LDA(At, 0, 1); STAGE(SA(0, 0), Rm, 0, tt + 2);
;         BAR; WAIT_L(0); MMA(1, 0, At, B0); BAR; SCHED;
.LBB0_314:
	v_add_u32_e32 v166, 0xc000, v146
	v_lshl_add_u64 v[244:245], s[62:63], 0, v[138:139]
	v_readfirstlane_b32 s3, v166
	v_add_u32_e32 v167, 0xe000, v146
	v_lshl_add_u64 v[228:229], v[244:245], 0, s[8:9]
	s_mov_b32 m0, s3
	v_lshl_add_u64 v[246:247], s[62:63], 0, v[140:141]
	v_readfirstlane_b32 s3, v167
	global_load_lds_dwordx4 v[228:229], off
	v_lshl_add_u64 v[228:229], v[246:247], 0, s[8:9]
	s_mov_b32 m0, s3
	s_nop 0
	global_load_lds_dwordx4 v[228:229], off
	ds_read_b128 v[168:171], v165
	ds_read_b128 v[184:187], v165 offset:1024
	ds_read_b128 v[188:191], v165 offset:2048
	ds_read_b128 v[192:195], v165 offset:3072
	ds_read_b128 v[196:199], v145
	ds_read_b128 v[200:203], v145 offset:1024
	ds_read_b128 v[204:207], v144
	ds_read_b128 v[208:211], v144 offset:1024
	ds_read_b128 v[212:215], v143
	ds_read_b128 v[216:219], v143 offset:1024
	ds_read_b128 v[220:223], v142
	ds_read_b128 v[224:227], v142 offset:1024
	s_waitcnt lgkmcnt(8)
	s_barrier
	s_waitcnt lgkmcnt(0)
	s_setprio 1
	s_waitcnt lgkmcnt(0)
	v_mfma_f32_16x16x32_bf16 v[126:129], v[196:199], v[168:171], v[126:129]
	v_mfma_f32_16x16x32_bf16 v[122:125], v[196:199], v[188:191], v[122:125]
	v_mfma_f32_16x16x32_bf16 v[118:121], v[204:207], v[168:171], v[118:121]
	v_mfma_f32_16x16x32_bf16 v[114:117], v[204:207], v[188:191], v[114:117]
	v_mfma_f32_16x16x32_bf16 v[110:113], v[212:215], v[168:171], v[110:113]
	v_mfma_f32_16x16x32_bf16 v[106:109], v[212:215], v[188:191], v[106:109]
	v_mfma_f32_16x16x32_bf16 v[102:105], v[220:223], v[168:171], v[102:105]
	v_mfma_f32_16x16x32_bf16 v[98:101], v[220:223], v[188:191], v[98:101]
	v_mfma_f32_16x16x32_bf16 v[126:129], v[200:203], v[184:187], v[126:129]
	v_mfma_f32_16x16x32_bf16 v[122:125], v[200:203], v[192:195], v[122:125]
	v_mfma_f32_16x16x32_bf16 v[118:121], v[208:211], v[184:187], v[118:121]
	v_mfma_f32_16x16x32_bf16 v[114:117], v[208:211], v[192:195], v[114:117]
	v_mfma_f32_16x16x32_bf16 v[110:113], v[216:219], v[184:187], v[110:113]
	v_mfma_f32_16x16x32_bf16 v[106:109], v[216:219], v[192:195], v[106:109]
	v_mfma_f32_16x16x32_bf16 v[102:105], v[224:227], v[184:187], v[102:105]
	v_mfma_f32_16x16x32_bf16 v[98:101], v[224:227], v[192:195], v[98:101]
	s_setprio 0
	s_barrier
	v_lshl_add_u64 v[248:249], s[62:63], 0, v[134:135]
	v_readfirstlane_b32 s3, v147
	v_lshl_add_u64 v[250:251], v[248:249], 0, s[10:11]
	s_mov_b32 m0, s3
	s_nop 0
	global_load_lds_dwordx4 v[250:251], off
	v_lshl_add_u64 v[250:251], s[62:63], 0, v[136:137]
	v_readfirstlane_b32 s3, v148
	v_lshl_add_u64 v[172:173], v[250:251], 0, s[10:11]
	s_mov_b32 m0, s3
	s_nop 0
	global_load_lds_dwordx4 v[172:173], off
	ds_read_b128 v[228:231], v164
	ds_read_b128 v[232:235], v164 offset:1024
	ds_read_b128 v[236:239], v164 offset:2048
	ds_read_b128 v[240:243], v164 offset:3072
	s_barrier
	s_waitcnt lgkmcnt(0)
	s_setprio 1
	s_waitcnt lgkmcnt(0)
	v_mfma_f32_16x16x32_bf16 v[94:97], v[196:199], v[228:231], v[94:97]
	v_mfma_f32_16x16x32_bf16 v[90:93], v[196:199], v[236:239], v[90:93]
	v_mfma_f32_16x16x32_bf16 v[86:89], v[204:207], v[228:231], v[86:89]
	v_mfma_f32_16x16x32_bf16 v[82:85], v[204:207], v[236:239], v[82:85]
	v_mfma_f32_16x16x32_bf16 v[78:81], v[212:215], v[228:231], v[78:81]
	v_mfma_f32_16x16x32_bf16 v[74:77], v[212:215], v[236:239], v[74:77]
	v_mfma_f32_16x16x32_bf16 v[70:73], v[220:223], v[228:231], v[70:73]
	v_mfma_f32_16x16x32_bf16 v[66:69], v[220:223], v[236:239], v[66:69]
	v_mfma_f32_16x16x32_bf16 v[94:97], v[200:203], v[232:235], v[94:97]
	v_mfma_f32_16x16x32_bf16 v[90:93], v[200:203], v[240:243], v[90:93]
	v_mfma_f32_16x16x32_bf16 v[86:89], v[208:211], v[232:235], v[86:89]
	v_mfma_f32_16x16x32_bf16 v[82:85], v[208:211], v[240:243], v[82:85]
	v_mfma_f32_16x16x32_bf16 v[78:81], v[216:219], v[232:235], v[78:81]
	v_mfma_f32_16x16x32_bf16 v[74:77], v[216:219], v[240:243], v[74:77]
	v_mfma_f32_16x16x32_bf16 v[70:73], v[224:227], v[232:235], v[70:73]
	v_mfma_f32_16x16x32_bf16 v[66:69], v[224:227], v[240:243], v[66:69]
	s_setprio 0
	v_readfirstlane_b32 s3, v146
	v_lshl_add_u64 v[172:173], v[244:245], 0, s[90:91]
	s_mov_b32 m0, s3
	v_readfirstlane_b32 s3, v150
	s_barrier
	global_load_lds_dwordx4 v[172:173], off
	v_lshl_add_u64 v[172:173], v[246:247], 0, s[90:91]
	s_mov_b32 m0, s3
	s_nop 0
	global_load_lds_dwordx4 v[172:173], off
	ds_read_b128 v[196:199], v145 offset:16384
	ds_read_b128 v[200:203], v145 offset:17408
	ds_read_b128 v[204:207], v144 offset:16384
	ds_read_b128 v[208:211], v144 offset:17408
	ds_read_b128 v[212:215], v143 offset:16384
	ds_read_b128 v[216:219], v143 offset:17408
	ds_read_b128 v[220:223], v142 offset:16384
	ds_read_b128 v[224:227], v142 offset:17408
	s_barrier
	s_waitcnt lgkmcnt(0)
	s_setprio 1
	s_waitcnt lgkmcnt(0)
	v_mfma_f32_16x16x32_bf16 v[62:65], v[196:199], v[168:171], v[62:65]
	v_mfma_f32_16x16x32_bf16 v[58:61], v[196:199], v[188:191], v[58:61]
	v_mfma_f32_16x16x32_bf16 v[54:57], v[204:207], v[168:171], v[54:57]
	v_mfma_f32_16x16x32_bf16 v[50:53], v[204:207], v[188:191], v[50:53]
	v_mfma_f32_16x16x32_bf16 v[46:49], v[212:215], v[168:171], v[46:49]
	v_mfma_f32_16x16x32_bf16 v[42:45], v[212:215], v[188:191], v[42:45]
	v_mfma_f32_16x16x32_bf16 v[38:41], v[220:223], v[168:171], v[38:41]
	v_mfma_f32_16x16x32_bf16 v[34:37], v[220:223], v[188:191], v[34:37]
	v_mfma_f32_16x16x32_bf16 v[62:65], v[200:203], v[184:187], v[62:65]
	v_mfma_f32_16x16x32_bf16 v[58:61], v[200:203], v[192:195], v[58:61]
	v_mfma_f32_16x16x32_bf16 v[54:57], v[208:211], v[184:187], v[54:57]
	v_mfma_f32_16x16x32_bf16 v[50:53], v[208:211], v[192:195], v[50:53]
	v_mfma_f32_16x16x32_bf16 v[46:49], v[216:219], v[184:187], v[46:49]
	v_mfma_f32_16x16x32_bf16 v[42:45], v[216:219], v[192:195], v[42:45]
	v_mfma_f32_16x16x32_bf16 v[38:41], v[224:227], v[184:187], v[38:41]
	v_mfma_f32_16x16x32_bf16 v[34:37], v[224:227], v[192:195], v[34:37]
	s_setprio 0
	s_barrier
; #define STAGE(P, BASE, br, kt) do { const bf16_t* g_ = (BASE) + (size_t)(br) * K + (size_t)(kt) * 64; \
;         _Pragma("unroll") for (int i_ = 0; i_ < 2; ++i_) \
;             __builtin_amdgcn_global_load_lds((const unsigned*)(g_ + gofs[i_]), (lds_ptr_t)((P) + wb + i_ * 8192), 16, 0, 0); } while (0)
; #define LDA(dst, b, hh) _Pragma("unroll") for (int m = 0; m < 4; ++m) _Pragma("unroll") for (int k = 0; k < 2; ++k) \
;         dst[m][k] = *(const bf16x8*)(SA(b, hh) + lds_byte(wr * 64 + m * 16 + fr, k * 32 + fq * 8))
; #define LDB(dst, b, hh) _Pragma("unroll") for (int n = 0; n < 2; ++n) _Pragma("unroll") for (int k = 0; k < 2; ++k) \
;         dst[n][k] = *(const bf16x8*)(SB(b, hh) + lds_byte(wc * 32 + n * 16 + fr, k * 32 + fq * 8))
; #define MMA(ai, bj, At_, Bt_) do { __builtin_amdgcn_s_setprio(1); \
;         _Pragma("unroll") for (int m = 0; m < 4; ++m) _Pragma("unroll") for (int n = 0; n < 2; ++n) _Pragma("unroll") for (int k = 0; k < 2; ++k) \
;             acc[ai][bj][m][n] = MFMA16(At_[m][k], Bt_[n][k], acc[ai][bj][m][n]); \
;         __builtin_amdgcn_s_setprio(0); } while (0)
; #define WAIT_V(n) asm volatile("s_waitcnt vmcnt(" #n ")" ::: "memory")
; #define WAIT_L(n) asm volatile("s_waitcnt lgkmcnt(" #n ")" ::: "memory")
; #define BAR __builtin_amdgcn_s_barrier()
; #define SCHED __builtin_amdgcn_sched_barrier(0)
; #define STAGE(P, BASE, br, kt) do { const int sg_ = (kt) >> 3; const bf16_t* g_ = (sg_ == 0 ? BASE##0 : sg_ == 1 ? BASE##1 : BASE##2) + (size_t)(br) * K + (size_t)((kt) & 7) * 64; \
;         _Pragma("unroll") for (int i_ = 0; i_ < 2; ++i_) \
;             __builtin_amdgcn_global_load_lds((const unsigned*)(g_ + gofs[i_]), (lds_ptr_t)((P) + wb + i_ * 8192), 16, 0, 0); } while (0)
; DI void gemm8(f32x4 (&acc)[2][2][4][2], const bf16_t* __restrict__ Rm, const bf16_t* __restrict__ Cm, int K, char* shm) {
;     ...
;         BAR; WAIT_L(0); MMA(1, 0, At, B0); BAR; SCHED;
;         STAGE(SB(0, 1), Cm, 128, tt + 2);
;         WAIT_V(6); BAR; MMA(1, 1, At, B1); BAR;
;         LDB(B0, 1, 0); SCHED; LDA(At, 1, 0); STAGE(SA(0, 1), Rm, 128, tt + 2);
;         WAIT_L(8); BAR; WAIT_L(0); MMA(0, 0, At, B0); BAR; SCHED;
;         LDB(B1, 1, 1); STAGE(SB(1, 0), Cm, 0, tt + 3);
;         BAR; WAIT_L(0); MMA(0, 1, At, B1); BAR;
;         LDA(At, 1, 1); STAGE(SA(1, 0), Rm, 0, tt + 3);
;         BAR; WAIT_L(0); MMA(1, 0, At, B0); BAR; SCHED;
	v_readfirstlane_b32 s3, v151
	v_lshl_add_u64 v[168:169], v[248:249], 0, s[12:13]
	s_mov_b32 m0, s3
	v_readfirstlane_b32 s3, v152
	global_load_lds_dwordx4 v[168:169], off
	v_lshl_add_u64 v[168:169], v[250:251], 0, s[12:13]
	s_mov_b32 m0, s3
	s_nop 0
	global_load_lds_dwordx4 v[168:169], off
	s_waitcnt vmcnt(6)
	s_barrier
	s_setprio 1
	v_mfma_f32_16x16x32_bf16 v[30:33], v[196:199], v[228:231], v[30:33]
	v_mfma_f32_16x16x32_bf16 v[26:29], v[196:199], v[236:239], v[26:29]
	v_mfma_f32_16x16x32_bf16 v[22:25], v[204:207], v[228:231], v[22:25]
	v_mfma_f32_16x16x32_bf16 v[18:21], v[204:207], v[236:239], v[18:21]
	v_mfma_f32_16x16x32_bf16 v[14:17], v[212:215], v[228:231], v[14:17]
	v_mfma_f32_16x16x32_bf16 v[10:13], v[212:215], v[236:239], v[10:13]
	v_mfma_f32_16x16x32_bf16 v[6:9], v[220:223], v[228:231], v[6:9]
	v_mfma_f32_16x16x32_bf16 v[2:5], v[220:223], v[236:239], v[2:5]
	v_mfma_f32_16x16x32_bf16 v[30:33], v[200:203], v[232:235], v[30:33]
	v_mfma_f32_16x16x32_bf16 v[26:29], v[200:203], v[240:243], v[26:29]
	v_mfma_f32_16x16x32_bf16 v[22:25], v[208:211], v[232:235], v[22:25]
	v_mfma_f32_16x16x32_bf16 v[18:21], v[208:211], v[240:243], v[18:21]
	v_mfma_f32_16x16x32_bf16 v[14:17], v[216:219], v[232:235], v[14:17]
	v_mfma_f32_16x16x32_bf16 v[10:13], v[216:219], v[240:243], v[10:13]
	v_mfma_f32_16x16x32_bf16 v[6:9], v[224:227], v[232:235], v[6:9]
	v_mfma_f32_16x16x32_bf16 v[2:5], v[224:227], v[240:243], v[2:5]
	s_setprio 0
	s_barrier
	v_readfirstlane_b32 s3, v153
	v_lshl_add_u64 v[172:173], v[244:245], 0, s[76:77]
	s_mov_b32 m0, s3
	v_readfirstlane_b32 s3, v155
	global_load_lds_dwordx4 v[172:173], off
	v_lshl_add_u64 v[172:173], v[246:247], 0, s[76:77]
	s_mov_b32 m0, s3
	s_nop 0
	global_load_lds_dwordx4 v[172:173], off
	ds_read_b128 v[168:171], v154
	ds_read_b128 v[184:187], v154 offset:1024
	ds_read_b128 v[188:191], v154 offset:2048
	ds_read_b128 v[192:195], v154 offset:3072
	ds_read_b128 v[196:199], v145 offset:32768
	ds_read_b128 v[200:203], v145 offset:33792
	ds_read_b128 v[204:207], v144 offset:32768
	ds_read_b128 v[208:211], v144 offset:33792
	ds_read_b128 v[212:215], v143 offset:32768
	ds_read_b128 v[216:219], v143 offset:33792
	ds_read_b128 v[220:223], v142 offset:32768
	ds_read_b128 v[224:227], v142 offset:33792
	s_waitcnt lgkmcnt(8)
	s_barrier
	s_waitcnt lgkmcnt(0)
	s_setprio 1
	s_waitcnt lgkmcnt(0)
	v_mfma_f32_16x16x32_bf16 v[126:129], v[196:199], v[168:171], v[126:129]
	v_mfma_f32_16x16x32_bf16 v[122:125], v[196:199], v[188:191], v[122:125]
	v_mfma_f32_16x16x32_bf16 v[118:121], v[204:207], v[168:171], v[118:121]
	v_mfma_f32_16x16x32_bf16 v[114:117], v[204:207], v[188:191], v[114:117]
	v_mfma_f32_16x16x32_bf16 v[110:113], v[212:215], v[168:171], v[110:113]
	v_mfma_f32_16x16x32_bf16 v[106:109], v[212:215], v[188:191], v[106:109]
	v_mfma_f32_16x16x32_bf16 v[102:105], v[220:223], v[168:171], v[102:105]
	v_mfma_f32_16x16x32_bf16 v[98:101], v[220:223], v[188:191], v[98:101]
	v_mfma_f32_16x16x32_bf16 v[126:129], v[200:203], v[184:187], v[126:129]
	v_mfma_f32_16x16x32_bf16 v[122:125], v[200:203], v[192:195], v[122:125]
	v_mfma_f32_16x16x32_bf16 v[118:121], v[208:211], v[184:187], v[118:121]
	v_mfma_f32_16x16x32_bf16 v[114:117], v[208:211], v[192:195], v[114:117]
	v_mfma_f32_16x16x32_bf16 v[110:113], v[216:219], v[184:187], v[110:113]
	v_mfma_f32_16x16x32_bf16 v[106:109], v[216:219], v[192:195], v[106:109]
	v_mfma_f32_16x16x32_bf16 v[102:105], v[224:227], v[184:187], v[102:105]
	v_mfma_f32_16x16x32_bf16 v[98:101], v[224:227], v[192:195], v[98:101]
	s_setprio 0
	s_barrier
	v_readfirstlane_b32 s3, v156
	v_lshl_add_u64 v[172:173], v[248:249], 0, s[14:15]
	s_mov_b32 m0, s3
	v_readfirstlane_b32 s3, v157
	global_load_lds_dwordx4 v[172:173], off
	v_lshl_add_u64 v[172:173], v[250:251], 0, s[14:15]
	s_mov_b32 m0, s3
	s_nop 0
	global_load_lds_dwordx4 v[172:173], off
	ds_read_b128 v[228:231], v149
	ds_read_b128 v[232:235], v149 offset:1024
	ds_read_b128 v[236:239], v149 offset:2048
	ds_read_b128 v[240:243], v149 offset:3072
	s_barrier
	s_waitcnt lgkmcnt(0)
	s_setprio 1
	s_waitcnt lgkmcnt(0)
	v_mfma_f32_16x16x32_bf16 v[94:97], v[196:199], v[228:231], v[94:97]
	v_mfma_f32_16x16x32_bf16 v[90:93], v[196:199], v[236:239], v[90:93]
	v_mfma_f32_16x16x32_bf16 v[86:89], v[204:207], v[228:231], v[86:89]
	v_mfma_f32_16x16x32_bf16 v[82:85], v[204:207], v[236:239], v[82:85]
	v_mfma_f32_16x16x32_bf16 v[78:81], v[212:215], v[228:231], v[78:81]
	v_mfma_f32_16x16x32_bf16 v[74:77], v[212:215], v[236:239], v[74:77]
	v_mfma_f32_16x16x32_bf16 v[70:73], v[220:223], v[228:231], v[70:73]
	v_mfma_f32_16x16x32_bf16 v[66:69], v[220:223], v[236:239], v[66:69]
	v_mfma_f32_16x16x32_bf16 v[94:97], v[200:203], v[232:235], v[94:97]
	v_mfma_f32_16x16x32_bf16 v[90:93], v[200:203], v[240:243], v[90:93]
	v_mfma_f32_16x16x32_bf16 v[86:89], v[208:211], v[232:235], v[86:89]
	v_mfma_f32_16x16x32_bf16 v[82:85], v[208:211], v[240:243], v[82:85]
	v_mfma_f32_16x16x32_bf16 v[78:81], v[216:219], v[232:235], v[78:81]
	v_mfma_f32_16x16x32_bf16 v[74:77], v[216:219], v[240:243], v[74:77]
	v_mfma_f32_16x16x32_bf16 v[70:73], v[224:227], v[232:235], v[70:73]
	v_mfma_f32_16x16x32_bf16 v[66:69], v[224:227], v[240:243], v[66:69]
	s_setprio 0
	v_readfirstlane_b32 s3, v158
	v_lshl_add_u64 v[172:173], v[244:245], 0, s[72:73]
	s_mov_b32 m0, s3
	v_readfirstlane_b32 s3, v159
	s_barrier
	global_load_lds_dwordx4 v[172:173], off
	v_lshl_add_u64 v[172:173], v[246:247], 0, s[72:73]
	s_mov_b32 m0, s3
	s_nop 0
	global_load_lds_dwordx4 v[172:173], off
	ds_read_b128 v[196:199], v145 offset:49152
	ds_read_b128 v[200:203], v145 offset:50176
	ds_read_b128 v[204:207], v144 offset:49152
	ds_read_b128 v[208:211], v144 offset:50176
	ds_read_b128 v[212:215], v143 offset:49152
	ds_read_b128 v[216:219], v143 offset:50176
	ds_read_b128 v[220:223], v142 offset:49152
	ds_read_b128 v[224:227], v142 offset:50176
	s_barrier
; #define STAGE(P, BASE, br, kt) do { const bf16_t* g_ = (BASE) + (size_t)(br) * K + (size_t)(kt) * 64; \
;         _Pragma("unroll") for (int i_ = 0; i_ < 2; ++i_) \
;             __builtin_amdgcn_global_load_lds((const unsigned*)(g_ + gofs[i_]), (lds_ptr_t)((P) + wb + i_ * 8192), 16, 0, 0); } while (0)
; #define LDA(dst, b, hh) _Pragma("unroll") for (int m = 0; m < 4; ++m) _Pragma("unroll") for (int k = 0; k < 2; ++k) \
;         dst[m][k] = *(const bf16x8*)(SA(b, hh) + lds_byte(wr * 64 + m * 16 + fr, k * 32 + fq * 8))
; #define LDB(dst, b, hh) _Pragma("unroll") for (int n = 0; n < 2; ++n) _Pragma("unroll") for (int k = 0; k < 2; ++k) \
;         dst[n][k] = *(const bf16x8*)(SB(b, hh) + lds_byte(wc * 32 + n * 16 + fr, k * 32 + fq * 8))
; #define MMA(ai, bj, At_, Bt_) do { __builtin_amdgcn_s_setprio(1); \
;         _Pragma("unroll") for (int m = 0; m < 4; ++m) _Pragma("unroll") for (int n = 0; n < 2; ++n) _Pragma("unroll") for (int k = 0; k < 2; ++k) \
;             acc[ai][bj][m][n] = MFMA16(At_[m][k], Bt_[n][k], acc[ai][bj][m][n]); \
;         __builtin_amdgcn_s_setprio(0); } while (0)
; #define WAIT_V(n) asm volatile("s_waitcnt vmcnt(" #n ")" ::: "memory")
; #define WAIT_L(n) asm volatile("s_waitcnt lgkmcnt(" #n ")" ::: "memory")
; #define BAR __builtin_amdgcn_s_barrier()
; #define SCHED __builtin_amdgcn_sched_barrier(0)
; #define STAGE(P, BASE, br, kt) do { const int sg_ = (kt) >> 3; const bf16_t* g_ = (sg_ == 0 ? BASE##0 : sg_ == 1 ? BASE##1 : BASE##2) + (size_t)(br) * K + (size_t)((kt) & 7) * 64; \
;         _Pragma("unroll") for (int i_ = 0; i_ < 2; ++i_) \
;             __builtin_amdgcn_global_load_lds((const unsigned*)(g_ + gofs[i_]), (lds_ptr_t)((P) + wb + i_ * 8192), 16, 0, 0); } while (0)
; #define LDA(dst, b, hh) _Pragma("unroll") for (int m = 0; m < 4; ++m) _Pragma("unroll") for (int k = 0; k < 2; ++k) \
;         dst[m][k] = *(const bf16x8*)(SA(b, hh) + lds_byte(wr * 64 + m * 16 + fr, k * 32 + fq * 8))
; #define BAR __builtin_amdgcn_s_barrier()
; DI void gemm8(f32x4 (&acc)[2][2][4][2], const bf16_t* __restrict__ Rm, const bf16_t* __restrict__ Cm, int K, char* shm) {
;     ...
;         BAR; WAIT_L(0); MMA(1, 0, At, B0); BAR; SCHED;
;         STAGE(SB(1, 1), Cm, 128, tt + 3);
;         WAIT_V(6); BAR; MMA(1, 1, At, B1); BAR;
;     }
;     { LDB(B0, 0, 0); LDA(At, 0, 0); STAGE(SA(1, 1), Rm, 128, nt - 1);
;       BAR; WAIT_L(0); MMA(0, 0, At, B0); BAR;
	s_waitcnt lgkmcnt(0)
	s_setprio 1
	s_waitcnt lgkmcnt(0)
	v_mfma_f32_16x16x32_bf16 v[62:65], v[196:199], v[168:171], v[62:65]
	v_mfma_f32_16x16x32_bf16 v[58:61], v[196:199], v[188:191], v[58:61]
	v_mfma_f32_16x16x32_bf16 v[54:57], v[204:207], v[168:171], v[54:57]
	v_mfma_f32_16x16x32_bf16 v[50:53], v[204:207], v[188:191], v[50:53]
	v_mfma_f32_16x16x32_bf16 v[46:49], v[212:215], v[168:171], v[46:49]
	v_mfma_f32_16x16x32_bf16 v[42:45], v[212:215], v[188:191], v[42:45]
	v_mfma_f32_16x16x32_bf16 v[38:41], v[220:223], v[168:171], v[38:41]
	v_mfma_f32_16x16x32_bf16 v[34:37], v[220:223], v[188:191], v[34:37]
	v_mfma_f32_16x16x32_bf16 v[62:65], v[200:203], v[184:187], v[62:65]
	v_mfma_f32_16x16x32_bf16 v[58:61], v[200:203], v[192:195], v[58:61]
	v_mfma_f32_16x16x32_bf16 v[54:57], v[208:211], v[184:187], v[54:57]
	v_mfma_f32_16x16x32_bf16 v[50:53], v[208:211], v[192:195], v[50:53]
	v_mfma_f32_16x16x32_bf16 v[46:49], v[216:219], v[184:187], v[46:49]
	v_mfma_f32_16x16x32_bf16 v[42:45], v[216:219], v[192:195], v[42:45]
	v_mfma_f32_16x16x32_bf16 v[38:41], v[224:227], v[184:187], v[38:41]
	v_mfma_f32_16x16x32_bf16 v[34:37], v[224:227], v[192:195], v[34:37]
	s_setprio 0
	s_barrier
	v_readfirstlane_b32 s3, v160
	v_lshl_add_u64 v[168:169], v[248:249], 0, s[16:17]
	s_mov_b32 m0, s3
	v_readfirstlane_b32 s3, v161
	global_load_lds_dwordx4 v[168:169], off
	v_lshl_add_u64 v[168:169], v[250:251], 0, s[16:17]
	s_mov_b32 m0, s3
	s_nop 0
	global_load_lds_dwordx4 v[168:169], off
	s_waitcnt vmcnt(6)
	s_barrier
	s_setprio 1
	v_mfma_f32_16x16x32_bf16 v[30:33], v[196:199], v[228:231], v[30:33]
	v_mfma_f32_16x16x32_bf16 v[26:29], v[196:199], v[236:239], v[26:29]
	v_mfma_f32_16x16x32_bf16 v[22:25], v[204:207], v[228:231], v[22:25]
	v_mfma_f32_16x16x32_bf16 v[18:21], v[204:207], v[236:239], v[18:21]
	v_mfma_f32_16x16x32_bf16 v[14:17], v[212:215], v[228:231], v[14:17]
	v_mfma_f32_16x16x32_bf16 v[10:13], v[212:215], v[236:239], v[10:13]
	v_mfma_f32_16x16x32_bf16 v[6:9], v[220:223], v[228:231], v[6:9]
	v_mfma_f32_16x16x32_bf16 v[2:5], v[220:223], v[236:239], v[2:5]
	v_mfma_f32_16x16x32_bf16 v[30:33], v[200:203], v[232:235], v[30:33]
	v_mfma_f32_16x16x32_bf16 v[26:29], v[200:203], v[240:243], v[26:29]
	v_mfma_f32_16x16x32_bf16 v[22:25], v[208:211], v[232:235], v[22:25]
	v_mfma_f32_16x16x32_bf16 v[18:21], v[208:211], v[240:243], v[18:21]
	v_mfma_f32_16x16x32_bf16 v[14:17], v[216:219], v[232:235], v[14:17]
	v_mfma_f32_16x16x32_bf16 v[10:13], v[216:219], v[240:243], v[10:13]
	v_mfma_f32_16x16x32_bf16 v[6:9], v[224:227], v[232:235], v[6:9]
	v_mfma_f32_16x16x32_bf16 v[2:5], v[224:227], v[240:243], v[2:5]
	s_setprio 0
	s_add_i32 s2, s2, 2
	v_lshl_add_u64 v[134:135], v[134:135], 0, s[90:91]
	v_lshl_add_u64 v[136:137], v[136:137], 0, s[90:91]
	v_lshl_add_u64 v[138:139], v[138:139], 0, s[90:91]
	s_cmp_lt_u32 s2, 12
	v_lshl_add_u64 v[140:141], v[140:141], 0, s[90:91]
	s_barrier
	s_cbranch_scc1 .LBB0_314
	s_add_u32 s2, s6, 0x40780
	s_addc_u32 s3, s7, 0
	v_readfirstlane_b32 s6, v166
	v_lshl_add_u64 v[130:131], v[130:131], 1, s[2:3]
	s_mov_b32 m0, s6
	ds_read_b128 v[134:137], v165
	ds_read_b128 v[138:141], v165 offset:1024
	ds_read_b128 v[150:153], v165 offset:2048
	ds_read_b128 v[156:159], v165 offset:3072
	ds_read_b128 v[168:171], v145
	ds_read_b128 v[184:187], v145 offset:1024
	ds_read_b128 v[188:191], v144
	ds_read_b128 v[192:195], v144 offset:1024
	ds_read_b128 v[196:199], v143
	ds_read_b128 v[200:203], v143 offset:1024
	ds_read_b128 v[204:207], v142
	ds_read_b128 v[208:211], v142 offset:1024
	global_load_lds_dwordx4 v[130:131], off
	v_lshl_add_u64 v[130:131], v[132:133], 1, s[2:3]
	v_readfirstlane_b32 s2, v167
	s_mov_b32 m0, s2
	s_nop 0
	global_load_lds_dwordx4 v[130:131], off
	s_barrier
	s_waitcnt lgkmcnt(0)
	s_setprio 1
	s_waitcnt lgkmcnt(0)
	v_mfma_f32_16x16x32_bf16 v[126:129], v[168:171], v[134:137], v[126:129]
	v_mfma_f32_16x16x32_bf16 v[122:125], v[168:171], v[150:153], v[122:125]
	v_mfma_f32_16x16x32_bf16 v[118:121], v[188:191], v[134:137], v[118:121]
	v_mfma_f32_16x16x32_bf16 v[114:117], v[188:191], v[150:153], v[114:117]
	v_mfma_f32_16x16x32_bf16 v[106:109], v[196:199], v[150:153], v[106:109]
	v_mfma_f32_16x16x32_bf16 v[98:101], v[204:207], v[150:153], v[98:101]
	v_mfma_f32_16x16x32_bf16 v[126:129], v[184:187], v[138:141], v[126:129]
	v_mfma_f32_16x16x32_bf16 v[122:125], v[184:187], v[156:159], v[122:125]
	v_mfma_f32_16x16x32_bf16 v[118:121], v[192:195], v[138:141], v[118:121]
	v_mfma_f32_16x16x32_bf16 v[114:117], v[192:195], v[156:159], v[114:117]
	v_mfma_f32_16x16x32_bf16 v[110:113], v[196:199], v[134:137], v[110:113]
	v_mfma_f32_16x16x32_bf16 v[106:109], v[200:203], v[156:159], v[106:109]
	v_mfma_f32_16x16x32_bf16 v[102:105], v[204:207], v[134:137], v[102:105]
	v_mfma_f32_16x16x32_bf16 v[98:101], v[208:211], v[156:159], v[98:101]
	v_mfma_f32_16x16x32_bf16 v[130:133], v[200:203], v[138:141], v[110:113]
	v_mfma_f32_16x16x32_bf16 v[212:215], v[208:211], v[138:141], v[102:105]
	s_setprio 0
	s_barrier
	s_nop 2
	ds_read_b128 v[102:105], v164
	ds_read_b128 v[110:113], v164 offset:1024
	ds_read_b128 v[216:219], v164 offset:2048
	ds_read_b128 v[164:167], v164 offset:3072
	s_barrier
; #define LDA(dst, b, hh) _Pragma("unroll") for (int m = 0; m < 4; ++m) _Pragma("unroll") for (int k = 0; k < 2; ++k) \
;         dst[m][k] = *(const bf16x8*)(SA(b, hh) + lds_byte(wr * 64 + m * 16 + fr, k * 32 + fq * 8))
; #define LDB(dst, b, hh) _Pragma("unroll") for (int n = 0; n < 2; ++n) _Pragma("unroll") for (int k = 0; k < 2; ++k) \
;         dst[n][k] = *(const bf16x8*)(SB(b, hh) + lds_byte(wc * 32 + n * 16 + fr, k * 32 + fq * 8))
; #define MMA(ai, bj, At_, Bt_) do { __builtin_amdgcn_s_setprio(1); \
;         _Pragma("unroll") for (int m = 0; m < 4; ++m) _Pragma("unroll") for (int n = 0; n < 2; ++n) _Pragma("unroll") for (int k = 0; k < 2; ++k) \
;             acc[ai][bj][m][n] = MFMA16(At_[m][k], Bt_[n][k], acc[ai][bj][m][n]); \
;         __builtin_amdgcn_s_setprio(0); } while (0)
; #define WAIT_V(n) asm volatile("s_waitcnt vmcnt(" #n ")" ::: "memory")
; #define WAIT_L(n) asm volatile("s_waitcnt lgkmcnt(" #n ")" ::: "memory")
; #define BAR __builtin_amdgcn_s_barrier()
; #define LDA(dst, b, hh) _Pragma("unroll") for (int m = 0; m < 4; ++m) _Pragma("unroll") for (int k = 0; k < 2; ++k) \
;         dst[m][k] = *(const bf16x8*)(SA(b, hh) + lds_byte(wr * 64 + m * 16 + fr, k * 32 + fq * 8))
; #define LDB(dst, b, hh) _Pragma("unroll") for (int n = 0; n < 2; ++n) _Pragma("unroll") for (int k = 0; k < 2; ++k) \
;         dst[n][k] = *(const bf16x8*)(SB(b, hh) + lds_byte(wc * 32 + n * 16 + fr, k * 32 + fq * 8))
; #define MMA(ai, bj, At_, Bt_) do { __builtin_amdgcn_s_setprio(1); \
;         _Pragma("unroll") for (int m = 0; m < 4; ++m) _Pragma("unroll") for (int n = 0; n < 2; ++n) _Pragma("unroll") for (int k = 0; k < 2; ++k) \
;             acc[ai][bj][m][n] = MFMA16(At_[m][k], Bt_[n][k], acc[ai][bj][m][n]); \
;         __builtin_amdgcn_s_setprio(0); } while (0)
; #define WAIT_V(n) asm volatile("s_waitcnt vmcnt(" #n ")" ::: "memory")
; #define WAIT_L(n) asm volatile("s_waitcnt lgkmcnt(" #n ")" ::: "memory")
; DI void gemm8(f32x4 (&acc)[2][2][4][2], const bf16_t* __restrict__ Rm, const bf16_t* __restrict__ Cm, int K, char* shm) {
;     ...
;       BAR; WAIT_L(0); MMA(0, 0, At, B0); BAR;
;       LDB(B1, 0, 1); BAR; WAIT_L(0); MMA(0, 1, At, B1); BAR;
;       LDA(At, 0, 1); WAIT_V(4); BAR; WAIT_L(0); MMA(1, 0, At, B0); MMA(1, 1, At, B1); BAR; }
;     { LDB(B0, 1, 0); LDA(At, 1, 0); WAIT_V(2); BAR; WAIT_L(0); MMA(0, 0, At, B0); BAR;
	s_waitcnt lgkmcnt(0)
	s_setprio 1
	s_waitcnt lgkmcnt(0)
	v_mfma_f32_16x16x32_bf16 v[90:93], v[168:171], v[216:219], v[90:93]
	v_mfma_f32_16x16x32_bf16 v[82:85], v[188:191], v[216:219], v[82:85]
	v_mfma_f32_16x16x32_bf16 v[74:77], v[196:199], v[216:219], v[74:77]
	v_mfma_f32_16x16x32_bf16 v[66:69], v[204:207], v[216:219], v[66:69]
	v_mfma_f32_16x16x32_bf16 v[94:97], v[168:171], v[102:105], v[94:97]
	v_mfma_f32_16x16x32_bf16 v[90:93], v[184:187], v[164:167], v[90:93]
	v_mfma_f32_16x16x32_bf16 v[86:89], v[188:191], v[102:105], v[86:89]
	v_mfma_f32_16x16x32_bf16 v[82:85], v[192:195], v[164:167], v[82:85]
	v_mfma_f32_16x16x32_bf16 v[78:81], v[196:199], v[102:105], v[78:81]
	v_mfma_f32_16x16x32_bf16 v[74:77], v[200:203], v[164:167], v[74:77]
	v_mfma_f32_16x16x32_bf16 v[70:73], v[204:207], v[102:105], v[70:73]
	v_mfma_f32_16x16x32_bf16 v[66:69], v[208:211], v[164:167], v[66:69]
	v_mfma_f32_16x16x32_bf16 v[220:223], v[184:187], v[110:113], v[94:97]
	v_mfma_f32_16x16x32_bf16 v[168:171], v[192:195], v[110:113], v[86:89]
	v_mfma_f32_16x16x32_bf16 v[184:187], v[200:203], v[110:113], v[78:81]
	v_mfma_f32_16x16x32_bf16 v[188:191], v[208:211], v[110:113], v[70:73]
	s_setprio 0
	s_barrier
	s_nop 0
	ds_read_b128 v[70:73], v145 offset:16384
	ds_read_b128 v[78:81], v145 offset:17408
	ds_read_b128 v[86:89], v144 offset:16384
	ds_read_b128 v[94:97], v144 offset:17408
	ds_read_b128 v[192:195], v143 offset:16384
	ds_read_b128 v[196:199], v143 offset:17408
	ds_read_b128 v[200:203], v142 offset:16384
	ds_read_b128 v[204:207], v142 offset:17408
	s_waitcnt vmcnt(4)
	s_barrier
	s_waitcnt lgkmcnt(0)
	s_setprio 1
	s_waitcnt lgkmcnt(0)
	v_mfma_f32_16x16x32_bf16 v[62:65], v[70:73], v[134:137], v[62:65]
	v_mfma_f32_16x16x32_bf16 v[58:61], v[70:73], v[150:153], v[58:61]
	v_mfma_f32_16x16x32_bf16 v[54:57], v[86:89], v[134:137], v[54:57]
	v_mfma_f32_16x16x32_bf16 v[50:53], v[86:89], v[150:153], v[50:53]
	v_mfma_f32_16x16x32_bf16 v[38:41], v[200:203], v[134:137], v[38:41]
	v_mfma_f32_16x16x32_bf16 v[34:37], v[200:203], v[150:153], v[34:37]
	v_mfma_f32_16x16x32_bf16 v[62:65], v[78:81], v[138:141], v[62:65]
	v_mfma_f32_16x16x32_bf16 v[58:61], v[78:81], v[156:159], v[58:61]
	v_mfma_f32_16x16x32_bf16 v[54:57], v[94:97], v[138:141], v[54:57]
	v_mfma_f32_16x16x32_bf16 v[50:53], v[94:97], v[156:159], v[50:53]
	v_mfma_f32_16x16x32_bf16 v[46:49], v[192:195], v[134:137], v[46:49]
	v_mfma_f32_16x16x32_bf16 v[42:45], v[192:195], v[150:153], v[42:45]
	v_mfma_f32_16x16x32_bf16 v[38:41], v[204:207], v[138:141], v[38:41]
	v_mfma_f32_16x16x32_bf16 v[34:37], v[204:207], v[156:159], v[34:37]
	v_mfma_f32_16x16x32_bf16 v[208:211], v[196:199], v[138:141], v[46:49]
	v_mfma_f32_16x16x32_bf16 v[224:227], v[196:199], v[156:159], v[42:45]
	s_setprio 0
	s_setprio 1
	v_mfma_f32_16x16x32_bf16 v[22:25], v[86:89], v[102:105], v[22:25]
	v_mfma_f32_16x16x32_bf16 v[18:21], v[86:89], v[216:219], v[18:21]
	v_mfma_f32_16x16x32_bf16 v[6:9], v[200:203], v[102:105], v[6:9]
	v_mfma_f32_16x16x32_bf16 v[2:5], v[200:203], v[216:219], v[2:5]
	v_mfma_f32_16x16x32_bf16 v[30:33], v[70:73], v[102:105], v[30:33]
	v_mfma_f32_16x16x32_bf16 v[26:29], v[70:73], v[216:219], v[26:29]
	v_mfma_f32_16x16x32_bf16 v[22:25], v[94:97], v[110:113], v[22:25]
	v_mfma_f32_16x16x32_bf16 v[18:21], v[94:97], v[164:167], v[18:21]
	v_mfma_f32_16x16x32_bf16 v[14:17], v[192:195], v[102:105], v[14:17]
	v_mfma_f32_16x16x32_bf16 v[10:13], v[192:195], v[216:219], v[10:13]
	v_mfma_f32_16x16x32_bf16 v[6:9], v[204:207], v[110:113], v[6:9]
	v_mfma_f32_16x16x32_bf16 v[2:5], v[204:207], v[164:167], v[2:5]
	v_mfma_f32_16x16x32_bf16 v[134:137], v[78:81], v[110:113], v[30:33]
	v_mfma_f32_16x16x32_bf16 v[138:141], v[78:81], v[164:167], v[26:29]
	v_mfma_f32_16x16x32_bf16 v[150:153], v[196:199], v[110:113], v[14:17]
	v_mfma_f32_16x16x32_bf16 v[156:159], v[196:199], v[164:167], v[10:13]
	s_setprio 0
	s_barrier
	s_nop 0
	ds_read_b128 v[10:13], v154
	ds_read_b128 v[14:17], v154 offset:1024
	ds_read_b128 v[164:167], v154 offset:2048
	ds_read_b128 v[192:195], v154 offset:3072
	ds_read_b128 v[26:29], v145 offset:32768
	ds_read_b128 v[30:33], v145 offset:33792
	ds_read_b128 v[42:45], v144 offset:32768
	ds_read_b128 v[46:49], v144 offset:33792
	ds_read_b128 v[196:199], v143 offset:32768
	ds_read_b128 v[200:203], v143 offset:33792
	ds_read_b128 v[204:207], v142 offset:32768
	ds_read_b128 v[216:219], v142 offset:33792
	s_waitcnt vmcnt(2)
	s_barrier
; #define LDA(dst, b, hh) _Pragma("unroll") for (int m = 0; m < 4; ++m) _Pragma("unroll") for (int k = 0; k < 2; ++k) \
;         dst[m][k] = *(const bf16x8*)(SA(b, hh) + lds_byte(wr * 64 + m * 16 + fr, k * 32 + fq * 8))
; #define LDB(dst, b, hh) _Pragma("unroll") for (int n = 0; n < 2; ++n) _Pragma("unroll") for (int k = 0; k < 2; ++k) \
;         dst[n][k] = *(const bf16x8*)(SB(b, hh) + lds_byte(wc * 32 + n * 16 + fr, k * 32 + fq * 8))
; #define MMA(ai, bj, At_, Bt_) do { __builtin_amdgcn_s_setprio(1); \
;         _Pragma("unroll") for (int m = 0; m < 4; ++m) _Pragma("unroll") for (int n = 0; n < 2; ++n) _Pragma("unroll") for (int k = 0; k < 2; ++k) \
;             acc[ai][bj][m][n] = MFMA16(At_[m][k], Bt_[n][k], acc[ai][bj][m][n]); \
;         __builtin_amdgcn_s_setprio(0); } while (0)
; #define WAIT_V(n) asm volatile("s_waitcnt vmcnt(" #n ")" ::: "memory")
; #define WAIT_L(n) asm volatile("s_waitcnt lgkmcnt(" #n ")" ::: "memory")
; #define BAR __builtin_amdgcn_s_barrier()
; #define LDA(dst, b, hh) _Pragma("unroll") for (int m = 0; m < 4; ++m) _Pragma("unroll") for (int k = 0; k < 2; ++k) \
;         dst[m][k] = *(const bf16x8*)(SA(b, hh) + lds_byte(wr * 64 + m * 16 + fr, k * 32 + fq * 8))
; #define LDB(dst, b, hh) _Pragma("unroll") for (int n = 0; n < 2; ++n) _Pragma("unroll") for (int k = 0; k < 2; ++k) \
;         dst[n][k] = *(const bf16x8*)(SB(b, hh) + lds_byte(wc * 32 + n * 16 + fr, k * 32 + fq * 8))
; #define MMA(ai, bj, At_, Bt_) do { __builtin_amdgcn_s_setprio(1); \
;         _Pragma("unroll") for (int m = 0; m < 4; ++m) _Pragma("unroll") for (int n = 0; n < 2; ++n) _Pragma("unroll") for (int k = 0; k < 2; ++k) \
;             acc[ai][bj][m][n] = MFMA16(At_[m][k], Bt_[n][k], acc[ai][bj][m][n]); \
;         __builtin_amdgcn_s_setprio(0); } while (0)
; #define WAIT_V(n) asm volatile("s_waitcnt vmcnt(" #n ")" ::: "memory")
; #define WAIT_L(n) asm volatile("s_waitcnt lgkmcnt(" #n ")" ::: "memory")
; #define BAR __builtin_amdgcn_s_barrier()
; DI void gemm8(f32x4 (&acc)[2][2][4][2], const bf16_t* __restrict__ Rm, const bf16_t* __restrict__ Cm, int K, char* shm) {
;     ...
;     { LDB(B0, 1, 0); LDA(At, 1, 0); WAIT_V(2); BAR; WAIT_L(0); MMA(0, 0, At, B0); BAR;
;       LDB(B1, 1, 1); WAIT_V(0); BAR; WAIT_L(0); MMA(0, 1, At, B1); BAR;
;       LDA(At, 1, 1); BAR; WAIT_L(0); MMA(1, 0, At, B0); MMA(1, 1, At, B1); BAR; }
;     if (wr == 0) BAR;
	s_waitcnt lgkmcnt(0)
	s_setprio 1
	s_waitcnt lgkmcnt(0)
	v_mfma_f32_16x16x32_bf16 v[70:73], v[26:29], v[10:13], v[126:129]
	v_mfma_f32_16x16x32_bf16 v[126:129], v[30:33], v[14:17], v[70:73]
	v_mfma_f32_16x16x32_bf16 v[70:73], v[26:29], v[164:167], v[122:125]
	v_mfma_f32_16x16x32_bf16 v[122:125], v[30:33], v[192:195], v[70:73]
	v_mfma_f32_16x16x32_bf16 v[70:73], v[42:45], v[10:13], v[118:121]
	v_mfma_f32_16x16x32_bf16 v[110:113], v[46:49], v[14:17], v[70:73]
	v_mfma_f32_16x16x32_bf16 v[70:73], v[42:45], v[164:167], v[114:117]
	v_mfma_f32_16x16x32_bf16 v[102:105], v[46:49], v[192:195], v[70:73]
	v_mfma_f32_16x16x32_bf16 v[70:73], v[196:199], v[10:13], v[130:133]
	v_mfma_f32_16x16x32_bf16 v[94:97], v[200:203], v[14:17], v[70:73]
	v_mfma_f32_16x16x32_bf16 v[70:73], v[196:199], v[164:167], v[106:109]
	v_mfma_f32_16x16x32_bf16 v[86:89], v[200:203], v[192:195], v[70:73]
	v_mfma_f32_16x16x32_bf16 v[70:73], v[204:207], v[10:13], v[212:215]
	v_mfma_f32_16x16x32_bf16 v[78:81], v[216:219], v[14:17], v[70:73]
	v_mfma_f32_16x16x32_bf16 v[70:73], v[204:207], v[164:167], v[98:101]
	v_mfma_f32_16x16x32_bf16 v[70:73], v[216:219], v[192:195], v[70:73]
	s_setprio 0
	s_barrier
	ds_read_b128 v[130:133], v149
	ds_read_b128 v[212:215], v149 offset:1024
	ds_read_b128 v[228:231], v149 offset:2048
	ds_read_b128 v[146:149], v149 offset:3072
	s_waitcnt vmcnt(0)
	s_barrier
	s_waitcnt lgkmcnt(0)
	s_setprio 1
	s_waitcnt lgkmcnt(0)
	v_mfma_f32_16x16x32_bf16 v[98:101], v[26:29], v[130:133], v[220:223]
	v_mfma_f32_16x16x32_bf16 v[26:29], v[26:29], v[228:231], v[90:93]
	v_mfma_f32_16x16x32_bf16 v[114:117], v[30:33], v[146:149], v[26:29]
	v_mfma_f32_16x16x32_bf16 v[26:29], v[42:45], v[130:133], v[168:171]
	v_mfma_f32_16x16x32_bf16 v[106:109], v[46:49], v[212:215], v[26:29]
	v_mfma_f32_16x16x32_bf16 v[26:29], v[42:45], v[228:231], v[82:85]
	v_mfma_f32_16x16x32_bf16 v[118:121], v[30:33], v[212:215], v[98:101]
	v_mfma_f32_16x16x32_bf16 v[98:101], v[46:49], v[146:149], v[26:29]
	v_mfma_f32_16x16x32_bf16 v[26:29], v[196:199], v[130:133], v[184:187]
	v_mfma_f32_16x16x32_bf16 v[90:93], v[200:203], v[212:215], v[26:29]
	v_mfma_f32_16x16x32_bf16 v[26:29], v[196:199], v[228:231], v[74:77]
	v_mfma_f32_16x16x32_bf16 v[82:85], v[200:203], v[146:149], v[26:29]
	v_mfma_f32_16x16x32_bf16 v[26:29], v[204:207], v[130:133], v[188:191]
	v_mfma_f32_16x16x32_bf16 v[74:77], v[216:219], v[212:215], v[26:29]
	v_mfma_f32_16x16x32_bf16 v[26:29], v[204:207], v[228:231], v[66:69]
	v_mfma_f32_16x16x32_bf16 v[66:69], v[216:219], v[146:149], v[26:29]
	s_setprio 0
	s_barrier
	ds_read_b128 v[168:171], v145 offset:49152
	ds_read_b128 v[184:187], v145 offset:50176
	ds_read_b128 v[188:191], v144 offset:49152
	ds_read_b128 v[196:199], v144 offset:50176
	ds_read_b128 v[200:203], v143 offset:49152
	ds_read_b128 v[204:207], v143 offset:50176
	ds_read_b128 v[216:219], v142 offset:49152
	ds_read_b128 v[142:145], v142 offset:50176
	s_barrier
	s_waitcnt lgkmcnt(0)
	s_setprio 1
	s_waitcnt lgkmcnt(0)
	v_mfma_f32_16x16x32_bf16 v[26:29], v[168:171], v[10:13], v[62:65]
	v_mfma_f32_16x16x32_bf16 v[62:65], v[184:187], v[14:17], v[26:29]
	v_mfma_f32_16x16x32_bf16 v[26:29], v[168:171], v[164:167], v[58:61]
	v_mfma_f32_16x16x32_bf16 v[58:61], v[184:187], v[192:195], v[26:29]
	v_mfma_f32_16x16x32_bf16 v[26:29], v[188:191], v[10:13], v[54:57]
	v_mfma_f32_16x16x32_bf16 v[46:49], v[196:199], v[14:17], v[26:29]
	v_mfma_f32_16x16x32_bf16 v[26:29], v[188:191], v[164:167], v[50:53]
	v_mfma_f32_16x16x32_bf16 v[42:45], v[196:199], v[192:195], v[26:29]
	v_mfma_f32_16x16x32_bf16 v[26:29], v[200:203], v[10:13], v[208:211]
	v_mfma_f32_16x16x32_bf16 v[10:13], v[216:219], v[10:13], v[38:41]
	v_mfma_f32_16x16x32_bf16 v[30:33], v[204:207], v[14:17], v[26:29]
	v_mfma_f32_16x16x32_bf16 v[26:29], v[200:203], v[164:167], v[224:227]
	v_mfma_f32_16x16x32_bf16 v[14:17], v[142:145], v[14:17], v[10:13]
	v_mfma_f32_16x16x32_bf16 v[10:13], v[216:219], v[164:167], v[34:37]
	v_mfma_f32_16x16x32_bf16 v[26:29], v[204:207], v[192:195], v[26:29]
	v_mfma_f32_16x16x32_bf16 v[10:13], v[142:145], v[192:195], v[10:13]
	s_setprio 0
	s_setprio 1
	v_mfma_f32_16x16x32_bf16 v[34:37], v[168:171], v[130:133], v[134:137]
	v_mfma_f32_16x16x32_bf16 v[54:57], v[184:187], v[212:215], v[34:37]
	v_mfma_f32_16x16x32_bf16 v[34:37], v[168:171], v[228:231], v[138:141]
	v_mfma_f32_16x16x32_bf16 v[18:21], v[188:191], v[228:231], v[18:21]
	v_mfma_f32_16x16x32_bf16 v[50:53], v[184:187], v[146:149], v[34:37]
	v_mfma_f32_16x16x32_bf16 v[22:25], v[188:191], v[130:133], v[22:25]
	v_mfma_f32_16x16x32_bf16 v[34:37], v[196:199], v[146:149], v[18:21]
	v_mfma_f32_16x16x32_bf16 v[18:21], v[200:203], v[130:133], v[150:153]
	v_mfma_f32_16x16x32_bf16 v[38:41], v[196:199], v[212:215], v[22:25]
	v_mfma_f32_16x16x32_bf16 v[22:25], v[204:207], v[212:215], v[18:21]
	v_mfma_f32_16x16x32_bf16 v[18:21], v[200:203], v[228:231], v[156:159]
	v_mfma_f32_16x16x32_bf16 v[6:9], v[216:219], v[130:133], v[6:9]
	v_mfma_f32_16x16x32_bf16 v[2:5], v[216:219], v[228:231], v[2:5]
	v_mfma_f32_16x16x32_bf16 v[18:21], v[204:207], v[146:149], v[18:21]
	v_mfma_f32_16x16x32_bf16 v[6:9], v[142:145], v[212:215], v[6:9]
	v_mfma_f32_16x16x32_bf16 v[2:5], v[142:145], v[146:149], v[2:5]
	s_setprio 0
	v_cmp_gt_u32_e32 vcc, s96, v0
	s_barrier
	s_and_saveexec_b64 s[6:7], vcc
	s_cbranch_execz .LBB0_317
	s_barrier
